# removed all s_setprio flips (240) from GEMM K-loops
# speedup vs baseline: 1.0006x; 1.0006x over previous
; #define PG8_STAGE(bufoff, gbase, voff) do { _Pragma("unroll") for (int _i = 0; _i < 2; ++_i) \
;         __builtin_amdgcn_global_load_lds((const unsigned*)((const char*)(gbase) + (voff)[_i]), (PG8_LAS unsigned*)(lds + (bufoff) + ldsw + _i * 8192), 16, 0, 0); } while (0)
; #define PG8_LDA(dst, b, h) do { _Pragma("unroll") for (int m = 0; m < 4; ++m) _Pragma("unroll") for (int k = 0; k < 2; ++k) dst[m][k] = *(const PG8_LAS bf16x8*)(lds + PG8_SA(b, h) + aoff + m * 2048 + k * 1024); } while (0)
; #define PG8_LDB(dst, b, h) do { _Pragma("unroll") for (int n = 0; n < 2; ++n) _Pragma("unroll") for (int k = 0; k < 2; ++k) dst[n][k] = *(const PG8_LAS bf16x8*)(lds + PG8_SB(b, h) + boff + n * 2048 + k * 1024); } while (0)
; #define PG8_WAIT_V(n) asm volatile("s_waitcnt vmcnt(" #n ")" ::: "memory")
; #define PG8_WAIT_L(n) asm volatile("s_waitcnt lgkmcnt(" #n ")" ::: "memory")
; #define PG8_BAR __builtin_amdgcn_s_barrier()
; template <class Epi, class Sched, bool ALIGN_EPI = false, bool SP2 = false>
; __device__ __forceinline__ void gemm_phase(PG8_LAS unsigned char* lds, const Gemm g, const Sched& S, const Epi& E) {
;     ...
;         const char* nA = has_next ? (const char*)g.A + (size_t)nxt.pm * tstep + (size_t)nxt.kt0 * kstep : cA; const char* nB = has_next ? (const char*)g.Bt + (size_t)nxt.pn * tstep + (size_t)nxt.kt0 * kstep : cB;
;         for (int t = 0; t < nt; t += 2) {
;             if constexpr (Epi::MIDHOOK) { if (t == (nt >> 1)) E.mid(acc, cur, wr, wc, fr, fq); }
;             const bool last = (t == nt - 2);
;             const char* a1 = cA + (size_t)(t + 1) * kstep;
;             const char* a2 = last ? nA : cA + (size_t)(t + 2) * kstep; const char* b2 = last ? nB : cB + (size_t)(t + 2) * kstep;
;             const char* a3 = a2 + kstep; const char* b3 = b2 + kstep;
;             if (last && has_next) S.a_ready(nxt);
;             if constexpr (SP2) {
;             PG8_LDB(B0, 0, 0); PG8_LDB(B1, 0, 1); PG8_SCHED; PG8_LDA(At, 0, 0); PG8_STAGE(PG8_SA(1, 1), a1 + hstep, voffA);
;             PG8_WAIT_V(8); PG8_WAIT_L(0); PG8_BAR; PG8_MMA(0, 0, At, B0); PG8_MMA(0, 1, At, B1); PG8_BAR; PG8_SCHED;
;             PG8_LDA(At, 0, 1); PG8_STAGE(PG8_SB(0, 0), b2, voffB); PG8_STAGE(PG8_SB(0, 1), b2 + hstep, voffB); PG8_STAGE(PG8_SA(0, 0), a2, voffA);
;             PG8_WAIT_V(8); PG8_WAIT_L(0); PG8_BAR; PG8_MMA(1, 0, At, B0); PG8_MMA(1, 1, At, B1); PG8_BAR; PG8_SCHED;
.LBB0_88:
	ds_read_b128 v[146:149], v153
	ds_read_b128 v[156:159], v153 offset:1024
	ds_read_b128 v[160:163], v153 offset:2048
	ds_read_b128 v[164:167], v153 offset:3072
	ds_read_b128 v[168:171], v154
	ds_read_b128 v[172:175], v154 offset:1024
	ds_read_b128 v[176:179], v154 offset:2048
	ds_read_b128 v[180:183], v154 offset:3072
	s_add_u32 s42, s40, 0xfff80080
	s_addc_u32 s43, s41, -1
	s_cmp_eq_u32 s52, 28
	s_cselect_b32 s45, s21, s43
	s_cselect_b32 s44, s48, s42
	s_cselect_b32 s43, s15, s51
	s_cselect_b32 s42, s49, s50
	v_lshl_add_u64 v[216:217], s[40:41], 0, v[138:139]
	s_add_i32 m0, s19, 0xc000
	ds_read_b128 v[184:187], v155
	ds_read_b128 v[188:191], v155 offset:1024
	ds_read_b128 v[192:195], v155 offset:2048
	ds_read_b128 v[196:199], v155 offset:3072
	ds_read_b128 v[200:203], v155 offset:4096
	ds_read_b128 v[204:207], v155 offset:5120
	ds_read_b128 v[208:211], v155 offset:6144
	ds_read_b128 v[212:215], v155 offset:7168
	global_load_lds_dwordx4 v[216:217], off
	v_lshl_add_u64 v[216:217], s[40:41], 0, v[140:141]
	s_add_i32 m0, s19, 0xe000
	s_nop 0
	global_load_lds_dwordx4 v[216:217], off
	s_waitcnt vmcnt(8)
	s_waitcnt lgkmcnt(0)
	s_barrier
	s_waitcnt lgkmcnt(0)
	v_mfma_f32_16x16x32_bf16 v[126:129], v[146:149], v[184:187], v[126:129]
	v_mfma_f32_16x16x32_bf16 v[122:125], v[160:163], v[184:187], v[122:125]
	v_mfma_f32_16x16x32_bf16 v[110:113], v[146:149], v[192:195], v[110:113]
	v_mfma_f32_16x16x32_bf16 v[106:109], v[160:163], v[192:195], v[106:109]
	v_mfma_f32_16x16x32_bf16 v[94:97], v[146:149], v[200:203], v[94:97]
	v_mfma_f32_16x16x32_bf16 v[90:93], v[160:163], v[200:203], v[90:93]
	v_mfma_f32_16x16x32_bf16 v[78:81], v[146:149], v[208:211], v[78:81]
	v_mfma_f32_16x16x32_bf16 v[74:77], v[160:163], v[208:211], v[74:77]
	v_mfma_f32_16x16x32_bf16 v[126:129], v[156:159], v[188:191], v[126:129]
	v_mfma_f32_16x16x32_bf16 v[122:125], v[164:167], v[188:191], v[122:125]
	v_mfma_f32_16x16x32_bf16 v[110:113], v[156:159], v[196:199], v[110:113]
	v_mfma_f32_16x16x32_bf16 v[106:109], v[164:167], v[196:199], v[106:109]
	v_mfma_f32_16x16x32_bf16 v[94:97], v[156:159], v[204:207], v[94:97]
	v_mfma_f32_16x16x32_bf16 v[90:93], v[164:167], v[204:207], v[90:93]
	v_mfma_f32_16x16x32_bf16 v[78:81], v[156:159], v[212:215], v[78:81]
	v_mfma_f32_16x16x32_bf16 v[74:77], v[164:167], v[212:215], v[74:77]
	v_mfma_f32_16x16x32_bf16 v[118:121], v[168:171], v[184:187], v[118:121]
	v_mfma_f32_16x16x32_bf16 v[114:117], v[176:179], v[184:187], v[114:117]
	v_mfma_f32_16x16x32_bf16 v[102:105], v[168:171], v[192:195], v[102:105]
	v_mfma_f32_16x16x32_bf16 v[98:101], v[176:179], v[192:195], v[98:101]
	v_mfma_f32_16x16x32_bf16 v[86:89], v[168:171], v[200:203], v[86:89]
	v_mfma_f32_16x16x32_bf16 v[82:85], v[176:179], v[200:203], v[82:85]
	v_mfma_f32_16x16x32_bf16 v[70:73], v[168:171], v[208:211], v[70:73]
	v_mfma_f32_16x16x32_bf16 v[66:69], v[176:179], v[208:211], v[66:69]
	v_mfma_f32_16x16x32_bf16 v[118:121], v[172:175], v[188:191], v[118:121]
	v_mfma_f32_16x16x32_bf16 v[114:117], v[180:183], v[188:191], v[114:117]
	v_mfma_f32_16x16x32_bf16 v[102:105], v[172:175], v[196:199], v[102:105]
	v_mfma_f32_16x16x32_bf16 v[98:101], v[180:183], v[196:199], v[98:101]
	v_mfma_f32_16x16x32_bf16 v[86:89], v[172:175], v[204:207], v[86:89]
	v_mfma_f32_16x16x32_bf16 v[82:85], v[180:183], v[204:207], v[82:85]
	v_mfma_f32_16x16x32_bf16 v[70:73], v[172:175], v[212:215], v[70:73]
	v_mfma_f32_16x16x32_bf16 v[66:69], v[180:183], v[212:215], v[66:69]
	s_barrier
	s_add_i32 s53, s31, s16
	v_lshl_add_u64 v[216:217], s[42:43], 0, v[134:135]
	s_mov_b32 m0, s53
	ds_read_b128 v[184:187], v155 offset:16384
	ds_read_b128 v[188:191], v155 offset:17408
	ds_read_b128 v[192:195], v155 offset:18432
	ds_read_b128 v[196:199], v155 offset:19456
	ds_read_b128 v[200:203], v155 offset:20480
	ds_read_b128 v[204:207], v155 offset:21504
	ds_read_b128 v[208:211], v155 offset:22528
	ds_read_b128 v[212:215], v155 offset:23552
	global_load_lds_dwordx4 v[216:217], off
	s_add_i32 m0, s53, 0x2000
	s_add_u32 s54, s42, 0x80000
	v_lshl_add_u64 v[218:219], s[42:43], 0, v[130:131]
	s_addc_u32 s55, s43, 0
	s_add_i32 s53, s39, s16
	global_load_lds_dwordx4 v[218:219], off
	v_lshl_add_u64 v[220:221], s[54:55], 0, v[134:135]
	s_mov_b32 m0, s53
	v_lshl_add_u64 v[222:223], s[44:45], 0, v[132:133]
	global_load_lds_dwordx4 v[220:221], off
	v_lshl_add_u64 v[220:221], s[54:55], 0, v[130:131]
	s_add_i32 m0, s53, 0x2000
	s_nop 0
	global_load_lds_dwordx4 v[220:221], off
	v_lshl_add_u64 v[220:221], s[44:45], 0, v[136:137]
	s_mov_b32 m0, s19
	s_nop 0
	global_load_lds_dwordx4 v[220:221], off
	s_mov_b32 m0, s24
	s_nop 0
	global_load_lds_dwordx4 v[222:223], off
	s_waitcnt vmcnt(8)
	s_waitcnt lgkmcnt(0)
	s_barrier
; #define PG8_STAGE(bufoff, gbase, voff) do { _Pragma("unroll") for (int _i = 0; _i < 2; ++_i) \
;         __builtin_amdgcn_global_load_lds((const unsigned*)((const char*)(gbase) + (voff)[_i]), (PG8_LAS unsigned*)(lds + (bufoff) + ldsw + _i * 8192), 16, 0, 0); } while (0)
; #define PG8_LDA(dst, b, h) do { _Pragma("unroll") for (int m = 0; m < 4; ++m) _Pragma("unroll") for (int k = 0; k < 2; ++k) dst[m][k] = *(const PG8_LAS bf16x8*)(lds + PG8_SA(b, h) + aoff + m * 2048 + k * 1024); } while (0)
; #define PG8_LDB(dst, b, h) do { _Pragma("unroll") for (int n = 0; n < 2; ++n) _Pragma("unroll") for (int k = 0; k < 2; ++k) dst[n][k] = *(const PG8_LAS bf16x8*)(lds + PG8_SB(b, h) + boff + n * 2048 + k * 1024); } while (0)
; #define PG8_MMA(ai, bj, At, Bt) do { __builtin_amdgcn_s_setprio(1); _Pragma("unroll") for (int m = 0; m < 4; ++m) _Pragma("unroll") for (int n = 0; n < 2; ++n) _Pragma("unroll") for (int k = 0; k < 2; ++k) \
;         acc[ai][bj][m][n] = __builtin_amdgcn_mfma_f32_16x16x32_bf16(Bt[n][k], At[m][k], acc[ai][bj][m][n], 0, 0, 0); __builtin_amdgcn_s_setprio(0); } while (0)
; #define PG8_WAIT_V(n) asm volatile("s_waitcnt vmcnt(" #n ")" ::: "memory")
; #define PG8_WAIT_L(n) asm volatile("s_waitcnt lgkmcnt(" #n ")" ::: "memory")
; #define PG8_BAR __builtin_amdgcn_s_barrier()
; #define PG8_SCHED __builtin_amdgcn_sched_barrier(0)
; template <class Epi, class Sched, bool ALIGN_EPI = false, bool SP2 = false>
; __device__ __forceinline__ void gemm_phase(PG8_LAS unsigned char* lds, const Gemm g, const Sched& S, const Epi& E) {
;     ...
;             PG8_WAIT_V(8); PG8_WAIT_L(0); PG8_BAR; PG8_MMA(1, 0, At, B0); PG8_MMA(1, 1, At, B1); PG8_BAR; PG8_SCHED;
;             PG8_LDB(B0, 1, 0); PG8_LDB(B1, 1, 1); PG8_SCHED; PG8_LDA(At, 1, 0); PG8_STAGE(PG8_SA(0, 1), a2 + hstep, voffA);
;             PG8_WAIT_V(8); PG8_WAIT_L(0); PG8_BAR; PG8_MMA(0, 0, At, B0); PG8_MMA(0, 1, At, B1); PG8_BAR; PG8_SCHED;
;             PG8_LDA(At, 1, 1); PG8_STAGE(PG8_SB(1, 0), b3, voffB); PG8_STAGE(PG8_SB(1, 1), b3 + hstep, voffB); PG8_STAGE(PG8_SA(1, 0), a3, voffA);
	s_waitcnt lgkmcnt(0)
	v_mfma_f32_16x16x32_bf16 v[62:65], v[146:149], v[184:187], v[62:65]
	v_mfma_f32_16x16x32_bf16 v[58:61], v[160:163], v[184:187], v[58:61]
	v_mfma_f32_16x16x32_bf16 v[46:49], v[146:149], v[192:195], v[46:49]
	v_mfma_f32_16x16x32_bf16 v[42:45], v[160:163], v[192:195], v[42:45]
	v_mfma_f32_16x16x32_bf16 v[30:33], v[146:149], v[200:203], v[30:33]
	v_mfma_f32_16x16x32_bf16 v[26:29], v[160:163], v[200:203], v[26:29]
	v_mfma_f32_16x16x32_bf16 v[14:17], v[146:149], v[208:211], v[14:17]
	v_mfma_f32_16x16x32_bf16 v[10:13], v[160:163], v[208:211], v[10:13]
	v_mfma_f32_16x16x32_bf16 v[62:65], v[156:159], v[188:191], v[62:65]
	v_mfma_f32_16x16x32_bf16 v[58:61], v[164:167], v[188:191], v[58:61]
	v_mfma_f32_16x16x32_bf16 v[46:49], v[156:159], v[196:199], v[46:49]
	v_mfma_f32_16x16x32_bf16 v[42:45], v[164:167], v[196:199], v[42:45]
	v_mfma_f32_16x16x32_bf16 v[30:33], v[156:159], v[204:207], v[30:33]
	v_mfma_f32_16x16x32_bf16 v[26:29], v[164:167], v[204:207], v[26:29]
	v_mfma_f32_16x16x32_bf16 v[14:17], v[156:159], v[212:215], v[14:17]
	v_mfma_f32_16x16x32_bf16 v[10:13], v[164:167], v[212:215], v[10:13]
	v_mfma_f32_16x16x32_bf16 v[54:57], v[168:171], v[184:187], v[54:57]
	v_mfma_f32_16x16x32_bf16 v[50:53], v[176:179], v[184:187], v[50:53]
	v_mfma_f32_16x16x32_bf16 v[38:41], v[168:171], v[192:195], v[38:41]
	v_mfma_f32_16x16x32_bf16 v[34:37], v[176:179], v[192:195], v[34:37]
	v_mfma_f32_16x16x32_bf16 v[22:25], v[168:171], v[200:203], v[22:25]
	v_mfma_f32_16x16x32_bf16 v[18:21], v[176:179], v[200:203], v[18:21]
	v_mfma_f32_16x16x32_bf16 v[6:9], v[168:171], v[208:211], v[6:9]
	v_mfma_f32_16x16x32_bf16 v[2:5], v[176:179], v[208:211], v[2:5]
	v_mfma_f32_16x16x32_bf16 v[54:57], v[172:175], v[188:191], v[54:57]
	v_mfma_f32_16x16x32_bf16 v[50:53], v[180:183], v[188:191], v[50:53]
	v_mfma_f32_16x16x32_bf16 v[38:41], v[172:175], v[196:199], v[38:41]
	v_mfma_f32_16x16x32_bf16 v[34:37], v[180:183], v[196:199], v[34:37]
	v_mfma_f32_16x16x32_bf16 v[22:25], v[172:175], v[204:207], v[22:25]
	v_mfma_f32_16x16x32_bf16 v[18:21], v[180:183], v[204:207], v[18:21]
	v_mfma_f32_16x16x32_bf16 v[6:9], v[172:175], v[212:215], v[6:9]
	v_mfma_f32_16x16x32_bf16 v[2:5], v[180:183], v[212:215], v[2:5]
	s_barrier
	s_add_i32 s53, 0, 0x18000
	s_add_i32 s54, 0, 0x1c000
	v_add_u32_e32 v164, s53, v151
	v_add_u32_e32 v180, s54, v151
	ds_read_b128 v[146:149], v164
	ds_read_b128 v[156:159], v164 offset:1024
	ds_read_b128 v[160:163], v164 offset:2048
	ds_read_b128 v[164:167], v164 offset:3072
	ds_read_b128 v[168:171], v180
	ds_read_b128 v[172:175], v180 offset:1024
	ds_read_b128 v[176:179], v180 offset:2048
	ds_read_b128 v[180:183], v180 offset:3072
	s_add_u32 s44, s44, 0x80000
	s_addc_u32 s45, s45, 0
	s_mov_b32 m0, s25
	v_lshl_add_u64 v[224:225], s[44:45], 0, v[136:137]
	ds_read_b128 v[184:187], v155 offset:32768
	ds_read_b128 v[188:191], v155 offset:33792
	ds_read_b128 v[192:195], v155 offset:34816
	ds_read_b128 v[196:199], v155 offset:35840
	ds_read_b128 v[200:203], v155 offset:36864
	ds_read_b128 v[204:207], v155 offset:37888
	ds_read_b128 v[208:211], v155 offset:38912
	ds_read_b128 v[212:215], v155 offset:39936
	global_load_lds_dwordx4 v[224:225], off
	v_lshl_add_u64 v[224:225], s[44:45], 0, v[132:133]
	s_mov_b32 m0, s26
	s_nop 0
	global_load_lds_dwordx4 v[224:225], off
	s_waitcnt vmcnt(8)
	s_waitcnt lgkmcnt(0)
	s_barrier
	s_waitcnt lgkmcnt(0)
	v_mfma_f32_16x16x32_bf16 v[126:129], v[146:149], v[184:187], v[126:129]
	v_mfma_f32_16x16x32_bf16 v[122:125], v[160:163], v[184:187], v[122:125]
	v_mfma_f32_16x16x32_bf16 v[110:113], v[146:149], v[192:195], v[110:113]
	v_mfma_f32_16x16x32_bf16 v[106:109], v[160:163], v[192:195], v[106:109]
	v_mfma_f32_16x16x32_bf16 v[94:97], v[146:149], v[200:203], v[94:97]
	v_mfma_f32_16x16x32_bf16 v[90:93], v[160:163], v[200:203], v[90:93]
	v_mfma_f32_16x16x32_bf16 v[78:81], v[146:149], v[208:211], v[78:81]
	v_mfma_f32_16x16x32_bf16 v[74:77], v[160:163], v[208:211], v[74:77]
	v_mfma_f32_16x16x32_bf16 v[126:129], v[156:159], v[188:191], v[126:129]
	v_mfma_f32_16x16x32_bf16 v[122:125], v[164:167], v[188:191], v[122:125]
	v_mfma_f32_16x16x32_bf16 v[110:113], v[156:159], v[196:199], v[110:113]
	v_mfma_f32_16x16x32_bf16 v[106:109], v[164:167], v[196:199], v[106:109]
	v_mfma_f32_16x16x32_bf16 v[94:97], v[156:159], v[204:207], v[94:97]
	v_mfma_f32_16x16x32_bf16 v[90:93], v[164:167], v[204:207], v[90:93]
	v_mfma_f32_16x16x32_bf16 v[78:81], v[156:159], v[212:215], v[78:81]
	v_mfma_f32_16x16x32_bf16 v[74:77], v[164:167], v[212:215], v[74:77]
	v_mfma_f32_16x16x32_bf16 v[118:121], v[168:171], v[184:187], v[118:121]
	v_mfma_f32_16x16x32_bf16 v[114:117], v[176:179], v[184:187], v[114:117]
	v_mfma_f32_16x16x32_bf16 v[102:105], v[168:171], v[192:195], v[102:105]
	v_mfma_f32_16x16x32_bf16 v[98:101], v[176:179], v[192:195], v[98:101]
	v_mfma_f32_16x16x32_bf16 v[86:89], v[168:171], v[200:203], v[86:89]
	v_mfma_f32_16x16x32_bf16 v[82:85], v[176:179], v[200:203], v[82:85]
	v_mfma_f32_16x16x32_bf16 v[70:73], v[168:171], v[208:211], v[70:73]
	v_mfma_f32_16x16x32_bf16 v[66:69], v[176:179], v[208:211], v[66:69]
	v_mfma_f32_16x16x32_bf16 v[118:121], v[172:175], v[188:191], v[118:121]
	v_mfma_f32_16x16x32_bf16 v[114:117], v[180:183], v[188:191], v[114:117]
	v_mfma_f32_16x16x32_bf16 v[102:105], v[172:175], v[196:199], v[102:105]
	v_mfma_f32_16x16x32_bf16 v[98:101], v[180:183], v[196:199], v[98:101]
	v_mfma_f32_16x16x32_bf16 v[86:89], v[172:175], v[204:207], v[86:89]
	v_mfma_f32_16x16x32_bf16 v[82:85], v[180:183], v[204:207], v[82:85]
	v_mfma_f32_16x16x32_bf16 v[70:73], v[172:175], v[212:215], v[70:73]
	v_mfma_f32_16x16x32_bf16 v[66:69], v[180:183], v[212:215], v[66:69]
	s_barrier
; #define PG8_STAGE(bufoff, gbase, voff) do { _Pragma("unroll") for (int _i = 0; _i < 2; ++_i) \
;         __builtin_amdgcn_global_load_lds((const unsigned*)((const char*)(gbase) + (voff)[_i]), (PG8_LAS unsigned*)(lds + (bufoff) + ldsw + _i * 8192), 16, 0, 0); } while (0)
; #define PG8_LDA(dst, b, h) do { _Pragma("unroll") for (int m = 0; m < 4; ++m) _Pragma("unroll") for (int k = 0; k < 2; ++k) dst[m][k] = *(const PG8_LAS bf16x8*)(lds + PG8_SA(b, h) + aoff + m * 2048 + k * 1024); } while (0)
; #define PG8_MMA(ai, bj, At, Bt) do { __builtin_amdgcn_s_setprio(1); _Pragma("unroll") for (int m = 0; m < 4; ++m) _Pragma("unroll") for (int n = 0; n < 2; ++n) _Pragma("unroll") for (int k = 0; k < 2; ++k) \
;         acc[ai][bj][m][n] = __builtin_amdgcn_mfma_f32_16x16x32_bf16(Bt[n][k], At[m][k], acc[ai][bj][m][n], 0, 0, 0); __builtin_amdgcn_s_setprio(0); } while (0)
; #define PG8_WAIT_V(n) asm volatile("s_waitcnt vmcnt(" #n ")" ::: "memory")
; #define PG8_WAIT_L(n) asm volatile("s_waitcnt lgkmcnt(" #n ")" ::: "memory")
; #define PG8_BAR __builtin_amdgcn_s_barrier()
; #define PG8_SCHED __builtin_amdgcn_sched_barrier(0)
; template <class Epi, class Sched, bool ALIGN_EPI = false, bool SP2 = false>
; __device__ __forceinline__ void gemm_phase(PG8_LAS unsigned char* lds, const Gemm g, const Sched& S, const Epi& E) {
;     ...
;             PG8_LDA(At, 1, 1); PG8_STAGE(PG8_SB(1, 0), b3, voffB); PG8_STAGE(PG8_SB(1, 1), b3 + hstep, voffB); PG8_STAGE(PG8_SA(1, 0), a3, voffA);
;             PG8_WAIT_V(8); PG8_WAIT_L(0); PG8_BAR; PG8_MMA(1, 0, At, B0); PG8_MMA(1, 1, At, B1); PG8_BAR; PG8_SCHED;
	s_add_i32 s44, s53, s16
	v_lshl_add_u64 v[216:217], v[216:217], 0, s[10:11]
	s_mov_b32 m0, s44
	ds_read_b128 v[184:187], v155 offset:49152
	ds_read_b128 v[188:191], v155 offset:50176
	ds_read_b128 v[192:195], v155 offset:51200
	ds_read_b128 v[196:199], v155 offset:52224
	ds_read_b128 v[200:203], v155 offset:53248
	ds_read_b128 v[204:207], v155 offset:54272
	ds_read_b128 v[208:211], v155 offset:55296
	ds_read_b128 v[212:215], v155 offset:56320
	global_load_lds_dwordx4 v[216:217], off
	s_add_i32 m0, s44, 0x2000
	s_add_u32 s42, s42, 0x80080
	v_lshl_add_u64 v[216:217], v[218:219], 0, s[10:11]
	s_addc_u32 s43, s43, 0
	s_add_i32 s44, s54, s16
	global_load_lds_dwordx4 v[216:217], off
	v_lshl_add_u64 v[216:217], s[42:43], 0, v[134:135]
	s_mov_b32 m0, s44
	s_nop 0
	global_load_lds_dwordx4 v[216:217], off
	v_lshl_add_u64 v[216:217], s[42:43], 0, v[130:131]
	s_add_i32 m0, s44, 0x2000
	s_nop 0
	global_load_lds_dwordx4 v[216:217], off
	v_lshl_add_u64 v[216:217], v[220:221], 0, s[10:11]
	s_mov_b32 m0, s29
	s_nop 0
	global_load_lds_dwordx4 v[216:217], off
	v_lshl_add_u64 v[216:217], v[222:223], 0, s[10:11]
	s_mov_b32 m0, s30
	s_nop 0
	global_load_lds_dwordx4 v[216:217], off
	s_waitcnt vmcnt(8)
	s_waitcnt lgkmcnt(0)
	s_barrier
	s_waitcnt lgkmcnt(0)
	v_mfma_f32_16x16x32_bf16 v[62:65], v[146:149], v[184:187], v[62:65]
	v_mfma_f32_16x16x32_bf16 v[58:61], v[160:163], v[184:187], v[58:61]
	v_mfma_f32_16x16x32_bf16 v[46:49], v[146:149], v[192:195], v[46:49]
	v_mfma_f32_16x16x32_bf16 v[42:45], v[160:163], v[192:195], v[42:45]
	v_mfma_f32_16x16x32_bf16 v[30:33], v[146:149], v[200:203], v[30:33]
	v_mfma_f32_16x16x32_bf16 v[26:29], v[160:163], v[200:203], v[26:29]
	v_mfma_f32_16x16x32_bf16 v[14:17], v[146:149], v[208:211], v[14:17]
	v_mfma_f32_16x16x32_bf16 v[10:13], v[160:163], v[208:211], v[10:13]
	v_mfma_f32_16x16x32_bf16 v[62:65], v[156:159], v[188:191], v[62:65]
	v_mfma_f32_16x16x32_bf16 v[58:61], v[164:167], v[188:191], v[58:61]
	v_mfma_f32_16x16x32_bf16 v[46:49], v[156:159], v[196:199], v[46:49]
	v_mfma_f32_16x16x32_bf16 v[42:45], v[164:167], v[196:199], v[42:45]
	v_mfma_f32_16x16x32_bf16 v[30:33], v[156:159], v[204:207], v[30:33]
	v_mfma_f32_16x16x32_bf16 v[26:29], v[164:167], v[204:207], v[26:29]
	v_mfma_f32_16x16x32_bf16 v[14:17], v[156:159], v[212:215], v[14:17]
	v_mfma_f32_16x16x32_bf16 v[10:13], v[164:167], v[212:215], v[10:13]
	v_mfma_f32_16x16x32_bf16 v[54:57], v[168:171], v[184:187], v[54:57]
	v_mfma_f32_16x16x32_bf16 v[50:53], v[176:179], v[184:187], v[50:53]
	v_mfma_f32_16x16x32_bf16 v[38:41], v[168:171], v[192:195], v[38:41]
	v_mfma_f32_16x16x32_bf16 v[34:37], v[176:179], v[192:195], v[34:37]
	v_mfma_f32_16x16x32_bf16 v[22:25], v[168:171], v[200:203], v[22:25]
	v_mfma_f32_16x16x32_bf16 v[18:21], v[176:179], v[200:203], v[18:21]
	v_mfma_f32_16x16x32_bf16 v[6:9], v[168:171], v[208:211], v[6:9]
	v_mfma_f32_16x16x32_bf16 v[2:5], v[176:179], v[208:211], v[2:5]
	v_mfma_f32_16x16x32_bf16 v[54:57], v[172:175], v[188:191], v[54:57]
	v_mfma_f32_16x16x32_bf16 v[50:53], v[180:183], v[188:191], v[50:53]
	v_mfma_f32_16x16x32_bf16 v[38:41], v[172:175], v[196:199], v[38:41]
	v_mfma_f32_16x16x32_bf16 v[34:37], v[180:183], v[196:199], v[34:37]
	v_mfma_f32_16x16x32_bf16 v[22:25], v[172:175], v[204:207], v[22:25]
	v_mfma_f32_16x16x32_bf16 v[18:21], v[180:183], v[204:207], v[18:21]
	v_mfma_f32_16x16x32_bf16 v[6:9], v[172:175], v[212:215], v[6:9]
	v_mfma_f32_16x16x32_bf16 v[2:5], v[180:183], v[212:215], v[2:5]
	s_barrier
	s_add_i32 s52, s52, 2
	s_add_u32 s40, s40, 0x100
	s_addc_u32 s41, s41, 0
	s_add_u32 s50, s50, 0x100
	s_addc_u32 s51, s51, 0
	s_cmp_gt_u32 s52, 29
	s_cbranch_scc0 .LBB0_88
	s_and_b64 vcc, exec, s[12:13]
	s_cbranch_vccz .LBB0_91
	s_barrier

; #define PG8_STAGE(bufoff, gbase, voff) do { _Pragma("unroll") for (int _i = 0; _i < 2; ++_i) \
;         __builtin_amdgcn_global_load_lds((const unsigned*)((const char*)(gbase) + (voff)[_i]), (PG8_LAS unsigned*)(lds + (bufoff) + ldsw + _i * 8192), 16, 0, 0); } while (0)
; #define PG8_LDA(dst, b, h) do { _Pragma("unroll") for (int m = 0; m < 4; ++m) _Pragma("unroll") for (int k = 0; k < 2; ++k) dst[m][k] = *(const PG8_LAS bf16x8*)(lds + PG8_SA(b, h) + aoff + m * 2048 + k * 1024); } while (0)
; #define PG8_LDB(dst, b, h) do { _Pragma("unroll") for (int n = 0; n < 2; ++n) _Pragma("unroll") for (int k = 0; k < 2; ++k) dst[n][k] = *(const PG8_LAS bf16x8*)(lds + PG8_SB(b, h) + boff + n * 2048 + k * 1024); } while (0)
; #define PG8_WAIT_V(n) asm volatile("s_waitcnt vmcnt(" #n ")" ::: "memory")
; #define PG8_WAIT_L(n) asm volatile("s_waitcnt lgkmcnt(" #n ")" ::: "memory")
; #define PG8_BAR __builtin_amdgcn_s_barrier()
; template <class Epi, class Sched, bool ALIGN_EPI = false, bool SP2 = false>
; __device__ __forceinline__ void gemm_phase(PG8_LAS unsigned char* lds, const Gemm g, const Sched& S, const Epi& E) {
;     ...
;         const char* nA = has_next ? (const char*)g.A + (size_t)nxt.pm * tstep + (size_t)nxt.kt0 * kstep : cA; const char* nB = has_next ? (const char*)g.Bt + (size_t)nxt.pn * tstep + (size_t)nxt.kt0 * kstep : cB;
;         for (int t = 0; t < nt; t += 2) {
;             if constexpr (Epi::MIDHOOK) { if (t == (nt >> 1)) E.mid(acc, cur, wr, wc, fr, fq); }
;             const bool last = (t == nt - 2);
;             const char* a1 = cA + (size_t)(t + 1) * kstep;
;             const char* a2 = last ? nA : cA + (size_t)(t + 2) * kstep; const char* b2 = last ? nB : cB + (size_t)(t + 2) * kstep;
;             const char* a3 = a2 + kstep; const char* b3 = b2 + kstep;
;             if (last && has_next) S.a_ready(nxt);
;             if constexpr (SP2) {
;             PG8_LDB(B0, 0, 0); PG8_LDB(B1, 0, 1); PG8_SCHED; PG8_LDA(At, 0, 0); PG8_STAGE(PG8_SA(1, 1), a1 + hstep, voffA);
;             PG8_WAIT_V(8); PG8_WAIT_L(0); PG8_BAR; PG8_MMA(0, 0, At, B0); PG8_MMA(0, 1, At, B1); PG8_BAR; PG8_SCHED;
;             PG8_LDA(At, 0, 1); PG8_STAGE(PG8_SB(0, 0), b2, voffB); PG8_STAGE(PG8_SB(0, 1), b2 + hstep, voffB); PG8_STAGE(PG8_SA(0, 0), a2, voffA);
;             PG8_WAIT_V(8); PG8_WAIT_L(0); PG8_BAR; PG8_MMA(1, 0, At, B0); PG8_MMA(1, 1, At, B1); PG8_BAR; PG8_SCHED;
.LBB0_173:
	ds_read_b128 v[154:157], v151
	ds_read_b128 v[158:161], v151 offset:1024
	ds_read_b128 v[162:165], v151 offset:2048
	ds_read_b128 v[166:169], v151 offset:3072
	ds_read_b128 v[170:173], v152
	ds_read_b128 v[174:177], v152 offset:1024
	ds_read_b128 v[178:181], v152 offset:2048
	ds_read_b128 v[182:185], v152 offset:3072
	s_add_u32 s36, s22, 0x100
	s_addc_u32 s37, s23, 0
	s_cmpk_eq_i32 s48, 0x54
	s_cselect_b32 s41, s7, s37
	s_cselect_b32 s40, s6, s36
	s_cselect_b32 s39, s21, s47
	s_cselect_b32 s38, s20, s46
	v_lshl_add_u64 v[146:147], s[22:23], 0, v[138:139]
	s_add_i32 m0, s18, 0xc000
	ds_read_b128 v[186:189], v153
	ds_read_b128 v[190:193], v153 offset:1024
	ds_read_b128 v[194:197], v153 offset:2048
	ds_read_b128 v[198:201], v153 offset:3072
	ds_read_b128 v[202:205], v153 offset:4096
	ds_read_b128 v[206:209], v153 offset:5120
	ds_read_b128 v[210:213], v153 offset:6144
	ds_read_b128 v[214:217], v153 offset:7168
	global_load_lds_dwordx4 v[146:147], off
	v_lshl_add_u64 v[146:147], s[22:23], 0, v[140:141]
	s_add_i32 m0, s18, 0xe000
	s_nop 0
	global_load_lds_dwordx4 v[146:147], off
	s_waitcnt vmcnt(8)
	s_waitcnt lgkmcnt(0)
	s_barrier
	s_waitcnt lgkmcnt(0)
	v_mfma_f32_16x16x32_bf16 v[126:129], v[154:157], v[186:189], v[126:129]
	v_mfma_f32_16x16x32_bf16 v[122:125], v[162:165], v[186:189], v[122:125]
	v_mfma_f32_16x16x32_bf16 v[118:121], v[154:157], v[194:197], v[118:121]
	v_mfma_f32_16x16x32_bf16 v[110:113], v[162:165], v[194:197], v[110:113]
	v_mfma_f32_16x16x32_bf16 v[102:105], v[154:157], v[202:205], v[102:105]
	v_mfma_f32_16x16x32_bf16 v[94:97], v[162:165], v[202:205], v[94:97]
	v_mfma_f32_16x16x32_bf16 v[86:89], v[154:157], v[210:213], v[86:89]
	v_mfma_f32_16x16x32_bf16 v[78:81], v[162:165], v[210:213], v[78:81]
	v_mfma_f32_16x16x32_bf16 v[126:129], v[158:161], v[190:193], v[126:129]
	v_mfma_f32_16x16x32_bf16 v[122:125], v[166:169], v[190:193], v[122:125]
	v_mfma_f32_16x16x32_bf16 v[118:121], v[158:161], v[198:201], v[118:121]
	v_mfma_f32_16x16x32_bf16 v[110:113], v[166:169], v[198:201], v[110:113]
	v_mfma_f32_16x16x32_bf16 v[102:105], v[158:161], v[206:209], v[102:105]
	v_mfma_f32_16x16x32_bf16 v[94:97], v[166:169], v[206:209], v[94:97]
	v_mfma_f32_16x16x32_bf16 v[86:89], v[158:161], v[214:217], v[86:89]
	v_mfma_f32_16x16x32_bf16 v[78:81], v[166:169], v[214:217], v[78:81]
	v_mfma_f32_16x16x32_bf16 v[114:117], v[170:173], v[186:189], v[114:117]
	v_mfma_f32_16x16x32_bf16 v[106:109], v[178:181], v[186:189], v[106:109]
	v_mfma_f32_16x16x32_bf16 v[98:101], v[170:173], v[194:197], v[98:101]
	v_mfma_f32_16x16x32_bf16 v[90:93], v[178:181], v[194:197], v[90:93]
	v_mfma_f32_16x16x32_bf16 v[82:85], v[170:173], v[202:205], v[82:85]
	v_mfma_f32_16x16x32_bf16 v[74:77], v[178:181], v[202:205], v[74:77]
	v_mfma_f32_16x16x32_bf16 v[70:73], v[170:173], v[210:213], v[70:73]
	v_mfma_f32_16x16x32_bf16 v[66:69], v[178:181], v[210:213], v[66:69]
	v_mfma_f32_16x16x32_bf16 v[114:117], v[174:177], v[190:193], v[114:117]
	v_mfma_f32_16x16x32_bf16 v[106:109], v[182:185], v[190:193], v[106:109]
	v_mfma_f32_16x16x32_bf16 v[98:101], v[174:177], v[198:201], v[98:101]
	v_mfma_f32_16x16x32_bf16 v[90:93], v[182:185], v[198:201], v[90:93]
	v_mfma_f32_16x16x32_bf16 v[82:85], v[174:177], v[206:209], v[82:85]
	v_mfma_f32_16x16x32_bf16 v[74:77], v[182:185], v[206:209], v[74:77]
	v_mfma_f32_16x16x32_bf16 v[70:73], v[174:177], v[214:217], v[70:73]
	v_mfma_f32_16x16x32_bf16 v[66:69], v[182:185], v[214:217], v[66:69]
	s_barrier
	s_add_i32 s22, s30, s16
	v_lshl_add_u64 v[146:147], s[38:39], 0, v[134:135]
	s_mov_b32 m0, s22
	ds_read_b128 v[186:189], v153 offset:16384
	ds_read_b128 v[190:193], v153 offset:17408
	ds_read_b128 v[194:197], v153 offset:18432
	ds_read_b128 v[198:201], v153 offset:19456
	ds_read_b128 v[202:205], v153 offset:20480
	ds_read_b128 v[206:209], v153 offset:21504
	ds_read_b128 v[210:213], v153 offset:22528
	ds_read_b128 v[214:217], v153 offset:23552
	global_load_lds_dwordx4 v[146:147], off
	s_add_i32 m0, s22, 0x2000
	s_add_u32 s22, s38, 0x160000
	v_lshl_add_u64 v[218:219], s[38:39], 0, v[130:131]
	s_addc_u32 s23, s39, 0
	s_add_i32 s49, s31, s16
	global_load_lds_dwordx4 v[218:219], off
	v_lshl_add_u64 v[220:221], s[22:23], 0, v[134:135]
	s_mov_b32 m0, s49
	v_lshl_add_u64 v[222:223], s[40:41], 0, v[132:133]
	global_load_lds_dwordx4 v[220:221], off
	v_lshl_add_u64 v[220:221], s[22:23], 0, v[130:131]
	s_add_i32 m0, s49, 0x2000
	s_nop 0
	global_load_lds_dwordx4 v[220:221], off
	v_lshl_add_u64 v[220:221], s[40:41], 0, v[136:137]
	s_mov_b32 m0, s18
	s_nop 0
	global_load_lds_dwordx4 v[220:221], off
	s_mov_b32 m0, s19
	s_nop 0
	global_load_lds_dwordx4 v[222:223], off
	s_waitcnt vmcnt(8)
	s_waitcnt lgkmcnt(0)
	s_barrier
; #define PG8_STAGE(bufoff, gbase, voff) do { _Pragma("unroll") for (int _i = 0; _i < 2; ++_i) \
;         __builtin_amdgcn_global_load_lds((const unsigned*)((const char*)(gbase) + (voff)[_i]), (PG8_LAS unsigned*)(lds + (bufoff) + ldsw + _i * 8192), 16, 0, 0); } while (0)
; #define PG8_LDA(dst, b, h) do { _Pragma("unroll") for (int m = 0; m < 4; ++m) _Pragma("unroll") for (int k = 0; k < 2; ++k) dst[m][k] = *(const PG8_LAS bf16x8*)(lds + PG8_SA(b, h) + aoff + m * 2048 + k * 1024); } while (0)
; #define PG8_LDB(dst, b, h) do { _Pragma("unroll") for (int n = 0; n < 2; ++n) _Pragma("unroll") for (int k = 0; k < 2; ++k) dst[n][k] = *(const PG8_LAS bf16x8*)(lds + PG8_SB(b, h) + boff + n * 2048 + k * 1024); } while (0)
; #define PG8_MMA(ai, bj, At, Bt) do { __builtin_amdgcn_s_setprio(1); _Pragma("unroll") for (int m = 0; m < 4; ++m) _Pragma("unroll") for (int n = 0; n < 2; ++n) _Pragma("unroll") for (int k = 0; k < 2; ++k) \
;         acc[ai][bj][m][n] = __builtin_amdgcn_mfma_f32_16x16x32_bf16(Bt[n][k], At[m][k], acc[ai][bj][m][n], 0, 0, 0); __builtin_amdgcn_s_setprio(0); } while (0)
; #define PG8_WAIT_V(n) asm volatile("s_waitcnt vmcnt(" #n ")" ::: "memory")
; #define PG8_WAIT_L(n) asm volatile("s_waitcnt lgkmcnt(" #n ")" ::: "memory")
; #define PG8_BAR __builtin_amdgcn_s_barrier()
; #define PG8_SCHED __builtin_amdgcn_sched_barrier(0)
; template <class Epi, class Sched, bool ALIGN_EPI = false, bool SP2 = false>
; __device__ __forceinline__ void gemm_phase(PG8_LAS unsigned char* lds, const Gemm g, const Sched& S, const Epi& E) {
;     ...
;             PG8_WAIT_V(8); PG8_WAIT_L(0); PG8_BAR; PG8_MMA(1, 0, At, B0); PG8_MMA(1, 1, At, B1); PG8_BAR; PG8_SCHED;
;             PG8_LDB(B0, 1, 0); PG8_LDB(B1, 1, 1); PG8_SCHED; PG8_LDA(At, 1, 0); PG8_STAGE(PG8_SA(0, 1), a2 + hstep, voffA);
;             PG8_WAIT_V(8); PG8_WAIT_L(0); PG8_BAR; PG8_MMA(0, 0, At, B0); PG8_MMA(0, 1, At, B1); PG8_BAR; PG8_SCHED;
;             PG8_LDA(At, 1, 1); PG8_STAGE(PG8_SB(1, 0), b3, voffB); PG8_STAGE(PG8_SB(1, 1), b3 + hstep, voffB); PG8_STAGE(PG8_SA(1, 0), a3, voffA);
	s_waitcnt lgkmcnt(0)
	v_mfma_f32_16x16x32_bf16 v[62:65], v[154:157], v[186:189], v[62:65]
	v_mfma_f32_16x16x32_bf16 v[58:61], v[162:165], v[186:189], v[58:61]
	v_mfma_f32_16x16x32_bf16 v[54:57], v[154:157], v[194:197], v[54:57]
	v_mfma_f32_16x16x32_bf16 v[46:49], v[162:165], v[194:197], v[46:49]
	v_mfma_f32_16x16x32_bf16 v[38:41], v[154:157], v[202:205], v[38:41]
	v_mfma_f32_16x16x32_bf16 v[30:33], v[162:165], v[202:205], v[30:33]
	v_mfma_f32_16x16x32_bf16 v[22:25], v[154:157], v[210:213], v[22:25]
	v_mfma_f32_16x16x32_bf16 v[14:17], v[162:165], v[210:213], v[14:17]
	v_mfma_f32_16x16x32_bf16 v[62:65], v[158:161], v[190:193], v[62:65]
	v_mfma_f32_16x16x32_bf16 v[58:61], v[166:169], v[190:193], v[58:61]
	v_mfma_f32_16x16x32_bf16 v[54:57], v[158:161], v[198:201], v[54:57]
	v_mfma_f32_16x16x32_bf16 v[46:49], v[166:169], v[198:201], v[46:49]
	v_mfma_f32_16x16x32_bf16 v[38:41], v[158:161], v[206:209], v[38:41]
	v_mfma_f32_16x16x32_bf16 v[30:33], v[166:169], v[206:209], v[30:33]
	v_mfma_f32_16x16x32_bf16 v[22:25], v[158:161], v[214:217], v[22:25]
	v_mfma_f32_16x16x32_bf16 v[14:17], v[166:169], v[214:217], v[14:17]
	v_mfma_f32_16x16x32_bf16 v[50:53], v[170:173], v[186:189], v[50:53]
	v_mfma_f32_16x16x32_bf16 v[42:45], v[178:181], v[186:189], v[42:45]
	v_mfma_f32_16x16x32_bf16 v[34:37], v[170:173], v[194:197], v[34:37]
	v_mfma_f32_16x16x32_bf16 v[26:29], v[178:181], v[194:197], v[26:29]
	v_mfma_f32_16x16x32_bf16 v[18:21], v[170:173], v[202:205], v[18:21]
	v_mfma_f32_16x16x32_bf16 v[10:13], v[178:181], v[202:205], v[10:13]
	v_mfma_f32_16x16x32_bf16 v[6:9], v[170:173], v[210:213], v[6:9]
	v_mfma_f32_16x16x32_bf16 v[2:5], v[178:181], v[210:213], v[2:5]
	v_mfma_f32_16x16x32_bf16 v[50:53], v[174:177], v[190:193], v[50:53]
	v_mfma_f32_16x16x32_bf16 v[42:45], v[182:185], v[190:193], v[42:45]
	v_mfma_f32_16x16x32_bf16 v[34:37], v[174:177], v[198:201], v[34:37]
	v_mfma_f32_16x16x32_bf16 v[26:29], v[182:185], v[198:201], v[26:29]
	v_mfma_f32_16x16x32_bf16 v[18:21], v[174:177], v[206:209], v[18:21]
	v_mfma_f32_16x16x32_bf16 v[10:13], v[182:185], v[206:209], v[10:13]
	v_mfma_f32_16x16x32_bf16 v[6:9], v[174:177], v[214:217], v[6:9]
	v_mfma_f32_16x16x32_bf16 v[2:5], v[182:185], v[214:217], v[2:5]
	s_barrier
	s_add_i32 s49, 0, 0x18000
	s_add_i32 s50, 0, 0x1c000
	v_add_u32_e32 v166, s49, v149
	v_add_u32_e32 v182, s50, v149
	ds_read_b128 v[154:157], v166
	ds_read_b128 v[158:161], v166 offset:1024
	ds_read_b128 v[162:165], v166 offset:2048
	ds_read_b128 v[166:169], v166 offset:3072
	ds_read_b128 v[170:173], v182
	ds_read_b128 v[174:177], v182 offset:1024
	ds_read_b128 v[178:181], v182 offset:2048
	ds_read_b128 v[182:185], v182 offset:3072
	s_add_u32 s22, s40, 0x160000
	s_addc_u32 s23, s41, 0
	s_mov_b32 m0, s24
	v_lshl_add_u64 v[224:225], s[22:23], 0, v[136:137]
	ds_read_b128 v[186:189], v153 offset:32768
	ds_read_b128 v[190:193], v153 offset:33792
	ds_read_b128 v[194:197], v153 offset:34816
	ds_read_b128 v[198:201], v153 offset:35840
	ds_read_b128 v[202:205], v153 offset:36864
	ds_read_b128 v[206:209], v153 offset:37888
	ds_read_b128 v[210:213], v153 offset:38912
	ds_read_b128 v[214:217], v153 offset:39936
	global_load_lds_dwordx4 v[224:225], off
	v_lshl_add_u64 v[224:225], s[22:23], 0, v[132:133]
	s_mov_b32 m0, s25
	s_nop 0
	global_load_lds_dwordx4 v[224:225], off
	s_waitcnt vmcnt(8)
	s_waitcnt lgkmcnt(0)
	s_barrier
	s_waitcnt lgkmcnt(0)
	v_mfma_f32_16x16x32_bf16 v[126:129], v[154:157], v[186:189], v[126:129]
	v_mfma_f32_16x16x32_bf16 v[122:125], v[162:165], v[186:189], v[122:125]
	v_mfma_f32_16x16x32_bf16 v[118:121], v[154:157], v[194:197], v[118:121]
	v_mfma_f32_16x16x32_bf16 v[110:113], v[162:165], v[194:197], v[110:113]
	v_mfma_f32_16x16x32_bf16 v[102:105], v[154:157], v[202:205], v[102:105]
	v_mfma_f32_16x16x32_bf16 v[94:97], v[162:165], v[202:205], v[94:97]
	v_mfma_f32_16x16x32_bf16 v[86:89], v[154:157], v[210:213], v[86:89]
	v_mfma_f32_16x16x32_bf16 v[78:81], v[162:165], v[210:213], v[78:81]
	v_mfma_f32_16x16x32_bf16 v[126:129], v[158:161], v[190:193], v[126:129]
	v_mfma_f32_16x16x32_bf16 v[122:125], v[166:169], v[190:193], v[122:125]
	v_mfma_f32_16x16x32_bf16 v[118:121], v[158:161], v[198:201], v[118:121]
	v_mfma_f32_16x16x32_bf16 v[110:113], v[166:169], v[198:201], v[110:113]
	v_mfma_f32_16x16x32_bf16 v[102:105], v[158:161], v[206:209], v[102:105]
	v_mfma_f32_16x16x32_bf16 v[94:97], v[166:169], v[206:209], v[94:97]
	v_mfma_f32_16x16x32_bf16 v[86:89], v[158:161], v[214:217], v[86:89]
	v_mfma_f32_16x16x32_bf16 v[78:81], v[166:169], v[214:217], v[78:81]
	v_mfma_f32_16x16x32_bf16 v[114:117], v[170:173], v[186:189], v[114:117]
	v_mfma_f32_16x16x32_bf16 v[106:109], v[178:181], v[186:189], v[106:109]
	v_mfma_f32_16x16x32_bf16 v[98:101], v[170:173], v[194:197], v[98:101]
	v_mfma_f32_16x16x32_bf16 v[90:93], v[178:181], v[194:197], v[90:93]
	v_mfma_f32_16x16x32_bf16 v[82:85], v[170:173], v[202:205], v[82:85]
	v_mfma_f32_16x16x32_bf16 v[74:77], v[178:181], v[202:205], v[74:77]
	v_mfma_f32_16x16x32_bf16 v[70:73], v[170:173], v[210:213], v[70:73]
	v_mfma_f32_16x16x32_bf16 v[66:69], v[178:181], v[210:213], v[66:69]
	v_mfma_f32_16x16x32_bf16 v[114:117], v[174:177], v[190:193], v[114:117]
	v_mfma_f32_16x16x32_bf16 v[106:109], v[182:185], v[190:193], v[106:109]
	v_mfma_f32_16x16x32_bf16 v[98:101], v[174:177], v[198:201], v[98:101]
	v_mfma_f32_16x16x32_bf16 v[90:93], v[182:185], v[198:201], v[90:93]
	v_mfma_f32_16x16x32_bf16 v[82:85], v[174:177], v[206:209], v[82:85]
	v_mfma_f32_16x16x32_bf16 v[74:77], v[182:185], v[206:209], v[74:77]
	v_mfma_f32_16x16x32_bf16 v[70:73], v[174:177], v[214:217], v[70:73]
	v_mfma_f32_16x16x32_bf16 v[66:69], v[182:185], v[214:217], v[66:69]
	s_barrier
; #define PG8_STAGE(bufoff, gbase, voff) do { _Pragma("unroll") for (int _i = 0; _i < 2; ++_i) \
;         __builtin_amdgcn_global_load_lds((const unsigned*)((const char*)(gbase) + (voff)[_i]), (PG8_LAS unsigned*)(lds + (bufoff) + ldsw + _i * 8192), 16, 0, 0); } while (0)
; #define PG8_LDA(dst, b, h) do { _Pragma("unroll") for (int m = 0; m < 4; ++m) _Pragma("unroll") for (int k = 0; k < 2; ++k) dst[m][k] = *(const PG8_LAS bf16x8*)(lds + PG8_SA(b, h) + aoff + m * 2048 + k * 1024); } while (0)
; #define PG8_MMA(ai, bj, At, Bt) do { __builtin_amdgcn_s_setprio(1); _Pragma("unroll") for (int m = 0; m < 4; ++m) _Pragma("unroll") for (int n = 0; n < 2; ++n) _Pragma("unroll") for (int k = 0; k < 2; ++k) \
;         acc[ai][bj][m][n] = __builtin_amdgcn_mfma_f32_16x16x32_bf16(Bt[n][k], At[m][k], acc[ai][bj][m][n], 0, 0, 0); __builtin_amdgcn_s_setprio(0); } while (0)
; #define PG8_WAIT_V(n) asm volatile("s_waitcnt vmcnt(" #n ")" ::: "memory")
; #define PG8_WAIT_L(n) asm volatile("s_waitcnt lgkmcnt(" #n ")" ::: "memory")
; #define PG8_BAR __builtin_amdgcn_s_barrier()
; #define PG8_SCHED __builtin_amdgcn_sched_barrier(0)
; template <class Epi, class Sched, bool ALIGN_EPI = false, bool SP2 = false>
; __device__ __forceinline__ void gemm_phase(PG8_LAS unsigned char* lds, const Gemm g, const Sched& S, const Epi& E) {
;     ...
;             PG8_LDA(At, 1, 1); PG8_STAGE(PG8_SB(1, 0), b3, voffB); PG8_STAGE(PG8_SB(1, 1), b3 + hstep, voffB); PG8_STAGE(PG8_SA(1, 0), a3, voffA);
;             PG8_WAIT_V(8); PG8_WAIT_L(0); PG8_BAR; PG8_MMA(1, 0, At, B0); PG8_MMA(1, 1, At, B1); PG8_BAR; PG8_SCHED;
	s_add_i32 s22, s49, s16
	v_lshl_add_u64 v[146:147], v[146:147], 0, s[12:13]
	s_mov_b32 m0, s22
	ds_read_b128 v[186:189], v153 offset:49152
	ds_read_b128 v[190:193], v153 offset:50176
	ds_read_b128 v[194:197], v153 offset:51200
	ds_read_b128 v[198:201], v153 offset:52224
	ds_read_b128 v[202:205], v153 offset:53248
	ds_read_b128 v[206:209], v153 offset:54272
	ds_read_b128 v[210:213], v153 offset:55296
	ds_read_b128 v[214:217], v153 offset:56320
	global_load_lds_dwordx4 v[146:147], off
	s_add_i32 m0, s22, 0x2000
	s_add_u32 s22, s38, 0x160080
	v_lshl_add_u64 v[146:147], v[218:219], 0, s[12:13]
	s_addc_u32 s23, s39, 0
	s_add_i32 s38, s50, s16
	global_load_lds_dwordx4 v[146:147], off
	v_lshl_add_u64 v[146:147], s[22:23], 0, v[134:135]
	s_mov_b32 m0, s38
	s_nop 0
	global_load_lds_dwordx4 v[146:147], off
	v_lshl_add_u64 v[146:147], s[22:23], 0, v[130:131]
	s_add_i32 m0, s38, 0x2000
	s_nop 0
	global_load_lds_dwordx4 v[146:147], off
	v_lshl_add_u64 v[146:147], v[220:221], 0, s[12:13]
	s_mov_b32 m0, s28
	s_nop 0
	global_load_lds_dwordx4 v[146:147], off
	v_lshl_add_u64 v[146:147], v[222:223], 0, s[12:13]
	s_mov_b32 m0, s29
	s_nop 0
	global_load_lds_dwordx4 v[146:147], off
	s_waitcnt vmcnt(8)
	s_waitcnt lgkmcnt(0)
	s_barrier
	s_waitcnt lgkmcnt(0)
	v_mfma_f32_16x16x32_bf16 v[62:65], v[154:157], v[186:189], v[62:65]
	v_mfma_f32_16x16x32_bf16 v[58:61], v[162:165], v[186:189], v[58:61]
	v_mfma_f32_16x16x32_bf16 v[54:57], v[154:157], v[194:197], v[54:57]
	v_mfma_f32_16x16x32_bf16 v[46:49], v[162:165], v[194:197], v[46:49]
	v_mfma_f32_16x16x32_bf16 v[38:41], v[154:157], v[202:205], v[38:41]
	v_mfma_f32_16x16x32_bf16 v[30:33], v[162:165], v[202:205], v[30:33]
	v_mfma_f32_16x16x32_bf16 v[22:25], v[154:157], v[210:213], v[22:25]
	v_mfma_f32_16x16x32_bf16 v[14:17], v[162:165], v[210:213], v[14:17]
	v_mfma_f32_16x16x32_bf16 v[62:65], v[158:161], v[190:193], v[62:65]
	v_mfma_f32_16x16x32_bf16 v[58:61], v[166:169], v[190:193], v[58:61]
	v_mfma_f32_16x16x32_bf16 v[54:57], v[158:161], v[198:201], v[54:57]
	v_mfma_f32_16x16x32_bf16 v[46:49], v[166:169], v[198:201], v[46:49]
	v_mfma_f32_16x16x32_bf16 v[38:41], v[158:161], v[206:209], v[38:41]
	v_mfma_f32_16x16x32_bf16 v[30:33], v[166:169], v[206:209], v[30:33]
	v_mfma_f32_16x16x32_bf16 v[22:25], v[158:161], v[214:217], v[22:25]
	v_mfma_f32_16x16x32_bf16 v[14:17], v[166:169], v[214:217], v[14:17]
	v_mfma_f32_16x16x32_bf16 v[50:53], v[170:173], v[186:189], v[50:53]
	v_mfma_f32_16x16x32_bf16 v[42:45], v[178:181], v[186:189], v[42:45]
	v_mfma_f32_16x16x32_bf16 v[34:37], v[170:173], v[194:197], v[34:37]
	v_mfma_f32_16x16x32_bf16 v[26:29], v[178:181], v[194:197], v[26:29]
	v_mfma_f32_16x16x32_bf16 v[18:21], v[170:173], v[202:205], v[18:21]
	v_mfma_f32_16x16x32_bf16 v[10:13], v[178:181], v[202:205], v[10:13]
	v_mfma_f32_16x16x32_bf16 v[6:9], v[170:173], v[210:213], v[6:9]
	v_mfma_f32_16x16x32_bf16 v[2:5], v[178:181], v[210:213], v[2:5]
	v_mfma_f32_16x16x32_bf16 v[50:53], v[174:177], v[190:193], v[50:53]
	v_mfma_f32_16x16x32_bf16 v[42:45], v[182:185], v[190:193], v[42:45]
	v_mfma_f32_16x16x32_bf16 v[34:37], v[174:177], v[198:201], v[34:37]
	v_mfma_f32_16x16x32_bf16 v[26:29], v[182:185], v[198:201], v[26:29]
	v_mfma_f32_16x16x32_bf16 v[18:21], v[174:177], v[206:209], v[18:21]
	v_mfma_f32_16x16x32_bf16 v[10:13], v[182:185], v[206:209], v[10:13]
	v_mfma_f32_16x16x32_bf16 v[6:9], v[174:177], v[214:217], v[6:9]
	v_mfma_f32_16x16x32_bf16 v[2:5], v[182:185], v[214:217], v[2:5]
	s_barrier
	s_add_i32 s48, s48, 2
	s_add_u32 s46, s46, 0x100
	s_addc_u32 s47, s47, 0
	s_cmpk_gt_u32 s48, 0x55
	s_mov_b64 s[22:23], s[36:37]
	s_cbranch_scc0 .LBB0_173
	s_and_b64 vcc, exec, s[14:15]
	s_cbranch_vccz .LBB0_176
	s_barrier

; #define PG8_STAGE(bufoff, gbase, voff) do { _Pragma("unroll") for (int _i = 0; _i < 2; ++_i) \
;         __builtin_amdgcn_global_load_lds((const unsigned*)((const char*)(gbase) + (voff)[_i]), (PG8_LAS unsigned*)(lds + (bufoff) + ldsw + _i * 8192), 16, 0, 0); } while (0)
; #define PG8_LDA(dst, b, h) do { _Pragma("unroll") for (int m = 0; m < 4; ++m) _Pragma("unroll") for (int k = 0; k < 2; ++k) dst[m][k] = *(const PG8_LAS bf16x8*)(lds + PG8_SA(b, h) + aoff + m * 2048 + k * 1024); } while (0)
; #define PG8_LDB(dst, b, h) do { _Pragma("unroll") for (int n = 0; n < 2; ++n) _Pragma("unroll") for (int k = 0; k < 2; ++k) dst[n][k] = *(const PG8_LAS bf16x8*)(lds + PG8_SB(b, h) + boff + n * 2048 + k * 1024); } while (0)
; #define PG8_WAIT_V(n) asm volatile("s_waitcnt vmcnt(" #n ")" ::: "memory")
; #define PG8_WAIT_L(n) asm volatile("s_waitcnt lgkmcnt(" #n ")" ::: "memory")
; #define PG8_BAR __builtin_amdgcn_s_barrier()
; template <class Epi, class Sched, bool ALIGN_EPI = false, bool SP2 = false>
; __device__ __forceinline__ void gemm_phase(PG8_LAS unsigned char* lds, const Gemm g, const Sched& S, const Epi& E) {
;     ...
;         const char* nA = has_next ? (const char*)g.A + (size_t)nxt.pm * tstep + (size_t)nxt.kt0 * kstep : cA; const char* nB = has_next ? (const char*)g.Bt + (size_t)nxt.pn * tstep + (size_t)nxt.kt0 * kstep : cB;
;         for (int t = 0; t < nt; t += 2) {
;             if constexpr (Epi::MIDHOOK) { if (t == (nt >> 1)) E.mid(acc, cur, wr, wc, fr, fq); }
;             const bool last = (t == nt - 2);
;             const char* a1 = cA + (size_t)(t + 1) * kstep;
;             const char* a2 = last ? nA : cA + (size_t)(t + 2) * kstep; const char* b2 = last ? nB : cB + (size_t)(t + 2) * kstep;
;             const char* a3 = a2 + kstep; const char* b3 = b2 + kstep;
;             if (last && has_next) S.a_ready(nxt);
;             if constexpr (SP2) {
;             PG8_LDB(B0, 0, 0); PG8_LDB(B1, 0, 1); PG8_SCHED; PG8_LDA(At, 0, 0); PG8_STAGE(PG8_SA(1, 1), a1 + hstep, voffA);
;             PG8_WAIT_V(8); PG8_WAIT_L(0); PG8_BAR; PG8_MMA(0, 0, At, B0); PG8_MMA(0, 1, At, B1); PG8_BAR; PG8_SCHED;
;             PG8_LDA(At, 0, 1); PG8_STAGE(PG8_SB(0, 0), b2, voffB); PG8_STAGE(PG8_SB(0, 1), b2 + hstep, voffB); PG8_STAGE(PG8_SA(0, 0), a2, voffA);
;             PG8_WAIT_V(8); PG8_WAIT_L(0); PG8_BAR; PG8_MMA(1, 0, At, B0); PG8_MMA(1, 1, At, B1); PG8_BAR; PG8_SCHED;
.LBB0_193:
	ds_read_b128 v[144:147], v141
	ds_read_b128 v[148:151], v141 offset:1024
	ds_read_b128 v[152:155], v141 offset:2048
	ds_read_b128 v[156:159], v141 offset:3072
	ds_read_b128 v[160:163], v142
	ds_read_b128 v[164:167], v142 offset:1024
	ds_read_b128 v[168:171], v142 offset:2048
	ds_read_b128 v[172:175], v142 offset:3072
	s_add_u32 s40, s38, 0x100
	s_addc_u32 s41, s39, 0
	s_cmp_eq_u32 s53, 18
	s_cselect_b32 s45, s23, s41
	s_cselect_b32 s44, s22, s40
	s_cselect_b32 s43, s37, s52
	s_cselect_b32 s42, s36, s11
	v_lshl_add_u64 v[208:209], s[38:39], 0, v[134:135]
	s_add_i32 m0, s19, 0xc000
	ds_read_b128 v[176:179], v143
	ds_read_b128 v[180:183], v143 offset:1024
	ds_read_b128 v[184:187], v143 offset:2048
	ds_read_b128 v[188:191], v143 offset:3072
	ds_read_b128 v[192:195], v143 offset:4096
	ds_read_b128 v[196:199], v143 offset:5120
	ds_read_b128 v[200:203], v143 offset:6144
	ds_read_b128 v[204:207], v143 offset:7168
	global_load_lds_dwordx4 v[208:209], off
	v_lshl_add_u64 v[208:209], s[38:39], 0, v[136:137]
	s_add_i32 m0, s19, 0xe000
	s_nop 0
	global_load_lds_dwordx4 v[208:209], off
	s_waitcnt vmcnt(8)
	s_waitcnt lgkmcnt(0)
	s_barrier
	s_waitcnt lgkmcnt(0)
	v_mfma_f32_16x16x32_bf16 v[126:129], v[144:147], v[176:179], v[126:129]
	v_mfma_f32_16x16x32_bf16 v[122:125], v[152:155], v[176:179], v[122:125]
	v_mfma_f32_16x16x32_bf16 v[118:121], v[144:147], v[184:187], v[118:121]
	v_mfma_f32_16x16x32_bf16 v[114:117], v[152:155], v[184:187], v[114:117]
	v_mfma_f32_16x16x32_bf16 v[106:109], v[144:147], v[192:195], v[106:109]
	v_mfma_f32_16x16x32_bf16 v[98:101], v[152:155], v[192:195], v[98:101]
	v_mfma_f32_16x16x32_bf16 v[90:93], v[144:147], v[200:203], v[90:93]
	v_mfma_f32_16x16x32_bf16 v[82:85], v[152:155], v[200:203], v[82:85]
	v_mfma_f32_16x16x32_bf16 v[126:129], v[148:151], v[180:183], v[126:129]
	v_mfma_f32_16x16x32_bf16 v[122:125], v[156:159], v[180:183], v[122:125]
	v_mfma_f32_16x16x32_bf16 v[118:121], v[148:151], v[188:191], v[118:121]
	v_mfma_f32_16x16x32_bf16 v[114:117], v[156:159], v[188:191], v[114:117]
	v_mfma_f32_16x16x32_bf16 v[106:109], v[148:151], v[196:199], v[106:109]
	v_mfma_f32_16x16x32_bf16 v[98:101], v[156:159], v[196:199], v[98:101]
	v_mfma_f32_16x16x32_bf16 v[90:93], v[148:151], v[204:207], v[90:93]
	v_mfma_f32_16x16x32_bf16 v[82:85], v[156:159], v[204:207], v[82:85]
	v_mfma_f32_16x16x32_bf16 v[110:113], v[160:163], v[176:179], v[110:113]
	v_mfma_f32_16x16x32_bf16 v[102:105], v[168:171], v[176:179], v[102:105]
	v_mfma_f32_16x16x32_bf16 v[94:97], v[160:163], v[184:187], v[94:97]
	v_mfma_f32_16x16x32_bf16 v[86:89], v[168:171], v[184:187], v[86:89]
	v_mfma_f32_16x16x32_bf16 v[78:81], v[160:163], v[192:195], v[78:81]
	v_mfma_f32_16x16x32_bf16 v[74:77], v[168:171], v[192:195], v[74:77]
	v_mfma_f32_16x16x32_bf16 v[70:73], v[160:163], v[200:203], v[70:73]
	v_mfma_f32_16x16x32_bf16 v[66:69], v[168:171], v[200:203], v[66:69]
	v_mfma_f32_16x16x32_bf16 v[110:113], v[164:167], v[180:183], v[110:113]
	v_mfma_f32_16x16x32_bf16 v[102:105], v[172:175], v[180:183], v[102:105]
	v_mfma_f32_16x16x32_bf16 v[94:97], v[164:167], v[188:191], v[94:97]
	v_mfma_f32_16x16x32_bf16 v[86:89], v[172:175], v[188:191], v[86:89]
	v_mfma_f32_16x16x32_bf16 v[78:81], v[164:167], v[196:199], v[78:81]
	v_mfma_f32_16x16x32_bf16 v[74:77], v[172:175], v[196:199], v[74:77]
	v_mfma_f32_16x16x32_bf16 v[70:73], v[164:167], v[204:207], v[70:73]
	v_mfma_f32_16x16x32_bf16 v[66:69], v[172:175], v[204:207], v[66:69]
	s_barrier
	s_add_i32 s38, s46, s16
	v_lshl_add_u64 v[208:209], s[42:43], 0, v[132:133]
	s_mov_b32 m0, s38
	ds_read_b128 v[176:179], v143 offset:16384
	ds_read_b128 v[180:183], v143 offset:17408
	ds_read_b128 v[184:187], v143 offset:18432
	ds_read_b128 v[188:191], v143 offset:19456
	ds_read_b128 v[192:195], v143 offset:20480
	ds_read_b128 v[196:199], v143 offset:21504
	ds_read_b128 v[200:203], v143 offset:22528
	ds_read_b128 v[204:207], v143 offset:23552
	global_load_lds_dwordx4 v[208:209], off
	s_add_i32 m0, s38, 0x2000
	s_add_u32 s38, s42, 0x160000
	v_lshl_add_u64 v[210:211], s[42:43], 0, v[130:131]
	s_addc_u32 s39, s43, 0
	s_add_i32 s54, s47, s16
	global_load_lds_dwordx4 v[210:211], off
	v_lshl_add_u64 v[212:213], s[38:39], 0, v[132:133]
	s_mov_b32 m0, s54
	v_lshl_add_u64 v[214:215], s[44:45], 0, v[130:131]
	global_load_lds_dwordx4 v[212:213], off
	v_lshl_add_u64 v[212:213], s[38:39], 0, v[130:131]
	s_add_i32 m0, s54, 0x2000
	s_nop 0
	global_load_lds_dwordx4 v[212:213], off
	v_lshl_add_u64 v[212:213], s[44:45], 0, v[132:133]
	s_mov_b32 m0, s19
	s_nop 0
	global_load_lds_dwordx4 v[212:213], off
	s_mov_b32 m0, s24
	s_nop 0
	global_load_lds_dwordx4 v[214:215], off
	s_waitcnt vmcnt(8)
	s_waitcnt lgkmcnt(0)
	s_barrier
; #define PG8_STAGE(bufoff, gbase, voff) do { _Pragma("unroll") for (int _i = 0; _i < 2; ++_i) \
;         __builtin_amdgcn_global_load_lds((const unsigned*)((const char*)(gbase) + (voff)[_i]), (PG8_LAS unsigned*)(lds + (bufoff) + ldsw + _i * 8192), 16, 0, 0); } while (0)
; #define PG8_LDA(dst, b, h) do { _Pragma("unroll") for (int m = 0; m < 4; ++m) _Pragma("unroll") for (int k = 0; k < 2; ++k) dst[m][k] = *(const PG8_LAS bf16x8*)(lds + PG8_SA(b, h) + aoff + m * 2048 + k * 1024); } while (0)
; #define PG8_LDB(dst, b, h) do { _Pragma("unroll") for (int n = 0; n < 2; ++n) _Pragma("unroll") for (int k = 0; k < 2; ++k) dst[n][k] = *(const PG8_LAS bf16x8*)(lds + PG8_SB(b, h) + boff + n * 2048 + k * 1024); } while (0)
; #define PG8_MMA(ai, bj, At, Bt) do { __builtin_amdgcn_s_setprio(1); _Pragma("unroll") for (int m = 0; m < 4; ++m) _Pragma("unroll") for (int n = 0; n < 2; ++n) _Pragma("unroll") for (int k = 0; k < 2; ++k) \
;         acc[ai][bj][m][n] = __builtin_amdgcn_mfma_f32_16x16x32_bf16(Bt[n][k], At[m][k], acc[ai][bj][m][n], 0, 0, 0); __builtin_amdgcn_s_setprio(0); } while (0)
; #define PG8_WAIT_V(n) asm volatile("s_waitcnt vmcnt(" #n ")" ::: "memory")
; #define PG8_WAIT_L(n) asm volatile("s_waitcnt lgkmcnt(" #n ")" ::: "memory")
; #define PG8_BAR __builtin_amdgcn_s_barrier()
; #define PG8_SCHED __builtin_amdgcn_sched_barrier(0)
; template <class Epi, class Sched, bool ALIGN_EPI = false, bool SP2 = false>
; __device__ __forceinline__ void gemm_phase(PG8_LAS unsigned char* lds, const Gemm g, const Sched& S, const Epi& E) {
;     ...
;             PG8_WAIT_V(8); PG8_WAIT_L(0); PG8_BAR; PG8_MMA(1, 0, At, B0); PG8_MMA(1, 1, At, B1); PG8_BAR; PG8_SCHED;
;             PG8_LDB(B0, 1, 0); PG8_LDB(B1, 1, 1); PG8_SCHED; PG8_LDA(At, 1, 0); PG8_STAGE(PG8_SA(0, 1), a2 + hstep, voffA);
;             PG8_WAIT_V(8); PG8_WAIT_L(0); PG8_BAR; PG8_MMA(0, 0, At, B0); PG8_MMA(0, 1, At, B1); PG8_BAR; PG8_SCHED;
;             PG8_LDA(At, 1, 1); PG8_STAGE(PG8_SB(1, 0), b3, voffB); PG8_STAGE(PG8_SB(1, 1), b3 + hstep, voffB); PG8_STAGE(PG8_SA(1, 0), a3, voffA);
	s_waitcnt lgkmcnt(0)
	v_mfma_f32_16x16x32_bf16 v[62:65], v[144:147], v[176:179], v[62:65]
	v_mfma_f32_16x16x32_bf16 v[58:61], v[152:155], v[176:179], v[58:61]
	v_mfma_f32_16x16x32_bf16 v[54:57], v[144:147], v[184:187], v[54:57]
	v_mfma_f32_16x16x32_bf16 v[50:53], v[152:155], v[184:187], v[50:53]
	v_mfma_f32_16x16x32_bf16 v[38:41], v[144:147], v[192:195], v[38:41]
	v_mfma_f32_16x16x32_bf16 v[34:37], v[152:155], v[192:195], v[34:37]
	v_mfma_f32_16x16x32_bf16 v[22:25], v[144:147], v[200:203], v[22:25]
	v_mfma_f32_16x16x32_bf16 v[18:21], v[152:155], v[200:203], v[18:21]
	v_mfma_f32_16x16x32_bf16 v[62:65], v[148:151], v[180:183], v[62:65]
	v_mfma_f32_16x16x32_bf16 v[58:61], v[156:159], v[180:183], v[58:61]
	v_mfma_f32_16x16x32_bf16 v[54:57], v[148:151], v[188:191], v[54:57]
	v_mfma_f32_16x16x32_bf16 v[50:53], v[156:159], v[188:191], v[50:53]
	v_mfma_f32_16x16x32_bf16 v[38:41], v[148:151], v[196:199], v[38:41]
	v_mfma_f32_16x16x32_bf16 v[34:37], v[156:159], v[196:199], v[34:37]
	v_mfma_f32_16x16x32_bf16 v[22:25], v[148:151], v[204:207], v[22:25]
	v_mfma_f32_16x16x32_bf16 v[18:21], v[156:159], v[204:207], v[18:21]
	v_mfma_f32_16x16x32_bf16 v[46:49], v[160:163], v[176:179], v[46:49]
	v_mfma_f32_16x16x32_bf16 v[42:45], v[168:171], v[176:179], v[42:45]
	v_mfma_f32_16x16x32_bf16 v[30:33], v[160:163], v[184:187], v[30:33]
	v_mfma_f32_16x16x32_bf16 v[26:29], v[168:171], v[184:187], v[26:29]
	v_mfma_f32_16x16x32_bf16 v[14:17], v[160:163], v[192:195], v[14:17]
	v_mfma_f32_16x16x32_bf16 v[10:13], v[168:171], v[192:195], v[10:13]
	v_mfma_f32_16x16x32_bf16 v[6:9], v[160:163], v[200:203], v[6:9]
	v_mfma_f32_16x16x32_bf16 v[2:5], v[168:171], v[200:203], v[2:5]
	v_mfma_f32_16x16x32_bf16 v[46:49], v[164:167], v[180:183], v[46:49]
	v_mfma_f32_16x16x32_bf16 v[42:45], v[172:175], v[180:183], v[42:45]
	v_mfma_f32_16x16x32_bf16 v[30:33], v[164:167], v[188:191], v[30:33]
	v_mfma_f32_16x16x32_bf16 v[26:29], v[172:175], v[188:191], v[26:29]
	v_mfma_f32_16x16x32_bf16 v[14:17], v[164:167], v[196:199], v[14:17]
	v_mfma_f32_16x16x32_bf16 v[10:13], v[172:175], v[196:199], v[10:13]
	v_mfma_f32_16x16x32_bf16 v[6:9], v[164:167], v[204:207], v[6:9]
	v_mfma_f32_16x16x32_bf16 v[2:5], v[172:175], v[204:207], v[2:5]
	s_barrier
	s_add_i32 s54, 0, 0x18000
	s_add_i32 s55, 0, 0x1c000
	v_add_u32_e32 v156, s54, v138
	v_add_u32_e32 v172, s55, v138
	ds_read_b128 v[144:147], v156
	ds_read_b128 v[148:151], v156 offset:1024
	ds_read_b128 v[152:155], v156 offset:2048
	ds_read_b128 v[156:159], v156 offset:3072
	ds_read_b128 v[160:163], v172
	ds_read_b128 v[164:167], v172 offset:1024
	ds_read_b128 v[168:171], v172 offset:2048
	ds_read_b128 v[172:175], v172 offset:3072
	s_add_u32 s38, s44, 0x160000
	s_addc_u32 s39, s45, 0
	s_mov_b32 m0, s25
	v_lshl_add_u64 v[216:217], s[38:39], 0, v[132:133]
	ds_read_b128 v[176:179], v143 offset:32768
	ds_read_b128 v[180:183], v143 offset:33792
	ds_read_b128 v[184:187], v143 offset:34816
	ds_read_b128 v[188:191], v143 offset:35840
	ds_read_b128 v[192:195], v143 offset:36864
	ds_read_b128 v[196:199], v143 offset:37888
	ds_read_b128 v[200:203], v143 offset:38912
	ds_read_b128 v[204:207], v143 offset:39936
	global_load_lds_dwordx4 v[216:217], off
	v_lshl_add_u64 v[216:217], s[38:39], 0, v[130:131]
	s_mov_b32 m0, s26
	s_nop 0
	global_load_lds_dwordx4 v[216:217], off
	s_waitcnt vmcnt(8)
	s_waitcnt lgkmcnt(0)
	s_barrier
	s_waitcnt lgkmcnt(0)
	v_mfma_f32_16x16x32_bf16 v[126:129], v[144:147], v[176:179], v[126:129]
	v_mfma_f32_16x16x32_bf16 v[122:125], v[152:155], v[176:179], v[122:125]
	v_mfma_f32_16x16x32_bf16 v[118:121], v[144:147], v[184:187], v[118:121]
	v_mfma_f32_16x16x32_bf16 v[114:117], v[152:155], v[184:187], v[114:117]
	v_mfma_f32_16x16x32_bf16 v[106:109], v[144:147], v[192:195], v[106:109]
	v_mfma_f32_16x16x32_bf16 v[98:101], v[152:155], v[192:195], v[98:101]
	v_mfma_f32_16x16x32_bf16 v[90:93], v[144:147], v[200:203], v[90:93]
	v_mfma_f32_16x16x32_bf16 v[82:85], v[152:155], v[200:203], v[82:85]
	v_mfma_f32_16x16x32_bf16 v[126:129], v[148:151], v[180:183], v[126:129]
	v_mfma_f32_16x16x32_bf16 v[122:125], v[156:159], v[180:183], v[122:125]
	v_mfma_f32_16x16x32_bf16 v[118:121], v[148:151], v[188:191], v[118:121]
	v_mfma_f32_16x16x32_bf16 v[114:117], v[156:159], v[188:191], v[114:117]
	v_mfma_f32_16x16x32_bf16 v[106:109], v[148:151], v[196:199], v[106:109]
	v_mfma_f32_16x16x32_bf16 v[98:101], v[156:159], v[196:199], v[98:101]
	v_mfma_f32_16x16x32_bf16 v[90:93], v[148:151], v[204:207], v[90:93]
	v_mfma_f32_16x16x32_bf16 v[82:85], v[156:159], v[204:207], v[82:85]
	v_mfma_f32_16x16x32_bf16 v[110:113], v[160:163], v[176:179], v[110:113]
	v_mfma_f32_16x16x32_bf16 v[102:105], v[168:171], v[176:179], v[102:105]
	v_mfma_f32_16x16x32_bf16 v[94:97], v[160:163], v[184:187], v[94:97]
	v_mfma_f32_16x16x32_bf16 v[86:89], v[168:171], v[184:187], v[86:89]
	v_mfma_f32_16x16x32_bf16 v[78:81], v[160:163], v[192:195], v[78:81]
	v_mfma_f32_16x16x32_bf16 v[74:77], v[168:171], v[192:195], v[74:77]
	v_mfma_f32_16x16x32_bf16 v[70:73], v[160:163], v[200:203], v[70:73]
	v_mfma_f32_16x16x32_bf16 v[66:69], v[168:171], v[200:203], v[66:69]
	v_mfma_f32_16x16x32_bf16 v[110:113], v[164:167], v[180:183], v[110:113]
	v_mfma_f32_16x16x32_bf16 v[102:105], v[172:175], v[180:183], v[102:105]
	v_mfma_f32_16x16x32_bf16 v[94:97], v[164:167], v[188:191], v[94:97]
	v_mfma_f32_16x16x32_bf16 v[86:89], v[172:175], v[188:191], v[86:89]
	v_mfma_f32_16x16x32_bf16 v[78:81], v[164:167], v[196:199], v[78:81]
	v_mfma_f32_16x16x32_bf16 v[74:77], v[172:175], v[196:199], v[74:77]
	v_mfma_f32_16x16x32_bf16 v[70:73], v[164:167], v[204:207], v[70:73]
	v_mfma_f32_16x16x32_bf16 v[66:69], v[172:175], v[204:207], v[66:69]
	s_barrier
; #define PG8_STAGE(bufoff, gbase, voff) do { _Pragma("unroll") for (int _i = 0; _i < 2; ++_i) \
;         __builtin_amdgcn_global_load_lds((const unsigned*)((const char*)(gbase) + (voff)[_i]), (PG8_LAS unsigned*)(lds + (bufoff) + ldsw + _i * 8192), 16, 0, 0); } while (0)
; #define PG8_LDA(dst, b, h) do { _Pragma("unroll") for (int m = 0; m < 4; ++m) _Pragma("unroll") for (int k = 0; k < 2; ++k) dst[m][k] = *(const PG8_LAS bf16x8*)(lds + PG8_SA(b, h) + aoff + m * 2048 + k * 1024); } while (0)
; #define PG8_MMA(ai, bj, At, Bt) do { __builtin_amdgcn_s_setprio(1); _Pragma("unroll") for (int m = 0; m < 4; ++m) _Pragma("unroll") for (int n = 0; n < 2; ++n) _Pragma("unroll") for (int k = 0; k < 2; ++k) \
;         acc[ai][bj][m][n] = __builtin_amdgcn_mfma_f32_16x16x32_bf16(Bt[n][k], At[m][k], acc[ai][bj][m][n], 0, 0, 0); __builtin_amdgcn_s_setprio(0); } while (0)
; #define PG8_WAIT_V(n) asm volatile("s_waitcnt vmcnt(" #n ")" ::: "memory")
; #define PG8_WAIT_L(n) asm volatile("s_waitcnt lgkmcnt(" #n ")" ::: "memory")
; #define PG8_BAR __builtin_amdgcn_s_barrier()
; #define PG8_SCHED __builtin_amdgcn_sched_barrier(0)
; template <class Epi, class Sched, bool ALIGN_EPI = false, bool SP2 = false>
; __device__ __forceinline__ void gemm_phase(PG8_LAS unsigned char* lds, const Gemm g, const Sched& S, const Epi& E) {
;     ...
;             PG8_LDA(At, 1, 1); PG8_STAGE(PG8_SB(1, 0), b3, voffB); PG8_STAGE(PG8_SB(1, 1), b3 + hstep, voffB); PG8_STAGE(PG8_SA(1, 0), a3, voffA);
;             PG8_WAIT_V(8); PG8_WAIT_L(0); PG8_BAR; PG8_MMA(1, 0, At, B0); PG8_MMA(1, 1, At, B1); PG8_BAR; PG8_SCHED;
	s_add_i32 s38, s54, s16
	v_lshl_add_u64 v[208:209], v[208:209], 0, s[14:15]
	s_mov_b32 m0, s38
	ds_read_b128 v[176:179], v143 offset:49152
	ds_read_b128 v[180:183], v143 offset:50176
	ds_read_b128 v[184:187], v143 offset:51200
	ds_read_b128 v[188:191], v143 offset:52224
	ds_read_b128 v[192:195], v143 offset:53248
	ds_read_b128 v[196:199], v143 offset:54272
	ds_read_b128 v[200:203], v143 offset:55296
	ds_read_b128 v[204:207], v143 offset:56320
	global_load_lds_dwordx4 v[208:209], off
	s_add_i32 m0, s38, 0x2000
	s_add_u32 s38, s42, 0x160080
	v_lshl_add_u64 v[208:209], v[210:211], 0, s[14:15]
	s_addc_u32 s39, s43, 0
	s_add_i32 s42, s55, s16
	global_load_lds_dwordx4 v[208:209], off
	v_lshl_add_u64 v[208:209], s[38:39], 0, v[132:133]
	s_mov_b32 m0, s42
	s_nop 0
	global_load_lds_dwordx4 v[208:209], off
	v_lshl_add_u64 v[208:209], s[38:39], 0, v[130:131]
	s_add_i32 m0, s42, 0x2000
	s_nop 0
	global_load_lds_dwordx4 v[208:209], off
	v_lshl_add_u64 v[208:209], v[212:213], 0, s[14:15]
	s_mov_b32 m0, s29
	s_nop 0
	global_load_lds_dwordx4 v[208:209], off
	v_lshl_add_u64 v[208:209], v[214:215], 0, s[14:15]
	s_mov_b32 m0, s30
	s_nop 0
	global_load_lds_dwordx4 v[208:209], off
	s_waitcnt vmcnt(8)
	s_waitcnt lgkmcnt(0)
	s_barrier
	s_waitcnt lgkmcnt(0)
	v_mfma_f32_16x16x32_bf16 v[62:65], v[144:147], v[176:179], v[62:65]
	v_mfma_f32_16x16x32_bf16 v[58:61], v[152:155], v[176:179], v[58:61]
	v_mfma_f32_16x16x32_bf16 v[54:57], v[144:147], v[184:187], v[54:57]
	v_mfma_f32_16x16x32_bf16 v[50:53], v[152:155], v[184:187], v[50:53]
	v_mfma_f32_16x16x32_bf16 v[38:41], v[144:147], v[192:195], v[38:41]
	v_mfma_f32_16x16x32_bf16 v[34:37], v[152:155], v[192:195], v[34:37]
	v_mfma_f32_16x16x32_bf16 v[22:25], v[144:147], v[200:203], v[22:25]
	v_mfma_f32_16x16x32_bf16 v[18:21], v[152:155], v[200:203], v[18:21]
	v_mfma_f32_16x16x32_bf16 v[62:65], v[148:151], v[180:183], v[62:65]
	v_mfma_f32_16x16x32_bf16 v[58:61], v[156:159], v[180:183], v[58:61]
	v_mfma_f32_16x16x32_bf16 v[54:57], v[148:151], v[188:191], v[54:57]
	v_mfma_f32_16x16x32_bf16 v[50:53], v[156:159], v[188:191], v[50:53]
	v_mfma_f32_16x16x32_bf16 v[38:41], v[148:151], v[196:199], v[38:41]
	v_mfma_f32_16x16x32_bf16 v[34:37], v[156:159], v[196:199], v[34:37]
	v_mfma_f32_16x16x32_bf16 v[22:25], v[148:151], v[204:207], v[22:25]
	v_mfma_f32_16x16x32_bf16 v[18:21], v[156:159], v[204:207], v[18:21]
	v_mfma_f32_16x16x32_bf16 v[46:49], v[160:163], v[176:179], v[46:49]
	v_mfma_f32_16x16x32_bf16 v[42:45], v[168:171], v[176:179], v[42:45]
	v_mfma_f32_16x16x32_bf16 v[30:33], v[160:163], v[184:187], v[30:33]
	v_mfma_f32_16x16x32_bf16 v[26:29], v[168:171], v[184:187], v[26:29]
	v_mfma_f32_16x16x32_bf16 v[14:17], v[160:163], v[192:195], v[14:17]
	v_mfma_f32_16x16x32_bf16 v[10:13], v[168:171], v[192:195], v[10:13]
	v_mfma_f32_16x16x32_bf16 v[6:9], v[160:163], v[200:203], v[6:9]
	v_mfma_f32_16x16x32_bf16 v[2:5], v[168:171], v[200:203], v[2:5]
	v_mfma_f32_16x16x32_bf16 v[46:49], v[164:167], v[180:183], v[46:49]
	v_mfma_f32_16x16x32_bf16 v[42:45], v[172:175], v[180:183], v[42:45]
	v_mfma_f32_16x16x32_bf16 v[30:33], v[164:167], v[188:191], v[30:33]
	v_mfma_f32_16x16x32_bf16 v[26:29], v[172:175], v[188:191], v[26:29]
	v_mfma_f32_16x16x32_bf16 v[14:17], v[164:167], v[196:199], v[14:17]
	v_mfma_f32_16x16x32_bf16 v[10:13], v[172:175], v[196:199], v[10:13]
	v_mfma_f32_16x16x32_bf16 v[6:9], v[164:167], v[204:207], v[6:9]
	v_mfma_f32_16x16x32_bf16 v[2:5], v[172:175], v[204:207], v[2:5]
	s_barrier
	s_add_i32 s53, s53, 2
	s_add_u32 s11, s11, 0x100
	s_addc_u32 s52, s52, 0
	s_cmp_gt_u32 s53, 19
	s_mov_b64 s[38:39], s[40:41]
	s_cbranch_scc0 .LBB0_193
	s_and_b64 vcc, exec, s[20:21]
	s_cbranch_vccz .LBB0_196
	s_barrier

; #define PG8_STAGE(bufoff, gbase, voff) do { _Pragma("unroll") for (int _i = 0; _i < 2; ++_i) \
;         __builtin_amdgcn_global_load_lds((const unsigned*)((const char*)(gbase) + (voff)[_i]), (PG8_LAS unsigned*)(lds + (bufoff) + ldsw + _i * 8192), 16, 0, 0); } while (0)
; #define PG8_LDA(dst, b, h) do { _Pragma("unroll") for (int m = 0; m < 4; ++m) _Pragma("unroll") for (int k = 0; k < 2; ++k) dst[m][k] = *(const PG8_LAS bf16x8*)(lds + PG8_SA(b, h) + aoff + m * 2048 + k * 1024); } while (0)
; #define PG8_LDB(dst, b, h) do { _Pragma("unroll") for (int n = 0; n < 2; ++n) _Pragma("unroll") for (int k = 0; k < 2; ++k) dst[n][k] = *(const PG8_LAS bf16x8*)(lds + PG8_SB(b, h) + boff + n * 2048 + k * 1024); } while (0)
; #define PG8_WAIT_V(n) asm volatile("s_waitcnt vmcnt(" #n ")" ::: "memory")
; #define PG8_WAIT_L(n) asm volatile("s_waitcnt lgkmcnt(" #n ")" ::: "memory")
; #define PG8_BAR __builtin_amdgcn_s_barrier()
; template <class Epi, class Sched, bool ALIGN_EPI = false, bool SP2 = false>
; __device__ __forceinline__ void gemm_phase(PG8_LAS unsigned char* lds, const Gemm g, const Sched& S, const Epi& E) {
;     ...
;         const char* nA = has_next ? (const char*)g.A + (size_t)nxt.pm * tstep + (size_t)nxt.kt0 * kstep : cA; const char* nB = has_next ? (const char*)g.Bt + (size_t)nxt.pn * tstep + (size_t)nxt.kt0 * kstep : cB;
;         for (int t = 0; t < nt; t += 2) {
;             if constexpr (Epi::MIDHOOK) { if (t == (nt >> 1)) E.mid(acc, cur, wr, wc, fr, fq); }
;             const bool last = (t == nt - 2);
;             const char* a1 = cA + (size_t)(t + 1) * kstep;
;             const char* a2 = last ? nA : cA + (size_t)(t + 2) * kstep; const char* b2 = last ? nB : cB + (size_t)(t + 2) * kstep;
;             const char* a3 = a2 + kstep; const char* b3 = b2 + kstep;
;             if (last && has_next) S.a_ready(nxt);
;             if constexpr (SP2) {
;             PG8_LDB(B0, 0, 0); PG8_LDB(B1, 0, 1); PG8_SCHED; PG8_LDA(At, 0, 0); PG8_STAGE(PG8_SA(1, 1), a1 + hstep, voffA);
;             PG8_WAIT_V(8); PG8_WAIT_L(0); PG8_BAR; PG8_MMA(0, 0, At, B0); PG8_MMA(0, 1, At, B1); PG8_BAR; PG8_SCHED;
;             PG8_LDA(At, 0, 1); PG8_STAGE(PG8_SB(0, 0), b2, voffB); PG8_STAGE(PG8_SB(0, 1), b2 + hstep, voffB); PG8_STAGE(PG8_SA(0, 0), a2, voffA);
;             PG8_WAIT_V(8); PG8_WAIT_L(0); PG8_BAR; PG8_MMA(1, 0, At, B0); PG8_MMA(1, 1, At, B1); PG8_BAR; PG8_SCHED;
.LBB0_346:
	ds_read_b128 v[150:153], v177
	ds_read_b128 v[154:157], v177 offset:1024
	ds_read_b128 v[158:161], v177 offset:2048
	ds_read_b128 v[162:165], v177 offset:3072
	ds_read_b128 v[166:169], v178
	ds_read_b128 v[182:185], v178 offset:1024
	ds_read_b128 v[186:189], v178 offset:2048
	ds_read_b128 v[190:193], v178 offset:3072
	s_add_u32 s14, s10, 0xfff80080
	s_addc_u32 s15, s11, -1
	s_cmp_eq_u32 s23, 28
	s_cselect_b32 s17, s6, s15
	s_cselect_b32 s16, s7, s14
	s_cselect_b32 s15, s13, s22
	s_cselect_b32 s14, s18, s19
	v_lshl_add_u64 v[170:171], s[10:11], 0, v[142:143]
	s_add_i32 m0, s59, 0xc000
	ds_read_b128 v[194:197], v179
	ds_read_b128 v[198:201], v179 offset:1024
	ds_read_b128 v[202:205], v179 offset:2048
	ds_read_b128 v[206:209], v179 offset:3072
	ds_read_b128 v[210:213], v179 offset:4096
	ds_read_b128 v[214:217], v179 offset:5120
	ds_read_b128 v[218:221], v179 offset:6144
	ds_read_b128 v[222:225], v179 offset:7168
	global_load_lds_dwordx4 v[170:171], off
	v_lshl_add_u64 v[170:171], s[10:11], 0, v[144:145]
	s_add_i32 m0, s59, 0xe000
	s_nop 0
	global_load_lds_dwordx4 v[170:171], off
	s_waitcnt vmcnt(8)
	s_waitcnt lgkmcnt(0)
	s_barrier
	s_waitcnt lgkmcnt(0)
	v_mfma_f32_16x16x32_bf16 v[58:61], v[150:153], v[194:197], v[58:61]
	v_mfma_f32_16x16x32_bf16 v[62:65], v[158:161], v[194:197], v[62:65]
	v_mfma_f32_16x16x32_bf16 v[50:53], v[150:153], v[202:205], v[50:53]
	v_mfma_f32_16x16x32_bf16 v[54:57], v[158:161], v[202:205], v[54:57]
	v_mfma_f32_16x16x32_bf16 v[42:45], v[150:153], v[210:213], v[42:45]
	v_mfma_f32_16x16x32_bf16 v[46:49], v[158:161], v[210:213], v[46:49]
	v_mfma_f32_16x16x32_bf16 v[34:37], v[150:153], v[218:221], v[34:37]
	v_mfma_f32_16x16x32_bf16 v[38:41], v[158:161], v[218:221], v[38:41]
	v_mfma_f32_16x16x32_bf16 v[58:61], v[154:157], v[198:201], v[58:61]
	v_mfma_f32_16x16x32_bf16 v[62:65], v[162:165], v[198:201], v[62:65]
	v_mfma_f32_16x16x32_bf16 v[50:53], v[154:157], v[206:209], v[50:53]
	v_mfma_f32_16x16x32_bf16 v[54:57], v[162:165], v[206:209], v[54:57]
	v_mfma_f32_16x16x32_bf16 v[42:45], v[154:157], v[214:217], v[42:45]
	v_mfma_f32_16x16x32_bf16 v[46:49], v[162:165], v[214:217], v[46:49]
	v_mfma_f32_16x16x32_bf16 v[34:37], v[154:157], v[222:225], v[34:37]
	v_mfma_f32_16x16x32_bf16 v[38:41], v[162:165], v[222:225], v[38:41]
	v_mfma_f32_16x16x32_bf16 v[126:129], v[166:169], v[194:197], v[126:129]
	v_mfma_f32_16x16x32_bf16 v[122:125], v[186:189], v[194:197], v[122:125]
	v_mfma_f32_16x16x32_bf16 v[118:121], v[166:169], v[202:205], v[118:121]
	v_mfma_f32_16x16x32_bf16 v[114:117], v[186:189], v[202:205], v[114:117]
	v_mfma_f32_16x16x32_bf16 v[110:113], v[166:169], v[210:213], v[110:113]
	v_mfma_f32_16x16x32_bf16 v[106:109], v[186:189], v[210:213], v[106:109]
	v_mfma_f32_16x16x32_bf16 v[102:105], v[166:169], v[218:221], v[102:105]
	v_mfma_f32_16x16x32_bf16 v[98:101], v[186:189], v[218:221], v[98:101]
	v_mfma_f32_16x16x32_bf16 v[126:129], v[182:185], v[198:201], v[126:129]
	v_mfma_f32_16x16x32_bf16 v[122:125], v[190:193], v[198:201], v[122:125]
	v_mfma_f32_16x16x32_bf16 v[118:121], v[182:185], v[206:209], v[118:121]
	v_mfma_f32_16x16x32_bf16 v[114:117], v[190:193], v[206:209], v[114:117]
	v_mfma_f32_16x16x32_bf16 v[110:113], v[182:185], v[214:217], v[110:113]
	v_mfma_f32_16x16x32_bf16 v[106:109], v[190:193], v[214:217], v[106:109]
	v_mfma_f32_16x16x32_bf16 v[102:105], v[182:185], v[222:225], v[102:105]
	v_mfma_f32_16x16x32_bf16 v[98:101], v[190:193], v[222:225], v[98:101]
	s_barrier
	s_add_i32 s24, s95, s55
	v_lshl_add_u64 v[170:171], s[14:15], 0, v[132:133]
	s_mov_b32 m0, s24
	ds_read_b128 v[194:197], v179 offset:16384
	ds_read_b128 v[198:201], v179 offset:17408
	ds_read_b128 v[202:205], v179 offset:18432
	ds_read_b128 v[206:209], v179 offset:19456
	ds_read_b128 v[210:213], v179 offset:20480
	ds_read_b128 v[214:217], v179 offset:21504
	ds_read_b128 v[218:221], v179 offset:22528
	ds_read_b128 v[222:225], v179 offset:23552
	global_load_lds_dwordx4 v[170:171], off
	s_add_i32 m0, s24, 0x2000
	s_add_u32 s24, s14, 0x80000
	v_lshl_add_u64 v[226:227], s[14:15], 0, v[136:137]
	s_addc_u32 s25, s15, 0
	s_add_i32 s26, s81, s55
	global_load_lds_dwordx4 v[226:227], off
	v_lshl_add_u64 v[228:229], s[24:25], 0, v[132:133]
	s_mov_b32 m0, s26
	v_lshl_add_u64 v[230:231], s[16:17], 0, v[134:135]
	global_load_lds_dwordx4 v[228:229], off
	v_lshl_add_u64 v[228:229], s[24:25], 0, v[136:137]
	s_add_i32 m0, s26, 0x2000
	s_nop 0
	global_load_lds_dwordx4 v[228:229], off
	v_lshl_add_u64 v[228:229], s[16:17], 0, v[130:131]
	s_mov_b32 m0, s59
	s_nop 0
	global_load_lds_dwordx4 v[228:229], off
	s_mov_b32 m0, s61
	s_nop 0
	global_load_lds_dwordx4 v[230:231], off
	s_waitcnt vmcnt(8)
	s_waitcnt lgkmcnt(0)
	s_barrier
; #define PG8_STAGE(bufoff, gbase, voff) do { _Pragma("unroll") for (int _i = 0; _i < 2; ++_i) \
;         __builtin_amdgcn_global_load_lds((const unsigned*)((const char*)(gbase) + (voff)[_i]), (PG8_LAS unsigned*)(lds + (bufoff) + ldsw + _i * 8192), 16, 0, 0); } while (0)
; #define PG8_LDA(dst, b, h) do { _Pragma("unroll") for (int m = 0; m < 4; ++m) _Pragma("unroll") for (int k = 0; k < 2; ++k) dst[m][k] = *(const PG8_LAS bf16x8*)(lds + PG8_SA(b, h) + aoff + m * 2048 + k * 1024); } while (0)
; #define PG8_LDB(dst, b, h) do { _Pragma("unroll") for (int n = 0; n < 2; ++n) _Pragma("unroll") for (int k = 0; k < 2; ++k) dst[n][k] = *(const PG8_LAS bf16x8*)(lds + PG8_SB(b, h) + boff + n * 2048 + k * 1024); } while (0)
; #define PG8_MMA(ai, bj, At, Bt) do { __builtin_amdgcn_s_setprio(1); _Pragma("unroll") for (int m = 0; m < 4; ++m) _Pragma("unroll") for (int n = 0; n < 2; ++n) _Pragma("unroll") for (int k = 0; k < 2; ++k) \
;         acc[ai][bj][m][n] = __builtin_amdgcn_mfma_f32_16x16x32_bf16(Bt[n][k], At[m][k], acc[ai][bj][m][n], 0, 0, 0); __builtin_amdgcn_s_setprio(0); } while (0)
; #define PG8_WAIT_V(n) asm volatile("s_waitcnt vmcnt(" #n ")" ::: "memory")
; #define PG8_WAIT_L(n) asm volatile("s_waitcnt lgkmcnt(" #n ")" ::: "memory")
; #define PG8_BAR __builtin_amdgcn_s_barrier()
; #define PG8_SCHED __builtin_amdgcn_sched_barrier(0)
; template <class Epi, class Sched, bool ALIGN_EPI = false, bool SP2 = false>
; __device__ __forceinline__ void gemm_phase(PG8_LAS unsigned char* lds, const Gemm g, const Sched& S, const Epi& E) {
;     ...
;             PG8_WAIT_V(8); PG8_WAIT_L(0); PG8_BAR; PG8_MMA(1, 0, At, B0); PG8_MMA(1, 1, At, B1); PG8_BAR; PG8_SCHED;
;             PG8_LDB(B0, 1, 0); PG8_LDB(B1, 1, 1); PG8_SCHED; PG8_LDA(At, 1, 0); PG8_STAGE(PG8_SA(0, 1), a2 + hstep, voffA);
;             PG8_WAIT_V(8); PG8_WAIT_L(0); PG8_BAR; PG8_MMA(0, 0, At, B0); PG8_MMA(0, 1, At, B1); PG8_BAR; PG8_SCHED;
;             PG8_LDA(At, 1, 1); PG8_STAGE(PG8_SB(1, 0), b3, voffB); PG8_STAGE(PG8_SB(1, 1), b3 + hstep, voffB); PG8_STAGE(PG8_SA(1, 0), a3, voffA);
	s_waitcnt lgkmcnt(0)
	v_mfma_f32_16x16x32_bf16 v[26:29], v[150:153], v[194:197], v[26:29]
	v_mfma_f32_16x16x32_bf16 v[30:33], v[158:161], v[194:197], v[30:33]
	v_mfma_f32_16x16x32_bf16 v[18:21], v[150:153], v[202:205], v[18:21]
	v_mfma_f32_16x16x32_bf16 v[22:25], v[158:161], v[202:205], v[22:25]
	v_mfma_f32_16x16x32_bf16 v[10:13], v[150:153], v[210:213], v[10:13]
	v_mfma_f32_16x16x32_bf16 v[14:17], v[158:161], v[210:213], v[14:17]
	v_mfma_f32_16x16x32_bf16 v[2:5], v[150:153], v[218:221], v[2:5]
	v_mfma_f32_16x16x32_bf16 v[6:9], v[158:161], v[218:221], v[6:9]
	v_mfma_f32_16x16x32_bf16 v[26:29], v[154:157], v[198:201], v[26:29]
	v_mfma_f32_16x16x32_bf16 v[30:33], v[162:165], v[198:201], v[30:33]
	v_mfma_f32_16x16x32_bf16 v[18:21], v[154:157], v[206:209], v[18:21]
	v_mfma_f32_16x16x32_bf16 v[22:25], v[162:165], v[206:209], v[22:25]
	v_mfma_f32_16x16x32_bf16 v[10:13], v[154:157], v[214:217], v[10:13]
	v_mfma_f32_16x16x32_bf16 v[14:17], v[162:165], v[214:217], v[14:17]
	v_mfma_f32_16x16x32_bf16 v[2:5], v[154:157], v[222:225], v[2:5]
	v_mfma_f32_16x16x32_bf16 v[6:9], v[162:165], v[222:225], v[6:9]
	v_mfma_f32_16x16x32_bf16 v[94:97], v[166:169], v[194:197], v[94:97]
	v_mfma_f32_16x16x32_bf16 v[90:93], v[186:189], v[194:197], v[90:93]
	v_mfma_f32_16x16x32_bf16 v[86:89], v[166:169], v[202:205], v[86:89]
	v_mfma_f32_16x16x32_bf16 v[82:85], v[186:189], v[202:205], v[82:85]
	v_mfma_f32_16x16x32_bf16 v[78:81], v[166:169], v[210:213], v[78:81]
	v_mfma_f32_16x16x32_bf16 v[74:77], v[186:189], v[210:213], v[74:77]
	v_mfma_f32_16x16x32_bf16 v[70:73], v[166:169], v[218:221], v[70:73]
	v_mfma_f32_16x16x32_bf16 v[66:69], v[186:189], v[218:221], v[66:69]
	v_mfma_f32_16x16x32_bf16 v[94:97], v[182:185], v[198:201], v[94:97]
	v_mfma_f32_16x16x32_bf16 v[90:93], v[190:193], v[198:201], v[90:93]
	v_mfma_f32_16x16x32_bf16 v[86:89], v[182:185], v[206:209], v[86:89]
	v_mfma_f32_16x16x32_bf16 v[82:85], v[190:193], v[206:209], v[82:85]
	v_mfma_f32_16x16x32_bf16 v[78:81], v[182:185], v[214:217], v[78:81]
	v_mfma_f32_16x16x32_bf16 v[74:77], v[190:193], v[214:217], v[74:77]
	v_mfma_f32_16x16x32_bf16 v[70:73], v[182:185], v[222:225], v[70:73]
	v_mfma_f32_16x16x32_bf16 v[66:69], v[190:193], v[222:225], v[66:69]
	s_barrier
	s_add_i32 s24, 0, 0x18000
	v_add_u32_e32 v138, s24, v172
	s_add_i32 s25, 0, 0x1c000
	ds_read_b128 v[150:153], v138
	ds_read_b128 v[154:157], v138 offset:1024
	ds_read_b128 v[158:161], v138 offset:2048
	ds_read_b128 v[162:165], v138 offset:3072
	v_add_u32_e32 v138, s25, v172
	ds_read_b128 v[166:169], v138
	ds_read_b128 v[182:185], v138 offset:1024
	ds_read_b128 v[186:189], v138 offset:2048
	ds_read_b128 v[190:193], v138 offset:3072
	s_add_u32 s16, s16, 0x80000
	s_addc_u32 s17, s17, 0
	s_mov_b32 m0, s63
	v_lshl_add_u64 v[232:233], s[16:17], 0, v[130:131]
	ds_read_b128 v[194:197], v179 offset:32768
	ds_read_b128 v[198:201], v179 offset:33792
	ds_read_b128 v[202:205], v179 offset:34816
	ds_read_b128 v[206:209], v179 offset:35840
	ds_read_b128 v[210:213], v179 offset:36864
	ds_read_b128 v[214:217], v179 offset:37888
	ds_read_b128 v[218:221], v179 offset:38912
	ds_read_b128 v[222:225], v179 offset:39936
	global_load_lds_dwordx4 v[232:233], off
	v_lshl_add_u64 v[232:233], s[16:17], 0, v[134:135]
	s_mov_b32 m0, s65
	s_nop 0
	global_load_lds_dwordx4 v[232:233], off
	s_waitcnt vmcnt(8)
	s_waitcnt lgkmcnt(0)
	s_barrier
	s_waitcnt lgkmcnt(0)
	v_mfma_f32_16x16x32_bf16 v[58:61], v[150:153], v[194:197], v[58:61]
	v_mfma_f32_16x16x32_bf16 v[62:65], v[158:161], v[194:197], v[62:65]
	v_mfma_f32_16x16x32_bf16 v[50:53], v[150:153], v[202:205], v[50:53]
	v_mfma_f32_16x16x32_bf16 v[54:57], v[158:161], v[202:205], v[54:57]
	v_mfma_f32_16x16x32_bf16 v[42:45], v[150:153], v[210:213], v[42:45]
	v_mfma_f32_16x16x32_bf16 v[46:49], v[158:161], v[210:213], v[46:49]
	v_mfma_f32_16x16x32_bf16 v[34:37], v[150:153], v[218:221], v[34:37]
	v_mfma_f32_16x16x32_bf16 v[38:41], v[158:161], v[218:221], v[38:41]
	v_mfma_f32_16x16x32_bf16 v[58:61], v[154:157], v[198:201], v[58:61]
	v_mfma_f32_16x16x32_bf16 v[62:65], v[162:165], v[198:201], v[62:65]
	v_mfma_f32_16x16x32_bf16 v[50:53], v[154:157], v[206:209], v[50:53]
	v_mfma_f32_16x16x32_bf16 v[54:57], v[162:165], v[206:209], v[54:57]
	v_mfma_f32_16x16x32_bf16 v[42:45], v[154:157], v[214:217], v[42:45]
	v_mfma_f32_16x16x32_bf16 v[46:49], v[162:165], v[214:217], v[46:49]
	v_mfma_f32_16x16x32_bf16 v[34:37], v[154:157], v[222:225], v[34:37]
	v_mfma_f32_16x16x32_bf16 v[38:41], v[162:165], v[222:225], v[38:41]
	v_mfma_f32_16x16x32_bf16 v[126:129], v[166:169], v[194:197], v[126:129]
	v_mfma_f32_16x16x32_bf16 v[122:125], v[186:189], v[194:197], v[122:125]
	v_mfma_f32_16x16x32_bf16 v[118:121], v[166:169], v[202:205], v[118:121]
	v_mfma_f32_16x16x32_bf16 v[114:117], v[186:189], v[202:205], v[114:117]
	v_mfma_f32_16x16x32_bf16 v[110:113], v[166:169], v[210:213], v[110:113]
	v_mfma_f32_16x16x32_bf16 v[106:109], v[186:189], v[210:213], v[106:109]
	v_mfma_f32_16x16x32_bf16 v[102:105], v[166:169], v[218:221], v[102:105]
	v_mfma_f32_16x16x32_bf16 v[98:101], v[186:189], v[218:221], v[98:101]
	v_mfma_f32_16x16x32_bf16 v[126:129], v[182:185], v[198:201], v[126:129]
	v_mfma_f32_16x16x32_bf16 v[122:125], v[190:193], v[198:201], v[122:125]
	v_mfma_f32_16x16x32_bf16 v[118:121], v[182:185], v[206:209], v[118:121]
	v_mfma_f32_16x16x32_bf16 v[114:117], v[190:193], v[206:209], v[114:117]
	v_mfma_f32_16x16x32_bf16 v[110:113], v[182:185], v[214:217], v[110:113]
	v_mfma_f32_16x16x32_bf16 v[106:109], v[190:193], v[214:217], v[106:109]
	v_mfma_f32_16x16x32_bf16 v[102:105], v[182:185], v[222:225], v[102:105]
	v_mfma_f32_16x16x32_bf16 v[98:101], v[190:193], v[222:225], v[98:101]
	s_barrier
; #define PG8_STAGE(bufoff, gbase, voff) do { _Pragma("unroll") for (int _i = 0; _i < 2; ++_i) \
;         __builtin_amdgcn_global_load_lds((const unsigned*)((const char*)(gbase) + (voff)[_i]), (PG8_LAS unsigned*)(lds + (bufoff) + ldsw + _i * 8192), 16, 0, 0); } while (0)
; #define PG8_LDA(dst, b, h) do { _Pragma("unroll") for (int m = 0; m < 4; ++m) _Pragma("unroll") for (int k = 0; k < 2; ++k) dst[m][k] = *(const PG8_LAS bf16x8*)(lds + PG8_SA(b, h) + aoff + m * 2048 + k * 1024); } while (0)
; #define PG8_MMA(ai, bj, At, Bt) do { __builtin_amdgcn_s_setprio(1); _Pragma("unroll") for (int m = 0; m < 4; ++m) _Pragma("unroll") for (int n = 0; n < 2; ++n) _Pragma("unroll") for (int k = 0; k < 2; ++k) \
;         acc[ai][bj][m][n] = __builtin_amdgcn_mfma_f32_16x16x32_bf16(Bt[n][k], At[m][k], acc[ai][bj][m][n], 0, 0, 0); __builtin_amdgcn_s_setprio(0); } while (0)
; #define PG8_WAIT_V(n) asm volatile("s_waitcnt vmcnt(" #n ")" ::: "memory")
; #define PG8_WAIT_L(n) asm volatile("s_waitcnt lgkmcnt(" #n ")" ::: "memory")
; #define PG8_BAR __builtin_amdgcn_s_barrier()
; #define PG8_SCHED __builtin_amdgcn_sched_barrier(0)
;     __device__ __forceinline__ void operator()(const f32x4 (&acc)[2][2][4][2], const Unit& u, int wr, int wc, int fr, int fq) const {
;         const int sec = u.pn >> 3, pnl = u.pn & 7;
;         if (sec == 7) {
; template <class Epi, class Sched, bool ALIGN_EPI = false, bool SP2 = false>
; __device__ __forceinline__ void gemm_phase(PG8_LAS unsigned char* lds, const Gemm g, const Sched& S, const Epi& E) {
;     ...
;             PG8_LDA(At, 1, 1); PG8_STAGE(PG8_SB(1, 0), b3, voffB); PG8_STAGE(PG8_SB(1, 1), b3 + hstep, voffB); PG8_STAGE(PG8_SA(1, 0), a3, voffA);
;             PG8_WAIT_V(8); PG8_WAIT_L(0); PG8_BAR; PG8_MMA(1, 0, At, B0); PG8_MMA(1, 1, At, B1); PG8_BAR; PG8_SCHED;
	s_add_i32 s16, s24, s55
	v_lshl_add_u64 v[170:171], v[170:171], 0, s[90:91]
	s_mov_b32 m0, s16
	ds_read_b128 v[194:197], v179 offset:49152
	ds_read_b128 v[198:201], v179 offset:50176
	ds_read_b128 v[202:205], v179 offset:51200
	ds_read_b128 v[206:209], v179 offset:52224
	ds_read_b128 v[210:213], v179 offset:53248
	ds_read_b128 v[214:217], v179 offset:54272
	ds_read_b128 v[218:221], v179 offset:55296
	ds_read_b128 v[222:225], v179 offset:56320
	global_load_lds_dwordx4 v[170:171], off
	s_add_i32 m0, s16, 0x2000
	s_add_u32 s14, s14, 0x80080
	v_lshl_add_u64 v[170:171], v[226:227], 0, s[90:91]
	s_addc_u32 s15, s15, 0
	s_add_i32 s16, s25, s55
	global_load_lds_dwordx4 v[170:171], off
	v_lshl_add_u64 v[170:171], s[14:15], 0, v[132:133]
	s_mov_b32 m0, s16
	s_nop 0
	global_load_lds_dwordx4 v[170:171], off
	v_lshl_add_u64 v[170:171], s[14:15], 0, v[136:137]
	s_add_i32 m0, s16, 0x2000
	s_nop 0
	global_load_lds_dwordx4 v[170:171], off
	v_lshl_add_u64 v[170:171], v[228:229], 0, s[90:91]
	s_mov_b32 m0, s92
	s_nop 0
	global_load_lds_dwordx4 v[170:171], off
	v_lshl_add_u64 v[170:171], v[230:231], 0, s[90:91]
	s_mov_b32 m0, s93
	s_nop 0
	global_load_lds_dwordx4 v[170:171], off
	s_waitcnt vmcnt(8)
	s_waitcnt lgkmcnt(0)
	s_barrier
	s_waitcnt lgkmcnt(0)
	v_mfma_f32_16x16x32_bf16 v[26:29], v[150:153], v[194:197], v[26:29]
	v_mfma_f32_16x16x32_bf16 v[30:33], v[158:161], v[194:197], v[30:33]
	v_mfma_f32_16x16x32_bf16 v[18:21], v[150:153], v[202:205], v[18:21]
	v_mfma_f32_16x16x32_bf16 v[22:25], v[158:161], v[202:205], v[22:25]
	v_mfma_f32_16x16x32_bf16 v[10:13], v[150:153], v[210:213], v[10:13]
	v_mfma_f32_16x16x32_bf16 v[14:17], v[158:161], v[210:213], v[14:17]
	v_mfma_f32_16x16x32_bf16 v[2:5], v[150:153], v[218:221], v[2:5]
	v_mfma_f32_16x16x32_bf16 v[6:9], v[158:161], v[218:221], v[6:9]
	v_mfma_f32_16x16x32_bf16 v[26:29], v[154:157], v[198:201], v[26:29]
	v_mfma_f32_16x16x32_bf16 v[30:33], v[162:165], v[198:201], v[30:33]
	v_mfma_f32_16x16x32_bf16 v[18:21], v[154:157], v[206:209], v[18:21]
	v_mfma_f32_16x16x32_bf16 v[22:25], v[162:165], v[206:209], v[22:25]
	v_mfma_f32_16x16x32_bf16 v[10:13], v[154:157], v[214:217], v[10:13]
	v_mfma_f32_16x16x32_bf16 v[14:17], v[162:165], v[214:217], v[14:17]
	v_mfma_f32_16x16x32_bf16 v[2:5], v[154:157], v[222:225], v[2:5]
	v_mfma_f32_16x16x32_bf16 v[6:9], v[162:165], v[222:225], v[6:9]
	v_mfma_f32_16x16x32_bf16 v[94:97], v[166:169], v[194:197], v[94:97]
	v_mfma_f32_16x16x32_bf16 v[90:93], v[186:189], v[194:197], v[90:93]
	v_mfma_f32_16x16x32_bf16 v[86:89], v[166:169], v[202:205], v[86:89]
	v_mfma_f32_16x16x32_bf16 v[82:85], v[186:189], v[202:205], v[82:85]
	v_mfma_f32_16x16x32_bf16 v[78:81], v[166:169], v[210:213], v[78:81]
	v_mfma_f32_16x16x32_bf16 v[74:77], v[186:189], v[210:213], v[74:77]
	v_mfma_f32_16x16x32_bf16 v[70:73], v[166:169], v[218:221], v[70:73]
	v_mfma_f32_16x16x32_bf16 v[66:69], v[186:189], v[218:221], v[66:69]
	v_mfma_f32_16x16x32_bf16 v[94:97], v[182:185], v[198:201], v[94:97]
	v_mfma_f32_16x16x32_bf16 v[90:93], v[190:193], v[198:201], v[90:93]
	v_mfma_f32_16x16x32_bf16 v[86:89], v[182:185], v[206:209], v[86:89]
	v_mfma_f32_16x16x32_bf16 v[82:85], v[190:193], v[206:209], v[82:85]
	v_mfma_f32_16x16x32_bf16 v[78:81], v[182:185], v[214:217], v[78:81]
	v_mfma_f32_16x16x32_bf16 v[74:77], v[190:193], v[214:217], v[74:77]
	v_mfma_f32_16x16x32_bf16 v[70:73], v[182:185], v[222:225], v[70:73]
	v_mfma_f32_16x16x32_bf16 v[66:69], v[190:193], v[222:225], v[66:69]
	s_barrier
	s_add_i32 s23, s23, 2
	s_add_u32 s10, s10, 0x100
	s_addc_u32 s11, s11, 0
	s_add_u32 s19, s19, 0x100
	s_addc_u32 s22, s22, 0
	s_cmp_gt_u32 s23, 29
	s_cbranch_scc0 .LBB0_346
	v_readlane_b32 s6, v244, 18
	v_readlane_b32 s7, v244, 19
	s_and_b64 vcc, exec, s[6:7]
	s_cbranch_vccnz .LBB0_351
	s_ashr_i32 s13, s12, 3
	s_cmp_lg_u32 s13, 7
	s_mov_b64 s[6:7], -1
	s_cbranch_scc1 .LBB0_352

; #define PG8_STAGE(bufoff, gbase, voff) do { _Pragma("unroll") for (int _i = 0; _i < 2; ++_i) \
;         __builtin_amdgcn_global_load_lds((const unsigned*)((const char*)(gbase) + (voff)[_i]), (PG8_LAS unsigned*)(lds + (bufoff) + ldsw + _i * 8192), 16, 0, 0); } while (0)
; #define PG8_LDA(dst, b, h) do { _Pragma("unroll") for (int m = 0; m < 4; ++m) _Pragma("unroll") for (int k = 0; k < 2; ++k) dst[m][k] = *(const PG8_LAS bf16x8*)(lds + PG8_SA(b, h) + aoff + m * 2048 + k * 1024); } while (0)
; #define PG8_LDB(dst, b, h) do { _Pragma("unroll") for (int n = 0; n < 2; ++n) _Pragma("unroll") for (int k = 0; k < 2; ++k) dst[n][k] = *(const PG8_LAS bf16x8*)(lds + PG8_SB(b, h) + boff + n * 2048 + k * 1024); } while (0)
; #define PG8_WAIT_V(n) asm volatile("s_waitcnt vmcnt(" #n ")" ::: "memory")
; #define PG8_WAIT_L(n) asm volatile("s_waitcnt lgkmcnt(" #n ")" ::: "memory")
; #define PG8_BAR __builtin_amdgcn_s_barrier()
; template <class Epi, class Sched, bool ALIGN_EPI = false, bool SP2 = false>
; __device__ __forceinline__ void gemm_phase(PG8_LAS unsigned char* lds, const Gemm g, const Sched& S, const Epi& E) {
;     ...
;         const char* nA = has_next ? (const char*)g.A + (size_t)nxt.pm * tstep + (size_t)nxt.kt0 * kstep : cA; const char* nB = has_next ? (const char*)g.Bt + (size_t)nxt.pn * tstep + (size_t)nxt.kt0 * kstep : cB;
;         for (int t = 0; t < nt; t += 2) {
;             if constexpr (Epi::MIDHOOK) { if (t == (nt >> 1)) E.mid(acc, cur, wr, wc, fr, fq); }
;             const bool last = (t == nt - 2);
;             const char* a1 = cA + (size_t)(t + 1) * kstep;
;             const char* a2 = last ? nA : cA + (size_t)(t + 2) * kstep; const char* b2 = last ? nB : cB + (size_t)(t + 2) * kstep;
;             const char* a3 = a2 + kstep; const char* b3 = b2 + kstep;
;             if (last && has_next) S.a_ready(nxt);
;             if constexpr (SP2) {
;             PG8_LDB(B0, 0, 0); PG8_LDB(B1, 0, 1); PG8_SCHED; PG8_LDA(At, 0, 0); PG8_STAGE(PG8_SA(1, 1), a1 + hstep, voffA);
;             PG8_WAIT_V(8); PG8_WAIT_L(0); PG8_BAR; PG8_MMA(0, 0, At, B0); PG8_MMA(0, 1, At, B1); PG8_BAR; PG8_SCHED;
;             PG8_LDA(At, 0, 1); PG8_STAGE(PG8_SB(0, 0), b2, voffB); PG8_STAGE(PG8_SB(0, 1), b2 + hstep, voffB); PG8_STAGE(PG8_SA(0, 0), a2, voffA);
;             PG8_WAIT_V(8); PG8_WAIT_L(0); PG8_BAR; PG8_MMA(1, 0, At, B0); PG8_MMA(1, 1, At, B1); PG8_BAR; PG8_SCHED;
.LBB0_1199:
	s_add_u32 s36, s28, s30
	s_addc_u32 s37, s29, s31
	s_add_u32 s36, s36, 0x100
	s_addc_u32 s37, s37, 0
	s_add_u32 s44, s59, s30
	s_addc_u32 s45, s60, s31
	s_add_i32 s62, 0, 0x10000
	v_add_u32_e32 v146, s62, v161
	ds_read_b128 v[130:133], v146
	ds_read_b128 v[134:137], v146 offset:1024
	ds_read_b128 v[166:169], v146 offset:2048
	ds_read_b128 v[170:173], v146 offset:3072
	v_add_u32_e32 v146, s54, v161
	ds_read_b128 v[174:177], v146
	ds_read_b128 v[178:181], v146 offset:1024
	ds_read_b128 v[182:185], v146 offset:2048
	ds_read_b128 v[186:189], v146 offset:3072
	s_cmpk_eq_i32 s30, 0x1f00
	s_cselect_b32 s39, s21, s37
	s_cselect_b32 s38, s55, s36
	s_cselect_b32 s37, s56, s45
	s_cselect_b32 s36, s57, s44
	v_lshl_add_u64 v[222:223], v[156:157], 0, s[30:31]
	s_add_i32 m0, s27, 0xc000
	ds_read_b128 v[190:193], v164
	ds_read_b128 v[194:197], v164 offset:1024
	ds_read_b128 v[198:201], v164 offset:2048
	ds_read_b128 v[202:205], v164 offset:3072
	ds_read_b128 v[206:209], v164 offset:4096
	ds_read_b128 v[210:213], v164 offset:5120
	ds_read_b128 v[214:217], v164 offset:6144
	ds_read_b128 v[218:221], v164 offset:7168
	global_load_lds_dwordx4 v[222:223], off
	v_lshl_add_u64 v[222:223], v[158:159], 0, s[30:31]
	s_add_i32 m0, s27, 0xe000
	s_nop 0
	global_load_lds_dwordx4 v[222:223], off
	s_waitcnt vmcnt(8)
	s_waitcnt lgkmcnt(0)
	s_barrier
	s_waitcnt lgkmcnt(0)
	v_mfma_f32_16x16x32_bf16 v[126:129], v[130:133], v[190:193], v[126:129]
	v_mfma_f32_16x16x32_bf16 v[122:125], v[166:169], v[190:193], v[122:125]
	v_mfma_f32_16x16x32_bf16 v[110:113], v[130:133], v[198:201], v[110:113]
	v_mfma_f32_16x16x32_bf16 v[106:109], v[166:169], v[198:201], v[106:109]
	v_mfma_f32_16x16x32_bf16 v[94:97], v[130:133], v[206:209], v[94:97]
	v_mfma_f32_16x16x32_bf16 v[90:93], v[166:169], v[206:209], v[90:93]
	v_mfma_f32_16x16x32_bf16 v[78:81], v[130:133], v[214:217], v[78:81]
	v_mfma_f32_16x16x32_bf16 v[74:77], v[166:169], v[214:217], v[74:77]
	v_mfma_f32_16x16x32_bf16 v[126:129], v[134:137], v[194:197], v[126:129]
	v_mfma_f32_16x16x32_bf16 v[122:125], v[170:173], v[194:197], v[122:125]
	v_mfma_f32_16x16x32_bf16 v[110:113], v[134:137], v[202:205], v[110:113]
	v_mfma_f32_16x16x32_bf16 v[106:109], v[170:173], v[202:205], v[106:109]
	v_mfma_f32_16x16x32_bf16 v[94:97], v[134:137], v[210:213], v[94:97]
	v_mfma_f32_16x16x32_bf16 v[90:93], v[170:173], v[210:213], v[90:93]
	v_mfma_f32_16x16x32_bf16 v[78:81], v[134:137], v[218:221], v[78:81]
	v_mfma_f32_16x16x32_bf16 v[74:77], v[170:173], v[218:221], v[74:77]
	v_mfma_f32_16x16x32_bf16 v[118:121], v[174:177], v[190:193], v[118:121]
	v_mfma_f32_16x16x32_bf16 v[114:117], v[182:185], v[190:193], v[114:117]
	v_mfma_f32_16x16x32_bf16 v[102:105], v[174:177], v[198:201], v[102:105]
	v_mfma_f32_16x16x32_bf16 v[98:101], v[182:185], v[198:201], v[98:101]
	v_mfma_f32_16x16x32_bf16 v[86:89], v[174:177], v[206:209], v[86:89]
	v_mfma_f32_16x16x32_bf16 v[82:85], v[182:185], v[206:209], v[82:85]
	v_mfma_f32_16x16x32_bf16 v[70:73], v[174:177], v[214:217], v[70:73]
	v_mfma_f32_16x16x32_bf16 v[66:69], v[182:185], v[214:217], v[66:69]
	v_mfma_f32_16x16x32_bf16 v[118:121], v[178:181], v[194:197], v[118:121]
	v_mfma_f32_16x16x32_bf16 v[114:117], v[186:189], v[194:197], v[114:117]
	v_mfma_f32_16x16x32_bf16 v[102:105], v[178:181], v[202:205], v[102:105]
	v_mfma_f32_16x16x32_bf16 v[98:101], v[186:189], v[202:205], v[98:101]
	v_mfma_f32_16x16x32_bf16 v[86:89], v[178:181], v[210:213], v[86:89]
	v_mfma_f32_16x16x32_bf16 v[82:85], v[186:189], v[210:213], v[82:85]
	v_mfma_f32_16x16x32_bf16 v[70:73], v[178:181], v[218:221], v[70:73]
	v_mfma_f32_16x16x32_bf16 v[66:69], v[186:189], v[218:221], v[66:69]
	s_barrier
	s_add_i32 s44, s62, s42
	v_lshl_add_u64 v[222:223], s[36:37], 0, v[142:143]
	s_mov_b32 m0, s44
	ds_read_b128 v[190:193], v164 offset:16384
	ds_read_b128 v[194:197], v164 offset:17408
	ds_read_b128 v[198:201], v164 offset:18432
	ds_read_b128 v[202:205], v164 offset:19456
	ds_read_b128 v[206:209], v164 offset:20480
	ds_read_b128 v[210:213], v164 offset:21504
	ds_read_b128 v[214:217], v164 offset:22528
	ds_read_b128 v[218:221], v164 offset:23552
	global_load_lds_dwordx4 v[222:223], off
	s_add_i32 m0, s44, 0x2000
	s_add_u32 s44, s36, 0x100000
	v_lshl_add_u64 v[224:225], s[36:37], 0, v[138:139]
	s_addc_u32 s45, s37, 0
	s_add_i32 s62, s54, s42
	global_load_lds_dwordx4 v[224:225], off
	v_lshl_add_u64 v[226:227], s[44:45], 0, v[142:143]
	s_mov_b32 m0, s62
	v_lshl_add_u64 v[228:229], s[38:39], 0, v[140:141]
	global_load_lds_dwordx4 v[226:227], off
	v_lshl_add_u64 v[226:227], s[44:45], 0, v[138:139]
	s_add_i32 m0, s62, 0x2000
	s_nop 0
	global_load_lds_dwordx4 v[226:227], off
	v_lshl_add_u64 v[226:227], s[38:39], 0, v[144:145]
	s_mov_b32 m0, s27
	s_nop 0
	global_load_lds_dwordx4 v[226:227], off
	s_mov_b32 m0, s46
	s_nop 0
	global_load_lds_dwordx4 v[228:229], off
	s_waitcnt vmcnt(8)
	s_waitcnt lgkmcnt(0)
	s_barrier
; #define PG8_STAGE(bufoff, gbase, voff) do { _Pragma("unroll") for (int _i = 0; _i < 2; ++_i) \
;         __builtin_amdgcn_global_load_lds((const unsigned*)((const char*)(gbase) + (voff)[_i]), (PG8_LAS unsigned*)(lds + (bufoff) + ldsw + _i * 8192), 16, 0, 0); } while (0)
; #define PG8_LDA(dst, b, h) do { _Pragma("unroll") for (int m = 0; m < 4; ++m) _Pragma("unroll") for (int k = 0; k < 2; ++k) dst[m][k] = *(const PG8_LAS bf16x8*)(lds + PG8_SA(b, h) + aoff + m * 2048 + k * 1024); } while (0)
; #define PG8_LDB(dst, b, h) do { _Pragma("unroll") for (int n = 0; n < 2; ++n) _Pragma("unroll") for (int k = 0; k < 2; ++k) dst[n][k] = *(const PG8_LAS bf16x8*)(lds + PG8_SB(b, h) + boff + n * 2048 + k * 1024); } while (0)
; #define PG8_MMA(ai, bj, At, Bt) do { __builtin_amdgcn_s_setprio(1); _Pragma("unroll") for (int m = 0; m < 4; ++m) _Pragma("unroll") for (int n = 0; n < 2; ++n) _Pragma("unroll") for (int k = 0; k < 2; ++k) \
;         acc[ai][bj][m][n] = __builtin_amdgcn_mfma_f32_16x16x32_bf16(Bt[n][k], At[m][k], acc[ai][bj][m][n], 0, 0, 0); __builtin_amdgcn_s_setprio(0); } while (0)
; #define PG8_WAIT_V(n) asm volatile("s_waitcnt vmcnt(" #n ")" ::: "memory")
; #define PG8_WAIT_L(n) asm volatile("s_waitcnt lgkmcnt(" #n ")" ::: "memory")
; #define PG8_BAR __builtin_amdgcn_s_barrier()
; #define PG8_SCHED __builtin_amdgcn_sched_barrier(0)
; template <class Epi, class Sched, bool ALIGN_EPI = false, bool SP2 = false>
; __device__ __forceinline__ void gemm_phase(PG8_LAS unsigned char* lds, const Gemm g, const Sched& S, const Epi& E) {
;     ...
;             PG8_WAIT_V(8); PG8_WAIT_L(0); PG8_BAR; PG8_MMA(1, 0, At, B0); PG8_MMA(1, 1, At, B1); PG8_BAR; PG8_SCHED;
;             PG8_LDB(B0, 1, 0); PG8_LDB(B1, 1, 1); PG8_SCHED; PG8_LDA(At, 1, 0); PG8_STAGE(PG8_SA(0, 1), a2 + hstep, voffA);
;             PG8_WAIT_V(8); PG8_WAIT_L(0); PG8_BAR; PG8_MMA(0, 0, At, B0); PG8_MMA(0, 1, At, B1); PG8_BAR; PG8_SCHED;
;             PG8_LDA(At, 1, 1); PG8_STAGE(PG8_SB(1, 0), b3, voffB); PG8_STAGE(PG8_SB(1, 1), b3 + hstep, voffB); PG8_STAGE(PG8_SA(1, 0), a3, voffA);
	s_waitcnt lgkmcnt(0)
	v_mfma_f32_16x16x32_bf16 v[62:65], v[130:133], v[190:193], v[62:65]
	v_mfma_f32_16x16x32_bf16 v[58:61], v[166:169], v[190:193], v[58:61]
	v_mfma_f32_16x16x32_bf16 v[46:49], v[130:133], v[198:201], v[46:49]
	v_mfma_f32_16x16x32_bf16 v[42:45], v[166:169], v[198:201], v[42:45]
	v_mfma_f32_16x16x32_bf16 v[30:33], v[130:133], v[206:209], v[30:33]
	v_mfma_f32_16x16x32_bf16 v[26:29], v[166:169], v[206:209], v[26:29]
	v_mfma_f32_16x16x32_bf16 v[14:17], v[130:133], v[214:217], v[14:17]
	v_mfma_f32_16x16x32_bf16 v[10:13], v[166:169], v[214:217], v[10:13]
	v_mfma_f32_16x16x32_bf16 v[62:65], v[134:137], v[194:197], v[62:65]
	v_mfma_f32_16x16x32_bf16 v[58:61], v[170:173], v[194:197], v[58:61]
	v_mfma_f32_16x16x32_bf16 v[46:49], v[134:137], v[202:205], v[46:49]
	v_mfma_f32_16x16x32_bf16 v[42:45], v[170:173], v[202:205], v[42:45]
	v_mfma_f32_16x16x32_bf16 v[30:33], v[134:137], v[210:213], v[30:33]
	v_mfma_f32_16x16x32_bf16 v[26:29], v[170:173], v[210:213], v[26:29]
	v_mfma_f32_16x16x32_bf16 v[14:17], v[134:137], v[218:221], v[14:17]
	v_mfma_f32_16x16x32_bf16 v[10:13], v[170:173], v[218:221], v[10:13]
	v_mfma_f32_16x16x32_bf16 v[54:57], v[174:177], v[190:193], v[54:57]
	v_mfma_f32_16x16x32_bf16 v[50:53], v[182:185], v[190:193], v[50:53]
	v_mfma_f32_16x16x32_bf16 v[38:41], v[174:177], v[198:201], v[38:41]
	v_mfma_f32_16x16x32_bf16 v[34:37], v[182:185], v[198:201], v[34:37]
	v_mfma_f32_16x16x32_bf16 v[22:25], v[174:177], v[206:209], v[22:25]
	v_mfma_f32_16x16x32_bf16 v[18:21], v[182:185], v[206:209], v[18:21]
	v_mfma_f32_16x16x32_bf16 v[6:9], v[174:177], v[214:217], v[6:9]
	v_mfma_f32_16x16x32_bf16 v[2:5], v[182:185], v[214:217], v[2:5]
	v_mfma_f32_16x16x32_bf16 v[54:57], v[178:181], v[194:197], v[54:57]
	v_mfma_f32_16x16x32_bf16 v[50:53], v[186:189], v[194:197], v[50:53]
	v_mfma_f32_16x16x32_bf16 v[38:41], v[178:181], v[202:205], v[38:41]
	v_mfma_f32_16x16x32_bf16 v[34:37], v[186:189], v[202:205], v[34:37]
	v_mfma_f32_16x16x32_bf16 v[22:25], v[178:181], v[210:213], v[22:25]
	v_mfma_f32_16x16x32_bf16 v[18:21], v[186:189], v[210:213], v[18:21]
	v_mfma_f32_16x16x32_bf16 v[6:9], v[178:181], v[218:221], v[6:9]
	v_mfma_f32_16x16x32_bf16 v[2:5], v[186:189], v[218:221], v[2:5]
	s_barrier
	s_add_i32 s44, 0, 0x18000
	v_add_u32_e32 v146, s44, v161
	s_add_i32 s45, 0, 0x1c000
	ds_read_b128 v[130:133], v146
	ds_read_b128 v[134:137], v146 offset:1024
	ds_read_b128 v[166:169], v146 offset:2048
	ds_read_b128 v[170:173], v146 offset:3072
	v_add_u32_e32 v146, s45, v161
	ds_read_b128 v[174:177], v146
	ds_read_b128 v[178:181], v146 offset:1024
	ds_read_b128 v[182:185], v146 offset:2048
	ds_read_b128 v[186:189], v146 offset:3072
	s_add_u32 s38, s38, 0x100000
	s_addc_u32 s39, s39, 0
	s_mov_b32 m0, s47
	v_lshl_add_u64 v[230:231], s[38:39], 0, v[144:145]
	ds_read_b128 v[190:193], v164 offset:32768
	ds_read_b128 v[194:197], v164 offset:33792
	ds_read_b128 v[198:201], v164 offset:34816
	ds_read_b128 v[202:205], v164 offset:35840
	ds_read_b128 v[206:209], v164 offset:36864
	ds_read_b128 v[210:213], v164 offset:37888
	ds_read_b128 v[214:217], v164 offset:38912
	ds_read_b128 v[218:221], v164 offset:39936
	global_load_lds_dwordx4 v[230:231], off
	v_lshl_add_u64 v[230:231], s[38:39], 0, v[140:141]
	s_mov_b32 m0, s48
	s_nop 0
	global_load_lds_dwordx4 v[230:231], off
	s_waitcnt vmcnt(8)
	s_waitcnt lgkmcnt(0)
	s_barrier
	s_waitcnt lgkmcnt(0)
	v_mfma_f32_16x16x32_bf16 v[126:129], v[130:133], v[190:193], v[126:129]
	v_mfma_f32_16x16x32_bf16 v[122:125], v[166:169], v[190:193], v[122:125]
	v_mfma_f32_16x16x32_bf16 v[110:113], v[130:133], v[198:201], v[110:113]
	v_mfma_f32_16x16x32_bf16 v[106:109], v[166:169], v[198:201], v[106:109]
	v_mfma_f32_16x16x32_bf16 v[94:97], v[130:133], v[206:209], v[94:97]
	v_mfma_f32_16x16x32_bf16 v[90:93], v[166:169], v[206:209], v[90:93]
	v_mfma_f32_16x16x32_bf16 v[78:81], v[130:133], v[214:217], v[78:81]
	v_mfma_f32_16x16x32_bf16 v[74:77], v[166:169], v[214:217], v[74:77]
	v_mfma_f32_16x16x32_bf16 v[126:129], v[134:137], v[194:197], v[126:129]
	v_mfma_f32_16x16x32_bf16 v[122:125], v[170:173], v[194:197], v[122:125]
	v_mfma_f32_16x16x32_bf16 v[110:113], v[134:137], v[202:205], v[110:113]
	v_mfma_f32_16x16x32_bf16 v[106:109], v[170:173], v[202:205], v[106:109]
	v_mfma_f32_16x16x32_bf16 v[94:97], v[134:137], v[210:213], v[94:97]
	v_mfma_f32_16x16x32_bf16 v[90:93], v[170:173], v[210:213], v[90:93]
	v_mfma_f32_16x16x32_bf16 v[78:81], v[134:137], v[218:221], v[78:81]
	v_mfma_f32_16x16x32_bf16 v[74:77], v[170:173], v[218:221], v[74:77]
	v_mfma_f32_16x16x32_bf16 v[118:121], v[174:177], v[190:193], v[118:121]
	v_mfma_f32_16x16x32_bf16 v[114:117], v[182:185], v[190:193], v[114:117]
	v_mfma_f32_16x16x32_bf16 v[102:105], v[174:177], v[198:201], v[102:105]
	v_mfma_f32_16x16x32_bf16 v[98:101], v[182:185], v[198:201], v[98:101]
	v_mfma_f32_16x16x32_bf16 v[86:89], v[174:177], v[206:209], v[86:89]
	v_mfma_f32_16x16x32_bf16 v[82:85], v[182:185], v[206:209], v[82:85]
	v_mfma_f32_16x16x32_bf16 v[70:73], v[174:177], v[214:217], v[70:73]
	v_mfma_f32_16x16x32_bf16 v[66:69], v[182:185], v[214:217], v[66:69]
	v_mfma_f32_16x16x32_bf16 v[118:121], v[178:181], v[194:197], v[118:121]
	v_mfma_f32_16x16x32_bf16 v[114:117], v[186:189], v[194:197], v[114:117]
	v_mfma_f32_16x16x32_bf16 v[102:105], v[178:181], v[202:205], v[102:105]
	v_mfma_f32_16x16x32_bf16 v[98:101], v[186:189], v[202:205], v[98:101]
	v_mfma_f32_16x16x32_bf16 v[86:89], v[178:181], v[210:213], v[86:89]
	v_mfma_f32_16x16x32_bf16 v[82:85], v[186:189], v[210:213], v[82:85]
	v_mfma_f32_16x16x32_bf16 v[70:73], v[178:181], v[218:221], v[70:73]
	v_mfma_f32_16x16x32_bf16 v[66:69], v[186:189], v[218:221], v[66:69]
	s_barrier
; #define PG8_STAGE(bufoff, gbase, voff) do { _Pragma("unroll") for (int _i = 0; _i < 2; ++_i) \
;         __builtin_amdgcn_global_load_lds((const unsigned*)((const char*)(gbase) + (voff)[_i]), (PG8_LAS unsigned*)(lds + (bufoff) + ldsw + _i * 8192), 16, 0, 0); } while (0)
; #define PG8_LDA(dst, b, h) do { _Pragma("unroll") for (int m = 0; m < 4; ++m) _Pragma("unroll") for (int k = 0; k < 2; ++k) dst[m][k] = *(const PG8_LAS bf16x8*)(lds + PG8_SA(b, h) + aoff + m * 2048 + k * 1024); } while (0)
; #define PG8_MMA(ai, bj, At, Bt) do { __builtin_amdgcn_s_setprio(1); _Pragma("unroll") for (int m = 0; m < 4; ++m) _Pragma("unroll") for (int n = 0; n < 2; ++n) _Pragma("unroll") for (int k = 0; k < 2; ++k) \
;         acc[ai][bj][m][n] = __builtin_amdgcn_mfma_f32_16x16x32_bf16(Bt[n][k], At[m][k], acc[ai][bj][m][n], 0, 0, 0); __builtin_amdgcn_s_setprio(0); } while (0)
; #define PG8_WAIT_V(n) asm volatile("s_waitcnt vmcnt(" #n ")" ::: "memory")
; #define PG8_WAIT_L(n) asm volatile("s_waitcnt lgkmcnt(" #n ")" ::: "memory")
; #define PG8_BAR __builtin_amdgcn_s_barrier()
; #define PG8_SCHED __builtin_amdgcn_sched_barrier(0)
; template <class Epi, class Sched, bool ALIGN_EPI = false, bool SP2 = false>
; __device__ __forceinline__ void gemm_phase(PG8_LAS unsigned char* lds, const Gemm g, const Sched& S, const Epi& E) {
;     ...
;             PG8_LDA(At, 1, 1); PG8_STAGE(PG8_SB(1, 0), b3, voffB); PG8_STAGE(PG8_SB(1, 1), b3 + hstep, voffB); PG8_STAGE(PG8_SA(1, 0), a3, voffA);
;             PG8_WAIT_V(8); PG8_WAIT_L(0); PG8_BAR; PG8_MMA(1, 0, At, B0); PG8_MMA(1, 1, At, B1); PG8_BAR; PG8_SCHED;
	s_add_i32 s38, s44, s42
	v_lshl_add_u64 v[222:223], v[222:223], 0, s[14:15]
	s_mov_b32 m0, s38
	ds_read_b128 v[190:193], v164 offset:49152
	ds_read_b128 v[194:197], v164 offset:50176
	ds_read_b128 v[198:201], v164 offset:51200
	ds_read_b128 v[202:205], v164 offset:52224
	ds_read_b128 v[206:209], v164 offset:53248
	ds_read_b128 v[210:213], v164 offset:54272
	ds_read_b128 v[214:217], v164 offset:55296
	ds_read_b128 v[218:221], v164 offset:56320
	global_load_lds_dwordx4 v[222:223], off
	s_add_i32 m0, s38, 0x2000
	s_add_u32 s36, s36, 0x100080
	v_lshl_add_u64 v[222:223], v[224:225], 0, s[14:15]
	s_addc_u32 s37, s37, 0
	s_add_i32 s38, s45, s42
	global_load_lds_dwordx4 v[222:223], off
	v_lshl_add_u64 v[222:223], s[36:37], 0, v[142:143]
	s_mov_b32 m0, s38
	s_nop 0
	global_load_lds_dwordx4 v[222:223], off
	v_lshl_add_u64 v[222:223], s[36:37], 0, v[138:139]
	s_add_i32 m0, s38, 0x2000
	s_nop 0
	global_load_lds_dwordx4 v[222:223], off
	v_lshl_add_u64 v[222:223], v[226:227], 0, s[14:15]
	s_mov_b32 m0, s51
	s_nop 0
	global_load_lds_dwordx4 v[222:223], off
	v_lshl_add_u64 v[222:223], v[228:229], 0, s[14:15]
	s_mov_b32 m0, s52
	s_nop 0
	global_load_lds_dwordx4 v[222:223], off
	s_waitcnt vmcnt(8)
	s_waitcnt lgkmcnt(0)
	s_barrier
	s_waitcnt lgkmcnt(0)
	v_mfma_f32_16x16x32_bf16 v[62:65], v[130:133], v[190:193], v[62:65]
	v_mfma_f32_16x16x32_bf16 v[58:61], v[166:169], v[190:193], v[58:61]
	v_mfma_f32_16x16x32_bf16 v[46:49], v[130:133], v[198:201], v[46:49]
	v_mfma_f32_16x16x32_bf16 v[42:45], v[166:169], v[198:201], v[42:45]
	v_mfma_f32_16x16x32_bf16 v[30:33], v[130:133], v[206:209], v[30:33]
	v_mfma_f32_16x16x32_bf16 v[26:29], v[166:169], v[206:209], v[26:29]
	v_mfma_f32_16x16x32_bf16 v[14:17], v[130:133], v[214:217], v[14:17]
	v_mfma_f32_16x16x32_bf16 v[10:13], v[166:169], v[214:217], v[10:13]
	v_mfma_f32_16x16x32_bf16 v[62:65], v[134:137], v[194:197], v[62:65]
	v_mfma_f32_16x16x32_bf16 v[58:61], v[170:173], v[194:197], v[58:61]
	v_mfma_f32_16x16x32_bf16 v[46:49], v[134:137], v[202:205], v[46:49]
	v_mfma_f32_16x16x32_bf16 v[42:45], v[170:173], v[202:205], v[42:45]
	v_mfma_f32_16x16x32_bf16 v[30:33], v[134:137], v[210:213], v[30:33]
	v_mfma_f32_16x16x32_bf16 v[26:29], v[170:173], v[210:213], v[26:29]
	v_mfma_f32_16x16x32_bf16 v[14:17], v[134:137], v[218:221], v[14:17]
	v_mfma_f32_16x16x32_bf16 v[10:13], v[170:173], v[218:221], v[10:13]
	v_mfma_f32_16x16x32_bf16 v[54:57], v[174:177], v[190:193], v[54:57]
	v_mfma_f32_16x16x32_bf16 v[50:53], v[182:185], v[190:193], v[50:53]
	v_mfma_f32_16x16x32_bf16 v[38:41], v[174:177], v[198:201], v[38:41]
	v_mfma_f32_16x16x32_bf16 v[34:37], v[182:185], v[198:201], v[34:37]
	v_mfma_f32_16x16x32_bf16 v[22:25], v[174:177], v[206:209], v[22:25]
	v_mfma_f32_16x16x32_bf16 v[18:21], v[182:185], v[206:209], v[18:21]
	v_mfma_f32_16x16x32_bf16 v[6:9], v[174:177], v[214:217], v[6:9]
	v_mfma_f32_16x16x32_bf16 v[2:5], v[182:185], v[214:217], v[2:5]
	v_mfma_f32_16x16x32_bf16 v[54:57], v[178:181], v[194:197], v[54:57]
	v_mfma_f32_16x16x32_bf16 v[50:53], v[186:189], v[194:197], v[50:53]
	v_mfma_f32_16x16x32_bf16 v[38:41], v[178:181], v[202:205], v[38:41]
	v_mfma_f32_16x16x32_bf16 v[34:37], v[186:189], v[202:205], v[34:37]
	v_mfma_f32_16x16x32_bf16 v[22:25], v[178:181], v[210:213], v[22:25]
	v_mfma_f32_16x16x32_bf16 v[18:21], v[186:189], v[210:213], v[18:21]
	v_mfma_f32_16x16x32_bf16 v[6:9], v[178:181], v[218:221], v[6:9]
	v_mfma_f32_16x16x32_bf16 v[2:5], v[186:189], v[218:221], v[2:5]
	s_barrier
	s_add_i32 s61, s61, 2
	s_add_u32 s30, s30, 0x100
	s_addc_u32 s31, s31, 0
	s_cmp_gt_u32 s61, 61
	s_cbranch_scc1 .LBB0_1202

; #define PG8_STAGE(bufoff, gbase, voff) do { _Pragma("unroll") for (int _i = 0; _i < 2; ++_i) \
;         __builtin_amdgcn_global_load_lds((const unsigned*)((const char*)(gbase) + (voff)[_i]), (PG8_LAS unsigned*)(lds + (bufoff) + ldsw + _i * 8192), 16, 0, 0); } while (0)
; #define PG8_LDA(dst, b, h) do { _Pragma("unroll") for (int m = 0; m < 4; ++m) _Pragma("unroll") for (int k = 0; k < 2; ++k) dst[m][k] = *(const PG8_LAS bf16x8*)(lds + PG8_SA(b, h) + aoff + m * 2048 + k * 1024); } while (0)
; #define PG8_LDB(dst, b, h) do { _Pragma("unroll") for (int n = 0; n < 2; ++n) _Pragma("unroll") for (int k = 0; k < 2; ++k) dst[n][k] = *(const PG8_LAS bf16x8*)(lds + PG8_SB(b, h) + boff + n * 2048 + k * 1024); } while (0)
; #define PG8_WAIT_V(n) asm volatile("s_waitcnt vmcnt(" #n ")" ::: "memory")
; #define PG8_WAIT_L(n) asm volatile("s_waitcnt lgkmcnt(" #n ")" ::: "memory")
; #define PG8_BAR __builtin_amdgcn_s_barrier()
; template <class Epi, class Sched, bool ALIGN_EPI = false, bool SP2 = false>
; __device__ __forceinline__ void gemm_phase(PG8_LAS unsigned char* lds, const Gemm g, const Sched& S, const Epi& E) {
;     ...
;         const char* nA = has_next ? (const char*)g.A + (size_t)nxt.pm * tstep + (size_t)nxt.kt0 * kstep : cA; const char* nB = has_next ? (const char*)g.Bt + (size_t)nxt.pn * tstep + (size_t)nxt.kt0 * kstep : cB;
;         for (int t = 0; t < nt; t += 2) {
;             if constexpr (Epi::MIDHOOK) { if (t == (nt >> 1)) E.mid(acc, cur, wr, wc, fr, fq); }
;             const bool last = (t == nt - 2);
;             const char* a1 = cA + (size_t)(t + 1) * kstep;
;             const char* a2 = last ? nA : cA + (size_t)(t + 2) * kstep; const char* b2 = last ? nB : cB + (size_t)(t + 2) * kstep;
;             const char* a3 = a2 + kstep; const char* b3 = b2 + kstep;
;             if (last && has_next) S.a_ready(nxt);
;             if constexpr (SP2) {
;             PG8_LDB(B0, 0, 0); PG8_LDB(B1, 0, 1); PG8_SCHED; PG8_LDA(At, 0, 0); PG8_STAGE(PG8_SA(1, 1), a1 + hstep, voffA);
;             PG8_WAIT_V(8); PG8_WAIT_L(0); PG8_BAR; PG8_MMA(0, 0, At, B0); PG8_MMA(0, 1, At, B1); PG8_BAR; PG8_SCHED;
;             PG8_LDA(At, 0, 1); PG8_STAGE(PG8_SB(0, 0), b2, voffB); PG8_STAGE(PG8_SB(0, 1), b2 + hstep, voffB); PG8_STAGE(PG8_SA(0, 0), a2, voffA);
;             PG8_WAIT_V(8); PG8_WAIT_L(0); PG8_BAR; PG8_MMA(1, 0, At, B0); PG8_MMA(1, 1, At, B1); PG8_BAR; PG8_SCHED;
.LBB0_1219:
	ds_read_b128 v[138:141], v147
	ds_read_b128 v[150:153], v147 offset:1024
	ds_read_b128 v[154:157], v147 offset:2048
	ds_read_b128 v[158:161], v147 offset:3072
	ds_read_b128 v[162:165], v148
	ds_read_b128 v[166:169], v148 offset:1024
	ds_read_b128 v[170:173], v148 offset:2048
	ds_read_b128 v[174:177], v148 offset:3072
	s_add_u32 s36, s30, 0xfff00080
	s_addc_u32 s37, s31, -1
	s_cmp_eq_u32 s61, 4
	s_cselect_b32 s39, s11, s37
	s_cselect_b32 s38, s21, s36
	s_cselect_b32 s37, s23, s60
	s_cselect_b32 s36, s58, s59
	v_lshl_add_u64 v[142:143], s[30:31], 0, v[134:135]
	s_add_i32 m0, s45, 0xc000
	ds_read_b128 v[178:181], v149
	ds_read_b128 v[182:185], v149 offset:1024
	ds_read_b128 v[186:189], v149 offset:2048
	ds_read_b128 v[190:193], v149 offset:3072
	ds_read_b128 v[194:197], v149 offset:4096
	ds_read_b128 v[198:201], v149 offset:5120
	ds_read_b128 v[202:205], v149 offset:6144
	ds_read_b128 v[206:209], v149 offset:7168
	global_load_lds_dwordx4 v[142:143], off
	v_lshl_add_u64 v[142:143], s[30:31], 0, v[136:137]
	s_add_i32 m0, s45, 0xe000
	s_nop 0
	global_load_lds_dwordx4 v[142:143], off
	s_waitcnt vmcnt(8)
	s_waitcnt lgkmcnt(0)
	s_barrier
	s_waitcnt lgkmcnt(0)
	v_mfma_f32_16x16x32_bf16 v[126:129], v[138:141], v[178:181], v[126:129]
	v_mfma_f32_16x16x32_bf16 v[122:125], v[154:157], v[178:181], v[122:125]
	v_mfma_f32_16x16x32_bf16 v[110:113], v[138:141], v[186:189], v[110:113]
	v_mfma_f32_16x16x32_bf16 v[106:109], v[154:157], v[186:189], v[106:109]
	v_mfma_f32_16x16x32_bf16 v[94:97], v[138:141], v[194:197], v[94:97]
	v_mfma_f32_16x16x32_bf16 v[90:93], v[154:157], v[194:197], v[90:93]
	v_mfma_f32_16x16x32_bf16 v[78:81], v[138:141], v[202:205], v[78:81]
	v_mfma_f32_16x16x32_bf16 v[74:77], v[154:157], v[202:205], v[74:77]
	v_mfma_f32_16x16x32_bf16 v[126:129], v[150:153], v[182:185], v[126:129]
	v_mfma_f32_16x16x32_bf16 v[122:125], v[158:161], v[182:185], v[122:125]
	v_mfma_f32_16x16x32_bf16 v[110:113], v[150:153], v[190:193], v[110:113]
	v_mfma_f32_16x16x32_bf16 v[106:109], v[158:161], v[190:193], v[106:109]
	v_mfma_f32_16x16x32_bf16 v[94:97], v[150:153], v[198:201], v[94:97]
	v_mfma_f32_16x16x32_bf16 v[90:93], v[158:161], v[198:201], v[90:93]
	v_mfma_f32_16x16x32_bf16 v[78:81], v[150:153], v[206:209], v[78:81]
	v_mfma_f32_16x16x32_bf16 v[74:77], v[158:161], v[206:209], v[74:77]
	v_mfma_f32_16x16x32_bf16 v[118:121], v[162:165], v[178:181], v[118:121]
	v_mfma_f32_16x16x32_bf16 v[114:117], v[170:173], v[178:181], v[114:117]
	v_mfma_f32_16x16x32_bf16 v[102:105], v[162:165], v[186:189], v[102:105]
	v_mfma_f32_16x16x32_bf16 v[98:101], v[170:173], v[186:189], v[98:101]
	v_mfma_f32_16x16x32_bf16 v[86:89], v[162:165], v[194:197], v[86:89]
	v_mfma_f32_16x16x32_bf16 v[82:85], v[170:173], v[194:197], v[82:85]
	v_mfma_f32_16x16x32_bf16 v[70:73], v[162:165], v[202:205], v[70:73]
	v_mfma_f32_16x16x32_bf16 v[66:69], v[170:173], v[202:205], v[66:69]
	v_mfma_f32_16x16x32_bf16 v[118:121], v[166:169], v[182:185], v[118:121]
	v_mfma_f32_16x16x32_bf16 v[114:117], v[174:177], v[182:185], v[114:117]
	v_mfma_f32_16x16x32_bf16 v[102:105], v[166:169], v[190:193], v[102:105]
	v_mfma_f32_16x16x32_bf16 v[98:101], v[174:177], v[190:193], v[98:101]
	v_mfma_f32_16x16x32_bf16 v[86:89], v[166:169], v[198:201], v[86:89]
	v_mfma_f32_16x16x32_bf16 v[82:85], v[174:177], v[198:201], v[82:85]
	v_mfma_f32_16x16x32_bf16 v[70:73], v[166:169], v[206:209], v[70:73]
	v_mfma_f32_16x16x32_bf16 v[66:69], v[174:177], v[206:209], v[66:69]
	s_barrier
	s_add_i32 s62, s54, s42
	v_lshl_add_u64 v[142:143], s[36:37], 0, v[132:133]
	s_mov_b32 m0, s62
	ds_read_b128 v[178:181], v149 offset:16384
	ds_read_b128 v[182:185], v149 offset:17408
	ds_read_b128 v[186:189], v149 offset:18432
	ds_read_b128 v[190:193], v149 offset:19456
	ds_read_b128 v[194:197], v149 offset:20480
	ds_read_b128 v[198:201], v149 offset:21504
	ds_read_b128 v[202:205], v149 offset:22528
	ds_read_b128 v[206:209], v149 offset:23552
	global_load_lds_dwordx4 v[142:143], off
	s_add_i32 m0, s62, 0x2000
	s_add_u32 s62, s36, 0x100000
	v_lshl_add_u64 v[210:211], s[36:37], 0, v[130:131]
	s_addc_u32 s63, s37, 0
	s_add_i32 s64, s55, s42
	global_load_lds_dwordx4 v[210:211], off
	v_lshl_add_u64 v[212:213], s[62:63], 0, v[132:133]
	s_mov_b32 m0, s64
	v_lshl_add_u64 v[214:215], s[38:39], 0, v[130:131]
	global_load_lds_dwordx4 v[212:213], off
	v_lshl_add_u64 v[212:213], s[62:63], 0, v[130:131]
	s_add_i32 m0, s64, 0x2000
	s_nop 0
	global_load_lds_dwordx4 v[212:213], off
	v_lshl_add_u64 v[212:213], s[38:39], 0, v[132:133]
	s_mov_b32 m0, s45
	s_nop 0
	global_load_lds_dwordx4 v[212:213], off
	s_mov_b32 m0, s46
	s_nop 0
	global_load_lds_dwordx4 v[214:215], off
	s_waitcnt vmcnt(8)
	s_waitcnt lgkmcnt(0)
	s_barrier
; #define PG8_STAGE(bufoff, gbase, voff) do { _Pragma("unroll") for (int _i = 0; _i < 2; ++_i) \
;         __builtin_amdgcn_global_load_lds((const unsigned*)((const char*)(gbase) + (voff)[_i]), (PG8_LAS unsigned*)(lds + (bufoff) + ldsw + _i * 8192), 16, 0, 0); } while (0)
; #define PG8_LDA(dst, b, h) do { _Pragma("unroll") for (int m = 0; m < 4; ++m) _Pragma("unroll") for (int k = 0; k < 2; ++k) dst[m][k] = *(const PG8_LAS bf16x8*)(lds + PG8_SA(b, h) + aoff + m * 2048 + k * 1024); } while (0)
; #define PG8_LDB(dst, b, h) do { _Pragma("unroll") for (int n = 0; n < 2; ++n) _Pragma("unroll") for (int k = 0; k < 2; ++k) dst[n][k] = *(const PG8_LAS bf16x8*)(lds + PG8_SB(b, h) + boff + n * 2048 + k * 1024); } while (0)
; #define PG8_MMA(ai, bj, At, Bt) do { __builtin_amdgcn_s_setprio(1); _Pragma("unroll") for (int m = 0; m < 4; ++m) _Pragma("unroll") for (int n = 0; n < 2; ++n) _Pragma("unroll") for (int k = 0; k < 2; ++k) \
;         acc[ai][bj][m][n] = __builtin_amdgcn_mfma_f32_16x16x32_bf16(Bt[n][k], At[m][k], acc[ai][bj][m][n], 0, 0, 0); __builtin_amdgcn_s_setprio(0); } while (0)
; #define PG8_WAIT_V(n) asm volatile("s_waitcnt vmcnt(" #n ")" ::: "memory")
; #define PG8_WAIT_L(n) asm volatile("s_waitcnt lgkmcnt(" #n ")" ::: "memory")
; #define PG8_BAR __builtin_amdgcn_s_barrier()
; #define PG8_SCHED __builtin_amdgcn_sched_barrier(0)
; template <class Epi, class Sched, bool ALIGN_EPI = false, bool SP2 = false>
; __device__ __forceinline__ void gemm_phase(PG8_LAS unsigned char* lds, const Gemm g, const Sched& S, const Epi& E) {
;     ...
;             PG8_WAIT_V(8); PG8_WAIT_L(0); PG8_BAR; PG8_MMA(1, 0, At, B0); PG8_MMA(1, 1, At, B1); PG8_BAR; PG8_SCHED;
;             PG8_LDB(B0, 1, 0); PG8_LDB(B1, 1, 1); PG8_SCHED; PG8_LDA(At, 1, 0); PG8_STAGE(PG8_SA(0, 1), a2 + hstep, voffA);
;             PG8_WAIT_V(8); PG8_WAIT_L(0); PG8_BAR; PG8_MMA(0, 0, At, B0); PG8_MMA(0, 1, At, B1); PG8_BAR; PG8_SCHED;
;             PG8_LDA(At, 1, 1); PG8_STAGE(PG8_SB(1, 0), b3, voffB); PG8_STAGE(PG8_SB(1, 1), b3 + hstep, voffB); PG8_STAGE(PG8_SA(1, 0), a3, voffA);
	s_waitcnt lgkmcnt(0)
	v_mfma_f32_16x16x32_bf16 v[62:65], v[138:141], v[178:181], v[62:65]
	v_mfma_f32_16x16x32_bf16 v[58:61], v[154:157], v[178:181], v[58:61]
	v_mfma_f32_16x16x32_bf16 v[46:49], v[138:141], v[186:189], v[46:49]
	v_mfma_f32_16x16x32_bf16 v[42:45], v[154:157], v[186:189], v[42:45]
	v_mfma_f32_16x16x32_bf16 v[30:33], v[138:141], v[194:197], v[30:33]
	v_mfma_f32_16x16x32_bf16 v[26:29], v[154:157], v[194:197], v[26:29]
	v_mfma_f32_16x16x32_bf16 v[14:17], v[138:141], v[202:205], v[14:17]
	v_mfma_f32_16x16x32_bf16 v[10:13], v[154:157], v[202:205], v[10:13]
	v_mfma_f32_16x16x32_bf16 v[62:65], v[150:153], v[182:185], v[62:65]
	v_mfma_f32_16x16x32_bf16 v[58:61], v[158:161], v[182:185], v[58:61]
	v_mfma_f32_16x16x32_bf16 v[46:49], v[150:153], v[190:193], v[46:49]
	v_mfma_f32_16x16x32_bf16 v[42:45], v[158:161], v[190:193], v[42:45]
	v_mfma_f32_16x16x32_bf16 v[30:33], v[150:153], v[198:201], v[30:33]
	v_mfma_f32_16x16x32_bf16 v[26:29], v[158:161], v[198:201], v[26:29]
	v_mfma_f32_16x16x32_bf16 v[14:17], v[150:153], v[206:209], v[14:17]
	v_mfma_f32_16x16x32_bf16 v[10:13], v[158:161], v[206:209], v[10:13]
	v_mfma_f32_16x16x32_bf16 v[54:57], v[162:165], v[178:181], v[54:57]
	v_mfma_f32_16x16x32_bf16 v[50:53], v[170:173], v[178:181], v[50:53]
	v_mfma_f32_16x16x32_bf16 v[38:41], v[162:165], v[186:189], v[38:41]
	v_mfma_f32_16x16x32_bf16 v[34:37], v[170:173], v[186:189], v[34:37]
	v_mfma_f32_16x16x32_bf16 v[22:25], v[162:165], v[194:197], v[22:25]
	v_mfma_f32_16x16x32_bf16 v[18:21], v[170:173], v[194:197], v[18:21]
	v_mfma_f32_16x16x32_bf16 v[6:9], v[162:165], v[202:205], v[6:9]
	v_mfma_f32_16x16x32_bf16 v[2:5], v[170:173], v[202:205], v[2:5]
	v_mfma_f32_16x16x32_bf16 v[54:57], v[166:169], v[182:185], v[54:57]
	v_mfma_f32_16x16x32_bf16 v[50:53], v[174:177], v[182:185], v[50:53]
	v_mfma_f32_16x16x32_bf16 v[38:41], v[166:169], v[190:193], v[38:41]
	v_mfma_f32_16x16x32_bf16 v[34:37], v[174:177], v[190:193], v[34:37]
	v_mfma_f32_16x16x32_bf16 v[22:25], v[166:169], v[198:201], v[22:25]
	v_mfma_f32_16x16x32_bf16 v[18:21], v[174:177], v[198:201], v[18:21]
	v_mfma_f32_16x16x32_bf16 v[6:9], v[166:169], v[206:209], v[6:9]
	v_mfma_f32_16x16x32_bf16 v[2:5], v[174:177], v[206:209], v[2:5]
	s_barrier
	s_add_i32 s62, 0, 0x18000
	s_add_i32 s63, 0, 0x1c000
	v_add_u32_e32 v158, s62, v144
	v_add_u32_e32 v174, s63, v144
	ds_read_b128 v[138:141], v158
	ds_read_b128 v[150:153], v158 offset:1024
	ds_read_b128 v[154:157], v158 offset:2048
	ds_read_b128 v[158:161], v158 offset:3072
	ds_read_b128 v[162:165], v174
	ds_read_b128 v[166:169], v174 offset:1024
	ds_read_b128 v[170:173], v174 offset:2048
	ds_read_b128 v[174:177], v174 offset:3072
	s_add_u32 s38, s38, 0x100000
	s_addc_u32 s39, s39, 0
	s_mov_b32 m0, s47
	v_lshl_add_u64 v[216:217], s[38:39], 0, v[132:133]
	ds_read_b128 v[178:181], v149 offset:32768
	ds_read_b128 v[182:185], v149 offset:33792
	ds_read_b128 v[186:189], v149 offset:34816
	ds_read_b128 v[190:193], v149 offset:35840
	ds_read_b128 v[194:197], v149 offset:36864
	ds_read_b128 v[198:201], v149 offset:37888
	ds_read_b128 v[202:205], v149 offset:38912
	ds_read_b128 v[206:209], v149 offset:39936
	global_load_lds_dwordx4 v[216:217], off
	v_lshl_add_u64 v[216:217], s[38:39], 0, v[130:131]
	s_mov_b32 m0, s48
	s_nop 0
	global_load_lds_dwordx4 v[216:217], off
	s_waitcnt vmcnt(8)
	s_waitcnt lgkmcnt(0)
	s_barrier
	s_waitcnt lgkmcnt(0)
	v_mfma_f32_16x16x32_bf16 v[126:129], v[138:141], v[178:181], v[126:129]
	v_mfma_f32_16x16x32_bf16 v[122:125], v[154:157], v[178:181], v[122:125]
	v_mfma_f32_16x16x32_bf16 v[110:113], v[138:141], v[186:189], v[110:113]
	v_mfma_f32_16x16x32_bf16 v[106:109], v[154:157], v[186:189], v[106:109]
	v_mfma_f32_16x16x32_bf16 v[94:97], v[138:141], v[194:197], v[94:97]
	v_mfma_f32_16x16x32_bf16 v[90:93], v[154:157], v[194:197], v[90:93]
	v_mfma_f32_16x16x32_bf16 v[78:81], v[138:141], v[202:205], v[78:81]
	v_mfma_f32_16x16x32_bf16 v[74:77], v[154:157], v[202:205], v[74:77]
	v_mfma_f32_16x16x32_bf16 v[126:129], v[150:153], v[182:185], v[126:129]
	v_mfma_f32_16x16x32_bf16 v[122:125], v[158:161], v[182:185], v[122:125]
	v_mfma_f32_16x16x32_bf16 v[110:113], v[150:153], v[190:193], v[110:113]
	v_mfma_f32_16x16x32_bf16 v[106:109], v[158:161], v[190:193], v[106:109]
	v_mfma_f32_16x16x32_bf16 v[94:97], v[150:153], v[198:201], v[94:97]
	v_mfma_f32_16x16x32_bf16 v[90:93], v[158:161], v[198:201], v[90:93]
	v_mfma_f32_16x16x32_bf16 v[78:81], v[150:153], v[206:209], v[78:81]
	v_mfma_f32_16x16x32_bf16 v[74:77], v[158:161], v[206:209], v[74:77]
	v_mfma_f32_16x16x32_bf16 v[118:121], v[162:165], v[178:181], v[118:121]
	v_mfma_f32_16x16x32_bf16 v[114:117], v[170:173], v[178:181], v[114:117]
	v_mfma_f32_16x16x32_bf16 v[102:105], v[162:165], v[186:189], v[102:105]
	v_mfma_f32_16x16x32_bf16 v[98:101], v[170:173], v[186:189], v[98:101]
	v_mfma_f32_16x16x32_bf16 v[86:89], v[162:165], v[194:197], v[86:89]
	v_mfma_f32_16x16x32_bf16 v[82:85], v[170:173], v[194:197], v[82:85]
	v_mfma_f32_16x16x32_bf16 v[70:73], v[162:165], v[202:205], v[70:73]
	v_mfma_f32_16x16x32_bf16 v[66:69], v[170:173], v[202:205], v[66:69]
	v_mfma_f32_16x16x32_bf16 v[118:121], v[166:169], v[182:185], v[118:121]
	v_mfma_f32_16x16x32_bf16 v[114:117], v[174:177], v[182:185], v[114:117]
	v_mfma_f32_16x16x32_bf16 v[102:105], v[166:169], v[190:193], v[102:105]
	v_mfma_f32_16x16x32_bf16 v[98:101], v[174:177], v[190:193], v[98:101]
	v_mfma_f32_16x16x32_bf16 v[86:89], v[166:169], v[198:201], v[86:89]
	v_mfma_f32_16x16x32_bf16 v[82:85], v[174:177], v[198:201], v[82:85]
	v_mfma_f32_16x16x32_bf16 v[70:73], v[166:169], v[206:209], v[70:73]
	v_mfma_f32_16x16x32_bf16 v[66:69], v[174:177], v[206:209], v[66:69]
	s_barrier
; #define PG8_STAGE(bufoff, gbase, voff) do { _Pragma("unroll") for (int _i = 0; _i < 2; ++_i) \
;         __builtin_amdgcn_global_load_lds((const unsigned*)((const char*)(gbase) + (voff)[_i]), (PG8_LAS unsigned*)(lds + (bufoff) + ldsw + _i * 8192), 16, 0, 0); } while (0)
; #define PG8_LDA(dst, b, h) do { _Pragma("unroll") for (int m = 0; m < 4; ++m) _Pragma("unroll") for (int k = 0; k < 2; ++k) dst[m][k] = *(const PG8_LAS bf16x8*)(lds + PG8_SA(b, h) + aoff + m * 2048 + k * 1024); } while (0)
; #define PG8_MMA(ai, bj, At, Bt) do { __builtin_amdgcn_s_setprio(1); _Pragma("unroll") for (int m = 0; m < 4; ++m) _Pragma("unroll") for (int n = 0; n < 2; ++n) _Pragma("unroll") for (int k = 0; k < 2; ++k) \
;         acc[ai][bj][m][n] = __builtin_amdgcn_mfma_f32_16x16x32_bf16(Bt[n][k], At[m][k], acc[ai][bj][m][n], 0, 0, 0); __builtin_amdgcn_s_setprio(0); } while (0)
; #define PG8_WAIT_V(n) asm volatile("s_waitcnt vmcnt(" #n ")" ::: "memory")
; #define PG8_WAIT_L(n) asm volatile("s_waitcnt lgkmcnt(" #n ")" ::: "memory")
; #define PG8_BAR __builtin_amdgcn_s_barrier()
; #define PG8_SCHED __builtin_amdgcn_sched_barrier(0)
; template <class Epi, class Sched, bool ALIGN_EPI = false, bool SP2 = false>
; __device__ __forceinline__ void gemm_phase(PG8_LAS unsigned char* lds, const Gemm g, const Sched& S, const Epi& E) {
;     ...
;             PG8_LDA(At, 1, 1); PG8_STAGE(PG8_SB(1, 0), b3, voffB); PG8_STAGE(PG8_SB(1, 1), b3 + hstep, voffB); PG8_STAGE(PG8_SA(1, 0), a3, voffA);
;             PG8_WAIT_V(8); PG8_WAIT_L(0); PG8_BAR; PG8_MMA(1, 0, At, B0); PG8_MMA(1, 1, At, B1); PG8_BAR; PG8_SCHED;
	s_add_i32 s38, s62, s42
	v_lshl_add_u64 v[142:143], v[142:143], 0, s[16:17]
	s_mov_b32 m0, s38
	ds_read_b128 v[178:181], v149 offset:49152
	ds_read_b128 v[182:185], v149 offset:50176
	ds_read_b128 v[186:189], v149 offset:51200
	ds_read_b128 v[190:193], v149 offset:52224
	ds_read_b128 v[194:197], v149 offset:53248
	ds_read_b128 v[198:201], v149 offset:54272
	ds_read_b128 v[202:205], v149 offset:55296
	ds_read_b128 v[206:209], v149 offset:56320
	global_load_lds_dwordx4 v[142:143], off
	s_add_i32 m0, s38, 0x2000
	s_add_u32 s36, s36, 0x100080
	v_lshl_add_u64 v[142:143], v[210:211], 0, s[16:17]
	s_addc_u32 s37, s37, 0
	s_add_i32 s38, s63, s42
	global_load_lds_dwordx4 v[142:143], off
	v_lshl_add_u64 v[142:143], s[36:37], 0, v[132:133]
	s_mov_b32 m0, s38
	s_nop 0
	global_load_lds_dwordx4 v[142:143], off
	v_lshl_add_u64 v[142:143], s[36:37], 0, v[130:131]
	s_add_i32 m0, s38, 0x2000
	s_nop 0
	global_load_lds_dwordx4 v[142:143], off
	v_lshl_add_u64 v[142:143], v[212:213], 0, s[16:17]
	s_mov_b32 m0, s51
	s_nop 0
	global_load_lds_dwordx4 v[142:143], off
	v_lshl_add_u64 v[142:143], v[214:215], 0, s[16:17]
	s_mov_b32 m0, s52
	s_nop 0
	global_load_lds_dwordx4 v[142:143], off
	s_waitcnt vmcnt(8)
	s_waitcnt lgkmcnt(0)
	s_barrier
	s_waitcnt lgkmcnt(0)
	v_mfma_f32_16x16x32_bf16 v[62:65], v[138:141], v[178:181], v[62:65]
	v_mfma_f32_16x16x32_bf16 v[58:61], v[154:157], v[178:181], v[58:61]
	v_mfma_f32_16x16x32_bf16 v[46:49], v[138:141], v[186:189], v[46:49]
	v_mfma_f32_16x16x32_bf16 v[42:45], v[154:157], v[186:189], v[42:45]
	v_mfma_f32_16x16x32_bf16 v[30:33], v[138:141], v[194:197], v[30:33]
	v_mfma_f32_16x16x32_bf16 v[26:29], v[154:157], v[194:197], v[26:29]
	v_mfma_f32_16x16x32_bf16 v[14:17], v[138:141], v[202:205], v[14:17]
	v_mfma_f32_16x16x32_bf16 v[10:13], v[154:157], v[202:205], v[10:13]
	v_mfma_f32_16x16x32_bf16 v[62:65], v[150:153], v[182:185], v[62:65]
	v_mfma_f32_16x16x32_bf16 v[58:61], v[158:161], v[182:185], v[58:61]
	v_mfma_f32_16x16x32_bf16 v[46:49], v[150:153], v[190:193], v[46:49]
	v_mfma_f32_16x16x32_bf16 v[42:45], v[158:161], v[190:193], v[42:45]
	v_mfma_f32_16x16x32_bf16 v[30:33], v[150:153], v[198:201], v[30:33]
	v_mfma_f32_16x16x32_bf16 v[26:29], v[158:161], v[198:201], v[26:29]
	v_mfma_f32_16x16x32_bf16 v[14:17], v[150:153], v[206:209], v[14:17]
	v_mfma_f32_16x16x32_bf16 v[10:13], v[158:161], v[206:209], v[10:13]
	v_mfma_f32_16x16x32_bf16 v[54:57], v[162:165], v[178:181], v[54:57]
	v_mfma_f32_16x16x32_bf16 v[50:53], v[170:173], v[178:181], v[50:53]
	v_mfma_f32_16x16x32_bf16 v[38:41], v[162:165], v[186:189], v[38:41]
	v_mfma_f32_16x16x32_bf16 v[34:37], v[170:173], v[186:189], v[34:37]
	v_mfma_f32_16x16x32_bf16 v[22:25], v[162:165], v[194:197], v[22:25]
	v_mfma_f32_16x16x32_bf16 v[18:21], v[170:173], v[194:197], v[18:21]
	v_mfma_f32_16x16x32_bf16 v[6:9], v[162:165], v[202:205], v[6:9]
	v_mfma_f32_16x16x32_bf16 v[2:5], v[170:173], v[202:205], v[2:5]
	v_mfma_f32_16x16x32_bf16 v[54:57], v[166:169], v[182:185], v[54:57]
	v_mfma_f32_16x16x32_bf16 v[50:53], v[174:177], v[182:185], v[50:53]
	v_mfma_f32_16x16x32_bf16 v[38:41], v[166:169], v[190:193], v[38:41]
	v_mfma_f32_16x16x32_bf16 v[34:37], v[174:177], v[190:193], v[34:37]
	v_mfma_f32_16x16x32_bf16 v[22:25], v[166:169], v[198:201], v[22:25]
	v_mfma_f32_16x16x32_bf16 v[18:21], v[174:177], v[198:201], v[18:21]
	v_mfma_f32_16x16x32_bf16 v[6:9], v[166:169], v[206:209], v[6:9]
	v_mfma_f32_16x16x32_bf16 v[2:5], v[174:177], v[206:209], v[2:5]
	s_barrier
	s_add_i32 s61, s61, 2
	s_add_u32 s30, s30, 0x100
	s_addc_u32 s31, s31, 0
	s_add_u32 s59, s59, 0x100
	s_addc_u32 s60, s60, 0
	s_cmp_gt_u32 s61, 5
	s_cbranch_scc0 .LBB0_1219
	s_and_b64 vcc, exec, s[18:19]
	s_cbranch_vccz .LBB0_1222
	s_barrier

; #define PG8_STAGE(bufoff, gbase, voff) do { _Pragma("unroll") for (int _i = 0; _i < 2; ++_i) \
;         __builtin_amdgcn_global_load_lds((const unsigned*)((const char*)(gbase) + (voff)[_i]), (PG8_LAS unsigned*)(lds + (bufoff) + ldsw + _i * 8192), 16, 0, 0); } while (0)
; #define PG8_LDA(dst, b, h) do { _Pragma("unroll") for (int m = 0; m < 4; ++m) _Pragma("unroll") for (int k = 0; k < 2; ++k) dst[m][k] = *(const PG8_LAS bf16x8*)(lds + PG8_SA(b, h) + aoff + m * 2048 + k * 1024); } while (0)
; #define PG8_LDB(dst, b, h) do { _Pragma("unroll") for (int n = 0; n < 2; ++n) _Pragma("unroll") for (int k = 0; k < 2; ++k) dst[n][k] = *(const PG8_LAS bf16x8*)(lds + PG8_SB(b, h) + boff + n * 2048 + k * 1024); } while (0)
; #define PG8_WAIT_V(n) asm volatile("s_waitcnt vmcnt(" #n ")" ::: "memory")
; #define PG8_WAIT_L(n) asm volatile("s_waitcnt lgkmcnt(" #n ")" ::: "memory")
; #define PG8_BAR __builtin_amdgcn_s_barrier()
; template <class Epi, class Sched, bool ALIGN_EPI = false, bool SP2 = false>
; __device__ __forceinline__ void gemm_phase(PG8_LAS unsigned char* lds, const Gemm g, const Sched& S, const Epi& E) {
;     ...
;         const char* nA = has_next ? (const char*)g.A + (size_t)nxt.pm * tstep + (size_t)nxt.kt0 * kstep : cA; const char* nB = has_next ? (const char*)g.Bt + (size_t)nxt.pn * tstep + (size_t)nxt.kt0 * kstep : cB;
;         for (int t = 0; t < nt; t += 2) {
;             if constexpr (Epi::MIDHOOK) { if (t == (nt >> 1)) E.mid(acc, cur, wr, wc, fr, fq); }
;             const bool last = (t == nt - 2);
;             const char* a1 = cA + (size_t)(t + 1) * kstep;
;             const char* a2 = last ? nA : cA + (size_t)(t + 2) * kstep; const char* b2 = last ? nB : cB + (size_t)(t + 2) * kstep;
;             const char* a3 = a2 + kstep; const char* b3 = b2 + kstep;
;             if (last && has_next) S.a_ready(nxt);
;             if constexpr (SP2) {
;             PG8_LDB(B0, 0, 0); PG8_LDB(B1, 0, 1); PG8_SCHED; PG8_LDA(At, 0, 0); PG8_STAGE(PG8_SA(1, 1), a1 + hstep, voffA);
;             PG8_WAIT_V(8); PG8_WAIT_L(0); PG8_BAR; PG8_MMA(0, 0, At, B0); PG8_MMA(0, 1, At, B1); PG8_BAR; PG8_SCHED;
;             PG8_LDA(At, 0, 1); PG8_STAGE(PG8_SB(0, 0), b2, voffB); PG8_STAGE(PG8_SB(0, 1), b2 + hstep, voffB); PG8_STAGE(PG8_SA(0, 0), a2, voffA);
;             PG8_WAIT_V(8); PG8_WAIT_L(0); PG8_BAR; PG8_MMA(1, 0, At, B0); PG8_MMA(1, 1, At, B1); PG8_BAR; PG8_SCHED;
.LBB0_1318:
	s_add_u32 s39, s28, s38
	s_addc_u32 s46, s29, 0
	s_add_u32 s42, s39, 0x100
	s_addc_u32 s43, s46, 0
	s_and_b64 s[40:41], s[36:37], exec
	s_cselect_b32 s41, s19, s43
	s_cselect_b32 s40, s62, s42
	s_add_u32 s38, s26, s38
	s_addc_u32 s42, s27, 0
	s_add_u32 s38, s38, 0x100
	s_addc_u32 s42, s42, 0
	s_and_b64 s[36:37], s[36:37], exec
	s_cselect_b32 s43, s17, s42
	s_cselect_b32 s42, s63, s38
	s_add_u32 s48, s39, 0x10080
	ds_read_b128 v[152:155], v148
	ds_read_b128 v[156:159], v148 offset:1024
	ds_read_b128 v[160:163], v148 offset:2048
	ds_read_b128 v[164:167], v148 offset:3072
	ds_read_b128 v[168:171], v149
	ds_read_b128 v[172:175], v149 offset:1024
	ds_read_b128 v[176:179], v149 offset:2048
	ds_read_b128 v[180:183], v149 offset:3072
	s_addc_u32 s49, s46, 0
	s_add_i32 s73, s59, s3
	s_add_i32 m0, s25, 0xc000
	s_add_i32 s74, s25, 0xe000
	s_add_i32 s70, s73, 0x2000
	s_add_u32 s46, s42, 0x10000
	s_addc_u32 s47, s43, 0
	s_add_i32 s72, s60, s3
	s_add_i32 s71, s72, 0x2000
	s_add_i32 s69, 0, 0x18000
	s_add_i32 s68, 0, 0x1c000
	s_add_u32 s38, s40, 0x10000
	s_addc_u32 s39, s41, 0
	s_add_i32 s67, s69, s3
	s_add_i32 s65, s67, 0x2000
	s_add_u32 s36, s42, 0x10080
	s_addc_u32 s37, s43, 0
	s_add_i32 s66, s68, s3
	s_add_i32 s64, s66, 0x2000
	v_lshl_add_u64 v[142:143], s[48:49], 0, v[136:137]
	ds_read_b128 v[184:187], v150
	ds_read_b128 v[188:191], v150 offset:1024
	ds_read_b128 v[192:195], v150 offset:2048
	ds_read_b128 v[196:199], v150 offset:3072
	ds_read_b128 v[200:203], v150 offset:4096
	ds_read_b128 v[204:207], v150 offset:5120
	ds_read_b128 v[208:211], v150 offset:6144
	ds_read_b128 v[212:215], v150 offset:7168
	global_load_lds_dwordx4 v[142:143], off
	v_lshl_add_u64 v[142:143], s[48:49], 0, v[132:133]
	s_mov_b32 m0, s74
	s_nop 0
	global_load_lds_dwordx4 v[142:143], off
	s_waitcnt vmcnt(8)
	s_waitcnt lgkmcnt(0)
	s_barrier
	s_waitcnt lgkmcnt(0)
	v_mfma_f32_16x16x32_bf16 v[126:129], v[152:155], v[184:187], v[126:129]
	v_mfma_f32_16x16x32_bf16 v[122:125], v[160:163], v[184:187], v[122:125]
	v_mfma_f32_16x16x32_bf16 v[118:121], v[152:155], v[192:195], v[118:121]
	v_mfma_f32_16x16x32_bf16 v[110:113], v[160:163], v[192:195], v[110:113]
	v_mfma_f32_16x16x32_bf16 v[102:105], v[152:155], v[200:203], v[102:105]
	v_mfma_f32_16x16x32_bf16 v[94:97], v[160:163], v[200:203], v[94:97]
	v_mfma_f32_16x16x32_bf16 v[86:89], v[152:155], v[208:211], v[86:89]
	v_mfma_f32_16x16x32_bf16 v[78:81], v[160:163], v[208:211], v[78:81]
	v_mfma_f32_16x16x32_bf16 v[126:129], v[156:159], v[188:191], v[126:129]
	v_mfma_f32_16x16x32_bf16 v[122:125], v[164:167], v[188:191], v[122:125]
	v_mfma_f32_16x16x32_bf16 v[118:121], v[156:159], v[196:199], v[118:121]
	v_mfma_f32_16x16x32_bf16 v[110:113], v[164:167], v[196:199], v[110:113]
	v_mfma_f32_16x16x32_bf16 v[102:105], v[156:159], v[204:207], v[102:105]
	v_mfma_f32_16x16x32_bf16 v[94:97], v[164:167], v[204:207], v[94:97]
	v_mfma_f32_16x16x32_bf16 v[86:89], v[156:159], v[212:215], v[86:89]
	v_mfma_f32_16x16x32_bf16 v[78:81], v[164:167], v[212:215], v[78:81]
	v_mfma_f32_16x16x32_bf16 v[114:117], v[168:171], v[184:187], v[114:117]
	v_mfma_f32_16x16x32_bf16 v[106:109], v[176:179], v[184:187], v[106:109]
	v_mfma_f32_16x16x32_bf16 v[98:101], v[168:171], v[192:195], v[98:101]
	v_mfma_f32_16x16x32_bf16 v[90:93], v[176:179], v[192:195], v[90:93]
	v_mfma_f32_16x16x32_bf16 v[82:85], v[168:171], v[200:203], v[82:85]
	v_mfma_f32_16x16x32_bf16 v[74:77], v[176:179], v[200:203], v[74:77]
	v_mfma_f32_16x16x32_bf16 v[70:73], v[168:171], v[208:211], v[70:73]
	v_mfma_f32_16x16x32_bf16 v[66:69], v[176:179], v[208:211], v[66:69]
	v_mfma_f32_16x16x32_bf16 v[114:117], v[172:175], v[188:191], v[114:117]
	v_mfma_f32_16x16x32_bf16 v[106:109], v[180:183], v[188:191], v[106:109]
	v_mfma_f32_16x16x32_bf16 v[98:101], v[172:175], v[196:199], v[98:101]
	v_mfma_f32_16x16x32_bf16 v[90:93], v[180:183], v[196:199], v[90:93]
	v_mfma_f32_16x16x32_bf16 v[82:85], v[172:175], v[204:207], v[82:85]
	v_mfma_f32_16x16x32_bf16 v[74:77], v[180:183], v[204:207], v[74:77]
	v_mfma_f32_16x16x32_bf16 v[70:73], v[172:175], v[212:215], v[70:73]
	v_mfma_f32_16x16x32_bf16 v[66:69], v[180:183], v[212:215], v[66:69]
	s_barrier
	s_mov_b32 m0, s73
	v_lshl_add_u64 v[142:143], s[42:43], 0, v[134:135]
	ds_read_b128 v[184:187], v150 offset:16384
	ds_read_b128 v[188:191], v150 offset:17408
	ds_read_b128 v[192:195], v150 offset:18432
	ds_read_b128 v[196:199], v150 offset:19456
	ds_read_b128 v[200:203], v150 offset:20480
	ds_read_b128 v[204:207], v150 offset:21504
	ds_read_b128 v[208:211], v150 offset:22528
	ds_read_b128 v[212:215], v150 offset:23552
	global_load_lds_dwordx4 v[142:143], off
	v_lshl_add_u64 v[216:217], s[42:43], 0, v[130:131]
	s_mov_b32 m0, s70
	v_lshl_add_u64 v[218:219], s[46:47], 0, v[134:135]
	global_load_lds_dwordx4 v[216:217], off
	s_mov_b32 m0, s72
	v_lshl_add_u64 v[220:221], s[40:41], 0, v[132:133]
	global_load_lds_dwordx4 v[218:219], off
	v_lshl_add_u64 v[218:219], s[46:47], 0, v[130:131]
	s_mov_b32 m0, s71
	s_nop 0
	global_load_lds_dwordx4 v[218:219], off
	v_lshl_add_u64 v[218:219], s[40:41], 0, v[136:137]
	s_mov_b32 m0, s25
	s_nop 0
	global_load_lds_dwordx4 v[218:219], off
	s_mov_b32 m0, s52
	s_nop 0
	global_load_lds_dwordx4 v[220:221], off
	s_waitcnt vmcnt(8)
	s_waitcnt lgkmcnt(0)
	s_barrier
; #define PG8_STAGE(bufoff, gbase, voff) do { _Pragma("unroll") for (int _i = 0; _i < 2; ++_i) \
;         __builtin_amdgcn_global_load_lds((const unsigned*)((const char*)(gbase) + (voff)[_i]), (PG8_LAS unsigned*)(lds + (bufoff) + ldsw + _i * 8192), 16, 0, 0); } while (0)
; #define PG8_LDA(dst, b, h) do { _Pragma("unroll") for (int m = 0; m < 4; ++m) _Pragma("unroll") for (int k = 0; k < 2; ++k) dst[m][k] = *(const PG8_LAS bf16x8*)(lds + PG8_SA(b, h) + aoff + m * 2048 + k * 1024); } while (0)
; #define PG8_LDB(dst, b, h) do { _Pragma("unroll") for (int n = 0; n < 2; ++n) _Pragma("unroll") for (int k = 0; k < 2; ++k) dst[n][k] = *(const PG8_LAS bf16x8*)(lds + PG8_SB(b, h) + boff + n * 2048 + k * 1024); } while (0)
; #define PG8_MMA(ai, bj, At, Bt) do { __builtin_amdgcn_s_setprio(1); _Pragma("unroll") for (int m = 0; m < 4; ++m) _Pragma("unroll") for (int n = 0; n < 2; ++n) _Pragma("unroll") for (int k = 0; k < 2; ++k) \
;         acc[ai][bj][m][n] = __builtin_amdgcn_mfma_f32_16x16x32_bf16(Bt[n][k], At[m][k], acc[ai][bj][m][n], 0, 0, 0); __builtin_amdgcn_s_setprio(0); } while (0)
; #define PG8_WAIT_V(n) asm volatile("s_waitcnt vmcnt(" #n ")" ::: "memory")
; #define PG8_WAIT_L(n) asm volatile("s_waitcnt lgkmcnt(" #n ")" ::: "memory")
; #define PG8_BAR __builtin_amdgcn_s_barrier()
; #define PG8_SCHED __builtin_amdgcn_sched_barrier(0)
; template <class Epi, class Sched, bool ALIGN_EPI = false, bool SP2 = false>
; __device__ __forceinline__ void gemm_phase(PG8_LAS unsigned char* lds, const Gemm g, const Sched& S, const Epi& E) {
;     ...
;             PG8_WAIT_V(8); PG8_WAIT_L(0); PG8_BAR; PG8_MMA(1, 0, At, B0); PG8_MMA(1, 1, At, B1); PG8_BAR; PG8_SCHED;
;             PG8_LDB(B0, 1, 0); PG8_LDB(B1, 1, 1); PG8_SCHED; PG8_LDA(At, 1, 0); PG8_STAGE(PG8_SA(0, 1), a2 + hstep, voffA);
;             PG8_WAIT_V(8); PG8_WAIT_L(0); PG8_BAR; PG8_MMA(0, 0, At, B0); PG8_MMA(0, 1, At, B1); PG8_BAR; PG8_SCHED;
;             PG8_LDA(At, 1, 1); PG8_STAGE(PG8_SB(1, 0), b3, voffB); PG8_STAGE(PG8_SB(1, 1), b3 + hstep, voffB); PG8_STAGE(PG8_SA(1, 0), a3, voffA);
	s_waitcnt lgkmcnt(0)
	v_mfma_f32_16x16x32_bf16 v[62:65], v[152:155], v[184:187], v[62:65]
	v_mfma_f32_16x16x32_bf16 v[58:61], v[160:163], v[184:187], v[58:61]
	v_mfma_f32_16x16x32_bf16 v[54:57], v[152:155], v[192:195], v[54:57]
	v_mfma_f32_16x16x32_bf16 v[46:49], v[160:163], v[192:195], v[46:49]
	v_mfma_f32_16x16x32_bf16 v[38:41], v[152:155], v[200:203], v[38:41]
	v_mfma_f32_16x16x32_bf16 v[30:33], v[160:163], v[200:203], v[30:33]
	v_mfma_f32_16x16x32_bf16 v[22:25], v[152:155], v[208:211], v[22:25]
	v_mfma_f32_16x16x32_bf16 v[14:17], v[160:163], v[208:211], v[14:17]
	v_mfma_f32_16x16x32_bf16 v[62:65], v[156:159], v[188:191], v[62:65]
	v_mfma_f32_16x16x32_bf16 v[58:61], v[164:167], v[188:191], v[58:61]
	v_mfma_f32_16x16x32_bf16 v[54:57], v[156:159], v[196:199], v[54:57]
	v_mfma_f32_16x16x32_bf16 v[46:49], v[164:167], v[196:199], v[46:49]
	v_mfma_f32_16x16x32_bf16 v[38:41], v[156:159], v[204:207], v[38:41]
	v_mfma_f32_16x16x32_bf16 v[30:33], v[164:167], v[204:207], v[30:33]
	v_mfma_f32_16x16x32_bf16 v[22:25], v[156:159], v[212:215], v[22:25]
	v_mfma_f32_16x16x32_bf16 v[14:17], v[164:167], v[212:215], v[14:17]
	v_mfma_f32_16x16x32_bf16 v[50:53], v[168:171], v[184:187], v[50:53]
	v_mfma_f32_16x16x32_bf16 v[42:45], v[176:179], v[184:187], v[42:45]
	v_mfma_f32_16x16x32_bf16 v[34:37], v[168:171], v[192:195], v[34:37]
	v_mfma_f32_16x16x32_bf16 v[26:29], v[176:179], v[192:195], v[26:29]
	v_mfma_f32_16x16x32_bf16 v[18:21], v[168:171], v[200:203], v[18:21]
	v_mfma_f32_16x16x32_bf16 v[10:13], v[176:179], v[200:203], v[10:13]
	v_mfma_f32_16x16x32_bf16 v[6:9], v[168:171], v[208:211], v[6:9]
	v_mfma_f32_16x16x32_bf16 v[2:5], v[176:179], v[208:211], v[2:5]
	v_mfma_f32_16x16x32_bf16 v[50:53], v[172:175], v[188:191], v[50:53]
	v_mfma_f32_16x16x32_bf16 v[42:45], v[180:183], v[188:191], v[42:45]
	v_mfma_f32_16x16x32_bf16 v[34:37], v[172:175], v[196:199], v[34:37]
	v_mfma_f32_16x16x32_bf16 v[26:29], v[180:183], v[196:199], v[26:29]
	v_mfma_f32_16x16x32_bf16 v[18:21], v[172:175], v[204:207], v[18:21]
	v_mfma_f32_16x16x32_bf16 v[10:13], v[180:183], v[204:207], v[10:13]
	v_mfma_f32_16x16x32_bf16 v[6:9], v[172:175], v[212:215], v[6:9]
	v_mfma_f32_16x16x32_bf16 v[2:5], v[180:183], v[212:215], v[2:5]
	s_barrier
	v_add_u32_e32 v151, s69, v146
	ds_read_b128 v[152:155], v151
	ds_read_b128 v[156:159], v151 offset:1024
	ds_read_b128 v[160:163], v151 offset:2048
	ds_read_b128 v[164:167], v151 offset:3072
	v_add_u32_e32 v151, s68, v146
	ds_read_b128 v[168:171], v151
	ds_read_b128 v[172:175], v151 offset:1024
	ds_read_b128 v[176:179], v151 offset:2048
	ds_read_b128 v[180:183], v151 offset:3072
	s_mov_b32 m0, s53
	v_lshl_add_u64 v[222:223], s[38:39], 0, v[136:137]
	ds_read_b128 v[184:187], v150 offset:32768
	ds_read_b128 v[188:191], v150 offset:33792
	ds_read_b128 v[192:195], v150 offset:34816
	ds_read_b128 v[196:199], v150 offset:35840
	ds_read_b128 v[200:203], v150 offset:36864
	ds_read_b128 v[204:207], v150 offset:37888
	ds_read_b128 v[208:211], v150 offset:38912
	ds_read_b128 v[212:215], v150 offset:39936
	global_load_lds_dwordx4 v[222:223], off
	v_lshl_add_u64 v[222:223], s[38:39], 0, v[132:133]
	s_mov_b32 m0, s54
	s_nop 0
	global_load_lds_dwordx4 v[222:223], off
	s_waitcnt vmcnt(8)
	s_waitcnt lgkmcnt(0)
	s_barrier
	s_waitcnt lgkmcnt(0)
	v_mfma_f32_16x16x32_bf16 v[126:129], v[152:155], v[184:187], v[126:129]
	v_mfma_f32_16x16x32_bf16 v[122:125], v[160:163], v[184:187], v[122:125]
	v_mfma_f32_16x16x32_bf16 v[118:121], v[152:155], v[192:195], v[118:121]
	v_mfma_f32_16x16x32_bf16 v[110:113], v[160:163], v[192:195], v[110:113]
	v_mfma_f32_16x16x32_bf16 v[102:105], v[152:155], v[200:203], v[102:105]
	v_mfma_f32_16x16x32_bf16 v[94:97], v[160:163], v[200:203], v[94:97]
	v_mfma_f32_16x16x32_bf16 v[86:89], v[152:155], v[208:211], v[86:89]
	v_mfma_f32_16x16x32_bf16 v[78:81], v[160:163], v[208:211], v[78:81]
	v_mfma_f32_16x16x32_bf16 v[126:129], v[156:159], v[188:191], v[126:129]
	v_mfma_f32_16x16x32_bf16 v[122:125], v[164:167], v[188:191], v[122:125]
	v_mfma_f32_16x16x32_bf16 v[118:121], v[156:159], v[196:199], v[118:121]
	v_mfma_f32_16x16x32_bf16 v[110:113], v[164:167], v[196:199], v[110:113]
	v_mfma_f32_16x16x32_bf16 v[102:105], v[156:159], v[204:207], v[102:105]
	v_mfma_f32_16x16x32_bf16 v[94:97], v[164:167], v[204:207], v[94:97]
	v_mfma_f32_16x16x32_bf16 v[86:89], v[156:159], v[212:215], v[86:89]
	v_mfma_f32_16x16x32_bf16 v[78:81], v[164:167], v[212:215], v[78:81]
	v_mfma_f32_16x16x32_bf16 v[114:117], v[168:171], v[184:187], v[114:117]
	v_mfma_f32_16x16x32_bf16 v[106:109], v[176:179], v[184:187], v[106:109]
	v_mfma_f32_16x16x32_bf16 v[98:101], v[168:171], v[192:195], v[98:101]
	v_mfma_f32_16x16x32_bf16 v[90:93], v[176:179], v[192:195], v[90:93]
	v_mfma_f32_16x16x32_bf16 v[82:85], v[168:171], v[200:203], v[82:85]
	v_mfma_f32_16x16x32_bf16 v[74:77], v[176:179], v[200:203], v[74:77]
	v_mfma_f32_16x16x32_bf16 v[70:73], v[168:171], v[208:211], v[70:73]
	v_mfma_f32_16x16x32_bf16 v[66:69], v[176:179], v[208:211], v[66:69]
	v_mfma_f32_16x16x32_bf16 v[114:117], v[172:175], v[188:191], v[114:117]
	v_mfma_f32_16x16x32_bf16 v[106:109], v[180:183], v[188:191], v[106:109]
	v_mfma_f32_16x16x32_bf16 v[98:101], v[172:175], v[196:199], v[98:101]
	v_mfma_f32_16x16x32_bf16 v[90:93], v[180:183], v[196:199], v[90:93]
	v_mfma_f32_16x16x32_bf16 v[82:85], v[172:175], v[204:207], v[82:85]
	v_mfma_f32_16x16x32_bf16 v[74:77], v[180:183], v[204:207], v[74:77]
	v_mfma_f32_16x16x32_bf16 v[70:73], v[172:175], v[212:215], v[70:73]
	v_mfma_f32_16x16x32_bf16 v[66:69], v[180:183], v[212:215], v[66:69]
	s_barrier
; #define PG8_STAGE(bufoff, gbase, voff) do { _Pragma("unroll") for (int _i = 0; _i < 2; ++_i) \
;         __builtin_amdgcn_global_load_lds((const unsigned*)((const char*)(gbase) + (voff)[_i]), (PG8_LAS unsigned*)(lds + (bufoff) + ldsw + _i * 8192), 16, 0, 0); } while (0)
; #define PG8_LDA(dst, b, h) do { _Pragma("unroll") for (int m = 0; m < 4; ++m) _Pragma("unroll") for (int k = 0; k < 2; ++k) dst[m][k] = *(const PG8_LAS bf16x8*)(lds + PG8_SA(b, h) + aoff + m * 2048 + k * 1024); } while (0)
; #define PG8_MMA(ai, bj, At, Bt) do { __builtin_amdgcn_s_setprio(1); _Pragma("unroll") for (int m = 0; m < 4; ++m) _Pragma("unroll") for (int n = 0; n < 2; ++n) _Pragma("unroll") for (int k = 0; k < 2; ++k) \
;         acc[ai][bj][m][n] = __builtin_amdgcn_mfma_f32_16x16x32_bf16(Bt[n][k], At[m][k], acc[ai][bj][m][n], 0, 0, 0); __builtin_amdgcn_s_setprio(0); } while (0)
; #define PG8_WAIT_V(n) asm volatile("s_waitcnt vmcnt(" #n ")" ::: "memory")
; #define PG8_WAIT_L(n) asm volatile("s_waitcnt lgkmcnt(" #n ")" ::: "memory")
; #define PG8_BAR __builtin_amdgcn_s_barrier()
; #define PG8_SCHED __builtin_amdgcn_sched_barrier(0)
; template <class Epi, class Sched, bool ALIGN_EPI = false, bool SP2 = false>
; __device__ __forceinline__ void gemm_phase(PG8_LAS unsigned char* lds, const Gemm g, const Sched& S, const Epi& E) {
;     ...
;             PG8_LDA(At, 1, 1); PG8_STAGE(PG8_SB(1, 0), b3, voffB); PG8_STAGE(PG8_SB(1, 1), b3 + hstep, voffB); PG8_STAGE(PG8_SA(1, 0), a3, voffA);
;             PG8_WAIT_V(8); PG8_WAIT_L(0); PG8_BAR; PG8_MMA(1, 0, At, B0); PG8_MMA(1, 1, At, B1); PG8_BAR; PG8_SCHED;
	s_mov_b32 m0, s67
	v_lshl_add_u64 v[142:143], v[142:143], 0, s[12:13]
	ds_read_b128 v[184:187], v150 offset:49152
	ds_read_b128 v[188:191], v150 offset:50176
	ds_read_b128 v[192:195], v150 offset:51200
	ds_read_b128 v[196:199], v150 offset:52224
	ds_read_b128 v[200:203], v150 offset:53248
	ds_read_b128 v[204:207], v150 offset:54272
	ds_read_b128 v[208:211], v150 offset:55296
	ds_read_b128 v[212:215], v150 offset:56320
	global_load_lds_dwordx4 v[142:143], off
	v_lshl_add_u64 v[142:143], v[216:217], 0, s[12:13]
	s_mov_b32 m0, s65
	s_nop 0
	global_load_lds_dwordx4 v[142:143], off
	v_lshl_add_u64 v[142:143], s[36:37], 0, v[134:135]
	s_mov_b32 m0, s66
	s_nop 0
	global_load_lds_dwordx4 v[142:143], off
	v_lshl_add_u64 v[142:143], s[36:37], 0, v[130:131]
	s_mov_b32 m0, s64
	s_nop 0
	global_load_lds_dwordx4 v[142:143], off
	v_lshl_add_u64 v[142:143], v[218:219], 0, s[12:13]
	s_mov_b32 m0, s57
	s_nop 0
	global_load_lds_dwordx4 v[142:143], off
	v_lshl_add_u64 v[142:143], v[220:221], 0, s[12:13]
	s_mov_b32 m0, s58
	s_nop 0
	global_load_lds_dwordx4 v[142:143], off
	s_waitcnt vmcnt(8)
	s_waitcnt lgkmcnt(0)
	s_barrier
	s_waitcnt lgkmcnt(0)
	v_mfma_f32_16x16x32_bf16 v[62:65], v[152:155], v[184:187], v[62:65]
	v_mfma_f32_16x16x32_bf16 v[58:61], v[160:163], v[184:187], v[58:61]
	v_mfma_f32_16x16x32_bf16 v[54:57], v[152:155], v[192:195], v[54:57]
	v_mfma_f32_16x16x32_bf16 v[46:49], v[160:163], v[192:195], v[46:49]
	v_mfma_f32_16x16x32_bf16 v[38:41], v[152:155], v[200:203], v[38:41]
	v_mfma_f32_16x16x32_bf16 v[30:33], v[160:163], v[200:203], v[30:33]
	v_mfma_f32_16x16x32_bf16 v[22:25], v[152:155], v[208:211], v[22:25]
	v_mfma_f32_16x16x32_bf16 v[14:17], v[160:163], v[208:211], v[14:17]
	v_mfma_f32_16x16x32_bf16 v[62:65], v[156:159], v[188:191], v[62:65]
	v_mfma_f32_16x16x32_bf16 v[58:61], v[164:167], v[188:191], v[58:61]
	v_mfma_f32_16x16x32_bf16 v[54:57], v[156:159], v[196:199], v[54:57]
	v_mfma_f32_16x16x32_bf16 v[46:49], v[164:167], v[196:199], v[46:49]
	v_mfma_f32_16x16x32_bf16 v[38:41], v[156:159], v[204:207], v[38:41]
	v_mfma_f32_16x16x32_bf16 v[30:33], v[164:167], v[204:207], v[30:33]
	v_mfma_f32_16x16x32_bf16 v[22:25], v[156:159], v[212:215], v[22:25]
	v_mfma_f32_16x16x32_bf16 v[14:17], v[164:167], v[212:215], v[14:17]
	v_mfma_f32_16x16x32_bf16 v[50:53], v[168:171], v[184:187], v[50:53]
	v_mfma_f32_16x16x32_bf16 v[42:45], v[176:179], v[184:187], v[42:45]
	v_mfma_f32_16x16x32_bf16 v[34:37], v[168:171], v[192:195], v[34:37]
	v_mfma_f32_16x16x32_bf16 v[26:29], v[176:179], v[192:195], v[26:29]
	v_mfma_f32_16x16x32_bf16 v[18:21], v[168:171], v[200:203], v[18:21]
	v_mfma_f32_16x16x32_bf16 v[10:13], v[176:179], v[200:203], v[10:13]
	v_mfma_f32_16x16x32_bf16 v[6:9], v[168:171], v[208:211], v[6:9]
	v_mfma_f32_16x16x32_bf16 v[2:5], v[176:179], v[208:211], v[2:5]
	v_mfma_f32_16x16x32_bf16 v[50:53], v[172:175], v[188:191], v[50:53]
	v_mfma_f32_16x16x32_bf16 v[42:45], v[180:183], v[188:191], v[42:45]
	v_mfma_f32_16x16x32_bf16 v[34:37], v[172:175], v[196:199], v[34:37]
	v_mfma_f32_16x16x32_bf16 v[26:29], v[180:183], v[196:199], v[26:29]
	v_mfma_f32_16x16x32_bf16 v[18:21], v[172:175], v[204:207], v[18:21]
	v_mfma_f32_16x16x32_bf16 v[10:13], v[180:183], v[204:207], v[10:13]
	v_mfma_f32_16x16x32_bf16 v[6:9], v[172:175], v[212:215], v[6:9]
	v_mfma_f32_16x16x32_bf16 v[2:5], v[180:183], v[212:215], v[2:5]
	s_barrier
	s_movk_i32 s38, 0x100
	s_andn2_b64 vcc, exec, s[30:31]
	s_mov_b64 s[36:37], -1
	s_mov_b64 s[30:31], 0
	s_cbranch_vccz .LBB0_1318
	s_and_b64 vcc, exec, s[14:15]
	s_cbranch_vccz .LBB0_1321
	s_barrier

; #define PG8_STAGE(bufoff, gbase, voff) do { _Pragma("unroll") for (int _i = 0; _i < 2; ++_i) \
;         __builtin_amdgcn_global_load_lds((const unsigned*)((const char*)(gbase) + (voff)[_i]), (PG8_LAS unsigned*)(lds + (bufoff) + ldsw + _i * 8192), 16, 0, 0); } while (0)
; #define PG8_LDA(dst, b, h) do { _Pragma("unroll") for (int m = 0; m < 4; ++m) _Pragma("unroll") for (int k = 0; k < 2; ++k) dst[m][k] = *(const PG8_LAS bf16x8*)(lds + PG8_SA(b, h) + aoff + m * 2048 + k * 1024); } while (0)
; #define PG8_LDB(dst, b, h) do { _Pragma("unroll") for (int n = 0; n < 2; ++n) _Pragma("unroll") for (int k = 0; k < 2; ++k) dst[n][k] = *(const PG8_LAS bf16x8*)(lds + PG8_SB(b, h) + boff + n * 2048 + k * 1024); } while (0)
; #define PG8_WAIT_V(n) asm volatile("s_waitcnt vmcnt(" #n ")" ::: "memory")
; #define PG8_WAIT_L(n) asm volatile("s_waitcnt lgkmcnt(" #n ")" ::: "memory")
; #define PG8_BAR __builtin_amdgcn_s_barrier()
; template <class Epi, class Sched, bool ALIGN_EPI = false, bool SP2 = false>
; __device__ __forceinline__ void gemm_phase(PG8_LAS unsigned char* lds, const Gemm g, const Sched& S, const Epi& E) {
;     ...
;         const char* nA = has_next ? (const char*)g.A + (size_t)nxt.pm * tstep + (size_t)nxt.kt0 * kstep : cA; const char* nB = has_next ? (const char*)g.Bt + (size_t)nxt.pn * tstep + (size_t)nxt.kt0 * kstep : cB;
;         for (int t = 0; t < nt; t += 2) {
;             if constexpr (Epi::MIDHOOK) { if (t == (nt >> 1)) E.mid(acc, cur, wr, wc, fr, fq); }
;             const bool last = (t == nt - 2);
;             const char* a1 = cA + (size_t)(t + 1) * kstep;
;             const char* a2 = last ? nA : cA + (size_t)(t + 2) * kstep; const char* b2 = last ? nB : cB + (size_t)(t + 2) * kstep;
;             const char* a3 = a2 + kstep; const char* b3 = b2 + kstep;
;             if (last && has_next) S.a_ready(nxt);
;             if constexpr (SP2) {
;             PG8_LDB(B0, 0, 0); PG8_LDB(B1, 0, 1); PG8_SCHED; PG8_LDA(At, 0, 0); PG8_STAGE(PG8_SA(1, 1), a1 + hstep, voffA);
;             PG8_WAIT_V(8); PG8_WAIT_L(0); PG8_BAR; PG8_MMA(0, 0, At, B0); PG8_MMA(0, 1, At, B1); PG8_BAR; PG8_SCHED;
;             PG8_LDA(At, 0, 1); PG8_STAGE(PG8_SB(0, 0), b2, voffB); PG8_STAGE(PG8_SB(0, 1), b2 + hstep, voffB); PG8_STAGE(PG8_SA(0, 0), a2, voffA);
;             PG8_WAIT_V(8); PG8_WAIT_L(0); PG8_BAR; PG8_MMA(1, 0, At, B0); PG8_MMA(1, 1, At, B1); PG8_BAR; PG8_SCHED;
.LBB0_1393:
	ds_read_b128 v[156:159], v152
	ds_read_b128 v[160:163], v152 offset:1024
	ds_read_b128 v[164:167], v152 offset:2048
	ds_read_b128 v[168:171], v152 offset:3072
	ds_read_b128 v[172:175], v153
	ds_read_b128 v[176:179], v153 offset:1024
	ds_read_b128 v[180:183], v153 offset:2048
	ds_read_b128 v[184:187], v153 offset:3072
	s_add_u32 s28, s26, 0xfff80080
	s_addc_u32 s29, s27, -1
	s_cmp_eq_u32 s54, 28
	s_cselect_b32 s31, s19, s29
	s_cselect_b32 s30, s50, s28
	s_cselect_b32 s29, s17, s53
	s_cselect_b32 s28, s51, s52
	v_lshl_add_u64 v[146:147], s[26:27], 0, v[138:139]
	s_add_i32 m0, s25, 0xc000
	ds_read_b128 v[188:191], v154
	ds_read_b128 v[192:195], v154 offset:1024
	ds_read_b128 v[196:199], v154 offset:2048
	ds_read_b128 v[200:203], v154 offset:3072
	ds_read_b128 v[204:207], v154 offset:4096
	ds_read_b128 v[208:211], v154 offset:5120
	ds_read_b128 v[212:215], v154 offset:6144
	ds_read_b128 v[216:219], v154 offset:7168
	global_load_lds_dwordx4 v[146:147], off
	v_lshl_add_u64 v[146:147], s[26:27], 0, v[140:141]
	s_add_i32 m0, s25, 0xe000
	s_nop 0
	global_load_lds_dwordx4 v[146:147], off
	s_waitcnt vmcnt(8)
	s_waitcnt lgkmcnt(0)
	s_barrier
	s_waitcnt lgkmcnt(0)
	v_mfma_f32_16x16x32_bf16 v[126:129], v[156:159], v[188:191], v[126:129]
	v_mfma_f32_16x16x32_bf16 v[122:125], v[164:167], v[188:191], v[122:125]
	v_mfma_f32_16x16x32_bf16 v[118:121], v[156:159], v[196:199], v[118:121]
	v_mfma_f32_16x16x32_bf16 v[110:113], v[164:167], v[196:199], v[110:113]
	v_mfma_f32_16x16x32_bf16 v[102:105], v[156:159], v[204:207], v[102:105]
	v_mfma_f32_16x16x32_bf16 v[94:97], v[164:167], v[204:207], v[94:97]
	v_mfma_f32_16x16x32_bf16 v[86:89], v[156:159], v[212:215], v[86:89]
	v_mfma_f32_16x16x32_bf16 v[78:81], v[164:167], v[212:215], v[78:81]
	v_mfma_f32_16x16x32_bf16 v[126:129], v[160:163], v[192:195], v[126:129]
	v_mfma_f32_16x16x32_bf16 v[122:125], v[168:171], v[192:195], v[122:125]
	v_mfma_f32_16x16x32_bf16 v[118:121], v[160:163], v[200:203], v[118:121]
	v_mfma_f32_16x16x32_bf16 v[110:113], v[168:171], v[200:203], v[110:113]
	v_mfma_f32_16x16x32_bf16 v[102:105], v[160:163], v[208:211], v[102:105]
	v_mfma_f32_16x16x32_bf16 v[94:97], v[168:171], v[208:211], v[94:97]
	v_mfma_f32_16x16x32_bf16 v[86:89], v[160:163], v[216:219], v[86:89]
	v_mfma_f32_16x16x32_bf16 v[78:81], v[168:171], v[216:219], v[78:81]
	v_mfma_f32_16x16x32_bf16 v[114:117], v[172:175], v[188:191], v[114:117]
	v_mfma_f32_16x16x32_bf16 v[106:109], v[180:183], v[188:191], v[106:109]
	v_mfma_f32_16x16x32_bf16 v[98:101], v[172:175], v[196:199], v[98:101]
	v_mfma_f32_16x16x32_bf16 v[90:93], v[180:183], v[196:199], v[90:93]
	v_mfma_f32_16x16x32_bf16 v[82:85], v[172:175], v[204:207], v[82:85]
	v_mfma_f32_16x16x32_bf16 v[74:77], v[180:183], v[204:207], v[74:77]
	v_mfma_f32_16x16x32_bf16 v[70:73], v[172:175], v[212:215], v[70:73]
	v_mfma_f32_16x16x32_bf16 v[66:69], v[180:183], v[212:215], v[66:69]
	v_mfma_f32_16x16x32_bf16 v[114:117], v[176:179], v[192:195], v[114:117]
	v_mfma_f32_16x16x32_bf16 v[106:109], v[184:187], v[192:195], v[106:109]
	v_mfma_f32_16x16x32_bf16 v[98:101], v[176:179], v[200:203], v[98:101]
	v_mfma_f32_16x16x32_bf16 v[90:93], v[184:187], v[200:203], v[90:93]
	v_mfma_f32_16x16x32_bf16 v[82:85], v[176:179], v[208:211], v[82:85]
	v_mfma_f32_16x16x32_bf16 v[74:77], v[184:187], v[208:211], v[74:77]
	v_mfma_f32_16x16x32_bf16 v[70:73], v[176:179], v[216:219], v[70:73]
	v_mfma_f32_16x16x32_bf16 v[66:69], v[184:187], v[216:219], v[66:69]
	s_barrier
	s_add_i32 s55, s45, s36
	v_lshl_add_u64 v[146:147], s[28:29], 0, v[134:135]
	s_mov_b32 m0, s55
	ds_read_b128 v[188:191], v154 offset:16384
	ds_read_b128 v[192:195], v154 offset:17408
	ds_read_b128 v[196:199], v154 offset:18432
	ds_read_b128 v[200:203], v154 offset:19456
	ds_read_b128 v[204:207], v154 offset:20480
	ds_read_b128 v[208:211], v154 offset:21504
	ds_read_b128 v[212:215], v154 offset:22528
	ds_read_b128 v[216:219], v154 offset:23552
	global_load_lds_dwordx4 v[146:147], off
	s_add_i32 m0, s55, 0x2000
	s_add_u32 s56, s28, 0x80000
	v_lshl_add_u64 v[220:221], s[28:29], 0, v[130:131]
	s_addc_u32 s57, s29, 0
	s_add_i32 s55, s46, s36
	global_load_lds_dwordx4 v[220:221], off
	v_lshl_add_u64 v[222:223], s[56:57], 0, v[134:135]
	s_mov_b32 m0, s55
	v_lshl_add_u64 v[224:225], s[30:31], 0, v[132:133]
	global_load_lds_dwordx4 v[222:223], off
	v_lshl_add_u64 v[222:223], s[56:57], 0, v[130:131]
	s_add_i32 m0, s55, 0x2000
	s_nop 0
	global_load_lds_dwordx4 v[222:223], off
	v_lshl_add_u64 v[222:223], s[30:31], 0, v[136:137]
	s_mov_b32 m0, s25
	s_nop 0
	global_load_lds_dwordx4 v[222:223], off
	s_mov_b32 m0, s38
	s_nop 0
	global_load_lds_dwordx4 v[224:225], off
	s_waitcnt vmcnt(8)
	s_waitcnt lgkmcnt(0)
	s_barrier
; #define PG8_STAGE(bufoff, gbase, voff) do { _Pragma("unroll") for (int _i = 0; _i < 2; ++_i) \
;         __builtin_amdgcn_global_load_lds((const unsigned*)((const char*)(gbase) + (voff)[_i]), (PG8_LAS unsigned*)(lds + (bufoff) + ldsw + _i * 8192), 16, 0, 0); } while (0)
; #define PG8_LDA(dst, b, h) do { _Pragma("unroll") for (int m = 0; m < 4; ++m) _Pragma("unroll") for (int k = 0; k < 2; ++k) dst[m][k] = *(const PG8_LAS bf16x8*)(lds + PG8_SA(b, h) + aoff + m * 2048 + k * 1024); } while (0)
; #define PG8_LDB(dst, b, h) do { _Pragma("unroll") for (int n = 0; n < 2; ++n) _Pragma("unroll") for (int k = 0; k < 2; ++k) dst[n][k] = *(const PG8_LAS bf16x8*)(lds + PG8_SB(b, h) + boff + n * 2048 + k * 1024); } while (0)
; #define PG8_MMA(ai, bj, At, Bt) do { __builtin_amdgcn_s_setprio(1); _Pragma("unroll") for (int m = 0; m < 4; ++m) _Pragma("unroll") for (int n = 0; n < 2; ++n) _Pragma("unroll") for (int k = 0; k < 2; ++k) \
;         acc[ai][bj][m][n] = __builtin_amdgcn_mfma_f32_16x16x32_bf16(Bt[n][k], At[m][k], acc[ai][bj][m][n], 0, 0, 0); __builtin_amdgcn_s_setprio(0); } while (0)
; #define PG8_WAIT_V(n) asm volatile("s_waitcnt vmcnt(" #n ")" ::: "memory")
; #define PG8_WAIT_L(n) asm volatile("s_waitcnt lgkmcnt(" #n ")" ::: "memory")
; #define PG8_BAR __builtin_amdgcn_s_barrier()
; #define PG8_SCHED __builtin_amdgcn_sched_barrier(0)
; template <class Epi, class Sched, bool ALIGN_EPI = false, bool SP2 = false>
; __device__ __forceinline__ void gemm_phase(PG8_LAS unsigned char* lds, const Gemm g, const Sched& S, const Epi& E) {
;     ...
;             PG8_WAIT_V(8); PG8_WAIT_L(0); PG8_BAR; PG8_MMA(1, 0, At, B0); PG8_MMA(1, 1, At, B1); PG8_BAR; PG8_SCHED;
;             PG8_LDB(B0, 1, 0); PG8_LDB(B1, 1, 1); PG8_SCHED; PG8_LDA(At, 1, 0); PG8_STAGE(PG8_SA(0, 1), a2 + hstep, voffA);
;             PG8_WAIT_V(8); PG8_WAIT_L(0); PG8_BAR; PG8_MMA(0, 0, At, B0); PG8_MMA(0, 1, At, B1); PG8_BAR; PG8_SCHED;
;             PG8_LDA(At, 1, 1); PG8_STAGE(PG8_SB(1, 0), b3, voffB); PG8_STAGE(PG8_SB(1, 1), b3 + hstep, voffB); PG8_STAGE(PG8_SA(1, 0), a3, voffA);
	s_waitcnt lgkmcnt(0)
	v_mfma_f32_16x16x32_bf16 v[62:65], v[156:159], v[188:191], v[62:65]
	v_mfma_f32_16x16x32_bf16 v[58:61], v[164:167], v[188:191], v[58:61]
	v_mfma_f32_16x16x32_bf16 v[54:57], v[156:159], v[196:199], v[54:57]
	v_mfma_f32_16x16x32_bf16 v[46:49], v[164:167], v[196:199], v[46:49]
	v_mfma_f32_16x16x32_bf16 v[38:41], v[156:159], v[204:207], v[38:41]
	v_mfma_f32_16x16x32_bf16 v[30:33], v[164:167], v[204:207], v[30:33]
	v_mfma_f32_16x16x32_bf16 v[22:25], v[156:159], v[212:215], v[22:25]
	v_mfma_f32_16x16x32_bf16 v[14:17], v[164:167], v[212:215], v[14:17]
	v_mfma_f32_16x16x32_bf16 v[62:65], v[160:163], v[192:195], v[62:65]
	v_mfma_f32_16x16x32_bf16 v[58:61], v[168:171], v[192:195], v[58:61]
	v_mfma_f32_16x16x32_bf16 v[54:57], v[160:163], v[200:203], v[54:57]
	v_mfma_f32_16x16x32_bf16 v[46:49], v[168:171], v[200:203], v[46:49]
	v_mfma_f32_16x16x32_bf16 v[38:41], v[160:163], v[208:211], v[38:41]
	v_mfma_f32_16x16x32_bf16 v[30:33], v[168:171], v[208:211], v[30:33]
	v_mfma_f32_16x16x32_bf16 v[22:25], v[160:163], v[216:219], v[22:25]
	v_mfma_f32_16x16x32_bf16 v[14:17], v[168:171], v[216:219], v[14:17]
	v_mfma_f32_16x16x32_bf16 v[50:53], v[172:175], v[188:191], v[50:53]
	v_mfma_f32_16x16x32_bf16 v[42:45], v[180:183], v[188:191], v[42:45]
	v_mfma_f32_16x16x32_bf16 v[34:37], v[172:175], v[196:199], v[34:37]
	v_mfma_f32_16x16x32_bf16 v[26:29], v[180:183], v[196:199], v[26:29]
	v_mfma_f32_16x16x32_bf16 v[18:21], v[172:175], v[204:207], v[18:21]
	v_mfma_f32_16x16x32_bf16 v[10:13], v[180:183], v[204:207], v[10:13]
	v_mfma_f32_16x16x32_bf16 v[6:9], v[172:175], v[212:215], v[6:9]
	v_mfma_f32_16x16x32_bf16 v[2:5], v[180:183], v[212:215], v[2:5]
	v_mfma_f32_16x16x32_bf16 v[50:53], v[176:179], v[192:195], v[50:53]
	v_mfma_f32_16x16x32_bf16 v[42:45], v[184:187], v[192:195], v[42:45]
	v_mfma_f32_16x16x32_bf16 v[34:37], v[176:179], v[200:203], v[34:37]
	v_mfma_f32_16x16x32_bf16 v[26:29], v[184:187], v[200:203], v[26:29]
	v_mfma_f32_16x16x32_bf16 v[18:21], v[176:179], v[208:211], v[18:21]
	v_mfma_f32_16x16x32_bf16 v[10:13], v[184:187], v[208:211], v[10:13]
	v_mfma_f32_16x16x32_bf16 v[6:9], v[176:179], v[216:219], v[6:9]
	v_mfma_f32_16x16x32_bf16 v[2:5], v[184:187], v[216:219], v[2:5]
	s_barrier
	s_add_i32 s55, 0, 0x18000
	v_add_u32_e32 v155, s55, v150
	s_add_i32 s56, 0, 0x1c000
	ds_read_b128 v[156:159], v155
	ds_read_b128 v[160:163], v155 offset:1024
	ds_read_b128 v[164:167], v155 offset:2048
	ds_read_b128 v[168:171], v155 offset:3072
	v_add_u32_e32 v155, s56, v150
	ds_read_b128 v[172:175], v155
	ds_read_b128 v[176:179], v155 offset:1024
	ds_read_b128 v[180:183], v155 offset:2048
	ds_read_b128 v[184:187], v155 offset:3072
	s_add_u32 s30, s30, 0x80000
	s_addc_u32 s31, s31, 0
	s_mov_b32 m0, s39
	v_lshl_add_u64 v[226:227], s[30:31], 0, v[136:137]
	ds_read_b128 v[188:191], v154 offset:32768
	ds_read_b128 v[192:195], v154 offset:33792
	ds_read_b128 v[196:199], v154 offset:34816
	ds_read_b128 v[200:203], v154 offset:35840
	ds_read_b128 v[204:207], v154 offset:36864
	ds_read_b128 v[208:211], v154 offset:37888
	ds_read_b128 v[212:215], v154 offset:38912
	ds_read_b128 v[216:219], v154 offset:39936
	global_load_lds_dwordx4 v[226:227], off
	v_lshl_add_u64 v[226:227], s[30:31], 0, v[132:133]
	s_mov_b32 m0, s40
	s_nop 0
	global_load_lds_dwordx4 v[226:227], off
	s_waitcnt vmcnt(8)
	s_waitcnt lgkmcnt(0)
	s_barrier
	s_waitcnt lgkmcnt(0)
	v_mfma_f32_16x16x32_bf16 v[126:129], v[156:159], v[188:191], v[126:129]
	v_mfma_f32_16x16x32_bf16 v[122:125], v[164:167], v[188:191], v[122:125]
	v_mfma_f32_16x16x32_bf16 v[118:121], v[156:159], v[196:199], v[118:121]
	v_mfma_f32_16x16x32_bf16 v[110:113], v[164:167], v[196:199], v[110:113]
	v_mfma_f32_16x16x32_bf16 v[102:105], v[156:159], v[204:207], v[102:105]
	v_mfma_f32_16x16x32_bf16 v[94:97], v[164:167], v[204:207], v[94:97]
	v_mfma_f32_16x16x32_bf16 v[86:89], v[156:159], v[212:215], v[86:89]
	v_mfma_f32_16x16x32_bf16 v[78:81], v[164:167], v[212:215], v[78:81]
	v_mfma_f32_16x16x32_bf16 v[126:129], v[160:163], v[192:195], v[126:129]
	v_mfma_f32_16x16x32_bf16 v[122:125], v[168:171], v[192:195], v[122:125]
	v_mfma_f32_16x16x32_bf16 v[118:121], v[160:163], v[200:203], v[118:121]
	v_mfma_f32_16x16x32_bf16 v[110:113], v[168:171], v[200:203], v[110:113]
	v_mfma_f32_16x16x32_bf16 v[102:105], v[160:163], v[208:211], v[102:105]
	v_mfma_f32_16x16x32_bf16 v[94:97], v[168:171], v[208:211], v[94:97]
	v_mfma_f32_16x16x32_bf16 v[86:89], v[160:163], v[216:219], v[86:89]
	v_mfma_f32_16x16x32_bf16 v[78:81], v[168:171], v[216:219], v[78:81]
	v_mfma_f32_16x16x32_bf16 v[114:117], v[172:175], v[188:191], v[114:117]
	v_mfma_f32_16x16x32_bf16 v[106:109], v[180:183], v[188:191], v[106:109]
	v_mfma_f32_16x16x32_bf16 v[98:101], v[172:175], v[196:199], v[98:101]
	v_mfma_f32_16x16x32_bf16 v[90:93], v[180:183], v[196:199], v[90:93]
	v_mfma_f32_16x16x32_bf16 v[82:85], v[172:175], v[204:207], v[82:85]
	v_mfma_f32_16x16x32_bf16 v[74:77], v[180:183], v[204:207], v[74:77]
	v_mfma_f32_16x16x32_bf16 v[70:73], v[172:175], v[212:215], v[70:73]
	v_mfma_f32_16x16x32_bf16 v[66:69], v[180:183], v[212:215], v[66:69]
	v_mfma_f32_16x16x32_bf16 v[114:117], v[176:179], v[192:195], v[114:117]
	v_mfma_f32_16x16x32_bf16 v[106:109], v[184:187], v[192:195], v[106:109]
	v_mfma_f32_16x16x32_bf16 v[98:101], v[176:179], v[200:203], v[98:101]
	v_mfma_f32_16x16x32_bf16 v[90:93], v[184:187], v[200:203], v[90:93]
	v_mfma_f32_16x16x32_bf16 v[82:85], v[176:179], v[208:211], v[82:85]
	v_mfma_f32_16x16x32_bf16 v[74:77], v[184:187], v[208:211], v[74:77]
	v_mfma_f32_16x16x32_bf16 v[70:73], v[176:179], v[216:219], v[70:73]
	v_mfma_f32_16x16x32_bf16 v[66:69], v[184:187], v[216:219], v[66:69]
	s_barrier
; #define PG8_STAGE(bufoff, gbase, voff) do { _Pragma("unroll") for (int _i = 0; _i < 2; ++_i) \
;         __builtin_amdgcn_global_load_lds((const unsigned*)((const char*)(gbase) + (voff)[_i]), (PG8_LAS unsigned*)(lds + (bufoff) + ldsw + _i * 8192), 16, 0, 0); } while (0)
; #define PG8_LDA(dst, b, h) do { _Pragma("unroll") for (int m = 0; m < 4; ++m) _Pragma("unroll") for (int k = 0; k < 2; ++k) dst[m][k] = *(const PG8_LAS bf16x8*)(lds + PG8_SA(b, h) + aoff + m * 2048 + k * 1024); } while (0)
; #define PG8_MMA(ai, bj, At, Bt) do { __builtin_amdgcn_s_setprio(1); _Pragma("unroll") for (int m = 0; m < 4; ++m) _Pragma("unroll") for (int n = 0; n < 2; ++n) _Pragma("unroll") for (int k = 0; k < 2; ++k) \
;         acc[ai][bj][m][n] = __builtin_amdgcn_mfma_f32_16x16x32_bf16(Bt[n][k], At[m][k], acc[ai][bj][m][n], 0, 0, 0); __builtin_amdgcn_s_setprio(0); } while (0)
; #define PG8_WAIT_V(n) asm volatile("s_waitcnt vmcnt(" #n ")" ::: "memory")
; #define PG8_WAIT_L(n) asm volatile("s_waitcnt lgkmcnt(" #n ")" ::: "memory")
; #define PG8_BAR __builtin_amdgcn_s_barrier()
; #define PG8_SCHED __builtin_amdgcn_sched_barrier(0)
; template <class Epi, class Sched, bool ALIGN_EPI = false, bool SP2 = false>
; __device__ __forceinline__ void gemm_phase(PG8_LAS unsigned char* lds, const Gemm g, const Sched& S, const Epi& E) {
;     ...
;             PG8_LDA(At, 1, 1); PG8_STAGE(PG8_SB(1, 0), b3, voffB); PG8_STAGE(PG8_SB(1, 1), b3 + hstep, voffB); PG8_STAGE(PG8_SA(1, 0), a3, voffA);
;             PG8_WAIT_V(8); PG8_WAIT_L(0); PG8_BAR; PG8_MMA(1, 0, At, B0); PG8_MMA(1, 1, At, B1); PG8_BAR; PG8_SCHED;
	s_add_i32 s30, s55, s36
	v_lshl_add_u64 v[146:147], v[146:147], 0, s[12:13]
	s_mov_b32 m0, s30
	ds_read_b128 v[188:191], v154 offset:49152
	ds_read_b128 v[192:195], v154 offset:50176
	ds_read_b128 v[196:199], v154 offset:51200
	ds_read_b128 v[200:203], v154 offset:52224
	ds_read_b128 v[204:207], v154 offset:53248
	ds_read_b128 v[208:211], v154 offset:54272
	ds_read_b128 v[212:215], v154 offset:55296
	ds_read_b128 v[216:219], v154 offset:56320
	global_load_lds_dwordx4 v[146:147], off
	s_add_i32 m0, s30, 0x2000
	s_add_u32 s28, s28, 0x80080
	v_lshl_add_u64 v[146:147], v[220:221], 0, s[12:13]
	s_addc_u32 s29, s29, 0
	s_add_i32 s30, s56, s36
	global_load_lds_dwordx4 v[146:147], off
	v_lshl_add_u64 v[146:147], s[28:29], 0, v[134:135]
	s_mov_b32 m0, s30
	s_nop 0
	global_load_lds_dwordx4 v[146:147], off
	v_lshl_add_u64 v[146:147], s[28:29], 0, v[130:131]
	s_add_i32 m0, s30, 0x2000
	s_nop 0
	global_load_lds_dwordx4 v[146:147], off
	v_lshl_add_u64 v[146:147], v[222:223], 0, s[12:13]
	s_mov_b32 m0, s43
	s_nop 0
	global_load_lds_dwordx4 v[146:147], off
	v_lshl_add_u64 v[146:147], v[224:225], 0, s[12:13]
	s_mov_b32 m0, s44
	s_nop 0
	global_load_lds_dwordx4 v[146:147], off
	s_waitcnt vmcnt(8)
	s_waitcnt lgkmcnt(0)
	s_barrier
	s_waitcnt lgkmcnt(0)
	v_mfma_f32_16x16x32_bf16 v[62:65], v[156:159], v[188:191], v[62:65]
	v_mfma_f32_16x16x32_bf16 v[58:61], v[164:167], v[188:191], v[58:61]
	v_mfma_f32_16x16x32_bf16 v[54:57], v[156:159], v[196:199], v[54:57]
	v_mfma_f32_16x16x32_bf16 v[46:49], v[164:167], v[196:199], v[46:49]
	v_mfma_f32_16x16x32_bf16 v[38:41], v[156:159], v[204:207], v[38:41]
	v_mfma_f32_16x16x32_bf16 v[30:33], v[164:167], v[204:207], v[30:33]
	v_mfma_f32_16x16x32_bf16 v[22:25], v[156:159], v[212:215], v[22:25]
	v_mfma_f32_16x16x32_bf16 v[14:17], v[164:167], v[212:215], v[14:17]
	v_mfma_f32_16x16x32_bf16 v[62:65], v[160:163], v[192:195], v[62:65]
	v_mfma_f32_16x16x32_bf16 v[58:61], v[168:171], v[192:195], v[58:61]
	v_mfma_f32_16x16x32_bf16 v[54:57], v[160:163], v[200:203], v[54:57]
	v_mfma_f32_16x16x32_bf16 v[46:49], v[168:171], v[200:203], v[46:49]
	v_mfma_f32_16x16x32_bf16 v[38:41], v[160:163], v[208:211], v[38:41]
	v_mfma_f32_16x16x32_bf16 v[30:33], v[168:171], v[208:211], v[30:33]
	v_mfma_f32_16x16x32_bf16 v[22:25], v[160:163], v[216:219], v[22:25]
	v_mfma_f32_16x16x32_bf16 v[14:17], v[168:171], v[216:219], v[14:17]
	v_mfma_f32_16x16x32_bf16 v[50:53], v[172:175], v[188:191], v[50:53]
	v_mfma_f32_16x16x32_bf16 v[42:45], v[180:183], v[188:191], v[42:45]
	v_mfma_f32_16x16x32_bf16 v[34:37], v[172:175], v[196:199], v[34:37]
	v_mfma_f32_16x16x32_bf16 v[26:29], v[180:183], v[196:199], v[26:29]
	v_mfma_f32_16x16x32_bf16 v[18:21], v[172:175], v[204:207], v[18:21]
	v_mfma_f32_16x16x32_bf16 v[10:13], v[180:183], v[204:207], v[10:13]
	v_mfma_f32_16x16x32_bf16 v[6:9], v[172:175], v[212:215], v[6:9]
	v_mfma_f32_16x16x32_bf16 v[2:5], v[180:183], v[212:215], v[2:5]
	v_mfma_f32_16x16x32_bf16 v[50:53], v[176:179], v[192:195], v[50:53]
	v_mfma_f32_16x16x32_bf16 v[42:45], v[184:187], v[192:195], v[42:45]
	v_mfma_f32_16x16x32_bf16 v[34:37], v[176:179], v[200:203], v[34:37]
	v_mfma_f32_16x16x32_bf16 v[26:29], v[184:187], v[200:203], v[26:29]
	v_mfma_f32_16x16x32_bf16 v[18:21], v[176:179], v[208:211], v[18:21]
	v_mfma_f32_16x16x32_bf16 v[10:13], v[184:187], v[208:211], v[10:13]
	v_mfma_f32_16x16x32_bf16 v[6:9], v[176:179], v[216:219], v[6:9]
	v_mfma_f32_16x16x32_bf16 v[2:5], v[184:187], v[216:219], v[2:5]
	s_barrier
	s_add_i32 s54, s54, 2
	s_add_u32 s26, s26, 0x100
	s_addc_u32 s27, s27, 0
	s_add_u32 s52, s52, 0x100
	s_addc_u32 s53, s53, 0
	s_cmp_gt_u32 s54, 29
	s_cbranch_scc0 .LBB0_1393
	s_and_b64 vcc, exec, s[14:15]
	s_cbranch_vccz .LBB0_1396
	s_barrier

; #define PG8_STAGE(bufoff, gbase, voff) do { _Pragma("unroll") for (int _i = 0; _i < 2; ++_i) \
;         __builtin_amdgcn_global_load_lds((const unsigned*)((const char*)(gbase) + (voff)[_i]), (PG8_LAS unsigned*)(lds + (bufoff) + ldsw + _i * 8192), 16, 0, 0); } while (0)
; #define PG8_LDA(dst, b, h) do { _Pragma("unroll") for (int m = 0; m < 4; ++m) _Pragma("unroll") for (int k = 0; k < 2; ++k) dst[m][k] = *(const PG8_LAS bf16x8*)(lds + PG8_SA(b, h) + aoff + m * 2048 + k * 1024); } while (0)
; #define PG8_LDB(dst, b, h) do { _Pragma("unroll") for (int n = 0; n < 2; ++n) _Pragma("unroll") for (int k = 0; k < 2; ++k) dst[n][k] = *(const PG8_LAS bf16x8*)(lds + PG8_SB(b, h) + boff + n * 2048 + k * 1024); } while (0)
; #define PG8_WAIT_V(n) asm volatile("s_waitcnt vmcnt(" #n ")" ::: "memory")
; #define PG8_WAIT_L(n) asm volatile("s_waitcnt lgkmcnt(" #n ")" ::: "memory")
; #define PG8_BAR __builtin_amdgcn_s_barrier()
; template <class Epi, class Sched, bool ALIGN_EPI = false, bool SP2 = false>
; __device__ __forceinline__ void gemm_phase(PG8_LAS unsigned char* lds, const Gemm g, const Sched& S, const Epi& E) {
;     ...
;         const char* nA = has_next ? (const char*)g.A + (size_t)nxt.pm * tstep + (size_t)nxt.kt0 * kstep : cA; const char* nB = has_next ? (const char*)g.Bt + (size_t)nxt.pn * tstep + (size_t)nxt.kt0 * kstep : cB;
;         for (int t = 0; t < nt; t += 2) {
;             if constexpr (Epi::MIDHOOK) { if (t == (nt >> 1)) E.mid(acc, cur, wr, wc, fr, fq); }
;             const bool last = (t == nt - 2);
;             const char* a1 = cA + (size_t)(t + 1) * kstep;
;             const char* a2 = last ? nA : cA + (size_t)(t + 2) * kstep; const char* b2 = last ? nB : cB + (size_t)(t + 2) * kstep;
;             const char* a3 = a2 + kstep; const char* b3 = b2 + kstep;
;             if (last && has_next) S.a_ready(nxt);
;             if constexpr (SP2) {
;             PG8_LDB(B0, 0, 0); PG8_LDB(B1, 0, 1); PG8_SCHED; PG8_LDA(At, 0, 0); PG8_STAGE(PG8_SA(1, 1), a1 + hstep, voffA);
;             PG8_WAIT_V(8); PG8_WAIT_L(0); PG8_BAR; PG8_MMA(0, 0, At, B0); PG8_MMA(0, 1, At, B1); PG8_BAR; PG8_SCHED;
;             PG8_LDA(At, 0, 1); PG8_STAGE(PG8_SB(0, 0), b2, voffB); PG8_STAGE(PG8_SB(0, 1), b2 + hstep, voffB); PG8_STAGE(PG8_SA(0, 0), a2, voffA);
;             PG8_WAIT_V(8); PG8_WAIT_L(0); PG8_BAR; PG8_MMA(1, 0, At, B0); PG8_MMA(1, 1, At, B1); PG8_BAR; PG8_SCHED;
.LBB0_1428:
	s_add_u32 s21, s16, s7
	s_addc_u32 s23, s17, 0
	s_add_u32 s38, s21, 0x100
	s_addc_u32 s39, s23, 0
	s_and_b64 s[36:37], s[30:31], exec
	s_cselect_b32 s39, s25, s39
	s_cselect_b32 s38, s24, s38
	s_add_u32 s7, s14, s7
	s_addc_u32 s36, s15, 0
	s_add_u32 s7, s7, 0x100
	s_addc_u32 s36, s36, 0
	s_and_b64 s[30:31], s[30:31], exec
	s_cselect_b32 s41, s27, s36
	s_cselect_b32 s40, s26, s7
	s_add_u32 s46, s21, 0x80080
	s_addc_u32 s47, s23, 0
	s_add_i32 s70, s60, s44
	ds_read_b128 v[140:143], v137
	ds_read_b128 v[144:147], v137 offset:1024
	ds_read_b128 v[148:151], v137 offset:2048
	ds_read_b128 v[152:155], v137 offset:3072
	ds_read_b128 v[156:159], v138
	ds_read_b128 v[160:163], v138 offset:1024
	ds_read_b128 v[164:167], v138 offset:2048
	ds_read_b128 v[168:171], v138 offset:3072
	s_add_i32 m0, s51, 0xc000
	s_add_i32 s71, s51, 0xe000
	s_add_i32 s67, s70, 0x2000
	s_add_u32 s42, s40, 0x80000
	s_addc_u32 s43, s41, 0
	s_add_i32 s69, s61, s44
	s_add_i32 s68, s69, 0x2000
	s_add_i32 s66, 0, 0x18000
	s_add_i32 s65, 0, 0x1c000
	s_add_u32 s36, s38, 0x80000
	s_addc_u32 s37, s39, 0
	s_add_i32 s64, s66, s44
	s_add_i32 s21, s64, 0x2000
	s_add_u32 s30, s40, 0x80080
	s_addc_u32 s31, s41, 0
	s_add_i32 s23, s65, s44
	s_add_i32 s7, s23, 0x2000
	v_lshl_add_u64 v[204:205], s[46:47], 0, v[132:133]
	ds_read_b128 v[172:175], v139
	ds_read_b128 v[176:179], v139 offset:1024
	ds_read_b128 v[180:183], v139 offset:2048
	ds_read_b128 v[184:187], v139 offset:3072
	ds_read_b128 v[188:191], v139 offset:4096
	ds_read_b128 v[192:195], v139 offset:5120
	ds_read_b128 v[196:199], v139 offset:6144
	ds_read_b128 v[200:203], v139 offset:7168
	global_load_lds_dwordx4 v[204:205], off
	v_lshl_add_u64 v[204:205], s[46:47], 0, v[130:131]
	s_mov_b32 m0, s71
	s_nop 0
	global_load_lds_dwordx4 v[204:205], off
	s_waitcnt vmcnt(8)
	s_waitcnt lgkmcnt(0)
	s_barrier
	s_waitcnt lgkmcnt(0)
	v_mfma_f32_16x16x32_bf16 v[126:129], v[140:143], v[172:175], v[126:129]
	v_mfma_f32_16x16x32_bf16 v[122:125], v[148:151], v[172:175], v[122:125]
	v_mfma_f32_16x16x32_bf16 v[118:121], v[140:143], v[180:183], v[118:121]
	v_mfma_f32_16x16x32_bf16 v[114:117], v[148:151], v[180:183], v[114:117]
	v_mfma_f32_16x16x32_bf16 v[106:109], v[140:143], v[188:191], v[106:109]
	v_mfma_f32_16x16x32_bf16 v[98:101], v[148:151], v[188:191], v[98:101]
	v_mfma_f32_16x16x32_bf16 v[90:93], v[140:143], v[196:199], v[90:93]
	v_mfma_f32_16x16x32_bf16 v[82:85], v[148:151], v[196:199], v[82:85]
	v_mfma_f32_16x16x32_bf16 v[126:129], v[144:147], v[176:179], v[126:129]
	v_mfma_f32_16x16x32_bf16 v[122:125], v[152:155], v[176:179], v[122:125]
	v_mfma_f32_16x16x32_bf16 v[118:121], v[144:147], v[184:187], v[118:121]
	v_mfma_f32_16x16x32_bf16 v[114:117], v[152:155], v[184:187], v[114:117]
	v_mfma_f32_16x16x32_bf16 v[106:109], v[144:147], v[192:195], v[106:109]
	v_mfma_f32_16x16x32_bf16 v[98:101], v[152:155], v[192:195], v[98:101]
	v_mfma_f32_16x16x32_bf16 v[90:93], v[144:147], v[200:203], v[90:93]
	v_mfma_f32_16x16x32_bf16 v[82:85], v[152:155], v[200:203], v[82:85]
	v_mfma_f32_16x16x32_bf16 v[110:113], v[156:159], v[172:175], v[110:113]
	v_mfma_f32_16x16x32_bf16 v[102:105], v[164:167], v[172:175], v[102:105]
	v_mfma_f32_16x16x32_bf16 v[94:97], v[156:159], v[180:183], v[94:97]
	v_mfma_f32_16x16x32_bf16 v[86:89], v[164:167], v[180:183], v[86:89]
	v_mfma_f32_16x16x32_bf16 v[78:81], v[156:159], v[188:191], v[78:81]
	v_mfma_f32_16x16x32_bf16 v[74:77], v[164:167], v[188:191], v[74:77]
	v_mfma_f32_16x16x32_bf16 v[70:73], v[156:159], v[196:199], v[70:73]
	v_mfma_f32_16x16x32_bf16 v[66:69], v[164:167], v[196:199], v[66:69]
	v_mfma_f32_16x16x32_bf16 v[110:113], v[160:163], v[176:179], v[110:113]
	v_mfma_f32_16x16x32_bf16 v[102:105], v[168:171], v[176:179], v[102:105]
	v_mfma_f32_16x16x32_bf16 v[94:97], v[160:163], v[184:187], v[94:97]
	v_mfma_f32_16x16x32_bf16 v[86:89], v[168:171], v[184:187], v[86:89]
	v_mfma_f32_16x16x32_bf16 v[78:81], v[160:163], v[192:195], v[78:81]
	v_mfma_f32_16x16x32_bf16 v[74:77], v[168:171], v[192:195], v[74:77]
	v_mfma_f32_16x16x32_bf16 v[70:73], v[160:163], v[200:203], v[70:73]
	v_mfma_f32_16x16x32_bf16 v[66:69], v[168:171], v[200:203], v[66:69]
	s_barrier
	s_mov_b32 m0, s70
	v_lshl_add_u64 v[204:205], s[40:41], 0, v[132:133]
	ds_read_b128 v[172:175], v139 offset:16384
	ds_read_b128 v[176:179], v139 offset:17408
	ds_read_b128 v[180:183], v139 offset:18432
	ds_read_b128 v[184:187], v139 offset:19456
	ds_read_b128 v[188:191], v139 offset:20480
	ds_read_b128 v[192:195], v139 offset:21504
	ds_read_b128 v[196:199], v139 offset:22528
	ds_read_b128 v[200:203], v139 offset:23552
	global_load_lds_dwordx4 v[204:205], off
	v_lshl_add_u64 v[206:207], s[40:41], 0, v[130:131]
	s_mov_b32 m0, s67
	v_lshl_add_u64 v[208:209], s[42:43], 0, v[132:133]
	global_load_lds_dwordx4 v[206:207], off
	s_mov_b32 m0, s69
	v_lshl_add_u64 v[210:211], s[38:39], 0, v[130:131]
	global_load_lds_dwordx4 v[208:209], off
	v_lshl_add_u64 v[208:209], s[42:43], 0, v[130:131]
	s_mov_b32 m0, s68
	s_nop 0
	global_load_lds_dwordx4 v[208:209], off
	v_lshl_add_u64 v[208:209], s[38:39], 0, v[132:133]
	s_mov_b32 m0, s51
	s_nop 0
	global_load_lds_dwordx4 v[208:209], off
	s_mov_b32 m0, s52
	s_nop 0
	global_load_lds_dwordx4 v[210:211], off
	s_waitcnt vmcnt(8)
	s_waitcnt lgkmcnt(0)
	s_barrier
; #define PG8_STAGE(bufoff, gbase, voff) do { _Pragma("unroll") for (int _i = 0; _i < 2; ++_i) \
;         __builtin_amdgcn_global_load_lds((const unsigned*)((const char*)(gbase) + (voff)[_i]), (PG8_LAS unsigned*)(lds + (bufoff) + ldsw + _i * 8192), 16, 0, 0); } while (0)
; #define PG8_LDA(dst, b, h) do { _Pragma("unroll") for (int m = 0; m < 4; ++m) _Pragma("unroll") for (int k = 0; k < 2; ++k) dst[m][k] = *(const PG8_LAS bf16x8*)(lds + PG8_SA(b, h) + aoff + m * 2048 + k * 1024); } while (0)
; #define PG8_LDB(dst, b, h) do { _Pragma("unroll") for (int n = 0; n < 2; ++n) _Pragma("unroll") for (int k = 0; k < 2; ++k) dst[n][k] = *(const PG8_LAS bf16x8*)(lds + PG8_SB(b, h) + boff + n * 2048 + k * 1024); } while (0)
; #define PG8_MMA(ai, bj, At, Bt) do { __builtin_amdgcn_s_setprio(1); _Pragma("unroll") for (int m = 0; m < 4; ++m) _Pragma("unroll") for (int n = 0; n < 2; ++n) _Pragma("unroll") for (int k = 0; k < 2; ++k) \
;         acc[ai][bj][m][n] = __builtin_amdgcn_mfma_f32_16x16x32_bf16(Bt[n][k], At[m][k], acc[ai][bj][m][n], 0, 0, 0); __builtin_amdgcn_s_setprio(0); } while (0)
; #define PG8_WAIT_V(n) asm volatile("s_waitcnt vmcnt(" #n ")" ::: "memory")
; template <class Epi, class Sched, bool ALIGN_EPI = false, bool SP2 = false>
; __device__ __forceinline__ void gemm_phase(PG8_LAS unsigned char* lds, const Gemm g, const Sched& S, const Epi& E) {
;     ...
;             PG8_LDB(B0, 0, 0); PG8_LDB(B1, 0, 1); PG8_SCHED; PG8_LDA(At, 0, 0); PG8_STAGE(PG8_SA(1, 1), a1 + hstep, voffA);
;             PG8_WAIT_V(8); PG8_WAIT_L(0); PG8_BAR; PG8_MMA(0, 0, At, B0); PG8_MMA(0, 1, At, B1); PG8_BAR; PG8_SCHED;
;             PG8_LDA(At, 0, 1); PG8_STAGE(PG8_SB(0, 0), b2, voffB); PG8_STAGE(PG8_SB(0, 1), b2 + hstep, voffB); PG8_STAGE(PG8_SA(0, 0), a2, voffA);
;             PG8_WAIT_V(8); PG8_WAIT_L(0); PG8_BAR; PG8_MMA(1, 0, At, B0); PG8_MMA(1, 1, At, B1); PG8_BAR; PG8_SCHED;
;             PG8_LDB(B0, 1, 0); PG8_LDB(B1, 1, 1); PG8_SCHED; PG8_LDA(At, 1, 0); PG8_STAGE(PG8_SA(0, 1), a2 + hstep, voffA);
;             PG8_WAIT_V(8); PG8_WAIT_L(0); PG8_BAR; PG8_MMA(0, 0, At, B0); PG8_MMA(0, 1, At, B1); PG8_BAR; PG8_SCHED;
;             PG8_LDA(At, 1, 1); PG8_STAGE(PG8_SB(1, 0), b3, voffB); PG8_STAGE(PG8_SB(1, 1), b3 + hstep, voffB); PG8_STAGE(PG8_SA(1, 0), a3, voffA);
;             PG8_WAIT_V(8); PG8_WAIT_L(0); PG8_BAR; PG8_MMA(1, 0, At, B0); PG8_MMA(1, 1, At, B1); PG8_BAR; PG8_SCHED;
	s_waitcnt lgkmcnt(0)
	v_mfma_f32_16x16x32_bf16 v[62:65], v[140:143], v[172:175], v[62:65]
	v_mfma_f32_16x16x32_bf16 v[58:61], v[148:151], v[172:175], v[58:61]
	v_mfma_f32_16x16x32_bf16 v[54:57], v[140:143], v[180:183], v[54:57]
	v_mfma_f32_16x16x32_bf16 v[50:53], v[148:151], v[180:183], v[50:53]
	v_mfma_f32_16x16x32_bf16 v[38:41], v[140:143], v[188:191], v[38:41]
	v_mfma_f32_16x16x32_bf16 v[34:37], v[148:151], v[188:191], v[34:37]
	v_mfma_f32_16x16x32_bf16 v[22:25], v[140:143], v[196:199], v[22:25]
	v_mfma_f32_16x16x32_bf16 v[18:21], v[148:151], v[196:199], v[18:21]
	v_mfma_f32_16x16x32_bf16 v[62:65], v[144:147], v[176:179], v[62:65]
	v_mfma_f32_16x16x32_bf16 v[58:61], v[152:155], v[176:179], v[58:61]
	v_mfma_f32_16x16x32_bf16 v[54:57], v[144:147], v[184:187], v[54:57]
	v_mfma_f32_16x16x32_bf16 v[50:53], v[152:155], v[184:187], v[50:53]
	v_mfma_f32_16x16x32_bf16 v[38:41], v[144:147], v[192:195], v[38:41]
	v_mfma_f32_16x16x32_bf16 v[34:37], v[152:155], v[192:195], v[34:37]
	v_mfma_f32_16x16x32_bf16 v[22:25], v[144:147], v[200:203], v[22:25]
	v_mfma_f32_16x16x32_bf16 v[18:21], v[152:155], v[200:203], v[18:21]
	v_mfma_f32_16x16x32_bf16 v[46:49], v[156:159], v[172:175], v[46:49]
	v_mfma_f32_16x16x32_bf16 v[42:45], v[164:167], v[172:175], v[42:45]
	v_mfma_f32_16x16x32_bf16 v[30:33], v[156:159], v[180:183], v[30:33]
	v_mfma_f32_16x16x32_bf16 v[26:29], v[164:167], v[180:183], v[26:29]
	v_mfma_f32_16x16x32_bf16 v[14:17], v[156:159], v[188:191], v[14:17]
	v_mfma_f32_16x16x32_bf16 v[10:13], v[164:167], v[188:191], v[10:13]
	v_mfma_f32_16x16x32_bf16 v[6:9], v[156:159], v[196:199], v[6:9]
	v_mfma_f32_16x16x32_bf16 v[2:5], v[164:167], v[196:199], v[2:5]
	v_mfma_f32_16x16x32_bf16 v[46:49], v[160:163], v[176:179], v[46:49]
	v_mfma_f32_16x16x32_bf16 v[42:45], v[168:171], v[176:179], v[42:45]
	v_mfma_f32_16x16x32_bf16 v[30:33], v[160:163], v[184:187], v[30:33]
	v_mfma_f32_16x16x32_bf16 v[26:29], v[168:171], v[184:187], v[26:29]
	v_mfma_f32_16x16x32_bf16 v[14:17], v[160:163], v[192:195], v[14:17]
	v_mfma_f32_16x16x32_bf16 v[10:13], v[168:171], v[192:195], v[10:13]
	v_mfma_f32_16x16x32_bf16 v[6:9], v[160:163], v[200:203], v[6:9]
	v_mfma_f32_16x16x32_bf16 v[2:5], v[168:171], v[200:203], v[2:5]
	s_barrier
	v_add_u32_e32 v152, s66, v134
	v_add_u32_e32 v168, s65, v134
	ds_read_b128 v[140:143], v152
	ds_read_b128 v[144:147], v152 offset:1024
	ds_read_b128 v[148:151], v152 offset:2048
	ds_read_b128 v[152:155], v152 offset:3072
	ds_read_b128 v[156:159], v168
	ds_read_b128 v[160:163], v168 offset:1024
	ds_read_b128 v[164:167], v168 offset:2048
	ds_read_b128 v[168:171], v168 offset:3072
	s_mov_b32 m0, s53
	v_lshl_add_u64 v[212:213], s[36:37], 0, v[132:133]
	ds_read_b128 v[172:175], v139 offset:32768
	ds_read_b128 v[176:179], v139 offset:33792
	ds_read_b128 v[180:183], v139 offset:34816
	ds_read_b128 v[184:187], v139 offset:35840
	ds_read_b128 v[188:191], v139 offset:36864
	ds_read_b128 v[192:195], v139 offset:37888
	ds_read_b128 v[196:199], v139 offset:38912
	ds_read_b128 v[200:203], v139 offset:39936
	global_load_lds_dwordx4 v[212:213], off
	v_lshl_add_u64 v[212:213], s[36:37], 0, v[130:131]
	s_mov_b32 m0, s54
	s_nop 0
	global_load_lds_dwordx4 v[212:213], off
	s_waitcnt vmcnt(8)
	s_waitcnt lgkmcnt(0)
	s_barrier
	s_waitcnt lgkmcnt(0)
	v_mfma_f32_16x16x32_bf16 v[126:129], v[140:143], v[172:175], v[126:129]
	v_mfma_f32_16x16x32_bf16 v[122:125], v[148:151], v[172:175], v[122:125]
	v_mfma_f32_16x16x32_bf16 v[118:121], v[140:143], v[180:183], v[118:121]
	v_mfma_f32_16x16x32_bf16 v[114:117], v[148:151], v[180:183], v[114:117]
	v_mfma_f32_16x16x32_bf16 v[106:109], v[140:143], v[188:191], v[106:109]
	v_mfma_f32_16x16x32_bf16 v[98:101], v[148:151], v[188:191], v[98:101]
	v_mfma_f32_16x16x32_bf16 v[90:93], v[140:143], v[196:199], v[90:93]
	v_mfma_f32_16x16x32_bf16 v[82:85], v[148:151], v[196:199], v[82:85]
	v_mfma_f32_16x16x32_bf16 v[126:129], v[144:147], v[176:179], v[126:129]
	v_mfma_f32_16x16x32_bf16 v[122:125], v[152:155], v[176:179], v[122:125]
	v_mfma_f32_16x16x32_bf16 v[118:121], v[144:147], v[184:187], v[118:121]
	v_mfma_f32_16x16x32_bf16 v[114:117], v[152:155], v[184:187], v[114:117]
	v_mfma_f32_16x16x32_bf16 v[106:109], v[144:147], v[192:195], v[106:109]
	v_mfma_f32_16x16x32_bf16 v[98:101], v[152:155], v[192:195], v[98:101]
	v_mfma_f32_16x16x32_bf16 v[90:93], v[144:147], v[200:203], v[90:93]
	v_mfma_f32_16x16x32_bf16 v[82:85], v[152:155], v[200:203], v[82:85]
	v_mfma_f32_16x16x32_bf16 v[110:113], v[156:159], v[172:175], v[110:113]
	v_mfma_f32_16x16x32_bf16 v[102:105], v[164:167], v[172:175], v[102:105]
	v_mfma_f32_16x16x32_bf16 v[94:97], v[156:159], v[180:183], v[94:97]
	v_mfma_f32_16x16x32_bf16 v[86:89], v[164:167], v[180:183], v[86:89]
	v_mfma_f32_16x16x32_bf16 v[78:81], v[156:159], v[188:191], v[78:81]
	v_mfma_f32_16x16x32_bf16 v[74:77], v[164:167], v[188:191], v[74:77]
	v_mfma_f32_16x16x32_bf16 v[70:73], v[156:159], v[196:199], v[70:73]
	v_mfma_f32_16x16x32_bf16 v[66:69], v[164:167], v[196:199], v[66:69]
	v_mfma_f32_16x16x32_bf16 v[110:113], v[160:163], v[176:179], v[110:113]
	v_mfma_f32_16x16x32_bf16 v[102:105], v[168:171], v[176:179], v[102:105]
	v_mfma_f32_16x16x32_bf16 v[94:97], v[160:163], v[184:187], v[94:97]
	v_mfma_f32_16x16x32_bf16 v[86:89], v[168:171], v[184:187], v[86:89]
	v_mfma_f32_16x16x32_bf16 v[78:81], v[160:163], v[192:195], v[78:81]
	v_mfma_f32_16x16x32_bf16 v[74:77], v[168:171], v[192:195], v[74:77]
	v_mfma_f32_16x16x32_bf16 v[70:73], v[160:163], v[200:203], v[70:73]
	v_mfma_f32_16x16x32_bf16 v[66:69], v[168:171], v[200:203], v[66:69]
	s_barrier
; #define PG8_STAGE(bufoff, gbase, voff) do { _Pragma("unroll") for (int _i = 0; _i < 2; ++_i) \
;         __builtin_amdgcn_global_load_lds((const unsigned*)((const char*)(gbase) + (voff)[_i]), (PG8_LAS unsigned*)(lds + (bufoff) + ldsw + _i * 8192), 16, 0, 0); } while (0)
; #define PG8_LDA(dst, b, h) do { _Pragma("unroll") for (int m = 0; m < 4; ++m) _Pragma("unroll") for (int k = 0; k < 2; ++k) dst[m][k] = *(const PG8_LAS bf16x8*)(lds + PG8_SA(b, h) + aoff + m * 2048 + k * 1024); } while (0)
; #define PG8_LDB(dst, b, h) do { _Pragma("unroll") for (int n = 0; n < 2; ++n) _Pragma("unroll") for (int k = 0; k < 2; ++k) dst[n][k] = *(const PG8_LAS bf16x8*)(lds + PG8_SB(b, h) + boff + n * 2048 + k * 1024); } while (0)
; #define PG8_MMA(ai, bj, At, Bt) do { __builtin_amdgcn_s_setprio(1); _Pragma("unroll") for (int m = 0; m < 4; ++m) _Pragma("unroll") for (int n = 0; n < 2; ++n) _Pragma("unroll") for (int k = 0; k < 2; ++k) \
;         acc[ai][bj][m][n] = __builtin_amdgcn_mfma_f32_16x16x32_bf16(Bt[n][k], At[m][k], acc[ai][bj][m][n], 0, 0, 0); __builtin_amdgcn_s_setprio(0); } while (0)
; #define PG8_WAIT_V(n) asm volatile("s_waitcnt vmcnt(" #n ")" ::: "memory")
; template <class Epi, class Sched, bool ALIGN_EPI = false, bool SP2 = false>
; __device__ __forceinline__ void gemm_phase(PG8_LAS unsigned char* lds, const Gemm g, const Sched& S, const Epi& E) {
;     ...
;             PG8_LDB(B0, 0, 0); PG8_LDB(B1, 0, 1); PG8_SCHED; PG8_LDA(At, 0, 0); PG8_STAGE(PG8_SA(1, 1), a1 + hstep, voffA);
;             PG8_WAIT_V(8); PG8_WAIT_L(0); PG8_BAR; PG8_MMA(0, 0, At, B0); PG8_MMA(0, 1, At, B1); PG8_BAR; PG8_SCHED;
;             PG8_LDA(At, 0, 1); PG8_STAGE(PG8_SB(0, 0), b2, voffB); PG8_STAGE(PG8_SB(0, 1), b2 + hstep, voffB); PG8_STAGE(PG8_SA(0, 0), a2, voffA);
;             PG8_WAIT_V(8); PG8_WAIT_L(0); PG8_BAR; PG8_MMA(1, 0, At, B0); PG8_MMA(1, 1, At, B1); PG8_BAR; PG8_SCHED;
;             PG8_LDB(B0, 1, 0); PG8_LDB(B1, 1, 1); PG8_SCHED; PG8_LDA(At, 1, 0); PG8_STAGE(PG8_SA(0, 1), a2 + hstep, voffA);
;             PG8_WAIT_V(8); PG8_WAIT_L(0); PG8_BAR; PG8_MMA(0, 0, At, B0); PG8_MMA(0, 1, At, B1); PG8_BAR; PG8_SCHED;
;             PG8_LDA(At, 1, 1); PG8_STAGE(PG8_SB(1, 0), b3, voffB); PG8_STAGE(PG8_SB(1, 1), b3 + hstep, voffB); PG8_STAGE(PG8_SA(1, 0), a3, voffA);
;             PG8_WAIT_V(8); PG8_WAIT_L(0); PG8_BAR; PG8_MMA(1, 0, At, B0); PG8_MMA(1, 1, At, B1); PG8_BAR; PG8_SCHED;
	s_mov_b32 m0, s64
	v_lshl_add_u64 v[204:205], v[204:205], 0, s[12:13]
	ds_read_b128 v[172:175], v139 offset:49152
	ds_read_b128 v[176:179], v139 offset:50176
	ds_read_b128 v[180:183], v139 offset:51200
	ds_read_b128 v[184:187], v139 offset:52224
	ds_read_b128 v[188:191], v139 offset:53248
	ds_read_b128 v[192:195], v139 offset:54272
	ds_read_b128 v[196:199], v139 offset:55296
	ds_read_b128 v[200:203], v139 offset:56320
	global_load_lds_dwordx4 v[204:205], off
	v_lshl_add_u64 v[204:205], v[206:207], 0, s[12:13]
	s_mov_b32 m0, s21
	s_nop 0
	global_load_lds_dwordx4 v[204:205], off
	v_lshl_add_u64 v[204:205], s[30:31], 0, v[132:133]
	s_mov_b32 m0, s23
	s_nop 0
	global_load_lds_dwordx4 v[204:205], off
	v_lshl_add_u64 v[204:205], s[30:31], 0, v[130:131]
	s_mov_b32 m0, s7
	s_nop 0
	global_load_lds_dwordx4 v[204:205], off
	v_lshl_add_u64 v[204:205], v[208:209], 0, s[12:13]
	s_mov_b32 m0, s57
	s_nop 0
	global_load_lds_dwordx4 v[204:205], off
	v_lshl_add_u64 v[204:205], v[210:211], 0, s[12:13]
	s_mov_b32 m0, s58
	s_nop 0
	global_load_lds_dwordx4 v[204:205], off
	s_waitcnt vmcnt(8)
	s_waitcnt lgkmcnt(0)
	s_barrier
	s_waitcnt lgkmcnt(0)
	v_mfma_f32_16x16x32_bf16 v[62:65], v[140:143], v[172:175], v[62:65]
	v_mfma_f32_16x16x32_bf16 v[58:61], v[148:151], v[172:175], v[58:61]
	v_mfma_f32_16x16x32_bf16 v[54:57], v[140:143], v[180:183], v[54:57]
	v_mfma_f32_16x16x32_bf16 v[50:53], v[148:151], v[180:183], v[50:53]
	v_mfma_f32_16x16x32_bf16 v[38:41], v[140:143], v[188:191], v[38:41]
	v_mfma_f32_16x16x32_bf16 v[34:37], v[148:151], v[188:191], v[34:37]
	v_mfma_f32_16x16x32_bf16 v[22:25], v[140:143], v[196:199], v[22:25]
	v_mfma_f32_16x16x32_bf16 v[18:21], v[148:151], v[196:199], v[18:21]
	v_mfma_f32_16x16x32_bf16 v[62:65], v[144:147], v[176:179], v[62:65]
	v_mfma_f32_16x16x32_bf16 v[58:61], v[152:155], v[176:179], v[58:61]
	v_mfma_f32_16x16x32_bf16 v[54:57], v[144:147], v[184:187], v[54:57]
	v_mfma_f32_16x16x32_bf16 v[50:53], v[152:155], v[184:187], v[50:53]
	v_mfma_f32_16x16x32_bf16 v[38:41], v[144:147], v[192:195], v[38:41]
	v_mfma_f32_16x16x32_bf16 v[34:37], v[152:155], v[192:195], v[34:37]
	v_mfma_f32_16x16x32_bf16 v[22:25], v[144:147], v[200:203], v[22:25]
	v_mfma_f32_16x16x32_bf16 v[18:21], v[152:155], v[200:203], v[18:21]
	v_mfma_f32_16x16x32_bf16 v[46:49], v[156:159], v[172:175], v[46:49]
	v_mfma_f32_16x16x32_bf16 v[42:45], v[164:167], v[172:175], v[42:45]
	v_mfma_f32_16x16x32_bf16 v[30:33], v[156:159], v[180:183], v[30:33]
	v_mfma_f32_16x16x32_bf16 v[26:29], v[164:167], v[180:183], v[26:29]
	v_mfma_f32_16x16x32_bf16 v[14:17], v[156:159], v[188:191], v[14:17]
	v_mfma_f32_16x16x32_bf16 v[10:13], v[164:167], v[188:191], v[10:13]
	v_mfma_f32_16x16x32_bf16 v[6:9], v[156:159], v[196:199], v[6:9]
	v_mfma_f32_16x16x32_bf16 v[2:5], v[164:167], v[196:199], v[2:5]
	v_mfma_f32_16x16x32_bf16 v[46:49], v[160:163], v[176:179], v[46:49]
	v_mfma_f32_16x16x32_bf16 v[42:45], v[168:171], v[176:179], v[42:45]
	v_mfma_f32_16x16x32_bf16 v[30:33], v[160:163], v[184:187], v[30:33]
	v_mfma_f32_16x16x32_bf16 v[26:29], v[168:171], v[184:187], v[26:29]
	v_mfma_f32_16x16x32_bf16 v[14:17], v[160:163], v[192:195], v[14:17]
	v_mfma_f32_16x16x32_bf16 v[10:13], v[168:171], v[192:195], v[10:13]
	v_mfma_f32_16x16x32_bf16 v[6:9], v[160:163], v[200:203], v[6:9]
	v_mfma_f32_16x16x32_bf16 v[2:5], v[168:171], v[200:203], v[2:5]
	s_barrier
	s_movk_i32 s7, 0x100
	s_andn2_b64 vcc, exec, s[28:29]
	s_mov_b64 s[30:31], -1
	s_mov_b64 s[28:29], 0
	s_cbranch_vccz .LBB0_1428
	s_and_b64 vcc, exec, s[18:19]
	s_cbranch_vccz .LBB0_1431
	s_barrier

; #define PG8_STAGE(bufoff, gbase, voff) do { _Pragma("unroll") for (int _i = 0; _i < 2; ++_i) \
;         __builtin_amdgcn_global_load_lds((const unsigned*)((const char*)(gbase) + (voff)[_i]), (PG8_LAS unsigned*)(lds + (bufoff) + ldsw + _i * 8192), 16, 0, 0); } while (0)
; #define PG8_LDA(dst, b, h) do { _Pragma("unroll") for (int m = 0; m < 4; ++m) _Pragma("unroll") for (int k = 0; k < 2; ++k) dst[m][k] = *(const PG8_LAS bf16x8*)(lds + PG8_SA(b, h) + aoff + m * 2048 + k * 1024); } while (0)
; #define PG8_LDB(dst, b, h) do { _Pragma("unroll") for (int n = 0; n < 2; ++n) _Pragma("unroll") for (int k = 0; k < 2; ++k) dst[n][k] = *(const PG8_LAS bf16x8*)(lds + PG8_SB(b, h) + boff + n * 2048 + k * 1024); } while (0)
; #define PG8_MMA(ai, bj, At, Bt) do { __builtin_amdgcn_s_setprio(1); _Pragma("unroll") for (int m = 0; m < 4; ++m) _Pragma("unroll") for (int n = 0; n < 2; ++n) _Pragma("unroll") for (int k = 0; k < 2; ++k) \
;         acc[ai][bj][m][n] = __builtin_amdgcn_mfma_f32_16x16x32_bf16(Bt[n][k], At[m][k], acc[ai][bj][m][n], 0, 0, 0); __builtin_amdgcn_s_setprio(0); } while (0)
; #define PG8_WAIT_V(n) asm volatile("s_waitcnt vmcnt(" #n ")" ::: "memory")
; template <class Epi, class Sched, bool ALIGN_EPI = false, bool SP2 = false>
; __device__ __forceinline__ void gemm_phase(PG8_LAS unsigned char* lds, const Gemm g, const Sched& S, const Epi& E) {
;     ...
;             PG8_LDB(B0, 0, 0); PG8_LDB(B1, 0, 1); PG8_SCHED; PG8_LDA(At, 0, 0); PG8_STAGE(PG8_SA(1, 1), a1 + hstep, voffA);
;             PG8_WAIT_V(8); PG8_WAIT_L(0); PG8_BAR; PG8_MMA(0, 0, At, B0); PG8_MMA(0, 1, At, B1); PG8_BAR; PG8_SCHED;
;             PG8_LDA(At, 0, 1); PG8_STAGE(PG8_SB(0, 0), b2, voffB); PG8_STAGE(PG8_SB(0, 1), b2 + hstep, voffB); PG8_STAGE(PG8_SA(0, 0), a2, voffA);
;             PG8_WAIT_V(8); PG8_WAIT_L(0); PG8_BAR; PG8_MMA(1, 0, At, B0); PG8_MMA(1, 1, At, B1); PG8_BAR; PG8_SCHED;
;             PG8_LDB(B0, 1, 0); PG8_LDB(B1, 1, 1); PG8_SCHED; PG8_LDA(At, 1, 0); PG8_STAGE(PG8_SA(0, 1), a2 + hstep, voffA);
;             PG8_WAIT_V(8); PG8_WAIT_L(0); PG8_BAR; PG8_MMA(0, 0, At, B0); PG8_MMA(0, 1, At, B1); PG8_BAR; PG8_SCHED;
;             PG8_LDA(At, 1, 1); PG8_STAGE(PG8_SB(1, 0), b3, voffB); PG8_STAGE(PG8_SB(1, 1), b3 + hstep, voffB); PG8_STAGE(PG8_SA(1, 0), a3, voffA);
;             PG8_WAIT_V(8); PG8_WAIT_L(0); PG8_BAR; PG8_MMA(1, 0, At, B0); PG8_MMA(1, 1, At, B1); PG8_BAR; PG8_SCHED;
.LBB0_1551:
	ds_read_b128 v[146:149], v153
	ds_read_b128 v[156:159], v153 offset:1024
	ds_read_b128 v[160:163], v153 offset:2048
	ds_read_b128 v[164:167], v153 offset:3072
	ds_read_b128 v[168:171], v154
	ds_read_b128 v[172:175], v154 offset:1024
	ds_read_b128 v[176:179], v154 offset:2048
	ds_read_b128 v[180:183], v154 offset:3072
	s_add_u32 s26, s24, 0xfff80080
	s_addc_u32 s27, s25, -1
	s_cmp_eq_u32 s52, 28
	s_cselect_b32 s29, s17, s27
	s_cselect_b32 s28, s48, s26
	s_cselect_b32 s27, s15, s51
	s_cselect_b32 s26, s49, s50
	v_lshl_add_u64 v[216:217], s[24:25], 0, v[138:139]
	s_add_i32 m0, s23, 0xc000
	ds_read_b128 v[184:187], v155
	ds_read_b128 v[188:191], v155 offset:1024
	ds_read_b128 v[192:195], v155 offset:2048
	ds_read_b128 v[196:199], v155 offset:3072
	ds_read_b128 v[200:203], v155 offset:4096
	ds_read_b128 v[204:207], v155 offset:5120
	ds_read_b128 v[208:211], v155 offset:6144
	ds_read_b128 v[212:215], v155 offset:7168
	global_load_lds_dwordx4 v[216:217], off
	v_lshl_add_u64 v[216:217], s[24:25], 0, v[140:141]
	s_add_i32 m0, s23, 0xe000
	s_nop 0
	global_load_lds_dwordx4 v[216:217], off
	s_waitcnt vmcnt(8)
	s_waitcnt lgkmcnt(0)
	s_barrier
	s_waitcnt lgkmcnt(0)
	v_mfma_f32_16x16x32_bf16 v[126:129], v[146:149], v[184:187], v[126:129]
	v_mfma_f32_16x16x32_bf16 v[122:125], v[160:163], v[184:187], v[122:125]
	v_mfma_f32_16x16x32_bf16 v[110:113], v[146:149], v[192:195], v[110:113]
	v_mfma_f32_16x16x32_bf16 v[106:109], v[160:163], v[192:195], v[106:109]
	v_mfma_f32_16x16x32_bf16 v[94:97], v[146:149], v[200:203], v[94:97]
	v_mfma_f32_16x16x32_bf16 v[90:93], v[160:163], v[200:203], v[90:93]
	v_mfma_f32_16x16x32_bf16 v[78:81], v[146:149], v[208:211], v[78:81]
	v_mfma_f32_16x16x32_bf16 v[74:77], v[160:163], v[208:211], v[74:77]
	v_mfma_f32_16x16x32_bf16 v[126:129], v[156:159], v[188:191], v[126:129]
	v_mfma_f32_16x16x32_bf16 v[122:125], v[164:167], v[188:191], v[122:125]
	v_mfma_f32_16x16x32_bf16 v[110:113], v[156:159], v[196:199], v[110:113]
	v_mfma_f32_16x16x32_bf16 v[106:109], v[164:167], v[196:199], v[106:109]
	v_mfma_f32_16x16x32_bf16 v[94:97], v[156:159], v[204:207], v[94:97]
	v_mfma_f32_16x16x32_bf16 v[90:93], v[164:167], v[204:207], v[90:93]
	v_mfma_f32_16x16x32_bf16 v[78:81], v[156:159], v[212:215], v[78:81]
	v_mfma_f32_16x16x32_bf16 v[74:77], v[164:167], v[212:215], v[74:77]
	v_mfma_f32_16x16x32_bf16 v[118:121], v[168:171], v[184:187], v[118:121]
	v_mfma_f32_16x16x32_bf16 v[114:117], v[176:179], v[184:187], v[114:117]
	v_mfma_f32_16x16x32_bf16 v[102:105], v[168:171], v[192:195], v[102:105]
	v_mfma_f32_16x16x32_bf16 v[98:101], v[176:179], v[192:195], v[98:101]
	v_mfma_f32_16x16x32_bf16 v[86:89], v[168:171], v[200:203], v[86:89]
	v_mfma_f32_16x16x32_bf16 v[82:85], v[176:179], v[200:203], v[82:85]
	v_mfma_f32_16x16x32_bf16 v[70:73], v[168:171], v[208:211], v[70:73]
	v_mfma_f32_16x16x32_bf16 v[66:69], v[176:179], v[208:211], v[66:69]
	v_mfma_f32_16x16x32_bf16 v[118:121], v[172:175], v[188:191], v[118:121]
	v_mfma_f32_16x16x32_bf16 v[114:117], v[180:183], v[188:191], v[114:117]
	v_mfma_f32_16x16x32_bf16 v[102:105], v[172:175], v[196:199], v[102:105]
	v_mfma_f32_16x16x32_bf16 v[98:101], v[180:183], v[196:199], v[98:101]
	v_mfma_f32_16x16x32_bf16 v[86:89], v[172:175], v[204:207], v[86:89]
	v_mfma_f32_16x16x32_bf16 v[82:85], v[180:183], v[204:207], v[82:85]
	v_mfma_f32_16x16x32_bf16 v[70:73], v[172:175], v[212:215], v[70:73]
	v_mfma_f32_16x16x32_bf16 v[66:69], v[180:183], v[212:215], v[66:69]
	s_barrier
	s_add_i32 s53, s44, s31
	v_lshl_add_u64 v[216:217], s[26:27], 0, v[134:135]
	s_mov_b32 m0, s53
	ds_read_b128 v[184:187], v155 offset:16384
	ds_read_b128 v[188:191], v155 offset:17408
	ds_read_b128 v[192:195], v155 offset:18432
	ds_read_b128 v[196:199], v155 offset:19456
	ds_read_b128 v[200:203], v155 offset:20480
	ds_read_b128 v[204:207], v155 offset:21504
	ds_read_b128 v[208:211], v155 offset:22528
	ds_read_b128 v[212:215], v155 offset:23552
	global_load_lds_dwordx4 v[216:217], off
	s_add_i32 m0, s53, 0x2000
	s_add_u32 s54, s26, 0x80000
	v_lshl_add_u64 v[218:219], s[26:27], 0, v[130:131]
	s_addc_u32 s55, s27, 0
	s_add_i32 s53, s45, s31
	global_load_lds_dwordx4 v[218:219], off
	v_lshl_add_u64 v[220:221], s[54:55], 0, v[134:135]
	s_mov_b32 m0, s53
	v_lshl_add_u64 v[222:223], s[28:29], 0, v[132:133]
	global_load_lds_dwordx4 v[220:221], off
	v_lshl_add_u64 v[220:221], s[54:55], 0, v[130:131]
	s_add_i32 m0, s53, 0x2000
	s_nop 0
	global_load_lds_dwordx4 v[220:221], off
	v_lshl_add_u64 v[220:221], s[28:29], 0, v[136:137]
	s_mov_b32 m0, s23
	s_nop 0
	global_load_lds_dwordx4 v[220:221], off
	s_mov_b32 m0, s37
	s_nop 0
	global_load_lds_dwordx4 v[222:223], off
	s_waitcnt vmcnt(8)
	s_waitcnt lgkmcnt(0)
	s_barrier
; #define PG8_STAGE(bufoff, gbase, voff) do { _Pragma("unroll") for (int _i = 0; _i < 2; ++_i) \
;         __builtin_amdgcn_global_load_lds((const unsigned*)((const char*)(gbase) + (voff)[_i]), (PG8_LAS unsigned*)(lds + (bufoff) + ldsw + _i * 8192), 16, 0, 0); } while (0)
; #define PG8_LDA(dst, b, h) do { _Pragma("unroll") for (int m = 0; m < 4; ++m) _Pragma("unroll") for (int k = 0; k < 2; ++k) dst[m][k] = *(const PG8_LAS bf16x8*)(lds + PG8_SA(b, h) + aoff + m * 2048 + k * 1024); } while (0)
; #define PG8_LDB(dst, b, h) do { _Pragma("unroll") for (int n = 0; n < 2; ++n) _Pragma("unroll") for (int k = 0; k < 2; ++k) dst[n][k] = *(const PG8_LAS bf16x8*)(lds + PG8_SB(b, h) + boff + n * 2048 + k * 1024); } while (0)
; #define PG8_MMA(ai, bj, At, Bt) do { __builtin_amdgcn_s_setprio(1); _Pragma("unroll") for (int m = 0; m < 4; ++m) _Pragma("unroll") for (int n = 0; n < 2; ++n) _Pragma("unroll") for (int k = 0; k < 2; ++k) \
;         acc[ai][bj][m][n] = __builtin_amdgcn_mfma_f32_16x16x32_bf16(Bt[n][k], At[m][k], acc[ai][bj][m][n], 0, 0, 0); __builtin_amdgcn_s_setprio(0); } while (0)
; #define PG8_WAIT_V(n) asm volatile("s_waitcnt vmcnt(" #n ")" ::: "memory")
; template <class Epi, class Sched, bool ALIGN_EPI = false, bool SP2 = false>
; __device__ __forceinline__ void gemm_phase(PG8_LAS unsigned char* lds, const Gemm g, const Sched& S, const Epi& E) {
;     ...
;             PG8_LDB(B0, 0, 0); PG8_LDB(B1, 0, 1); PG8_SCHED; PG8_LDA(At, 0, 0); PG8_STAGE(PG8_SA(1, 1), a1 + hstep, voffA);
;             PG8_WAIT_V(8); PG8_WAIT_L(0); PG8_BAR; PG8_MMA(0, 0, At, B0); PG8_MMA(0, 1, At, B1); PG8_BAR; PG8_SCHED;
;             PG8_LDA(At, 0, 1); PG8_STAGE(PG8_SB(0, 0), b2, voffB); PG8_STAGE(PG8_SB(0, 1), b2 + hstep, voffB); PG8_STAGE(PG8_SA(0, 0), a2, voffA);
;             PG8_WAIT_V(8); PG8_WAIT_L(0); PG8_BAR; PG8_MMA(1, 0, At, B0); PG8_MMA(1, 1, At, B1); PG8_BAR; PG8_SCHED;
;             PG8_LDB(B0, 1, 0); PG8_LDB(B1, 1, 1); PG8_SCHED; PG8_LDA(At, 1, 0); PG8_STAGE(PG8_SA(0, 1), a2 + hstep, voffA);
;             PG8_WAIT_V(8); PG8_WAIT_L(0); PG8_BAR; PG8_MMA(0, 0, At, B0); PG8_MMA(0, 1, At, B1); PG8_BAR; PG8_SCHED;
;             PG8_LDA(At, 1, 1); PG8_STAGE(PG8_SB(1, 0), b3, voffB); PG8_STAGE(PG8_SB(1, 1), b3 + hstep, voffB); PG8_STAGE(PG8_SA(1, 0), a3, voffA);
;             PG8_WAIT_V(8); PG8_WAIT_L(0); PG8_BAR; PG8_MMA(1, 0, At, B0); PG8_MMA(1, 1, At, B1); PG8_BAR; PG8_SCHED;
	s_waitcnt lgkmcnt(0)
	v_mfma_f32_16x16x32_bf16 v[62:65], v[146:149], v[184:187], v[62:65]
	v_mfma_f32_16x16x32_bf16 v[58:61], v[160:163], v[184:187], v[58:61]
	v_mfma_f32_16x16x32_bf16 v[46:49], v[146:149], v[192:195], v[46:49]
	v_mfma_f32_16x16x32_bf16 v[42:45], v[160:163], v[192:195], v[42:45]
	v_mfma_f32_16x16x32_bf16 v[30:33], v[146:149], v[200:203], v[30:33]
	v_mfma_f32_16x16x32_bf16 v[26:29], v[160:163], v[200:203], v[26:29]
	v_mfma_f32_16x16x32_bf16 v[14:17], v[146:149], v[208:211], v[14:17]
	v_mfma_f32_16x16x32_bf16 v[10:13], v[160:163], v[208:211], v[10:13]
	v_mfma_f32_16x16x32_bf16 v[62:65], v[156:159], v[188:191], v[62:65]
	v_mfma_f32_16x16x32_bf16 v[58:61], v[164:167], v[188:191], v[58:61]
	v_mfma_f32_16x16x32_bf16 v[46:49], v[156:159], v[196:199], v[46:49]
	v_mfma_f32_16x16x32_bf16 v[42:45], v[164:167], v[196:199], v[42:45]
	v_mfma_f32_16x16x32_bf16 v[30:33], v[156:159], v[204:207], v[30:33]
	v_mfma_f32_16x16x32_bf16 v[26:29], v[164:167], v[204:207], v[26:29]
	v_mfma_f32_16x16x32_bf16 v[14:17], v[156:159], v[212:215], v[14:17]
	v_mfma_f32_16x16x32_bf16 v[10:13], v[164:167], v[212:215], v[10:13]
	v_mfma_f32_16x16x32_bf16 v[54:57], v[168:171], v[184:187], v[54:57]
	v_mfma_f32_16x16x32_bf16 v[50:53], v[176:179], v[184:187], v[50:53]
	v_mfma_f32_16x16x32_bf16 v[38:41], v[168:171], v[192:195], v[38:41]
	v_mfma_f32_16x16x32_bf16 v[34:37], v[176:179], v[192:195], v[34:37]
	v_mfma_f32_16x16x32_bf16 v[22:25], v[168:171], v[200:203], v[22:25]
	v_mfma_f32_16x16x32_bf16 v[18:21], v[176:179], v[200:203], v[18:21]
	v_mfma_f32_16x16x32_bf16 v[6:9], v[168:171], v[208:211], v[6:9]
	v_mfma_f32_16x16x32_bf16 v[2:5], v[176:179], v[208:211], v[2:5]
	v_mfma_f32_16x16x32_bf16 v[54:57], v[172:175], v[188:191], v[54:57]
	v_mfma_f32_16x16x32_bf16 v[50:53], v[180:183], v[188:191], v[50:53]
	v_mfma_f32_16x16x32_bf16 v[38:41], v[172:175], v[196:199], v[38:41]
	v_mfma_f32_16x16x32_bf16 v[34:37], v[180:183], v[196:199], v[34:37]
	v_mfma_f32_16x16x32_bf16 v[22:25], v[172:175], v[204:207], v[22:25]
	v_mfma_f32_16x16x32_bf16 v[18:21], v[180:183], v[204:207], v[18:21]
	v_mfma_f32_16x16x32_bf16 v[6:9], v[172:175], v[212:215], v[6:9]
	v_mfma_f32_16x16x32_bf16 v[2:5], v[180:183], v[212:215], v[2:5]
	s_barrier
	s_add_i32 s53, 0, 0x18000
	s_add_i32 s54, 0, 0x1c000
	v_add_u32_e32 v164, s53, v151
	v_add_u32_e32 v180, s54, v151
	ds_read_b128 v[146:149], v164
	ds_read_b128 v[156:159], v164 offset:1024
	ds_read_b128 v[160:163], v164 offset:2048
	ds_read_b128 v[164:167], v164 offset:3072
	ds_read_b128 v[168:171], v180
	ds_read_b128 v[172:175], v180 offset:1024
	ds_read_b128 v[176:179], v180 offset:2048
	ds_read_b128 v[180:183], v180 offset:3072
	s_add_u32 s28, s28, 0x80000
	s_addc_u32 s29, s29, 0
	s_mov_b32 m0, s38
	v_lshl_add_u64 v[224:225], s[28:29], 0, v[136:137]
	ds_read_b128 v[184:187], v155 offset:32768
	ds_read_b128 v[188:191], v155 offset:33792
	ds_read_b128 v[192:195], v155 offset:34816
	ds_read_b128 v[196:199], v155 offset:35840
	ds_read_b128 v[200:203], v155 offset:36864
	ds_read_b128 v[204:207], v155 offset:37888
	ds_read_b128 v[208:211], v155 offset:38912
	ds_read_b128 v[212:215], v155 offset:39936
	global_load_lds_dwordx4 v[224:225], off
	v_lshl_add_u64 v[224:225], s[28:29], 0, v[132:133]
	s_mov_b32 m0, s39
	s_nop 0
	global_load_lds_dwordx4 v[224:225], off
	s_waitcnt vmcnt(8)
	s_waitcnt lgkmcnt(0)
	s_barrier
	s_waitcnt lgkmcnt(0)
	v_mfma_f32_16x16x32_bf16 v[126:129], v[146:149], v[184:187], v[126:129]
	v_mfma_f32_16x16x32_bf16 v[122:125], v[160:163], v[184:187], v[122:125]
	v_mfma_f32_16x16x32_bf16 v[110:113], v[146:149], v[192:195], v[110:113]
	v_mfma_f32_16x16x32_bf16 v[106:109], v[160:163], v[192:195], v[106:109]
	v_mfma_f32_16x16x32_bf16 v[94:97], v[146:149], v[200:203], v[94:97]
	v_mfma_f32_16x16x32_bf16 v[90:93], v[160:163], v[200:203], v[90:93]
	v_mfma_f32_16x16x32_bf16 v[78:81], v[146:149], v[208:211], v[78:81]
	v_mfma_f32_16x16x32_bf16 v[74:77], v[160:163], v[208:211], v[74:77]
	v_mfma_f32_16x16x32_bf16 v[126:129], v[156:159], v[188:191], v[126:129]
	v_mfma_f32_16x16x32_bf16 v[122:125], v[164:167], v[188:191], v[122:125]
	v_mfma_f32_16x16x32_bf16 v[110:113], v[156:159], v[196:199], v[110:113]
	v_mfma_f32_16x16x32_bf16 v[106:109], v[164:167], v[196:199], v[106:109]
	v_mfma_f32_16x16x32_bf16 v[94:97], v[156:159], v[204:207], v[94:97]
	v_mfma_f32_16x16x32_bf16 v[90:93], v[164:167], v[204:207], v[90:93]
	v_mfma_f32_16x16x32_bf16 v[78:81], v[156:159], v[212:215], v[78:81]
	v_mfma_f32_16x16x32_bf16 v[74:77], v[164:167], v[212:215], v[74:77]
	v_mfma_f32_16x16x32_bf16 v[118:121], v[168:171], v[184:187], v[118:121]
	v_mfma_f32_16x16x32_bf16 v[114:117], v[176:179], v[184:187], v[114:117]
	v_mfma_f32_16x16x32_bf16 v[102:105], v[168:171], v[192:195], v[102:105]
	v_mfma_f32_16x16x32_bf16 v[98:101], v[176:179], v[192:195], v[98:101]
	v_mfma_f32_16x16x32_bf16 v[86:89], v[168:171], v[200:203], v[86:89]
	v_mfma_f32_16x16x32_bf16 v[82:85], v[176:179], v[200:203], v[82:85]
	v_mfma_f32_16x16x32_bf16 v[70:73], v[168:171], v[208:211], v[70:73]
	v_mfma_f32_16x16x32_bf16 v[66:69], v[176:179], v[208:211], v[66:69]
	v_mfma_f32_16x16x32_bf16 v[118:121], v[172:175], v[188:191], v[118:121]
	v_mfma_f32_16x16x32_bf16 v[114:117], v[180:183], v[188:191], v[114:117]
	v_mfma_f32_16x16x32_bf16 v[102:105], v[172:175], v[196:199], v[102:105]
	v_mfma_f32_16x16x32_bf16 v[98:101], v[180:183], v[196:199], v[98:101]
	v_mfma_f32_16x16x32_bf16 v[86:89], v[172:175], v[204:207], v[86:89]
	v_mfma_f32_16x16x32_bf16 v[82:85], v[180:183], v[204:207], v[82:85]
	v_mfma_f32_16x16x32_bf16 v[70:73], v[172:175], v[212:215], v[70:73]
	v_mfma_f32_16x16x32_bf16 v[66:69], v[180:183], v[212:215], v[66:69]
	s_barrier
; #define PG8_STAGE(bufoff, gbase, voff) do { _Pragma("unroll") for (int _i = 0; _i < 2; ++_i) \
;         __builtin_amdgcn_global_load_lds((const unsigned*)((const char*)(gbase) + (voff)[_i]), (PG8_LAS unsigned*)(lds + (bufoff) + ldsw + _i * 8192), 16, 0, 0); } while (0)
; #define PG8_LDA(dst, b, h) do { _Pragma("unroll") for (int m = 0; m < 4; ++m) _Pragma("unroll") for (int k = 0; k < 2; ++k) dst[m][k] = *(const PG8_LAS bf16x8*)(lds + PG8_SA(b, h) + aoff + m * 2048 + k * 1024); } while (0)
; #define PG8_LDB(dst, b, h) do { _Pragma("unroll") for (int n = 0; n < 2; ++n) _Pragma("unroll") for (int k = 0; k < 2; ++k) dst[n][k] = *(const PG8_LAS bf16x8*)(lds + PG8_SB(b, h) + boff + n * 2048 + k * 1024); } while (0)
; #define PG8_MMA(ai, bj, At, Bt) do { __builtin_amdgcn_s_setprio(1); _Pragma("unroll") for (int m = 0; m < 4; ++m) _Pragma("unroll") for (int n = 0; n < 2; ++n) _Pragma("unroll") for (int k = 0; k < 2; ++k) \
;         acc[ai][bj][m][n] = __builtin_amdgcn_mfma_f32_16x16x32_bf16(Bt[n][k], At[m][k], acc[ai][bj][m][n], 0, 0, 0); __builtin_amdgcn_s_setprio(0); } while (0)
; #define PG8_WAIT_V(n) asm volatile("s_waitcnt vmcnt(" #n ")" ::: "memory")
; template <class Epi, class Sched, bool ALIGN_EPI = false, bool SP2 = false>
; __device__ __forceinline__ void gemm_phase(PG8_LAS unsigned char* lds, const Gemm g, const Sched& S, const Epi& E) {
;     ...
;             PG8_LDB(B0, 0, 0); PG8_LDB(B1, 0, 1); PG8_SCHED; PG8_LDA(At, 0, 0); PG8_STAGE(PG8_SA(1, 1), a1 + hstep, voffA);
;             PG8_WAIT_V(8); PG8_WAIT_L(0); PG8_BAR; PG8_MMA(0, 0, At, B0); PG8_MMA(0, 1, At, B1); PG8_BAR; PG8_SCHED;
;             PG8_LDA(At, 0, 1); PG8_STAGE(PG8_SB(0, 0), b2, voffB); PG8_STAGE(PG8_SB(0, 1), b2 + hstep, voffB); PG8_STAGE(PG8_SA(0, 0), a2, voffA);
;             PG8_WAIT_V(8); PG8_WAIT_L(0); PG8_BAR; PG8_MMA(1, 0, At, B0); PG8_MMA(1, 1, At, B1); PG8_BAR; PG8_SCHED;
;             PG8_LDB(B0, 1, 0); PG8_LDB(B1, 1, 1); PG8_SCHED; PG8_LDA(At, 1, 0); PG8_STAGE(PG8_SA(0, 1), a2 + hstep, voffA);
;             PG8_WAIT_V(8); PG8_WAIT_L(0); PG8_BAR; PG8_MMA(0, 0, At, B0); PG8_MMA(0, 1, At, B1); PG8_BAR; PG8_SCHED;
;             PG8_LDA(At, 1, 1); PG8_STAGE(PG8_SB(1, 0), b3, voffB); PG8_STAGE(PG8_SB(1, 1), b3 + hstep, voffB); PG8_STAGE(PG8_SA(1, 0), a3, voffA);
;             PG8_WAIT_V(8); PG8_WAIT_L(0); PG8_BAR; PG8_MMA(1, 0, At, B0); PG8_MMA(1, 1, At, B1); PG8_BAR; PG8_SCHED;
	s_add_i32 s28, s53, s31
	v_lshl_add_u64 v[216:217], v[216:217], 0, s[10:11]
	s_mov_b32 m0, s28
	ds_read_b128 v[184:187], v155 offset:49152
	ds_read_b128 v[188:191], v155 offset:50176
	ds_read_b128 v[192:195], v155 offset:51200
	ds_read_b128 v[196:199], v155 offset:52224
	ds_read_b128 v[200:203], v155 offset:53248
	ds_read_b128 v[204:207], v155 offset:54272
	ds_read_b128 v[208:211], v155 offset:55296
	ds_read_b128 v[212:215], v155 offset:56320
	global_load_lds_dwordx4 v[216:217], off
	s_add_i32 m0, s28, 0x2000
	s_add_u32 s26, s26, 0x80080
	v_lshl_add_u64 v[216:217], v[218:219], 0, s[10:11]
	s_addc_u32 s27, s27, 0
	s_add_i32 s28, s54, s31
	global_load_lds_dwordx4 v[216:217], off
	v_lshl_add_u64 v[216:217], s[26:27], 0, v[134:135]
	s_mov_b32 m0, s28
	s_nop 0
	global_load_lds_dwordx4 v[216:217], off
	v_lshl_add_u64 v[216:217], s[26:27], 0, v[130:131]
	s_add_i32 m0, s28, 0x2000
	s_nop 0
	global_load_lds_dwordx4 v[216:217], off
	v_lshl_add_u64 v[216:217], v[220:221], 0, s[10:11]
	s_mov_b32 m0, s42
	s_nop 0
	global_load_lds_dwordx4 v[216:217], off
	v_lshl_add_u64 v[216:217], v[222:223], 0, s[10:11]
	s_mov_b32 m0, s43
	s_nop 0
	global_load_lds_dwordx4 v[216:217], off
	s_waitcnt vmcnt(8)
	s_waitcnt lgkmcnt(0)
	s_barrier
	s_waitcnt lgkmcnt(0)
	v_mfma_f32_16x16x32_bf16 v[62:65], v[146:149], v[184:187], v[62:65]
	v_mfma_f32_16x16x32_bf16 v[58:61], v[160:163], v[184:187], v[58:61]
	v_mfma_f32_16x16x32_bf16 v[46:49], v[146:149], v[192:195], v[46:49]
	v_mfma_f32_16x16x32_bf16 v[42:45], v[160:163], v[192:195], v[42:45]
	v_mfma_f32_16x16x32_bf16 v[30:33], v[146:149], v[200:203], v[30:33]
	v_mfma_f32_16x16x32_bf16 v[26:29], v[160:163], v[200:203], v[26:29]
	v_mfma_f32_16x16x32_bf16 v[14:17], v[146:149], v[208:211], v[14:17]
	v_mfma_f32_16x16x32_bf16 v[10:13], v[160:163], v[208:211], v[10:13]
	v_mfma_f32_16x16x32_bf16 v[62:65], v[156:159], v[188:191], v[62:65]
	v_mfma_f32_16x16x32_bf16 v[58:61], v[164:167], v[188:191], v[58:61]
	v_mfma_f32_16x16x32_bf16 v[46:49], v[156:159], v[196:199], v[46:49]
	v_mfma_f32_16x16x32_bf16 v[42:45], v[164:167], v[196:199], v[42:45]
	v_mfma_f32_16x16x32_bf16 v[30:33], v[156:159], v[204:207], v[30:33]
	v_mfma_f32_16x16x32_bf16 v[26:29], v[164:167], v[204:207], v[26:29]
	v_mfma_f32_16x16x32_bf16 v[14:17], v[156:159], v[212:215], v[14:17]
	v_mfma_f32_16x16x32_bf16 v[10:13], v[164:167], v[212:215], v[10:13]
	v_mfma_f32_16x16x32_bf16 v[54:57], v[168:171], v[184:187], v[54:57]
	v_mfma_f32_16x16x32_bf16 v[50:53], v[176:179], v[184:187], v[50:53]
	v_mfma_f32_16x16x32_bf16 v[38:41], v[168:171], v[192:195], v[38:41]
	v_mfma_f32_16x16x32_bf16 v[34:37], v[176:179], v[192:195], v[34:37]
	v_mfma_f32_16x16x32_bf16 v[22:25], v[168:171], v[200:203], v[22:25]
	v_mfma_f32_16x16x32_bf16 v[18:21], v[176:179], v[200:203], v[18:21]
	v_mfma_f32_16x16x32_bf16 v[6:9], v[168:171], v[208:211], v[6:9]
	v_mfma_f32_16x16x32_bf16 v[2:5], v[176:179], v[208:211], v[2:5]
	v_mfma_f32_16x16x32_bf16 v[54:57], v[172:175], v[188:191], v[54:57]
	v_mfma_f32_16x16x32_bf16 v[50:53], v[180:183], v[188:191], v[50:53]
	v_mfma_f32_16x16x32_bf16 v[38:41], v[172:175], v[196:199], v[38:41]
	v_mfma_f32_16x16x32_bf16 v[34:37], v[180:183], v[196:199], v[34:37]
	v_mfma_f32_16x16x32_bf16 v[22:25], v[172:175], v[204:207], v[22:25]
	v_mfma_f32_16x16x32_bf16 v[18:21], v[180:183], v[204:207], v[18:21]
	v_mfma_f32_16x16x32_bf16 v[6:9], v[172:175], v[212:215], v[6:9]
	v_mfma_f32_16x16x32_bf16 v[2:5], v[180:183], v[212:215], v[2:5]
	s_barrier
	s_add_i32 s52, s52, 2
	s_add_u32 s24, s24, 0x100
	s_addc_u32 s25, s25, 0
	s_add_u32 s50, s50, 0x100
	s_addc_u32 s51, s51, 0
	s_cmp_gt_u32 s52, 29
	s_cbranch_scc0 .LBB0_1551
	s_and_b64 vcc, exec, s[12:13]
	s_cbranch_vccz .LBB0_1554
	s_barrier

; #define PG8_STAGE(bufoff, gbase, voff) do { _Pragma("unroll") for (int _i = 0; _i < 2; ++_i) \
;         __builtin_amdgcn_global_load_lds((const unsigned*)((const char*)(gbase) + (voff)[_i]), (PG8_LAS unsigned*)(lds + (bufoff) + ldsw + _i * 8192), 16, 0, 0); } while (0)
; #define PG8_LDA(dst, b, h) do { _Pragma("unroll") for (int m = 0; m < 4; ++m) _Pragma("unroll") for (int k = 0; k < 2; ++k) dst[m][k] = *(const PG8_LAS bf16x8*)(lds + PG8_SA(b, h) + aoff + m * 2048 + k * 1024); } while (0)
; #define PG8_LDB(dst, b, h) do { _Pragma("unroll") for (int n = 0; n < 2; ++n) _Pragma("unroll") for (int k = 0; k < 2; ++k) dst[n][k] = *(const PG8_LAS bf16x8*)(lds + PG8_SB(b, h) + boff + n * 2048 + k * 1024); } while (0)
; #define PG8_MMA(ai, bj, At, Bt) do { __builtin_amdgcn_s_setprio(1); _Pragma("unroll") for (int m = 0; m < 4; ++m) _Pragma("unroll") for (int n = 0; n < 2; ++n) _Pragma("unroll") for (int k = 0; k < 2; ++k) \
;         acc[ai][bj][m][n] = __builtin_amdgcn_mfma_f32_16x16x32_bf16(Bt[n][k], At[m][k], acc[ai][bj][m][n], 0, 0, 0); __builtin_amdgcn_s_setprio(0); } while (0)
; #define PG8_WAIT_V(n) asm volatile("s_waitcnt vmcnt(" #n ")" ::: "memory")
; template <class Epi, class Sched, bool ALIGN_EPI = false, bool SP2 = false>
; __device__ __forceinline__ void gemm_phase(PG8_LAS unsigned char* lds, const Gemm g, const Sched& S, const Epi& E) {
;     ...
;             PG8_LDB(B0, 0, 0); PG8_LDB(B1, 0, 1); PG8_SCHED; PG8_LDA(At, 0, 0); PG8_STAGE(PG8_SA(1, 1), a1 + hstep, voffA);
;             PG8_WAIT_V(8); PG8_WAIT_L(0); PG8_BAR; PG8_MMA(0, 0, At, B0); PG8_MMA(0, 1, At, B1); PG8_BAR; PG8_SCHED;
;             PG8_LDA(At, 0, 1); PG8_STAGE(PG8_SB(0, 0), b2, voffB); PG8_STAGE(PG8_SB(0, 1), b2 + hstep, voffB); PG8_STAGE(PG8_SA(0, 0), a2, voffA);
;             PG8_WAIT_V(8); PG8_WAIT_L(0); PG8_BAR; PG8_MMA(1, 0, At, B0); PG8_MMA(1, 1, At, B1); PG8_BAR; PG8_SCHED;
;             PG8_LDB(B0, 1, 0); PG8_LDB(B1, 1, 1); PG8_SCHED; PG8_LDA(At, 1, 0); PG8_STAGE(PG8_SA(0, 1), a2 + hstep, voffA);
;             PG8_WAIT_V(8); PG8_WAIT_L(0); PG8_BAR; PG8_MMA(0, 0, At, B0); PG8_MMA(0, 1, At, B1); PG8_BAR; PG8_SCHED;
;             PG8_LDA(At, 1, 1); PG8_STAGE(PG8_SB(1, 0), b3, voffB); PG8_STAGE(PG8_SB(1, 1), b3 + hstep, voffB); PG8_STAGE(PG8_SA(1, 0), a3, voffA);
;             PG8_WAIT_V(8); PG8_WAIT_L(0); PG8_BAR; PG8_MMA(1, 0, At, B0); PG8_MMA(1, 1, At, B1); PG8_BAR; PG8_SCHED;
.LBB0_1656:
	ds_read_b128 v[154:157], v151
	ds_read_b128 v[158:161], v151 offset:1024
	ds_read_b128 v[162:165], v151 offset:2048
	ds_read_b128 v[166:169], v151 offset:3072
	ds_read_b128 v[170:173], v152
	ds_read_b128 v[174:177], v152 offset:1024
	ds_read_b128 v[178:181], v152 offset:2048
	ds_read_b128 v[182:185], v152 offset:3072
	s_add_u32 s26, s24, 0x100
	s_addc_u32 s27, s25, 0
	s_cmpk_eq_i32 s58, 0x54
	s_cselect_b32 s31, s7, s27
	s_cselect_b32 s30, s6, s26
	s_cselect_b32 s29, s23, s57
	s_cselect_b32 s28, s22, s56
	v_lshl_add_u64 v[146:147], s[24:25], 0, v[138:139]
	s_add_i32 m0, s38, 0xc000
	ds_read_b128 v[186:189], v153
	ds_read_b128 v[190:193], v153 offset:1024
	ds_read_b128 v[194:197], v153 offset:2048
	ds_read_b128 v[198:201], v153 offset:3072
	ds_read_b128 v[202:205], v153 offset:4096
	ds_read_b128 v[206:209], v153 offset:5120
	ds_read_b128 v[210:213], v153 offset:6144
	ds_read_b128 v[214:217], v153 offset:7168
	global_load_lds_dwordx4 v[146:147], off
	v_lshl_add_u64 v[146:147], s[24:25], 0, v[140:141]
	s_add_i32 m0, s38, 0xe000
	s_nop 0
	global_load_lds_dwordx4 v[146:147], off
	s_waitcnt vmcnt(8)
	s_waitcnt lgkmcnt(0)
	s_barrier
	s_waitcnt lgkmcnt(0)
	v_mfma_f32_16x16x32_bf16 v[126:129], v[154:157], v[186:189], v[126:129]
	v_mfma_f32_16x16x32_bf16 v[122:125], v[162:165], v[186:189], v[122:125]
	v_mfma_f32_16x16x32_bf16 v[118:121], v[154:157], v[194:197], v[118:121]
	v_mfma_f32_16x16x32_bf16 v[110:113], v[162:165], v[194:197], v[110:113]
	v_mfma_f32_16x16x32_bf16 v[102:105], v[154:157], v[202:205], v[102:105]
	v_mfma_f32_16x16x32_bf16 v[94:97], v[162:165], v[202:205], v[94:97]
	v_mfma_f32_16x16x32_bf16 v[86:89], v[154:157], v[210:213], v[86:89]
	v_mfma_f32_16x16x32_bf16 v[78:81], v[162:165], v[210:213], v[78:81]
	v_mfma_f32_16x16x32_bf16 v[126:129], v[158:161], v[190:193], v[126:129]
	v_mfma_f32_16x16x32_bf16 v[122:125], v[166:169], v[190:193], v[122:125]
	v_mfma_f32_16x16x32_bf16 v[118:121], v[158:161], v[198:201], v[118:121]
	v_mfma_f32_16x16x32_bf16 v[110:113], v[166:169], v[198:201], v[110:113]
	v_mfma_f32_16x16x32_bf16 v[102:105], v[158:161], v[206:209], v[102:105]
	v_mfma_f32_16x16x32_bf16 v[94:97], v[166:169], v[206:209], v[94:97]
	v_mfma_f32_16x16x32_bf16 v[86:89], v[158:161], v[214:217], v[86:89]
	v_mfma_f32_16x16x32_bf16 v[78:81], v[166:169], v[214:217], v[78:81]
	v_mfma_f32_16x16x32_bf16 v[114:117], v[170:173], v[186:189], v[114:117]
	v_mfma_f32_16x16x32_bf16 v[106:109], v[178:181], v[186:189], v[106:109]
	v_mfma_f32_16x16x32_bf16 v[98:101], v[170:173], v[194:197], v[98:101]
	v_mfma_f32_16x16x32_bf16 v[90:93], v[178:181], v[194:197], v[90:93]
	v_mfma_f32_16x16x32_bf16 v[82:85], v[170:173], v[202:205], v[82:85]
	v_mfma_f32_16x16x32_bf16 v[74:77], v[178:181], v[202:205], v[74:77]
	v_mfma_f32_16x16x32_bf16 v[70:73], v[170:173], v[210:213], v[70:73]
	v_mfma_f32_16x16x32_bf16 v[66:69], v[178:181], v[210:213], v[66:69]
	v_mfma_f32_16x16x32_bf16 v[114:117], v[174:177], v[190:193], v[114:117]
	v_mfma_f32_16x16x32_bf16 v[106:109], v[182:185], v[190:193], v[106:109]
	v_mfma_f32_16x16x32_bf16 v[98:101], v[174:177], v[198:201], v[98:101]
	v_mfma_f32_16x16x32_bf16 v[90:93], v[182:185], v[198:201], v[90:93]
	v_mfma_f32_16x16x32_bf16 v[82:85], v[174:177], v[206:209], v[82:85]
	v_mfma_f32_16x16x32_bf16 v[74:77], v[182:185], v[206:209], v[74:77]
	v_mfma_f32_16x16x32_bf16 v[70:73], v[174:177], v[214:217], v[70:73]
	v_mfma_f32_16x16x32_bf16 v[66:69], v[182:185], v[214:217], v[66:69]
	s_barrier
	s_add_i32 s24, s46, s36
	v_lshl_add_u64 v[146:147], s[28:29], 0, v[134:135]
	s_mov_b32 m0, s24
	ds_read_b128 v[186:189], v153 offset:16384
	ds_read_b128 v[190:193], v153 offset:17408
	ds_read_b128 v[194:197], v153 offset:18432
	ds_read_b128 v[198:201], v153 offset:19456
	ds_read_b128 v[202:205], v153 offset:20480
	ds_read_b128 v[206:209], v153 offset:21504
	ds_read_b128 v[210:213], v153 offset:22528
	ds_read_b128 v[214:217], v153 offset:23552
	global_load_lds_dwordx4 v[146:147], off
	s_add_i32 m0, s24, 0x2000
	s_add_u32 s24, s28, 0x160000
	v_lshl_add_u64 v[218:219], s[28:29], 0, v[130:131]
	s_addc_u32 s25, s29, 0
	s_add_i32 s59, s47, s36
	global_load_lds_dwordx4 v[218:219], off
	v_lshl_add_u64 v[220:221], s[24:25], 0, v[134:135]
	s_mov_b32 m0, s59
	v_lshl_add_u64 v[222:223], s[30:31], 0, v[132:133]
	global_load_lds_dwordx4 v[220:221], off
	v_lshl_add_u64 v[220:221], s[24:25], 0, v[130:131]
	s_add_i32 m0, s59, 0x2000
	s_nop 0
	global_load_lds_dwordx4 v[220:221], off
	v_lshl_add_u64 v[220:221], s[30:31], 0, v[136:137]
	s_mov_b32 m0, s38
	s_nop 0
	global_load_lds_dwordx4 v[220:221], off
	s_mov_b32 m0, s39
	s_nop 0
	global_load_lds_dwordx4 v[222:223], off
	s_waitcnt vmcnt(8)
	s_waitcnt lgkmcnt(0)
	s_barrier
; #define PG8_STAGE(bufoff, gbase, voff) do { _Pragma("unroll") for (int _i = 0; _i < 2; ++_i) \
;         __builtin_amdgcn_global_load_lds((const unsigned*)((const char*)(gbase) + (voff)[_i]), (PG8_LAS unsigned*)(lds + (bufoff) + ldsw + _i * 8192), 16, 0, 0); } while (0)
; #define PG8_LDA(dst, b, h) do { _Pragma("unroll") for (int m = 0; m < 4; ++m) _Pragma("unroll") for (int k = 0; k < 2; ++k) dst[m][k] = *(const PG8_LAS bf16x8*)(lds + PG8_SA(b, h) + aoff + m * 2048 + k * 1024); } while (0)
; #define PG8_LDB(dst, b, h) do { _Pragma("unroll") for (int n = 0; n < 2; ++n) _Pragma("unroll") for (int k = 0; k < 2; ++k) dst[n][k] = *(const PG8_LAS bf16x8*)(lds + PG8_SB(b, h) + boff + n * 2048 + k * 1024); } while (0)
; #define PG8_MMA(ai, bj, At, Bt) do { __builtin_amdgcn_s_setprio(1); _Pragma("unroll") for (int m = 0; m < 4; ++m) _Pragma("unroll") for (int n = 0; n < 2; ++n) _Pragma("unroll") for (int k = 0; k < 2; ++k) \
;         acc[ai][bj][m][n] = __builtin_amdgcn_mfma_f32_16x16x32_bf16(Bt[n][k], At[m][k], acc[ai][bj][m][n], 0, 0, 0); __builtin_amdgcn_s_setprio(0); } while (0)
; #define PG8_WAIT_V(n) asm volatile("s_waitcnt vmcnt(" #n ")" ::: "memory")
; template <class Epi, class Sched, bool ALIGN_EPI = false, bool SP2 = false>
; __device__ __forceinline__ void gemm_phase(PG8_LAS unsigned char* lds, const Gemm g, const Sched& S, const Epi& E) {
;     ...
;             PG8_LDB(B0, 0, 0); PG8_LDB(B1, 0, 1); PG8_SCHED; PG8_LDA(At, 0, 0); PG8_STAGE(PG8_SA(1, 1), a1 + hstep, voffA);
;             PG8_WAIT_V(8); PG8_WAIT_L(0); PG8_BAR; PG8_MMA(0, 0, At, B0); PG8_MMA(0, 1, At, B1); PG8_BAR; PG8_SCHED;
;             PG8_LDA(At, 0, 1); PG8_STAGE(PG8_SB(0, 0), b2, voffB); PG8_STAGE(PG8_SB(0, 1), b2 + hstep, voffB); PG8_STAGE(PG8_SA(0, 0), a2, voffA);
;             PG8_WAIT_V(8); PG8_WAIT_L(0); PG8_BAR; PG8_MMA(1, 0, At, B0); PG8_MMA(1, 1, At, B1); PG8_BAR; PG8_SCHED;
;             PG8_LDB(B0, 1, 0); PG8_LDB(B1, 1, 1); PG8_SCHED; PG8_LDA(At, 1, 0); PG8_STAGE(PG8_SA(0, 1), a2 + hstep, voffA);
;             PG8_WAIT_V(8); PG8_WAIT_L(0); PG8_BAR; PG8_MMA(0, 0, At, B0); PG8_MMA(0, 1, At, B1); PG8_BAR; PG8_SCHED;
;             PG8_LDA(At, 1, 1); PG8_STAGE(PG8_SB(1, 0), b3, voffB); PG8_STAGE(PG8_SB(1, 1), b3 + hstep, voffB); PG8_STAGE(PG8_SA(1, 0), a3, voffA);
;             PG8_WAIT_V(8); PG8_WAIT_L(0); PG8_BAR; PG8_MMA(1, 0, At, B0); PG8_MMA(1, 1, At, B1); PG8_BAR; PG8_SCHED;
	s_waitcnt lgkmcnt(0)
	v_mfma_f32_16x16x32_bf16 v[62:65], v[154:157], v[186:189], v[62:65]
	v_mfma_f32_16x16x32_bf16 v[58:61], v[162:165], v[186:189], v[58:61]
	v_mfma_f32_16x16x32_bf16 v[54:57], v[154:157], v[194:197], v[54:57]
	v_mfma_f32_16x16x32_bf16 v[46:49], v[162:165], v[194:197], v[46:49]
	v_mfma_f32_16x16x32_bf16 v[38:41], v[154:157], v[202:205], v[38:41]
	v_mfma_f32_16x16x32_bf16 v[30:33], v[162:165], v[202:205], v[30:33]
	v_mfma_f32_16x16x32_bf16 v[22:25], v[154:157], v[210:213], v[22:25]
	v_mfma_f32_16x16x32_bf16 v[14:17], v[162:165], v[210:213], v[14:17]
	v_mfma_f32_16x16x32_bf16 v[62:65], v[158:161], v[190:193], v[62:65]
	v_mfma_f32_16x16x32_bf16 v[58:61], v[166:169], v[190:193], v[58:61]
	v_mfma_f32_16x16x32_bf16 v[54:57], v[158:161], v[198:201], v[54:57]
	v_mfma_f32_16x16x32_bf16 v[46:49], v[166:169], v[198:201], v[46:49]
	v_mfma_f32_16x16x32_bf16 v[38:41], v[158:161], v[206:209], v[38:41]
	v_mfma_f32_16x16x32_bf16 v[30:33], v[166:169], v[206:209], v[30:33]
	v_mfma_f32_16x16x32_bf16 v[22:25], v[158:161], v[214:217], v[22:25]
	v_mfma_f32_16x16x32_bf16 v[14:17], v[166:169], v[214:217], v[14:17]
	v_mfma_f32_16x16x32_bf16 v[50:53], v[170:173], v[186:189], v[50:53]
	v_mfma_f32_16x16x32_bf16 v[42:45], v[178:181], v[186:189], v[42:45]
	v_mfma_f32_16x16x32_bf16 v[34:37], v[170:173], v[194:197], v[34:37]
	v_mfma_f32_16x16x32_bf16 v[26:29], v[178:181], v[194:197], v[26:29]
	v_mfma_f32_16x16x32_bf16 v[18:21], v[170:173], v[202:205], v[18:21]
	v_mfma_f32_16x16x32_bf16 v[10:13], v[178:181], v[202:205], v[10:13]
	v_mfma_f32_16x16x32_bf16 v[6:9], v[170:173], v[210:213], v[6:9]
	v_mfma_f32_16x16x32_bf16 v[2:5], v[178:181], v[210:213], v[2:5]
	v_mfma_f32_16x16x32_bf16 v[50:53], v[174:177], v[190:193], v[50:53]
	v_mfma_f32_16x16x32_bf16 v[42:45], v[182:185], v[190:193], v[42:45]
	v_mfma_f32_16x16x32_bf16 v[34:37], v[174:177], v[198:201], v[34:37]
	v_mfma_f32_16x16x32_bf16 v[26:29], v[182:185], v[198:201], v[26:29]
	v_mfma_f32_16x16x32_bf16 v[18:21], v[174:177], v[206:209], v[18:21]
	v_mfma_f32_16x16x32_bf16 v[10:13], v[182:185], v[206:209], v[10:13]
	v_mfma_f32_16x16x32_bf16 v[6:9], v[174:177], v[214:217], v[6:9]
	v_mfma_f32_16x16x32_bf16 v[2:5], v[182:185], v[214:217], v[2:5]
	s_barrier
	s_add_i32 s59, 0, 0x18000
	s_add_i32 s60, 0, 0x1c000
	v_add_u32_e32 v166, s59, v149
	v_add_u32_e32 v182, s60, v149
	ds_read_b128 v[154:157], v166
	ds_read_b128 v[158:161], v166 offset:1024
	ds_read_b128 v[162:165], v166 offset:2048
	ds_read_b128 v[166:169], v166 offset:3072
	ds_read_b128 v[170:173], v182
	ds_read_b128 v[174:177], v182 offset:1024
	ds_read_b128 v[178:181], v182 offset:2048
	ds_read_b128 v[182:185], v182 offset:3072
	s_add_u32 s24, s30, 0x160000
	s_addc_u32 s25, s31, 0
	s_mov_b32 m0, s40
	v_lshl_add_u64 v[224:225], s[24:25], 0, v[136:137]
	ds_read_b128 v[186:189], v153 offset:32768
	ds_read_b128 v[190:193], v153 offset:33792
	ds_read_b128 v[194:197], v153 offset:34816
	ds_read_b128 v[198:201], v153 offset:35840
	ds_read_b128 v[202:205], v153 offset:36864
	ds_read_b128 v[206:209], v153 offset:37888
	ds_read_b128 v[210:213], v153 offset:38912
	ds_read_b128 v[214:217], v153 offset:39936
	global_load_lds_dwordx4 v[224:225], off
	v_lshl_add_u64 v[224:225], s[24:25], 0, v[132:133]
	s_mov_b32 m0, s41
	s_nop 0
	global_load_lds_dwordx4 v[224:225], off
	s_waitcnt vmcnt(8)
	s_waitcnt lgkmcnt(0)
	s_barrier
	s_waitcnt lgkmcnt(0)
	v_mfma_f32_16x16x32_bf16 v[126:129], v[154:157], v[186:189], v[126:129]
	v_mfma_f32_16x16x32_bf16 v[122:125], v[162:165], v[186:189], v[122:125]
	v_mfma_f32_16x16x32_bf16 v[118:121], v[154:157], v[194:197], v[118:121]
	v_mfma_f32_16x16x32_bf16 v[110:113], v[162:165], v[194:197], v[110:113]
	v_mfma_f32_16x16x32_bf16 v[102:105], v[154:157], v[202:205], v[102:105]
	v_mfma_f32_16x16x32_bf16 v[94:97], v[162:165], v[202:205], v[94:97]
	v_mfma_f32_16x16x32_bf16 v[86:89], v[154:157], v[210:213], v[86:89]
	v_mfma_f32_16x16x32_bf16 v[78:81], v[162:165], v[210:213], v[78:81]
	v_mfma_f32_16x16x32_bf16 v[126:129], v[158:161], v[190:193], v[126:129]
	v_mfma_f32_16x16x32_bf16 v[122:125], v[166:169], v[190:193], v[122:125]
	v_mfma_f32_16x16x32_bf16 v[118:121], v[158:161], v[198:201], v[118:121]
	v_mfma_f32_16x16x32_bf16 v[110:113], v[166:169], v[198:201], v[110:113]
	v_mfma_f32_16x16x32_bf16 v[102:105], v[158:161], v[206:209], v[102:105]
	v_mfma_f32_16x16x32_bf16 v[94:97], v[166:169], v[206:209], v[94:97]
	v_mfma_f32_16x16x32_bf16 v[86:89], v[158:161], v[214:217], v[86:89]
	v_mfma_f32_16x16x32_bf16 v[78:81], v[166:169], v[214:217], v[78:81]
	v_mfma_f32_16x16x32_bf16 v[114:117], v[170:173], v[186:189], v[114:117]
	v_mfma_f32_16x16x32_bf16 v[106:109], v[178:181], v[186:189], v[106:109]
	v_mfma_f32_16x16x32_bf16 v[98:101], v[170:173], v[194:197], v[98:101]
	v_mfma_f32_16x16x32_bf16 v[90:93], v[178:181], v[194:197], v[90:93]
	v_mfma_f32_16x16x32_bf16 v[82:85], v[170:173], v[202:205], v[82:85]
	v_mfma_f32_16x16x32_bf16 v[74:77], v[178:181], v[202:205], v[74:77]
	v_mfma_f32_16x16x32_bf16 v[70:73], v[170:173], v[210:213], v[70:73]
	v_mfma_f32_16x16x32_bf16 v[66:69], v[178:181], v[210:213], v[66:69]
	v_mfma_f32_16x16x32_bf16 v[114:117], v[174:177], v[190:193], v[114:117]
	v_mfma_f32_16x16x32_bf16 v[106:109], v[182:185], v[190:193], v[106:109]
	v_mfma_f32_16x16x32_bf16 v[98:101], v[174:177], v[198:201], v[98:101]
	v_mfma_f32_16x16x32_bf16 v[90:93], v[182:185], v[198:201], v[90:93]
	v_mfma_f32_16x16x32_bf16 v[82:85], v[174:177], v[206:209], v[82:85]
	v_mfma_f32_16x16x32_bf16 v[74:77], v[182:185], v[206:209], v[74:77]
	v_mfma_f32_16x16x32_bf16 v[70:73], v[174:177], v[214:217], v[70:73]
	v_mfma_f32_16x16x32_bf16 v[66:69], v[182:185], v[214:217], v[66:69]
	s_barrier
; #define PG8_STAGE(bufoff, gbase, voff) do { _Pragma("unroll") for (int _i = 0; _i < 2; ++_i) \
;         __builtin_amdgcn_global_load_lds((const unsigned*)((const char*)(gbase) + (voff)[_i]), (PG8_LAS unsigned*)(lds + (bufoff) + ldsw + _i * 8192), 16, 0, 0); } while (0)
; #define PG8_LDA(dst, b, h) do { _Pragma("unroll") for (int m = 0; m < 4; ++m) _Pragma("unroll") for (int k = 0; k < 2; ++k) dst[m][k] = *(const PG8_LAS bf16x8*)(lds + PG8_SA(b, h) + aoff + m * 2048 + k * 1024); } while (0)
; #define PG8_LDB(dst, b, h) do { _Pragma("unroll") for (int n = 0; n < 2; ++n) _Pragma("unroll") for (int k = 0; k < 2; ++k) dst[n][k] = *(const PG8_LAS bf16x8*)(lds + PG8_SB(b, h) + boff + n * 2048 + k * 1024); } while (0)
; #define PG8_MMA(ai, bj, At, Bt) do { __builtin_amdgcn_s_setprio(1); _Pragma("unroll") for (int m = 0; m < 4; ++m) _Pragma("unroll") for (int n = 0; n < 2; ++n) _Pragma("unroll") for (int k = 0; k < 2; ++k) \
;         acc[ai][bj][m][n] = __builtin_amdgcn_mfma_f32_16x16x32_bf16(Bt[n][k], At[m][k], acc[ai][bj][m][n], 0, 0, 0); __builtin_amdgcn_s_setprio(0); } while (0)
; #define PG8_WAIT_V(n) asm volatile("s_waitcnt vmcnt(" #n ")" ::: "memory")
; template <class Epi, class Sched, bool ALIGN_EPI = false, bool SP2 = false>
; __device__ __forceinline__ void gemm_phase(PG8_LAS unsigned char* lds, const Gemm g, const Sched& S, const Epi& E) {
;     ...
;             PG8_LDB(B0, 0, 0); PG8_LDB(B1, 0, 1); PG8_SCHED; PG8_LDA(At, 0, 0); PG8_STAGE(PG8_SA(1, 1), a1 + hstep, voffA);
;             PG8_WAIT_V(8); PG8_WAIT_L(0); PG8_BAR; PG8_MMA(0, 0, At, B0); PG8_MMA(0, 1, At, B1); PG8_BAR; PG8_SCHED;
;             PG8_LDA(At, 0, 1); PG8_STAGE(PG8_SB(0, 0), b2, voffB); PG8_STAGE(PG8_SB(0, 1), b2 + hstep, voffB); PG8_STAGE(PG8_SA(0, 0), a2, voffA);
;             PG8_WAIT_V(8); PG8_WAIT_L(0); PG8_BAR; PG8_MMA(1, 0, At, B0); PG8_MMA(1, 1, At, B1); PG8_BAR; PG8_SCHED;
;             PG8_LDB(B0, 1, 0); PG8_LDB(B1, 1, 1); PG8_SCHED; PG8_LDA(At, 1, 0); PG8_STAGE(PG8_SA(0, 1), a2 + hstep, voffA);
;             PG8_WAIT_V(8); PG8_WAIT_L(0); PG8_BAR; PG8_MMA(0, 0, At, B0); PG8_MMA(0, 1, At, B1); PG8_BAR; PG8_SCHED;
;             PG8_LDA(At, 1, 1); PG8_STAGE(PG8_SB(1, 0), b3, voffB); PG8_STAGE(PG8_SB(1, 1), b3 + hstep, voffB); PG8_STAGE(PG8_SA(1, 0), a3, voffA);
;             PG8_WAIT_V(8); PG8_WAIT_L(0); PG8_BAR; PG8_MMA(1, 0, At, B0); PG8_MMA(1, 1, At, B1); PG8_BAR; PG8_SCHED;
	s_add_i32 s24, s59, s36
	v_lshl_add_u64 v[146:147], v[146:147], 0, s[10:11]
	s_mov_b32 m0, s24
	ds_read_b128 v[186:189], v153 offset:49152
	ds_read_b128 v[190:193], v153 offset:50176
	ds_read_b128 v[194:197], v153 offset:51200
	ds_read_b128 v[198:201], v153 offset:52224
	ds_read_b128 v[202:205], v153 offset:53248
	ds_read_b128 v[206:209], v153 offset:54272
	ds_read_b128 v[210:213], v153 offset:55296
	ds_read_b128 v[214:217], v153 offset:56320
	global_load_lds_dwordx4 v[146:147], off
	s_add_i32 m0, s24, 0x2000
	s_add_u32 s24, s28, 0x160080
	v_lshl_add_u64 v[146:147], v[218:219], 0, s[10:11]
	s_addc_u32 s25, s29, 0
	s_add_i32 s28, s60, s36
	global_load_lds_dwordx4 v[146:147], off
	v_lshl_add_u64 v[146:147], s[24:25], 0, v[134:135]
	s_mov_b32 m0, s28
	s_nop 0
	global_load_lds_dwordx4 v[146:147], off
	v_lshl_add_u64 v[146:147], s[24:25], 0, v[130:131]
	s_add_i32 m0, s28, 0x2000
	s_nop 0
	global_load_lds_dwordx4 v[146:147], off
	v_lshl_add_u64 v[146:147], v[220:221], 0, s[10:11]
	s_mov_b32 m0, s44
	s_nop 0
	global_load_lds_dwordx4 v[146:147], off
	v_lshl_add_u64 v[146:147], v[222:223], 0, s[10:11]
	s_mov_b32 m0, s45
	s_nop 0
	global_load_lds_dwordx4 v[146:147], off
	s_waitcnt vmcnt(8)
	s_waitcnt lgkmcnt(0)
	s_barrier
	s_waitcnt lgkmcnt(0)
	v_mfma_f32_16x16x32_bf16 v[62:65], v[154:157], v[186:189], v[62:65]
	v_mfma_f32_16x16x32_bf16 v[58:61], v[162:165], v[186:189], v[58:61]
	v_mfma_f32_16x16x32_bf16 v[54:57], v[154:157], v[194:197], v[54:57]
	v_mfma_f32_16x16x32_bf16 v[46:49], v[162:165], v[194:197], v[46:49]
	v_mfma_f32_16x16x32_bf16 v[38:41], v[154:157], v[202:205], v[38:41]
	v_mfma_f32_16x16x32_bf16 v[30:33], v[162:165], v[202:205], v[30:33]
	v_mfma_f32_16x16x32_bf16 v[22:25], v[154:157], v[210:213], v[22:25]
	v_mfma_f32_16x16x32_bf16 v[14:17], v[162:165], v[210:213], v[14:17]
	v_mfma_f32_16x16x32_bf16 v[62:65], v[158:161], v[190:193], v[62:65]
	v_mfma_f32_16x16x32_bf16 v[58:61], v[166:169], v[190:193], v[58:61]
	v_mfma_f32_16x16x32_bf16 v[54:57], v[158:161], v[198:201], v[54:57]
	v_mfma_f32_16x16x32_bf16 v[46:49], v[166:169], v[198:201], v[46:49]
	v_mfma_f32_16x16x32_bf16 v[38:41], v[158:161], v[206:209], v[38:41]
	v_mfma_f32_16x16x32_bf16 v[30:33], v[166:169], v[206:209], v[30:33]
	v_mfma_f32_16x16x32_bf16 v[22:25], v[158:161], v[214:217], v[22:25]
	v_mfma_f32_16x16x32_bf16 v[14:17], v[166:169], v[214:217], v[14:17]
	v_mfma_f32_16x16x32_bf16 v[50:53], v[170:173], v[186:189], v[50:53]
	v_mfma_f32_16x16x32_bf16 v[42:45], v[178:181], v[186:189], v[42:45]
	v_mfma_f32_16x16x32_bf16 v[34:37], v[170:173], v[194:197], v[34:37]
	v_mfma_f32_16x16x32_bf16 v[26:29], v[178:181], v[194:197], v[26:29]
	v_mfma_f32_16x16x32_bf16 v[18:21], v[170:173], v[202:205], v[18:21]
	v_mfma_f32_16x16x32_bf16 v[10:13], v[178:181], v[202:205], v[10:13]
	v_mfma_f32_16x16x32_bf16 v[6:9], v[170:173], v[210:213], v[6:9]
	v_mfma_f32_16x16x32_bf16 v[2:5], v[178:181], v[210:213], v[2:5]
	v_mfma_f32_16x16x32_bf16 v[50:53], v[174:177], v[190:193], v[50:53]
	v_mfma_f32_16x16x32_bf16 v[42:45], v[182:185], v[190:193], v[42:45]
	v_mfma_f32_16x16x32_bf16 v[34:37], v[174:177], v[198:201], v[34:37]
	v_mfma_f32_16x16x32_bf16 v[26:29], v[182:185], v[198:201], v[26:29]
	v_mfma_f32_16x16x32_bf16 v[18:21], v[174:177], v[206:209], v[18:21]
	v_mfma_f32_16x16x32_bf16 v[10:13], v[182:185], v[206:209], v[10:13]
	v_mfma_f32_16x16x32_bf16 v[6:9], v[174:177], v[214:217], v[6:9]
	v_mfma_f32_16x16x32_bf16 v[2:5], v[182:185], v[214:217], v[2:5]
	s_barrier
	s_add_i32 s58, s58, 2
	s_add_u32 s56, s56, 0x100
	s_addc_u32 s57, s57, 0
	s_cmpk_gt_u32 s58, 0x55
	s_mov_b64 s[24:25], s[26:27]
	s_cbranch_scc0 .LBB0_1656
	s_and_b64 vcc, exec, s[12:13]
	s_cbranch_vccz .LBB0_1659
	s_barrier

; #define PG8_STAGE(bufoff, gbase, voff) do { _Pragma("unroll") for (int _i = 0; _i < 2; ++_i) \
;         __builtin_amdgcn_global_load_lds((const unsigned*)((const char*)(gbase) + (voff)[_i]), (PG8_LAS unsigned*)(lds + (bufoff) + ldsw + _i * 8192), 16, 0, 0); } while (0)
; #define PG8_LDA(dst, b, h) do { _Pragma("unroll") for (int m = 0; m < 4; ++m) _Pragma("unroll") for (int k = 0; k < 2; ++k) dst[m][k] = *(const PG8_LAS bf16x8*)(lds + PG8_SA(b, h) + aoff + m * 2048 + k * 1024); } while (0)
; #define PG8_LDB(dst, b, h) do { _Pragma("unroll") for (int n = 0; n < 2; ++n) _Pragma("unroll") for (int k = 0; k < 2; ++k) dst[n][k] = *(const PG8_LAS bf16x8*)(lds + PG8_SB(b, h) + boff + n * 2048 + k * 1024); } while (0)
; #define PG8_MMA(ai, bj, At, Bt) do { __builtin_amdgcn_s_setprio(1); _Pragma("unroll") for (int m = 0; m < 4; ++m) _Pragma("unroll") for (int n = 0; n < 2; ++n) _Pragma("unroll") for (int k = 0; k < 2; ++k) \
;         acc[ai][bj][m][n] = __builtin_amdgcn_mfma_f32_16x16x32_bf16(Bt[n][k], At[m][k], acc[ai][bj][m][n], 0, 0, 0); __builtin_amdgcn_s_setprio(0); } while (0)
; #define PG8_WAIT_V(n) asm volatile("s_waitcnt vmcnt(" #n ")" ::: "memory")
; template <class Epi, class Sched, bool ALIGN_EPI = false, bool SP2 = false>
; __device__ __forceinline__ void gemm_phase(PG8_LAS unsigned char* lds, const Gemm g, const Sched& S, const Epi& E) {
;     ...
;             PG8_LDB(B0, 0, 0); PG8_LDB(B1, 0, 1); PG8_SCHED; PG8_LDA(At, 0, 0); PG8_STAGE(PG8_SA(1, 1), a1 + hstep, voffA);
;             PG8_WAIT_V(8); PG8_WAIT_L(0); PG8_BAR; PG8_MMA(0, 0, At, B0); PG8_MMA(0, 1, At, B1); PG8_BAR; PG8_SCHED;
;             PG8_LDA(At, 0, 1); PG8_STAGE(PG8_SB(0, 0), b2, voffB); PG8_STAGE(PG8_SB(0, 1), b2 + hstep, voffB); PG8_STAGE(PG8_SA(0, 0), a2, voffA);
;             PG8_WAIT_V(8); PG8_WAIT_L(0); PG8_BAR; PG8_MMA(1, 0, At, B0); PG8_MMA(1, 1, At, B1); PG8_BAR; PG8_SCHED;
;             PG8_LDB(B0, 1, 0); PG8_LDB(B1, 1, 1); PG8_SCHED; PG8_LDA(At, 1, 0); PG8_STAGE(PG8_SA(0, 1), a2 + hstep, voffA);
;             PG8_WAIT_V(8); PG8_WAIT_L(0); PG8_BAR; PG8_MMA(0, 0, At, B0); PG8_MMA(0, 1, At, B1); PG8_BAR; PG8_SCHED;
;             PG8_LDA(At, 1, 1); PG8_STAGE(PG8_SB(1, 0), b3, voffB); PG8_STAGE(PG8_SB(1, 1), b3 + hstep, voffB); PG8_STAGE(PG8_SA(1, 0), a3, voffA);
;             PG8_WAIT_V(8); PG8_WAIT_L(0); PG8_BAR; PG8_MMA(1, 0, At, B0); PG8_MMA(1, 1, At, B1); PG8_BAR; PG8_SCHED;
.LBB0_1676:
	ds_read_b128 v[144:147], v141
	ds_read_b128 v[148:151], v141 offset:1024
	ds_read_b128 v[152:155], v141 offset:2048
	ds_read_b128 v[156:159], v141 offset:3072
	ds_read_b128 v[160:163], v142
	ds_read_b128 v[164:167], v142 offset:1024
	ds_read_b128 v[168:171], v142 offset:2048
	ds_read_b128 v[172:175], v142 offset:3072
	s_add_u32 s28, s26, 0x100
	s_addc_u32 s29, s27, 0
	s_cmp_eq_u32 s60, 18
	s_cselect_b32 s37, s23, s29
	s_cselect_b32 s36, s22, s28
	s_cselect_b32 s31, s25, s59
	s_cselect_b32 s30, s24, s7
	v_lshl_add_u64 v[208:209], s[26:27], 0, v[134:135]
	s_add_i32 m0, s41, 0xc000
	ds_read_b128 v[176:179], v143
	ds_read_b128 v[180:183], v143 offset:1024
	ds_read_b128 v[184:187], v143 offset:2048
	ds_read_b128 v[188:191], v143 offset:3072
	ds_read_b128 v[192:195], v143 offset:4096
	ds_read_b128 v[196:199], v143 offset:5120
	ds_read_b128 v[200:203], v143 offset:6144
	ds_read_b128 v[204:207], v143 offset:7168
	global_load_lds_dwordx4 v[208:209], off
	v_lshl_add_u64 v[208:209], s[26:27], 0, v[136:137]
	s_add_i32 m0, s41, 0xe000
	s_nop 0
	global_load_lds_dwordx4 v[208:209], off
	s_waitcnt vmcnt(8)
	s_waitcnt lgkmcnt(0)
	s_barrier
	s_waitcnt lgkmcnt(0)
	v_mfma_f32_16x16x32_bf16 v[126:129], v[144:147], v[176:179], v[126:129]
	v_mfma_f32_16x16x32_bf16 v[122:125], v[152:155], v[176:179], v[122:125]
	v_mfma_f32_16x16x32_bf16 v[118:121], v[144:147], v[184:187], v[118:121]
	v_mfma_f32_16x16x32_bf16 v[114:117], v[152:155], v[184:187], v[114:117]
	v_mfma_f32_16x16x32_bf16 v[106:109], v[144:147], v[192:195], v[106:109]
	v_mfma_f32_16x16x32_bf16 v[98:101], v[152:155], v[192:195], v[98:101]
	v_mfma_f32_16x16x32_bf16 v[90:93], v[144:147], v[200:203], v[90:93]
	v_mfma_f32_16x16x32_bf16 v[82:85], v[152:155], v[200:203], v[82:85]
	v_mfma_f32_16x16x32_bf16 v[126:129], v[148:151], v[180:183], v[126:129]
	v_mfma_f32_16x16x32_bf16 v[122:125], v[156:159], v[180:183], v[122:125]
	v_mfma_f32_16x16x32_bf16 v[118:121], v[148:151], v[188:191], v[118:121]
	v_mfma_f32_16x16x32_bf16 v[114:117], v[156:159], v[188:191], v[114:117]
	v_mfma_f32_16x16x32_bf16 v[106:109], v[148:151], v[196:199], v[106:109]
	v_mfma_f32_16x16x32_bf16 v[98:101], v[156:159], v[196:199], v[98:101]
	v_mfma_f32_16x16x32_bf16 v[90:93], v[148:151], v[204:207], v[90:93]
	v_mfma_f32_16x16x32_bf16 v[82:85], v[156:159], v[204:207], v[82:85]
	v_mfma_f32_16x16x32_bf16 v[110:113], v[160:163], v[176:179], v[110:113]
	v_mfma_f32_16x16x32_bf16 v[102:105], v[168:171], v[176:179], v[102:105]
	v_mfma_f32_16x16x32_bf16 v[94:97], v[160:163], v[184:187], v[94:97]
	v_mfma_f32_16x16x32_bf16 v[86:89], v[168:171], v[184:187], v[86:89]
	v_mfma_f32_16x16x32_bf16 v[78:81], v[160:163], v[192:195], v[78:81]
	v_mfma_f32_16x16x32_bf16 v[74:77], v[168:171], v[192:195], v[74:77]
	v_mfma_f32_16x16x32_bf16 v[70:73], v[160:163], v[200:203], v[70:73]
	v_mfma_f32_16x16x32_bf16 v[66:69], v[168:171], v[200:203], v[66:69]
	v_mfma_f32_16x16x32_bf16 v[110:113], v[164:167], v[180:183], v[110:113]
	v_mfma_f32_16x16x32_bf16 v[102:105], v[172:175], v[180:183], v[102:105]
	v_mfma_f32_16x16x32_bf16 v[94:97], v[164:167], v[188:191], v[94:97]
	v_mfma_f32_16x16x32_bf16 v[86:89], v[172:175], v[188:191], v[86:89]
	v_mfma_f32_16x16x32_bf16 v[78:81], v[164:167], v[196:199], v[78:81]
	v_mfma_f32_16x16x32_bf16 v[74:77], v[172:175], v[196:199], v[74:77]
	v_mfma_f32_16x16x32_bf16 v[70:73], v[164:167], v[204:207], v[70:73]
	v_mfma_f32_16x16x32_bf16 v[66:69], v[172:175], v[204:207], v[66:69]
	s_barrier
	s_add_i32 s26, s50, s39
	v_lshl_add_u64 v[208:209], s[30:31], 0, v[132:133]
	s_mov_b32 m0, s26
	ds_read_b128 v[176:179], v143 offset:16384
	ds_read_b128 v[180:183], v143 offset:17408
	ds_read_b128 v[184:187], v143 offset:18432
	ds_read_b128 v[188:191], v143 offset:19456
	ds_read_b128 v[192:195], v143 offset:20480
	ds_read_b128 v[196:199], v143 offset:21504
	ds_read_b128 v[200:203], v143 offset:22528
	ds_read_b128 v[204:207], v143 offset:23552
	global_load_lds_dwordx4 v[208:209], off
	s_add_i32 m0, s26, 0x2000
	s_add_u32 s26, s30, 0x160000
	v_lshl_add_u64 v[210:211], s[30:31], 0, v[130:131]
	s_addc_u32 s27, s31, 0
	s_add_i32 s61, s51, s39
	global_load_lds_dwordx4 v[210:211], off
	v_lshl_add_u64 v[212:213], s[26:27], 0, v[132:133]
	s_mov_b32 m0, s61
	v_lshl_add_u64 v[214:215], s[36:37], 0, v[130:131]
	global_load_lds_dwordx4 v[212:213], off
	v_lshl_add_u64 v[212:213], s[26:27], 0, v[130:131]
	s_add_i32 m0, s61, 0x2000
	s_nop 0
	global_load_lds_dwordx4 v[212:213], off
	v_lshl_add_u64 v[212:213], s[36:37], 0, v[132:133]
	s_mov_b32 m0, s41
	s_nop 0
	global_load_lds_dwordx4 v[212:213], off
	s_mov_b32 m0, s42
	s_nop 0
	global_load_lds_dwordx4 v[214:215], off
	s_waitcnt vmcnt(8)
	s_waitcnt lgkmcnt(0)
	s_barrier
; #define PG8_STAGE(bufoff, gbase, voff) do { _Pragma("unroll") for (int _i = 0; _i < 2; ++_i) \
;         __builtin_amdgcn_global_load_lds((const unsigned*)((const char*)(gbase) + (voff)[_i]), (PG8_LAS unsigned*)(lds + (bufoff) + ldsw + _i * 8192), 16, 0, 0); } while (0)
; #define PG8_LDA(dst, b, h) do { _Pragma("unroll") for (int m = 0; m < 4; ++m) _Pragma("unroll") for (int k = 0; k < 2; ++k) dst[m][k] = *(const PG8_LAS bf16x8*)(lds + PG8_SA(b, h) + aoff + m * 2048 + k * 1024); } while (0)
; #define PG8_LDB(dst, b, h) do { _Pragma("unroll") for (int n = 0; n < 2; ++n) _Pragma("unroll") for (int k = 0; k < 2; ++k) dst[n][k] = *(const PG8_LAS bf16x8*)(lds + PG8_SB(b, h) + boff + n * 2048 + k * 1024); } while (0)
; #define PG8_MMA(ai, bj, At, Bt) do { __builtin_amdgcn_s_setprio(1); _Pragma("unroll") for (int m = 0; m < 4; ++m) _Pragma("unroll") for (int n = 0; n < 2; ++n) _Pragma("unroll") for (int k = 0; k < 2; ++k) \
;         acc[ai][bj][m][n] = __builtin_amdgcn_mfma_f32_16x16x32_bf16(Bt[n][k], At[m][k], acc[ai][bj][m][n], 0, 0, 0); __builtin_amdgcn_s_setprio(0); } while (0)
; #define PG8_WAIT_V(n) asm volatile("s_waitcnt vmcnt(" #n ")" ::: "memory")
; template <class Epi, class Sched, bool ALIGN_EPI = false, bool SP2 = false>
; __device__ __forceinline__ void gemm_phase(PG8_LAS unsigned char* lds, const Gemm g, const Sched& S, const Epi& E) {
;     ...
;             PG8_LDB(B0, 0, 0); PG8_LDB(B1, 0, 1); PG8_SCHED; PG8_LDA(At, 0, 0); PG8_STAGE(PG8_SA(1, 1), a1 + hstep, voffA);
;             PG8_WAIT_V(8); PG8_WAIT_L(0); PG8_BAR; PG8_MMA(0, 0, At, B0); PG8_MMA(0, 1, At, B1); PG8_BAR; PG8_SCHED;
;             PG8_LDA(At, 0, 1); PG8_STAGE(PG8_SB(0, 0), b2, voffB); PG8_STAGE(PG8_SB(0, 1), b2 + hstep, voffB); PG8_STAGE(PG8_SA(0, 0), a2, voffA);
;             PG8_WAIT_V(8); PG8_WAIT_L(0); PG8_BAR; PG8_MMA(1, 0, At, B0); PG8_MMA(1, 1, At, B1); PG8_BAR; PG8_SCHED;
;             PG8_LDB(B0, 1, 0); PG8_LDB(B1, 1, 1); PG8_SCHED; PG8_LDA(At, 1, 0); PG8_STAGE(PG8_SA(0, 1), a2 + hstep, voffA);
;             PG8_WAIT_V(8); PG8_WAIT_L(0); PG8_BAR; PG8_MMA(0, 0, At, B0); PG8_MMA(0, 1, At, B1); PG8_BAR; PG8_SCHED;
;             PG8_LDA(At, 1, 1); PG8_STAGE(PG8_SB(1, 0), b3, voffB); PG8_STAGE(PG8_SB(1, 1), b3 + hstep, voffB); PG8_STAGE(PG8_SA(1, 0), a3, voffA);
;             PG8_WAIT_V(8); PG8_WAIT_L(0); PG8_BAR; PG8_MMA(1, 0, At, B0); PG8_MMA(1, 1, At, B1); PG8_BAR; PG8_SCHED;
	s_waitcnt lgkmcnt(0)
	v_mfma_f32_16x16x32_bf16 v[62:65], v[144:147], v[176:179], v[62:65]
	v_mfma_f32_16x16x32_bf16 v[58:61], v[152:155], v[176:179], v[58:61]
	v_mfma_f32_16x16x32_bf16 v[54:57], v[144:147], v[184:187], v[54:57]
	v_mfma_f32_16x16x32_bf16 v[50:53], v[152:155], v[184:187], v[50:53]
	v_mfma_f32_16x16x32_bf16 v[42:45], v[144:147], v[192:195], v[42:45]
	v_mfma_f32_16x16x32_bf16 v[34:37], v[152:155], v[192:195], v[34:37]
	v_mfma_f32_16x16x32_bf16 v[26:29], v[144:147], v[200:203], v[26:29]
	v_mfma_f32_16x16x32_bf16 v[18:21], v[152:155], v[200:203], v[18:21]
	v_mfma_f32_16x16x32_bf16 v[62:65], v[148:151], v[180:183], v[62:65]
	v_mfma_f32_16x16x32_bf16 v[58:61], v[156:159], v[180:183], v[58:61]
	v_mfma_f32_16x16x32_bf16 v[54:57], v[148:151], v[188:191], v[54:57]
	v_mfma_f32_16x16x32_bf16 v[50:53], v[156:159], v[188:191], v[50:53]
	v_mfma_f32_16x16x32_bf16 v[42:45], v[148:151], v[196:199], v[42:45]
	v_mfma_f32_16x16x32_bf16 v[34:37], v[156:159], v[196:199], v[34:37]
	v_mfma_f32_16x16x32_bf16 v[26:29], v[148:151], v[204:207], v[26:29]
	v_mfma_f32_16x16x32_bf16 v[18:21], v[156:159], v[204:207], v[18:21]
	v_mfma_f32_16x16x32_bf16 v[46:49], v[160:163], v[176:179], v[46:49]
	v_mfma_f32_16x16x32_bf16 v[38:41], v[168:171], v[176:179], v[38:41]
	v_mfma_f32_16x16x32_bf16 v[30:33], v[160:163], v[184:187], v[30:33]
	v_mfma_f32_16x16x32_bf16 v[22:25], v[168:171], v[184:187], v[22:25]
	v_mfma_f32_16x16x32_bf16 v[14:17], v[160:163], v[192:195], v[14:17]
	v_mfma_f32_16x16x32_bf16 v[10:13], v[168:171], v[192:195], v[10:13]
	v_mfma_f32_16x16x32_bf16 v[6:9], v[160:163], v[200:203], v[6:9]
	v_mfma_f32_16x16x32_bf16 v[2:5], v[168:171], v[200:203], v[2:5]
	v_mfma_f32_16x16x32_bf16 v[46:49], v[164:167], v[180:183], v[46:49]
	v_mfma_f32_16x16x32_bf16 v[38:41], v[172:175], v[180:183], v[38:41]
	v_mfma_f32_16x16x32_bf16 v[30:33], v[164:167], v[188:191], v[30:33]
	v_mfma_f32_16x16x32_bf16 v[22:25], v[172:175], v[188:191], v[22:25]
	v_mfma_f32_16x16x32_bf16 v[14:17], v[164:167], v[196:199], v[14:17]
	v_mfma_f32_16x16x32_bf16 v[10:13], v[172:175], v[196:199], v[10:13]
	v_mfma_f32_16x16x32_bf16 v[6:9], v[164:167], v[204:207], v[6:9]
	v_mfma_f32_16x16x32_bf16 v[2:5], v[172:175], v[204:207], v[2:5]
	s_barrier
	s_add_i32 s61, 0, 0x18000
	s_add_i32 s62, 0, 0x1c000
	v_add_u32_e32 v156, s61, v138
	v_add_u32_e32 v172, s62, v138
	ds_read_b128 v[144:147], v156
	ds_read_b128 v[148:151], v156 offset:1024
	ds_read_b128 v[152:155], v156 offset:2048
	ds_read_b128 v[156:159], v156 offset:3072
	ds_read_b128 v[160:163], v172
	ds_read_b128 v[164:167], v172 offset:1024
	ds_read_b128 v[168:171], v172 offset:2048
	ds_read_b128 v[172:175], v172 offset:3072
	s_add_u32 s26, s36, 0x160000
	s_addc_u32 s27, s37, 0
	s_mov_b32 m0, s43
	v_lshl_add_u64 v[216:217], s[26:27], 0, v[132:133]
	ds_read_b128 v[176:179], v143 offset:32768
	ds_read_b128 v[180:183], v143 offset:33792
	ds_read_b128 v[184:187], v143 offset:34816
	ds_read_b128 v[188:191], v143 offset:35840
	ds_read_b128 v[192:195], v143 offset:36864
	ds_read_b128 v[196:199], v143 offset:37888
	ds_read_b128 v[200:203], v143 offset:38912
	ds_read_b128 v[204:207], v143 offset:39936
	global_load_lds_dwordx4 v[216:217], off
	v_lshl_add_u64 v[216:217], s[26:27], 0, v[130:131]
	s_mov_b32 m0, s44
	s_nop 0
	global_load_lds_dwordx4 v[216:217], off
	s_waitcnt vmcnt(8)
	s_waitcnt lgkmcnt(0)
	s_barrier
	s_waitcnt lgkmcnt(0)
	v_mfma_f32_16x16x32_bf16 v[126:129], v[144:147], v[176:179], v[126:129]
	v_mfma_f32_16x16x32_bf16 v[122:125], v[152:155], v[176:179], v[122:125]
	v_mfma_f32_16x16x32_bf16 v[118:121], v[144:147], v[184:187], v[118:121]
	v_mfma_f32_16x16x32_bf16 v[114:117], v[152:155], v[184:187], v[114:117]
	v_mfma_f32_16x16x32_bf16 v[106:109], v[144:147], v[192:195], v[106:109]
	v_mfma_f32_16x16x32_bf16 v[98:101], v[152:155], v[192:195], v[98:101]
	v_mfma_f32_16x16x32_bf16 v[90:93], v[144:147], v[200:203], v[90:93]
	v_mfma_f32_16x16x32_bf16 v[82:85], v[152:155], v[200:203], v[82:85]
	v_mfma_f32_16x16x32_bf16 v[126:129], v[148:151], v[180:183], v[126:129]
	v_mfma_f32_16x16x32_bf16 v[122:125], v[156:159], v[180:183], v[122:125]
	v_mfma_f32_16x16x32_bf16 v[118:121], v[148:151], v[188:191], v[118:121]
	v_mfma_f32_16x16x32_bf16 v[114:117], v[156:159], v[188:191], v[114:117]
	v_mfma_f32_16x16x32_bf16 v[106:109], v[148:151], v[196:199], v[106:109]
	v_mfma_f32_16x16x32_bf16 v[98:101], v[156:159], v[196:199], v[98:101]
	v_mfma_f32_16x16x32_bf16 v[90:93], v[148:151], v[204:207], v[90:93]
	v_mfma_f32_16x16x32_bf16 v[82:85], v[156:159], v[204:207], v[82:85]
	v_mfma_f32_16x16x32_bf16 v[110:113], v[160:163], v[176:179], v[110:113]
	v_mfma_f32_16x16x32_bf16 v[102:105], v[168:171], v[176:179], v[102:105]
	v_mfma_f32_16x16x32_bf16 v[94:97], v[160:163], v[184:187], v[94:97]
	v_mfma_f32_16x16x32_bf16 v[86:89], v[168:171], v[184:187], v[86:89]
	v_mfma_f32_16x16x32_bf16 v[78:81], v[160:163], v[192:195], v[78:81]
	v_mfma_f32_16x16x32_bf16 v[74:77], v[168:171], v[192:195], v[74:77]
	v_mfma_f32_16x16x32_bf16 v[70:73], v[160:163], v[200:203], v[70:73]
	v_mfma_f32_16x16x32_bf16 v[66:69], v[168:171], v[200:203], v[66:69]
	v_mfma_f32_16x16x32_bf16 v[110:113], v[164:167], v[180:183], v[110:113]
	v_mfma_f32_16x16x32_bf16 v[102:105], v[172:175], v[180:183], v[102:105]
	v_mfma_f32_16x16x32_bf16 v[94:97], v[164:167], v[188:191], v[94:97]
	v_mfma_f32_16x16x32_bf16 v[86:89], v[172:175], v[188:191], v[86:89]
	v_mfma_f32_16x16x32_bf16 v[78:81], v[164:167], v[196:199], v[78:81]
	v_mfma_f32_16x16x32_bf16 v[74:77], v[172:175], v[196:199], v[74:77]
	v_mfma_f32_16x16x32_bf16 v[70:73], v[164:167], v[204:207], v[70:73]
	v_mfma_f32_16x16x32_bf16 v[66:69], v[172:175], v[204:207], v[66:69]
	s_barrier
; #define PG8_STAGE(bufoff, gbase, voff) do { _Pragma("unroll") for (int _i = 0; _i < 2; ++_i) \
;         __builtin_amdgcn_global_load_lds((const unsigned*)((const char*)(gbase) + (voff)[_i]), (PG8_LAS unsigned*)(lds + (bufoff) + ldsw + _i * 8192), 16, 0, 0); } while (0)
; #define PG8_LDA(dst, b, h) do { _Pragma("unroll") for (int m = 0; m < 4; ++m) _Pragma("unroll") for (int k = 0; k < 2; ++k) dst[m][k] = *(const PG8_LAS bf16x8*)(lds + PG8_SA(b, h) + aoff + m * 2048 + k * 1024); } while (0)
; #define PG8_LDB(dst, b, h) do { _Pragma("unroll") for (int n = 0; n < 2; ++n) _Pragma("unroll") for (int k = 0; k < 2; ++k) dst[n][k] = *(const PG8_LAS bf16x8*)(lds + PG8_SB(b, h) + boff + n * 2048 + k * 1024); } while (0)
; #define PG8_MMA(ai, bj, At, Bt) do { __builtin_amdgcn_s_setprio(1); _Pragma("unroll") for (int m = 0; m < 4; ++m) _Pragma("unroll") for (int n = 0; n < 2; ++n) _Pragma("unroll") for (int k = 0; k < 2; ++k) \
;         acc[ai][bj][m][n] = __builtin_amdgcn_mfma_f32_16x16x32_bf16(Bt[n][k], At[m][k], acc[ai][bj][m][n], 0, 0, 0); __builtin_amdgcn_s_setprio(0); } while (0)
; #define PG8_WAIT_V(n) asm volatile("s_waitcnt vmcnt(" #n ")" ::: "memory")
; template <class Epi, class Sched, bool ALIGN_EPI = false, bool SP2 = false>
; __device__ __forceinline__ void gemm_phase(PG8_LAS unsigned char* lds, const Gemm g, const Sched& S, const Epi& E) {
;     ...
;             PG8_LDB(B0, 0, 0); PG8_LDB(B1, 0, 1); PG8_SCHED; PG8_LDA(At, 0, 0); PG8_STAGE(PG8_SA(1, 1), a1 + hstep, voffA);
;             PG8_WAIT_V(8); PG8_WAIT_L(0); PG8_BAR; PG8_MMA(0, 0, At, B0); PG8_MMA(0, 1, At, B1); PG8_BAR; PG8_SCHED;
;             PG8_LDA(At, 0, 1); PG8_STAGE(PG8_SB(0, 0), b2, voffB); PG8_STAGE(PG8_SB(0, 1), b2 + hstep, voffB); PG8_STAGE(PG8_SA(0, 0), a2, voffA);
;             PG8_WAIT_V(8); PG8_WAIT_L(0); PG8_BAR; PG8_MMA(1, 0, At, B0); PG8_MMA(1, 1, At, B1); PG8_BAR; PG8_SCHED;
;             PG8_LDB(B0, 1, 0); PG8_LDB(B1, 1, 1); PG8_SCHED; PG8_LDA(At, 1, 0); PG8_STAGE(PG8_SA(0, 1), a2 + hstep, voffA);
;             PG8_WAIT_V(8); PG8_WAIT_L(0); PG8_BAR; PG8_MMA(0, 0, At, B0); PG8_MMA(0, 1, At, B1); PG8_BAR; PG8_SCHED;
;             PG8_LDA(At, 1, 1); PG8_STAGE(PG8_SB(1, 0), b3, voffB); PG8_STAGE(PG8_SB(1, 1), b3 + hstep, voffB); PG8_STAGE(PG8_SA(1, 0), a3, voffA);
;             PG8_WAIT_V(8); PG8_WAIT_L(0); PG8_BAR; PG8_MMA(1, 0, At, B0); PG8_MMA(1, 1, At, B1); PG8_BAR; PG8_SCHED;
	s_add_i32 s26, s61, s39
	v_lshl_add_u64 v[208:209], v[208:209], 0, s[12:13]
	s_mov_b32 m0, s26
	ds_read_b128 v[176:179], v143 offset:49152
	ds_read_b128 v[180:183], v143 offset:50176
	ds_read_b128 v[184:187], v143 offset:51200
	ds_read_b128 v[188:191], v143 offset:52224
	ds_read_b128 v[192:195], v143 offset:53248
	ds_read_b128 v[196:199], v143 offset:54272
	ds_read_b128 v[200:203], v143 offset:55296
	ds_read_b128 v[204:207], v143 offset:56320
	global_load_lds_dwordx4 v[208:209], off
	s_add_i32 m0, s26, 0x2000
	s_add_u32 s26, s30, 0x160080
	v_lshl_add_u64 v[208:209], v[210:211], 0, s[12:13]
	s_addc_u32 s27, s31, 0
	s_add_i32 s30, s62, s39
	global_load_lds_dwordx4 v[208:209], off
	v_lshl_add_u64 v[208:209], s[26:27], 0, v[132:133]
	s_mov_b32 m0, s30
	s_nop 0
	global_load_lds_dwordx4 v[208:209], off
	v_lshl_add_u64 v[208:209], s[26:27], 0, v[130:131]
	s_add_i32 m0, s30, 0x2000
	s_nop 0
	global_load_lds_dwordx4 v[208:209], off
	v_lshl_add_u64 v[208:209], v[212:213], 0, s[12:13]
	s_mov_b32 m0, s47
	s_nop 0
	global_load_lds_dwordx4 v[208:209], off
	v_lshl_add_u64 v[208:209], v[214:215], 0, s[12:13]
	s_mov_b32 m0, s48
	s_nop 0
	global_load_lds_dwordx4 v[208:209], off
	s_waitcnt vmcnt(8)
	s_waitcnt lgkmcnt(0)
	s_barrier
	s_waitcnt lgkmcnt(0)
	v_mfma_f32_16x16x32_bf16 v[62:65], v[144:147], v[176:179], v[62:65]
	v_mfma_f32_16x16x32_bf16 v[58:61], v[152:155], v[176:179], v[58:61]
	v_mfma_f32_16x16x32_bf16 v[54:57], v[144:147], v[184:187], v[54:57]
	v_mfma_f32_16x16x32_bf16 v[50:53], v[152:155], v[184:187], v[50:53]
	v_mfma_f32_16x16x32_bf16 v[42:45], v[144:147], v[192:195], v[42:45]
	v_mfma_f32_16x16x32_bf16 v[34:37], v[152:155], v[192:195], v[34:37]
	v_mfma_f32_16x16x32_bf16 v[26:29], v[144:147], v[200:203], v[26:29]
	v_mfma_f32_16x16x32_bf16 v[18:21], v[152:155], v[200:203], v[18:21]
	v_mfma_f32_16x16x32_bf16 v[62:65], v[148:151], v[180:183], v[62:65]
	v_mfma_f32_16x16x32_bf16 v[58:61], v[156:159], v[180:183], v[58:61]
	v_mfma_f32_16x16x32_bf16 v[54:57], v[148:151], v[188:191], v[54:57]
	v_mfma_f32_16x16x32_bf16 v[50:53], v[156:159], v[188:191], v[50:53]
	v_mfma_f32_16x16x32_bf16 v[42:45], v[148:151], v[196:199], v[42:45]
	v_mfma_f32_16x16x32_bf16 v[34:37], v[156:159], v[196:199], v[34:37]
	v_mfma_f32_16x16x32_bf16 v[26:29], v[148:151], v[204:207], v[26:29]
	v_mfma_f32_16x16x32_bf16 v[18:21], v[156:159], v[204:207], v[18:21]
	v_mfma_f32_16x16x32_bf16 v[46:49], v[160:163], v[176:179], v[46:49]
	v_mfma_f32_16x16x32_bf16 v[38:41], v[168:171], v[176:179], v[38:41]
	v_mfma_f32_16x16x32_bf16 v[30:33], v[160:163], v[184:187], v[30:33]
	v_mfma_f32_16x16x32_bf16 v[22:25], v[168:171], v[184:187], v[22:25]
	v_mfma_f32_16x16x32_bf16 v[14:17], v[160:163], v[192:195], v[14:17]
	v_mfma_f32_16x16x32_bf16 v[10:13], v[168:171], v[192:195], v[10:13]
	v_mfma_f32_16x16x32_bf16 v[6:9], v[160:163], v[200:203], v[6:9]
	v_mfma_f32_16x16x32_bf16 v[2:5], v[168:171], v[200:203], v[2:5]
	v_mfma_f32_16x16x32_bf16 v[46:49], v[164:167], v[180:183], v[46:49]
	v_mfma_f32_16x16x32_bf16 v[38:41], v[172:175], v[180:183], v[38:41]
	v_mfma_f32_16x16x32_bf16 v[30:33], v[164:167], v[188:191], v[30:33]
	v_mfma_f32_16x16x32_bf16 v[22:25], v[172:175], v[188:191], v[22:25]
	v_mfma_f32_16x16x32_bf16 v[14:17], v[164:167], v[196:199], v[14:17]
	v_mfma_f32_16x16x32_bf16 v[10:13], v[172:175], v[196:199], v[10:13]
	v_mfma_f32_16x16x32_bf16 v[6:9], v[164:167], v[204:207], v[6:9]
	v_mfma_f32_16x16x32_bf16 v[2:5], v[172:175], v[204:207], v[2:5]
	s_barrier
	s_add_i32 s60, s60, 2
	s_add_u32 s7, s7, 0x100
	s_addc_u32 s59, s59, 0
	s_cmp_gt_u32 s60, 19
	s_mov_b64 s[26:27], s[28:29]
	s_cbranch_scc0 .LBB0_1676
	s_and_b64 vcc, exec, s[14:15]
	s_cbranch_vccz .LBB0_1679
	s_barrier

; #define PG8_STAGE(bufoff, gbase, voff) do { _Pragma("unroll") for (int _i = 0; _i < 2; ++_i) \
;         __builtin_amdgcn_global_load_lds((const unsigned*)((const char*)(gbase) + (voff)[_i]), (PG8_LAS unsigned*)(lds + (bufoff) + ldsw + _i * 8192), 16, 0, 0); } while (0)
; #define PG8_LDA(dst, b, h) do { _Pragma("unroll") for (int m = 0; m < 4; ++m) _Pragma("unroll") for (int k = 0; k < 2; ++k) dst[m][k] = *(const PG8_LAS bf16x8*)(lds + PG8_SA(b, h) + aoff + m * 2048 + k * 1024); } while (0)
; #define PG8_LDB(dst, b, h) do { _Pragma("unroll") for (int n = 0; n < 2; ++n) _Pragma("unroll") for (int k = 0; k < 2; ++k) dst[n][k] = *(const PG8_LAS bf16x8*)(lds + PG8_SB(b, h) + boff + n * 2048 + k * 1024); } while (0)
; #define PG8_MMA(ai, bj, At, Bt) do { __builtin_amdgcn_s_setprio(1); _Pragma("unroll") for (int m = 0; m < 4; ++m) _Pragma("unroll") for (int n = 0; n < 2; ++n) _Pragma("unroll") for (int k = 0; k < 2; ++k) \
;         acc[ai][bj][m][n] = __builtin_amdgcn_mfma_f32_16x16x32_bf16(Bt[n][k], At[m][k], acc[ai][bj][m][n], 0, 0, 0); __builtin_amdgcn_s_setprio(0); } while (0)
; #define PG8_WAIT_V(n) asm volatile("s_waitcnt vmcnt(" #n ")" ::: "memory")
; template <class Epi, class Sched, bool ALIGN_EPI = false, bool SP2 = false>
; __device__ __forceinline__ void gemm_phase(PG8_LAS unsigned char* lds, const Gemm g, const Sched& S, const Epi& E) {
;     ...
;             PG8_LDB(B0, 0, 0); PG8_LDB(B1, 0, 1); PG8_SCHED; PG8_LDA(At, 0, 0); PG8_STAGE(PG8_SA(1, 1), a1 + hstep, voffA);
;             PG8_WAIT_V(8); PG8_WAIT_L(0); PG8_BAR; PG8_MMA(0, 0, At, B0); PG8_MMA(0, 1, At, B1); PG8_BAR; PG8_SCHED;
;             PG8_LDA(At, 0, 1); PG8_STAGE(PG8_SB(0, 0), b2, voffB); PG8_STAGE(PG8_SB(0, 1), b2 + hstep, voffB); PG8_STAGE(PG8_SA(0, 0), a2, voffA);
;             PG8_WAIT_V(8); PG8_WAIT_L(0); PG8_BAR; PG8_MMA(1, 0, At, B0); PG8_MMA(1, 1, At, B1); PG8_BAR; PG8_SCHED;
;             PG8_LDB(B0, 1, 0); PG8_LDB(B1, 1, 1); PG8_SCHED; PG8_LDA(At, 1, 0); PG8_STAGE(PG8_SA(0, 1), a2 + hstep, voffA);
;             PG8_WAIT_V(8); PG8_WAIT_L(0); PG8_BAR; PG8_MMA(0, 0, At, B0); PG8_MMA(0, 1, At, B1); PG8_BAR; PG8_SCHED;
;             PG8_LDA(At, 1, 1); PG8_STAGE(PG8_SB(1, 0), b3, voffB); PG8_STAGE(PG8_SB(1, 1), b3 + hstep, voffB); PG8_STAGE(PG8_SA(1, 0), a3, voffA);
;             PG8_WAIT_V(8); PG8_WAIT_L(0); PG8_BAR; PG8_MMA(1, 0, At, B0); PG8_MMA(1, 1, At, B1); PG8_BAR; PG8_SCHED;
.LBB0_1693:
	s_add_u32 s37, s26, s36
	s_addc_u32 s42, s27, 0
	s_add_u32 s40, s37, 0x100
	s_addc_u32 s41, s42, 0
	s_and_b64 s[38:39], s[30:31], exec
	s_cselect_b32 s39, s19, s41
	s_cselect_b32 s38, s63, s40
	s_add_u32 s36, s24, s36
	s_addc_u32 s40, s25, 0
	s_add_u32 s36, s36, 0x100
	s_addc_u32 s40, s40, 0
	s_and_b64 s[30:31], s[30:31], exec
	s_cselect_b32 s41, s17, s40
	s_cselect_b32 s40, s64, s36
	s_add_u32 s44, s37, 0x10080
	ds_read_b128 v[150:153], v147
	ds_read_b128 v[154:157], v147 offset:1024
	ds_read_b128 v[158:161], v147 offset:2048
	ds_read_b128 v[162:165], v147 offset:3072
	ds_read_b128 v[166:169], v148
	ds_read_b128 v[170:173], v148 offset:1024
	ds_read_b128 v[174:177], v148 offset:2048
	ds_read_b128 v[178:181], v148 offset:3072
	s_addc_u32 s45, s42, 0
	s_add_i32 s74, s57, s33
	s_add_i32 m0, s50, 0xc000
	s_add_i32 s75, s50, 0xe000
	s_add_i32 s71, s74, 0x2000
	s_add_u32 s42, s40, 0x10000
	s_addc_u32 s43, s41, 0
	s_add_i32 s73, s58, s33
	s_add_i32 s72, s73, 0x2000
	s_add_i32 s70, 0, 0x18000
	s_add_i32 s69, 0, 0x1c000
	s_add_u32 s36, s38, 0x10000
	s_addc_u32 s37, s39, 0
	s_add_i32 s68, s70, s33
	s_add_i32 s66, s68, 0x2000
	s_add_u32 s30, s40, 0x10080
	s_addc_u32 s31, s41, 0
	s_add_i32 s67, s69, s33
	s_add_i32 s65, s67, 0x2000
	v_lshl_add_u64 v[142:143], s[44:45], 0, v[136:137]
	ds_read_b128 v[182:185], v149
	ds_read_b128 v[186:189], v149 offset:1024
	ds_read_b128 v[190:193], v149 offset:2048
	ds_read_b128 v[194:197], v149 offset:3072
	ds_read_b128 v[198:201], v149 offset:4096
	ds_read_b128 v[202:205], v149 offset:5120
	ds_read_b128 v[206:209], v149 offset:6144
	ds_read_b128 v[210:213], v149 offset:7168
	global_load_lds_dwordx4 v[142:143], off
	v_lshl_add_u64 v[142:143], s[44:45], 0, v[132:133]
	s_mov_b32 m0, s75
	s_nop 0
	global_load_lds_dwordx4 v[142:143], off
	s_waitcnt vmcnt(8)
	s_waitcnt lgkmcnt(0)
	s_barrier
	s_waitcnt lgkmcnt(0)
	v_mfma_f32_16x16x32_bf16 v[126:129], v[150:153], v[182:185], v[126:129]
	v_mfma_f32_16x16x32_bf16 v[122:125], v[158:161], v[182:185], v[122:125]
	v_mfma_f32_16x16x32_bf16 v[118:121], v[150:153], v[190:193], v[118:121]
	v_mfma_f32_16x16x32_bf16 v[110:113], v[158:161], v[190:193], v[110:113]
	v_mfma_f32_16x16x32_bf16 v[102:105], v[150:153], v[198:201], v[102:105]
	v_mfma_f32_16x16x32_bf16 v[94:97], v[158:161], v[198:201], v[94:97]
	v_mfma_f32_16x16x32_bf16 v[86:89], v[150:153], v[206:209], v[86:89]
	v_mfma_f32_16x16x32_bf16 v[78:81], v[158:161], v[206:209], v[78:81]
	v_mfma_f32_16x16x32_bf16 v[126:129], v[154:157], v[186:189], v[126:129]
	v_mfma_f32_16x16x32_bf16 v[122:125], v[162:165], v[186:189], v[122:125]
	v_mfma_f32_16x16x32_bf16 v[118:121], v[154:157], v[194:197], v[118:121]
	v_mfma_f32_16x16x32_bf16 v[110:113], v[162:165], v[194:197], v[110:113]
	v_mfma_f32_16x16x32_bf16 v[102:105], v[154:157], v[202:205], v[102:105]
	v_mfma_f32_16x16x32_bf16 v[94:97], v[162:165], v[202:205], v[94:97]
	v_mfma_f32_16x16x32_bf16 v[86:89], v[154:157], v[210:213], v[86:89]
	v_mfma_f32_16x16x32_bf16 v[78:81], v[162:165], v[210:213], v[78:81]
	v_mfma_f32_16x16x32_bf16 v[114:117], v[166:169], v[182:185], v[114:117]
	v_mfma_f32_16x16x32_bf16 v[106:109], v[174:177], v[182:185], v[106:109]
	v_mfma_f32_16x16x32_bf16 v[98:101], v[166:169], v[190:193], v[98:101]
	v_mfma_f32_16x16x32_bf16 v[90:93], v[174:177], v[190:193], v[90:93]
	v_mfma_f32_16x16x32_bf16 v[82:85], v[166:169], v[198:201], v[82:85]
	v_mfma_f32_16x16x32_bf16 v[74:77], v[174:177], v[198:201], v[74:77]
	v_mfma_f32_16x16x32_bf16 v[70:73], v[166:169], v[206:209], v[70:73]
	v_mfma_f32_16x16x32_bf16 v[66:69], v[174:177], v[206:209], v[66:69]
	v_mfma_f32_16x16x32_bf16 v[114:117], v[170:173], v[186:189], v[114:117]
	v_mfma_f32_16x16x32_bf16 v[106:109], v[178:181], v[186:189], v[106:109]
	v_mfma_f32_16x16x32_bf16 v[98:101], v[170:173], v[194:197], v[98:101]
	v_mfma_f32_16x16x32_bf16 v[90:93], v[178:181], v[194:197], v[90:93]
	v_mfma_f32_16x16x32_bf16 v[82:85], v[170:173], v[202:205], v[82:85]
	v_mfma_f32_16x16x32_bf16 v[74:77], v[178:181], v[202:205], v[74:77]
	v_mfma_f32_16x16x32_bf16 v[70:73], v[170:173], v[210:213], v[70:73]
	v_mfma_f32_16x16x32_bf16 v[66:69], v[178:181], v[210:213], v[66:69]
	s_barrier
	s_mov_b32 m0, s74
	v_lshl_add_u64 v[142:143], s[40:41], 0, v[134:135]
	ds_read_b128 v[182:185], v149 offset:16384
	ds_read_b128 v[186:189], v149 offset:17408
	ds_read_b128 v[190:193], v149 offset:18432
	ds_read_b128 v[194:197], v149 offset:19456
	ds_read_b128 v[198:201], v149 offset:20480
	ds_read_b128 v[202:205], v149 offset:21504
	ds_read_b128 v[206:209], v149 offset:22528
	ds_read_b128 v[210:213], v149 offset:23552
	global_load_lds_dwordx4 v[142:143], off
	v_lshl_add_u64 v[214:215], s[40:41], 0, v[130:131]
	s_mov_b32 m0, s71
	v_lshl_add_u64 v[216:217], s[42:43], 0, v[134:135]
	global_load_lds_dwordx4 v[214:215], off
	s_mov_b32 m0, s73
	v_lshl_add_u64 v[218:219], s[38:39], 0, v[132:133]
	global_load_lds_dwordx4 v[216:217], off
	v_lshl_add_u64 v[216:217], s[42:43], 0, v[130:131]
	s_mov_b32 m0, s72
	s_nop 0
	global_load_lds_dwordx4 v[216:217], off
	v_lshl_add_u64 v[216:217], s[38:39], 0, v[136:137]
	s_mov_b32 m0, s50
	s_nop 0
	global_load_lds_dwordx4 v[216:217], off
	s_mov_b32 m0, s51
	s_nop 0
	global_load_lds_dwordx4 v[218:219], off
	s_waitcnt vmcnt(8)
	s_waitcnt lgkmcnt(0)
	s_barrier
; #define PG8_STAGE(bufoff, gbase, voff) do { _Pragma("unroll") for (int _i = 0; _i < 2; ++_i) \
;         __builtin_amdgcn_global_load_lds((const unsigned*)((const char*)(gbase) + (voff)[_i]), (PG8_LAS unsigned*)(lds + (bufoff) + ldsw + _i * 8192), 16, 0, 0); } while (0)
; #define PG8_LDA(dst, b, h) do { _Pragma("unroll") for (int m = 0; m < 4; ++m) _Pragma("unroll") for (int k = 0; k < 2; ++k) dst[m][k] = *(const PG8_LAS bf16x8*)(lds + PG8_SA(b, h) + aoff + m * 2048 + k * 1024); } while (0)
; #define PG8_LDB(dst, b, h) do { _Pragma("unroll") for (int n = 0; n < 2; ++n) _Pragma("unroll") for (int k = 0; k < 2; ++k) dst[n][k] = *(const PG8_LAS bf16x8*)(lds + PG8_SB(b, h) + boff + n * 2048 + k * 1024); } while (0)
; #define PG8_MMA(ai, bj, At, Bt) do { __builtin_amdgcn_s_setprio(1); _Pragma("unroll") for (int m = 0; m < 4; ++m) _Pragma("unroll") for (int n = 0; n < 2; ++n) _Pragma("unroll") for (int k = 0; k < 2; ++k) \
;         acc[ai][bj][m][n] = __builtin_amdgcn_mfma_f32_16x16x32_bf16(Bt[n][k], At[m][k], acc[ai][bj][m][n], 0, 0, 0); __builtin_amdgcn_s_setprio(0); } while (0)
; #define PG8_WAIT_V(n) asm volatile("s_waitcnt vmcnt(" #n ")" ::: "memory")
; template <class Epi, class Sched, bool ALIGN_EPI = false, bool SP2 = false>
; __device__ __forceinline__ void gemm_phase(PG8_LAS unsigned char* lds, const Gemm g, const Sched& S, const Epi& E) {
;     ...
;             PG8_LDB(B0, 0, 0); PG8_LDB(B1, 0, 1); PG8_SCHED; PG8_LDA(At, 0, 0); PG8_STAGE(PG8_SA(1, 1), a1 + hstep, voffA);
;             PG8_WAIT_V(8); PG8_WAIT_L(0); PG8_BAR; PG8_MMA(0, 0, At, B0); PG8_MMA(0, 1, At, B1); PG8_BAR; PG8_SCHED;
;             PG8_LDA(At, 0, 1); PG8_STAGE(PG8_SB(0, 0), b2, voffB); PG8_STAGE(PG8_SB(0, 1), b2 + hstep, voffB); PG8_STAGE(PG8_SA(0, 0), a2, voffA);
;             PG8_WAIT_V(8); PG8_WAIT_L(0); PG8_BAR; PG8_MMA(1, 0, At, B0); PG8_MMA(1, 1, At, B1); PG8_BAR; PG8_SCHED;
;             PG8_LDB(B0, 1, 0); PG8_LDB(B1, 1, 1); PG8_SCHED; PG8_LDA(At, 1, 0); PG8_STAGE(PG8_SA(0, 1), a2 + hstep, voffA);
;             PG8_WAIT_V(8); PG8_WAIT_L(0); PG8_BAR; PG8_MMA(0, 0, At, B0); PG8_MMA(0, 1, At, B1); PG8_BAR; PG8_SCHED;
;             PG8_LDA(At, 1, 1); PG8_STAGE(PG8_SB(1, 0), b3, voffB); PG8_STAGE(PG8_SB(1, 1), b3 + hstep, voffB); PG8_STAGE(PG8_SA(1, 0), a3, voffA);
;             PG8_WAIT_V(8); PG8_WAIT_L(0); PG8_BAR; PG8_MMA(1, 0, At, B0); PG8_MMA(1, 1, At, B1); PG8_BAR; PG8_SCHED;
	s_waitcnt lgkmcnt(0)
	v_mfma_f32_16x16x32_bf16 v[62:65], v[150:153], v[182:185], v[62:65]
	v_mfma_f32_16x16x32_bf16 v[58:61], v[158:161], v[182:185], v[58:61]
	v_mfma_f32_16x16x32_bf16 v[54:57], v[150:153], v[190:193], v[54:57]
	v_mfma_f32_16x16x32_bf16 v[46:49], v[158:161], v[190:193], v[46:49]
	v_mfma_f32_16x16x32_bf16 v[38:41], v[150:153], v[198:201], v[38:41]
	v_mfma_f32_16x16x32_bf16 v[30:33], v[158:161], v[198:201], v[30:33]
	v_mfma_f32_16x16x32_bf16 v[22:25], v[150:153], v[206:209], v[22:25]
	v_mfma_f32_16x16x32_bf16 v[14:17], v[158:161], v[206:209], v[14:17]
	v_mfma_f32_16x16x32_bf16 v[62:65], v[154:157], v[186:189], v[62:65]
	v_mfma_f32_16x16x32_bf16 v[58:61], v[162:165], v[186:189], v[58:61]
	v_mfma_f32_16x16x32_bf16 v[54:57], v[154:157], v[194:197], v[54:57]
	v_mfma_f32_16x16x32_bf16 v[46:49], v[162:165], v[194:197], v[46:49]
	v_mfma_f32_16x16x32_bf16 v[38:41], v[154:157], v[202:205], v[38:41]
	v_mfma_f32_16x16x32_bf16 v[30:33], v[162:165], v[202:205], v[30:33]
	v_mfma_f32_16x16x32_bf16 v[22:25], v[154:157], v[210:213], v[22:25]
	v_mfma_f32_16x16x32_bf16 v[14:17], v[162:165], v[210:213], v[14:17]
	v_mfma_f32_16x16x32_bf16 v[50:53], v[166:169], v[182:185], v[50:53]
	v_mfma_f32_16x16x32_bf16 v[42:45], v[174:177], v[182:185], v[42:45]
	v_mfma_f32_16x16x32_bf16 v[34:37], v[166:169], v[190:193], v[34:37]
	v_mfma_f32_16x16x32_bf16 v[26:29], v[174:177], v[190:193], v[26:29]
	v_mfma_f32_16x16x32_bf16 v[18:21], v[166:169], v[198:201], v[18:21]
	v_mfma_f32_16x16x32_bf16 v[10:13], v[174:177], v[198:201], v[10:13]
	v_mfma_f32_16x16x32_bf16 v[6:9], v[166:169], v[206:209], v[6:9]
	v_mfma_f32_16x16x32_bf16 v[2:5], v[174:177], v[206:209], v[2:5]
	v_mfma_f32_16x16x32_bf16 v[50:53], v[170:173], v[186:189], v[50:53]
	v_mfma_f32_16x16x32_bf16 v[42:45], v[178:181], v[186:189], v[42:45]
	v_mfma_f32_16x16x32_bf16 v[34:37], v[170:173], v[194:197], v[34:37]
	v_mfma_f32_16x16x32_bf16 v[26:29], v[178:181], v[194:197], v[26:29]
	v_mfma_f32_16x16x32_bf16 v[18:21], v[170:173], v[202:205], v[18:21]
	v_mfma_f32_16x16x32_bf16 v[10:13], v[178:181], v[202:205], v[10:13]
	v_mfma_f32_16x16x32_bf16 v[6:9], v[170:173], v[210:213], v[6:9]
	v_mfma_f32_16x16x32_bf16 v[2:5], v[178:181], v[210:213], v[2:5]
	s_barrier
	v_add_u32_e32 v162, s70, v145
	v_add_u32_e32 v178, s69, v145
	ds_read_b128 v[150:153], v162
	ds_read_b128 v[154:157], v162 offset:1024
	ds_read_b128 v[158:161], v162 offset:2048
	ds_read_b128 v[162:165], v162 offset:3072
	ds_read_b128 v[166:169], v178
	ds_read_b128 v[170:173], v178 offset:1024
	ds_read_b128 v[174:177], v178 offset:2048
	ds_read_b128 v[178:181], v178 offset:3072
	s_mov_b32 m0, s52
	v_lshl_add_u64 v[220:221], s[36:37], 0, v[136:137]
	ds_read_b128 v[182:185], v149 offset:32768
	ds_read_b128 v[186:189], v149 offset:33792
	ds_read_b128 v[190:193], v149 offset:34816
	ds_read_b128 v[194:197], v149 offset:35840
	ds_read_b128 v[198:201], v149 offset:36864
	ds_read_b128 v[202:205], v149 offset:37888
	ds_read_b128 v[206:209], v149 offset:38912
	ds_read_b128 v[210:213], v149 offset:39936
	global_load_lds_dwordx4 v[220:221], off
	v_lshl_add_u64 v[220:221], s[36:37], 0, v[132:133]
	s_mov_b32 m0, s53
	s_nop 0
	global_load_lds_dwordx4 v[220:221], off
	s_waitcnt vmcnt(8)
	s_waitcnt lgkmcnt(0)
	s_barrier
	s_waitcnt lgkmcnt(0)
	v_mfma_f32_16x16x32_bf16 v[126:129], v[150:153], v[182:185], v[126:129]
	v_mfma_f32_16x16x32_bf16 v[122:125], v[158:161], v[182:185], v[122:125]
	v_mfma_f32_16x16x32_bf16 v[118:121], v[150:153], v[190:193], v[118:121]
	v_mfma_f32_16x16x32_bf16 v[110:113], v[158:161], v[190:193], v[110:113]
	v_mfma_f32_16x16x32_bf16 v[102:105], v[150:153], v[198:201], v[102:105]
	v_mfma_f32_16x16x32_bf16 v[94:97], v[158:161], v[198:201], v[94:97]
	v_mfma_f32_16x16x32_bf16 v[86:89], v[150:153], v[206:209], v[86:89]
	v_mfma_f32_16x16x32_bf16 v[78:81], v[158:161], v[206:209], v[78:81]
	v_mfma_f32_16x16x32_bf16 v[126:129], v[154:157], v[186:189], v[126:129]
	v_mfma_f32_16x16x32_bf16 v[122:125], v[162:165], v[186:189], v[122:125]
	v_mfma_f32_16x16x32_bf16 v[118:121], v[154:157], v[194:197], v[118:121]
	v_mfma_f32_16x16x32_bf16 v[110:113], v[162:165], v[194:197], v[110:113]
	v_mfma_f32_16x16x32_bf16 v[102:105], v[154:157], v[202:205], v[102:105]
	v_mfma_f32_16x16x32_bf16 v[94:97], v[162:165], v[202:205], v[94:97]
	v_mfma_f32_16x16x32_bf16 v[86:89], v[154:157], v[210:213], v[86:89]
	v_mfma_f32_16x16x32_bf16 v[78:81], v[162:165], v[210:213], v[78:81]
	v_mfma_f32_16x16x32_bf16 v[114:117], v[166:169], v[182:185], v[114:117]
	v_mfma_f32_16x16x32_bf16 v[106:109], v[174:177], v[182:185], v[106:109]
	v_mfma_f32_16x16x32_bf16 v[98:101], v[166:169], v[190:193], v[98:101]
	v_mfma_f32_16x16x32_bf16 v[90:93], v[174:177], v[190:193], v[90:93]
	v_mfma_f32_16x16x32_bf16 v[82:85], v[166:169], v[198:201], v[82:85]
	v_mfma_f32_16x16x32_bf16 v[74:77], v[174:177], v[198:201], v[74:77]
	v_mfma_f32_16x16x32_bf16 v[70:73], v[166:169], v[206:209], v[70:73]
	v_mfma_f32_16x16x32_bf16 v[66:69], v[174:177], v[206:209], v[66:69]
	v_mfma_f32_16x16x32_bf16 v[114:117], v[170:173], v[186:189], v[114:117]
	v_mfma_f32_16x16x32_bf16 v[106:109], v[178:181], v[186:189], v[106:109]
	v_mfma_f32_16x16x32_bf16 v[98:101], v[170:173], v[194:197], v[98:101]
	v_mfma_f32_16x16x32_bf16 v[90:93], v[178:181], v[194:197], v[90:93]
	v_mfma_f32_16x16x32_bf16 v[82:85], v[170:173], v[202:205], v[82:85]
	v_mfma_f32_16x16x32_bf16 v[74:77], v[178:181], v[202:205], v[74:77]
	v_mfma_f32_16x16x32_bf16 v[70:73], v[170:173], v[210:213], v[70:73]
	v_mfma_f32_16x16x32_bf16 v[66:69], v[178:181], v[210:213], v[66:69]
	s_barrier
; #define PG8_STAGE(bufoff, gbase, voff) do { _Pragma("unroll") for (int _i = 0; _i < 2; ++_i) \
;         __builtin_amdgcn_global_load_lds((const unsigned*)((const char*)(gbase) + (voff)[_i]), (PG8_LAS unsigned*)(lds + (bufoff) + ldsw + _i * 8192), 16, 0, 0); } while (0)
; #define PG8_LDA(dst, b, h) do { _Pragma("unroll") for (int m = 0; m < 4; ++m) _Pragma("unroll") for (int k = 0; k < 2; ++k) dst[m][k] = *(const PG8_LAS bf16x8*)(lds + PG8_SA(b, h) + aoff + m * 2048 + k * 1024); } while (0)
; #define PG8_LDB(dst, b, h) do { _Pragma("unroll") for (int n = 0; n < 2; ++n) _Pragma("unroll") for (int k = 0; k < 2; ++k) dst[n][k] = *(const PG8_LAS bf16x8*)(lds + PG8_SB(b, h) + boff + n * 2048 + k * 1024); } while (0)
; #define PG8_MMA(ai, bj, At, Bt) do { __builtin_amdgcn_s_setprio(1); _Pragma("unroll") for (int m = 0; m < 4; ++m) _Pragma("unroll") for (int n = 0; n < 2; ++n) _Pragma("unroll") for (int k = 0; k < 2; ++k) \
;         acc[ai][bj][m][n] = __builtin_amdgcn_mfma_f32_16x16x32_bf16(Bt[n][k], At[m][k], acc[ai][bj][m][n], 0, 0, 0); __builtin_amdgcn_s_setprio(0); } while (0)
; #define PG8_WAIT_V(n) asm volatile("s_waitcnt vmcnt(" #n ")" ::: "memory")
; template <class Epi, class Sched, bool ALIGN_EPI = false, bool SP2 = false>
; __device__ __forceinline__ void gemm_phase(PG8_LAS unsigned char* lds, const Gemm g, const Sched& S, const Epi& E) {
;     ...
;             PG8_LDB(B0, 0, 0); PG8_LDB(B1, 0, 1); PG8_SCHED; PG8_LDA(At, 0, 0); PG8_STAGE(PG8_SA(1, 1), a1 + hstep, voffA);
;             PG8_WAIT_V(8); PG8_WAIT_L(0); PG8_BAR; PG8_MMA(0, 0, At, B0); PG8_MMA(0, 1, At, B1); PG8_BAR; PG8_SCHED;
;             PG8_LDA(At, 0, 1); PG8_STAGE(PG8_SB(0, 0), b2, voffB); PG8_STAGE(PG8_SB(0, 1), b2 + hstep, voffB); PG8_STAGE(PG8_SA(0, 0), a2, voffA);
;             PG8_WAIT_V(8); PG8_WAIT_L(0); PG8_BAR; PG8_MMA(1, 0, At, B0); PG8_MMA(1, 1, At, B1); PG8_BAR; PG8_SCHED;
;             PG8_LDB(B0, 1, 0); PG8_LDB(B1, 1, 1); PG8_SCHED; PG8_LDA(At, 1, 0); PG8_STAGE(PG8_SA(0, 1), a2 + hstep, voffA);
;             PG8_WAIT_V(8); PG8_WAIT_L(0); PG8_BAR; PG8_MMA(0, 0, At, B0); PG8_MMA(0, 1, At, B1); PG8_BAR; PG8_SCHED;
;             PG8_LDA(At, 1, 1); PG8_STAGE(PG8_SB(1, 0), b3, voffB); PG8_STAGE(PG8_SB(1, 1), b3 + hstep, voffB); PG8_STAGE(PG8_SA(1, 0), a3, voffA);
;             PG8_WAIT_V(8); PG8_WAIT_L(0); PG8_BAR; PG8_MMA(1, 0, At, B0); PG8_MMA(1, 1, At, B1); PG8_BAR; PG8_SCHED;
	s_mov_b32 m0, s68
	v_lshl_add_u64 v[142:143], v[142:143], 0, s[10:11]
	ds_read_b128 v[182:185], v149 offset:49152
	ds_read_b128 v[186:189], v149 offset:50176
	ds_read_b128 v[190:193], v149 offset:51200
	ds_read_b128 v[194:197], v149 offset:52224
	ds_read_b128 v[198:201], v149 offset:53248
	ds_read_b128 v[202:205], v149 offset:54272
	ds_read_b128 v[206:209], v149 offset:55296
	ds_read_b128 v[210:213], v149 offset:56320
	global_load_lds_dwordx4 v[142:143], off
	v_lshl_add_u64 v[142:143], v[214:215], 0, s[10:11]
	s_mov_b32 m0, s66
	s_nop 0
	global_load_lds_dwordx4 v[142:143], off
	v_lshl_add_u64 v[142:143], s[30:31], 0, v[134:135]
	s_mov_b32 m0, s67
	s_nop 0
	global_load_lds_dwordx4 v[142:143], off
	v_lshl_add_u64 v[142:143], s[30:31], 0, v[130:131]
	s_mov_b32 m0, s65
	s_nop 0
	global_load_lds_dwordx4 v[142:143], off
	v_lshl_add_u64 v[142:143], v[216:217], 0, s[10:11]
	s_mov_b32 m0, s55
	s_nop 0
	global_load_lds_dwordx4 v[142:143], off
	v_lshl_add_u64 v[142:143], v[218:219], 0, s[10:11]
	s_mov_b32 m0, s56
	s_nop 0
	global_load_lds_dwordx4 v[142:143], off
	s_waitcnt vmcnt(8)
	s_waitcnt lgkmcnt(0)
	s_barrier
	s_waitcnt lgkmcnt(0)
	v_mfma_f32_16x16x32_bf16 v[62:65], v[150:153], v[182:185], v[62:65]
	v_mfma_f32_16x16x32_bf16 v[58:61], v[158:161], v[182:185], v[58:61]
	v_mfma_f32_16x16x32_bf16 v[54:57], v[150:153], v[190:193], v[54:57]
	v_mfma_f32_16x16x32_bf16 v[46:49], v[158:161], v[190:193], v[46:49]
	v_mfma_f32_16x16x32_bf16 v[38:41], v[150:153], v[198:201], v[38:41]
	v_mfma_f32_16x16x32_bf16 v[30:33], v[158:161], v[198:201], v[30:33]
	v_mfma_f32_16x16x32_bf16 v[22:25], v[150:153], v[206:209], v[22:25]
	v_mfma_f32_16x16x32_bf16 v[14:17], v[158:161], v[206:209], v[14:17]
	v_mfma_f32_16x16x32_bf16 v[62:65], v[154:157], v[186:189], v[62:65]
	v_mfma_f32_16x16x32_bf16 v[58:61], v[162:165], v[186:189], v[58:61]
	v_mfma_f32_16x16x32_bf16 v[54:57], v[154:157], v[194:197], v[54:57]
	v_mfma_f32_16x16x32_bf16 v[46:49], v[162:165], v[194:197], v[46:49]
	v_mfma_f32_16x16x32_bf16 v[38:41], v[154:157], v[202:205], v[38:41]
	v_mfma_f32_16x16x32_bf16 v[30:33], v[162:165], v[202:205], v[30:33]
	v_mfma_f32_16x16x32_bf16 v[22:25], v[154:157], v[210:213], v[22:25]
	v_mfma_f32_16x16x32_bf16 v[14:17], v[162:165], v[210:213], v[14:17]
	v_mfma_f32_16x16x32_bf16 v[50:53], v[166:169], v[182:185], v[50:53]
	v_mfma_f32_16x16x32_bf16 v[42:45], v[174:177], v[182:185], v[42:45]
	v_mfma_f32_16x16x32_bf16 v[34:37], v[166:169], v[190:193], v[34:37]
	v_mfma_f32_16x16x32_bf16 v[26:29], v[174:177], v[190:193], v[26:29]
	v_mfma_f32_16x16x32_bf16 v[18:21], v[166:169], v[198:201], v[18:21]
	v_mfma_f32_16x16x32_bf16 v[10:13], v[174:177], v[198:201], v[10:13]
	v_mfma_f32_16x16x32_bf16 v[6:9], v[166:169], v[206:209], v[6:9]
	v_mfma_f32_16x16x32_bf16 v[2:5], v[174:177], v[206:209], v[2:5]
	v_mfma_f32_16x16x32_bf16 v[50:53], v[170:173], v[186:189], v[50:53]
	v_mfma_f32_16x16x32_bf16 v[42:45], v[178:181], v[186:189], v[42:45]
	v_mfma_f32_16x16x32_bf16 v[34:37], v[170:173], v[194:197], v[34:37]
	v_mfma_f32_16x16x32_bf16 v[26:29], v[178:181], v[194:197], v[26:29]
	v_mfma_f32_16x16x32_bf16 v[18:21], v[170:173], v[202:205], v[18:21]
	v_mfma_f32_16x16x32_bf16 v[10:13], v[178:181], v[202:205], v[10:13]
	v_mfma_f32_16x16x32_bf16 v[6:9], v[170:173], v[210:213], v[6:9]
	v_mfma_f32_16x16x32_bf16 v[2:5], v[178:181], v[210:213], v[2:5]
	s_barrier
	s_movk_i32 s36, 0x100
	s_andn2_b64 vcc, exec, s[28:29]
	s_mov_b64 s[30:31], -1
	s_mov_b64 s[28:29], 0
	s_cbranch_vccz .LBB0_1693
	s_and_b64 vcc, exec, s[12:13]
	s_cbranch_vccz .LBB0_1696
	s_barrier

; #define PG8_STAGE(bufoff, gbase, voff) do { _Pragma("unroll") for (int _i = 0; _i < 2; ++_i) \
;         __builtin_amdgcn_global_load_lds((const unsigned*)((const char*)(gbase) + (voff)[_i]), (PG8_LAS unsigned*)(lds + (bufoff) + ldsw + _i * 8192), 16, 0, 0); } while (0)
; #define PG8_LDA(dst, b, h) do { _Pragma("unroll") for (int m = 0; m < 4; ++m) _Pragma("unroll") for (int k = 0; k < 2; ++k) dst[m][k] = *(const PG8_LAS bf16x8*)(lds + PG8_SA(b, h) + aoff + m * 2048 + k * 1024); } while (0)
; #define PG8_LDB(dst, b, h) do { _Pragma("unroll") for (int n = 0; n < 2; ++n) _Pragma("unroll") for (int k = 0; k < 2; ++k) dst[n][k] = *(const PG8_LAS bf16x8*)(lds + PG8_SB(b, h) + boff + n * 2048 + k * 1024); } while (0)
; #define PG8_MMA(ai, bj, At, Bt) do { __builtin_amdgcn_s_setprio(1); _Pragma("unroll") for (int m = 0; m < 4; ++m) _Pragma("unroll") for (int n = 0; n < 2; ++n) _Pragma("unroll") for (int k = 0; k < 2; ++k) \
;         acc[ai][bj][m][n] = __builtin_amdgcn_mfma_f32_16x16x32_bf16(Bt[n][k], At[m][k], acc[ai][bj][m][n], 0, 0, 0); __builtin_amdgcn_s_setprio(0); } while (0)
; #define PG8_WAIT_V(n) asm volatile("s_waitcnt vmcnt(" #n ")" ::: "memory")
; template <class Epi, class Sched, bool ALIGN_EPI = false, bool SP2 = false>
; __device__ __forceinline__ void gemm_phase(PG8_LAS unsigned char* lds, const Gemm g, const Sched& S, const Epi& E) {
;     ...
;             PG8_LDB(B0, 0, 0); PG8_LDB(B1, 0, 1); PG8_SCHED; PG8_LDA(At, 0, 0); PG8_STAGE(PG8_SA(1, 1), a1 + hstep, voffA);
;             PG8_WAIT_V(8); PG8_WAIT_L(0); PG8_BAR; PG8_MMA(0, 0, At, B0); PG8_MMA(0, 1, At, B1); PG8_BAR; PG8_SCHED;
;             PG8_LDA(At, 0, 1); PG8_STAGE(PG8_SB(0, 0), b2, voffB); PG8_STAGE(PG8_SB(0, 1), b2 + hstep, voffB); PG8_STAGE(PG8_SA(0, 0), a2, voffA);
;             PG8_WAIT_V(8); PG8_WAIT_L(0); PG8_BAR; PG8_MMA(1, 0, At, B0); PG8_MMA(1, 1, At, B1); PG8_BAR; PG8_SCHED;
;             PG8_LDB(B0, 1, 0); PG8_LDB(B1, 1, 1); PG8_SCHED; PG8_LDA(At, 1, 0); PG8_STAGE(PG8_SA(0, 1), a2 + hstep, voffA);
;             PG8_WAIT_V(8); PG8_WAIT_L(0); PG8_BAR; PG8_MMA(0, 0, At, B0); PG8_MMA(0, 1, At, B1); PG8_BAR; PG8_SCHED;
;             PG8_LDA(At, 1, 1); PG8_STAGE(PG8_SB(1, 0), b3, voffB); PG8_STAGE(PG8_SB(1, 1), b3 + hstep, voffB); PG8_STAGE(PG8_SA(1, 0), a3, voffA);
;             PG8_WAIT_V(8); PG8_WAIT_L(0); PG8_BAR; PG8_MMA(1, 0, At, B0); PG8_MMA(1, 1, At, B1); PG8_BAR; PG8_SCHED;
.LBB0_1820:
	ds_read_b128 v[146:149], v155
	ds_read_b128 v[158:161], v155 offset:1024
	ds_read_b128 v[162:165], v155 offset:2048
	ds_read_b128 v[166:169], v155 offset:3072
	ds_read_b128 v[170:173], v156
	ds_read_b128 v[174:177], v156 offset:1024
	ds_read_b128 v[178:181], v156 offset:2048
	ds_read_b128 v[182:185], v156 offset:3072
	s_add_u32 s38, s36, 0xfff80080
	s_addc_u32 s39, s37, -1
	s_cmp_eq_u32 s58, 28
	s_cselect_b32 s41, s25, s39
	s_cselect_b32 s40, s54, s38
	s_cselect_b32 s39, s23, s57
	s_cselect_b32 s38, s55, s56
	v_lshl_add_u64 v[150:151], s[36:37], 0, v[138:139]
	s_add_i32 m0, s31, 0xc000
	ds_read_b128 v[186:189], v157
	ds_read_b128 v[190:193], v157 offset:1024
	ds_read_b128 v[194:197], v157 offset:2048
	ds_read_b128 v[198:201], v157 offset:3072
	ds_read_b128 v[202:205], v157 offset:4096
	ds_read_b128 v[206:209], v157 offset:5120
	ds_read_b128 v[210:213], v157 offset:6144
	ds_read_b128 v[214:217], v157 offset:7168
	global_load_lds_dwordx4 v[150:151], off
	v_lshl_add_u64 v[150:151], s[36:37], 0, v[140:141]
	s_add_i32 m0, s31, 0xe000
	s_nop 0
	global_load_lds_dwordx4 v[150:151], off
	s_waitcnt vmcnt(8)
	s_waitcnt lgkmcnt(0)
	s_barrier
	s_waitcnt lgkmcnt(0)
	v_mfma_f32_16x16x32_bf16 v[126:129], v[146:149], v[186:189], v[126:129]
	v_mfma_f32_16x16x32_bf16 v[122:125], v[162:165], v[186:189], v[122:125]
	v_mfma_f32_16x16x32_bf16 v[110:113], v[146:149], v[194:197], v[110:113]
	v_mfma_f32_16x16x32_bf16 v[106:109], v[162:165], v[194:197], v[106:109]
	v_mfma_f32_16x16x32_bf16 v[94:97], v[146:149], v[202:205], v[94:97]
	v_mfma_f32_16x16x32_bf16 v[90:93], v[162:165], v[202:205], v[90:93]
	v_mfma_f32_16x16x32_bf16 v[78:81], v[146:149], v[210:213], v[78:81]
	v_mfma_f32_16x16x32_bf16 v[74:77], v[162:165], v[210:213], v[74:77]
	v_mfma_f32_16x16x32_bf16 v[126:129], v[158:161], v[190:193], v[126:129]
	v_mfma_f32_16x16x32_bf16 v[122:125], v[166:169], v[190:193], v[122:125]
	v_mfma_f32_16x16x32_bf16 v[110:113], v[158:161], v[198:201], v[110:113]
	v_mfma_f32_16x16x32_bf16 v[106:109], v[166:169], v[198:201], v[106:109]
	v_mfma_f32_16x16x32_bf16 v[94:97], v[158:161], v[206:209], v[94:97]
	v_mfma_f32_16x16x32_bf16 v[90:93], v[166:169], v[206:209], v[90:93]
	v_mfma_f32_16x16x32_bf16 v[78:81], v[158:161], v[214:217], v[78:81]
	v_mfma_f32_16x16x32_bf16 v[74:77], v[166:169], v[214:217], v[74:77]
	v_mfma_f32_16x16x32_bf16 v[118:121], v[170:173], v[186:189], v[118:121]
	v_mfma_f32_16x16x32_bf16 v[114:117], v[178:181], v[186:189], v[114:117]
	v_mfma_f32_16x16x32_bf16 v[102:105], v[170:173], v[194:197], v[102:105]
	v_mfma_f32_16x16x32_bf16 v[98:101], v[178:181], v[194:197], v[98:101]
	v_mfma_f32_16x16x32_bf16 v[86:89], v[170:173], v[202:205], v[86:89]
	v_mfma_f32_16x16x32_bf16 v[82:85], v[178:181], v[202:205], v[82:85]
	v_mfma_f32_16x16x32_bf16 v[70:73], v[170:173], v[210:213], v[70:73]
	v_mfma_f32_16x16x32_bf16 v[66:69], v[178:181], v[210:213], v[66:69]
	v_mfma_f32_16x16x32_bf16 v[118:121], v[174:177], v[190:193], v[118:121]
	v_mfma_f32_16x16x32_bf16 v[114:117], v[182:185], v[190:193], v[114:117]
	v_mfma_f32_16x16x32_bf16 v[102:105], v[174:177], v[198:201], v[102:105]
	v_mfma_f32_16x16x32_bf16 v[98:101], v[182:185], v[198:201], v[98:101]
	v_mfma_f32_16x16x32_bf16 v[86:89], v[174:177], v[206:209], v[86:89]
	v_mfma_f32_16x16x32_bf16 v[82:85], v[182:185], v[206:209], v[82:85]
	v_mfma_f32_16x16x32_bf16 v[70:73], v[174:177], v[214:217], v[70:73]
	v_mfma_f32_16x16x32_bf16 v[66:69], v[182:185], v[214:217], v[66:69]
	s_barrier
	s_add_i32 s59, s51, s3
	v_lshl_add_u64 v[150:151], s[38:39], 0, v[134:135]
	s_mov_b32 m0, s59
	ds_read_b128 v[186:189], v157 offset:16384
	ds_read_b128 v[190:193], v157 offset:17408
	ds_read_b128 v[194:197], v157 offset:18432
	ds_read_b128 v[198:201], v157 offset:19456
	ds_read_b128 v[202:205], v157 offset:20480
	ds_read_b128 v[206:209], v157 offset:21504
	ds_read_b128 v[210:213], v157 offset:22528
	ds_read_b128 v[214:217], v157 offset:23552
	global_load_lds_dwordx4 v[150:151], off
	s_add_i32 m0, s59, 0x2000
	s_add_u32 s60, s38, 0x80000
	v_lshl_add_u64 v[218:219], s[38:39], 0, v[130:131]
	s_addc_u32 s61, s39, 0
	s_add_i32 s59, s52, s3
	global_load_lds_dwordx4 v[218:219], off
	v_lshl_add_u64 v[220:221], s[60:61], 0, v[134:135]
	s_mov_b32 m0, s59
	v_lshl_add_u64 v[222:223], s[40:41], 0, v[132:133]
	global_load_lds_dwordx4 v[220:221], off
	v_lshl_add_u64 v[220:221], s[60:61], 0, v[130:131]
	s_add_i32 m0, s59, 0x2000
	s_nop 0
	global_load_lds_dwordx4 v[220:221], off
	v_lshl_add_u64 v[220:221], s[40:41], 0, v[136:137]
	s_mov_b32 m0, s31
	s_nop 0
	global_load_lds_dwordx4 v[220:221], off
	s_mov_b32 m0, s43
	s_nop 0
	global_load_lds_dwordx4 v[222:223], off
	s_waitcnt vmcnt(8)
	s_waitcnt lgkmcnt(0)
	s_barrier
; #define PG8_STAGE(bufoff, gbase, voff) do { _Pragma("unroll") for (int _i = 0; _i < 2; ++_i) \
;         __builtin_amdgcn_global_load_lds((const unsigned*)((const char*)(gbase) + (voff)[_i]), (PG8_LAS unsigned*)(lds + (bufoff) + ldsw + _i * 8192), 16, 0, 0); } while (0)
; #define PG8_LDA(dst, b, h) do { _Pragma("unroll") for (int m = 0; m < 4; ++m) _Pragma("unroll") for (int k = 0; k < 2; ++k) dst[m][k] = *(const PG8_LAS bf16x8*)(lds + PG8_SA(b, h) + aoff + m * 2048 + k * 1024); } while (0)
; #define PG8_LDB(dst, b, h) do { _Pragma("unroll") for (int n = 0; n < 2; ++n) _Pragma("unroll") for (int k = 0; k < 2; ++k) dst[n][k] = *(const PG8_LAS bf16x8*)(lds + PG8_SB(b, h) + boff + n * 2048 + k * 1024); } while (0)
; #define PG8_MMA(ai, bj, At, Bt) do { __builtin_amdgcn_s_setprio(1); _Pragma("unroll") for (int m = 0; m < 4; ++m) _Pragma("unroll") for (int n = 0; n < 2; ++n) _Pragma("unroll") for (int k = 0; k < 2; ++k) \
;         acc[ai][bj][m][n] = __builtin_amdgcn_mfma_f32_16x16x32_bf16(Bt[n][k], At[m][k], acc[ai][bj][m][n], 0, 0, 0); __builtin_amdgcn_s_setprio(0); } while (0)
; #define PG8_WAIT_V(n) asm volatile("s_waitcnt vmcnt(" #n ")" ::: "memory")
; template <class Epi, class Sched, bool ALIGN_EPI = false, bool SP2 = false>
; __device__ __forceinline__ void gemm_phase(PG8_LAS unsigned char* lds, const Gemm g, const Sched& S, const Epi& E) {
;     ...
;             PG8_LDB(B0, 0, 0); PG8_LDB(B1, 0, 1); PG8_SCHED; PG8_LDA(At, 0, 0); PG8_STAGE(PG8_SA(1, 1), a1 + hstep, voffA);
;             PG8_WAIT_V(8); PG8_WAIT_L(0); PG8_BAR; PG8_MMA(0, 0, At, B0); PG8_MMA(0, 1, At, B1); PG8_BAR; PG8_SCHED;
;             PG8_LDA(At, 0, 1); PG8_STAGE(PG8_SB(0, 0), b2, voffB); PG8_STAGE(PG8_SB(0, 1), b2 + hstep, voffB); PG8_STAGE(PG8_SA(0, 0), a2, voffA);
;             PG8_WAIT_V(8); PG8_WAIT_L(0); PG8_BAR; PG8_MMA(1, 0, At, B0); PG8_MMA(1, 1, At, B1); PG8_BAR; PG8_SCHED;
;             PG8_LDB(B0, 1, 0); PG8_LDB(B1, 1, 1); PG8_SCHED; PG8_LDA(At, 1, 0); PG8_STAGE(PG8_SA(0, 1), a2 + hstep, voffA);
;             PG8_WAIT_V(8); PG8_WAIT_L(0); PG8_BAR; PG8_MMA(0, 0, At, B0); PG8_MMA(0, 1, At, B1); PG8_BAR; PG8_SCHED;
;             PG8_LDA(At, 1, 1); PG8_STAGE(PG8_SB(1, 0), b3, voffB); PG8_STAGE(PG8_SB(1, 1), b3 + hstep, voffB); PG8_STAGE(PG8_SA(1, 0), a3, voffA);
;             PG8_WAIT_V(8); PG8_WAIT_L(0); PG8_BAR; PG8_MMA(1, 0, At, B0); PG8_MMA(1, 1, At, B1); PG8_BAR; PG8_SCHED;
	s_waitcnt lgkmcnt(0)
	v_mfma_f32_16x16x32_bf16 v[62:65], v[146:149], v[186:189], v[62:65]
	v_mfma_f32_16x16x32_bf16 v[58:61], v[162:165], v[186:189], v[58:61]
	v_mfma_f32_16x16x32_bf16 v[46:49], v[146:149], v[194:197], v[46:49]
	v_mfma_f32_16x16x32_bf16 v[42:45], v[162:165], v[194:197], v[42:45]
	v_mfma_f32_16x16x32_bf16 v[30:33], v[146:149], v[202:205], v[30:33]
	v_mfma_f32_16x16x32_bf16 v[26:29], v[162:165], v[202:205], v[26:29]
	v_mfma_f32_16x16x32_bf16 v[14:17], v[146:149], v[210:213], v[14:17]
	v_mfma_f32_16x16x32_bf16 v[10:13], v[162:165], v[210:213], v[10:13]
	v_mfma_f32_16x16x32_bf16 v[62:65], v[158:161], v[190:193], v[62:65]
	v_mfma_f32_16x16x32_bf16 v[58:61], v[166:169], v[190:193], v[58:61]
	v_mfma_f32_16x16x32_bf16 v[46:49], v[158:161], v[198:201], v[46:49]
	v_mfma_f32_16x16x32_bf16 v[42:45], v[166:169], v[198:201], v[42:45]
	v_mfma_f32_16x16x32_bf16 v[30:33], v[158:161], v[206:209], v[30:33]
	v_mfma_f32_16x16x32_bf16 v[26:29], v[166:169], v[206:209], v[26:29]
	v_mfma_f32_16x16x32_bf16 v[14:17], v[158:161], v[214:217], v[14:17]
	v_mfma_f32_16x16x32_bf16 v[10:13], v[166:169], v[214:217], v[10:13]
	v_mfma_f32_16x16x32_bf16 v[54:57], v[170:173], v[186:189], v[54:57]
	v_mfma_f32_16x16x32_bf16 v[50:53], v[178:181], v[186:189], v[50:53]
	v_mfma_f32_16x16x32_bf16 v[38:41], v[170:173], v[194:197], v[38:41]
	v_mfma_f32_16x16x32_bf16 v[34:37], v[178:181], v[194:197], v[34:37]
	v_mfma_f32_16x16x32_bf16 v[22:25], v[170:173], v[202:205], v[22:25]
	v_mfma_f32_16x16x32_bf16 v[18:21], v[178:181], v[202:205], v[18:21]
	v_mfma_f32_16x16x32_bf16 v[6:9], v[170:173], v[210:213], v[6:9]
	v_mfma_f32_16x16x32_bf16 v[2:5], v[178:181], v[210:213], v[2:5]
	v_mfma_f32_16x16x32_bf16 v[54:57], v[174:177], v[190:193], v[54:57]
	v_mfma_f32_16x16x32_bf16 v[50:53], v[182:185], v[190:193], v[50:53]
	v_mfma_f32_16x16x32_bf16 v[38:41], v[174:177], v[198:201], v[38:41]
	v_mfma_f32_16x16x32_bf16 v[34:37], v[182:185], v[198:201], v[34:37]
	v_mfma_f32_16x16x32_bf16 v[22:25], v[174:177], v[206:209], v[22:25]
	v_mfma_f32_16x16x32_bf16 v[18:21], v[182:185], v[206:209], v[18:21]
	v_mfma_f32_16x16x32_bf16 v[6:9], v[174:177], v[214:217], v[6:9]
	v_mfma_f32_16x16x32_bf16 v[2:5], v[182:185], v[214:217], v[2:5]
	s_barrier
	s_add_i32 s59, 0, 0x18000
	s_add_i32 s60, 0, 0x1c000
	v_add_u32_e32 v166, s59, v153
	v_add_u32_e32 v182, s60, v153
	ds_read_b128 v[146:149], v166
	ds_read_b128 v[158:161], v166 offset:1024
	ds_read_b128 v[162:165], v166 offset:2048
	ds_read_b128 v[166:169], v166 offset:3072
	ds_read_b128 v[170:173], v182
	ds_read_b128 v[174:177], v182 offset:1024
	ds_read_b128 v[178:181], v182 offset:2048
	ds_read_b128 v[182:185], v182 offset:3072
	s_add_u32 s40, s40, 0x80000
	s_addc_u32 s41, s41, 0
	s_mov_b32 m0, s44
	v_lshl_add_u64 v[224:225], s[40:41], 0, v[136:137]
	ds_read_b128 v[186:189], v157 offset:32768
	ds_read_b128 v[190:193], v157 offset:33792
	ds_read_b128 v[194:197], v157 offset:34816
	ds_read_b128 v[198:201], v157 offset:35840
	ds_read_b128 v[202:205], v157 offset:36864
	ds_read_b128 v[206:209], v157 offset:37888
	ds_read_b128 v[210:213], v157 offset:38912
	ds_read_b128 v[214:217], v157 offset:39936
	global_load_lds_dwordx4 v[224:225], off
	v_lshl_add_u64 v[224:225], s[40:41], 0, v[132:133]
	s_mov_b32 m0, s45
	s_nop 0
	global_load_lds_dwordx4 v[224:225], off
	s_waitcnt vmcnt(8)
	s_waitcnt lgkmcnt(0)
	s_barrier
	s_waitcnt lgkmcnt(0)
	v_mfma_f32_16x16x32_bf16 v[126:129], v[146:149], v[186:189], v[126:129]
	v_mfma_f32_16x16x32_bf16 v[122:125], v[162:165], v[186:189], v[122:125]
	v_mfma_f32_16x16x32_bf16 v[110:113], v[146:149], v[194:197], v[110:113]
	v_mfma_f32_16x16x32_bf16 v[106:109], v[162:165], v[194:197], v[106:109]
	v_mfma_f32_16x16x32_bf16 v[94:97], v[146:149], v[202:205], v[94:97]
	v_mfma_f32_16x16x32_bf16 v[90:93], v[162:165], v[202:205], v[90:93]
	v_mfma_f32_16x16x32_bf16 v[78:81], v[146:149], v[210:213], v[78:81]
	v_mfma_f32_16x16x32_bf16 v[74:77], v[162:165], v[210:213], v[74:77]
	v_mfma_f32_16x16x32_bf16 v[126:129], v[158:161], v[190:193], v[126:129]
	v_mfma_f32_16x16x32_bf16 v[122:125], v[166:169], v[190:193], v[122:125]
	v_mfma_f32_16x16x32_bf16 v[110:113], v[158:161], v[198:201], v[110:113]
	v_mfma_f32_16x16x32_bf16 v[106:109], v[166:169], v[198:201], v[106:109]
	v_mfma_f32_16x16x32_bf16 v[94:97], v[158:161], v[206:209], v[94:97]
	v_mfma_f32_16x16x32_bf16 v[90:93], v[166:169], v[206:209], v[90:93]
	v_mfma_f32_16x16x32_bf16 v[78:81], v[158:161], v[214:217], v[78:81]
	v_mfma_f32_16x16x32_bf16 v[74:77], v[166:169], v[214:217], v[74:77]
	v_mfma_f32_16x16x32_bf16 v[118:121], v[170:173], v[186:189], v[118:121]
	v_mfma_f32_16x16x32_bf16 v[114:117], v[178:181], v[186:189], v[114:117]
	v_mfma_f32_16x16x32_bf16 v[102:105], v[170:173], v[194:197], v[102:105]
	v_mfma_f32_16x16x32_bf16 v[98:101], v[178:181], v[194:197], v[98:101]
	v_mfma_f32_16x16x32_bf16 v[86:89], v[170:173], v[202:205], v[86:89]
	v_mfma_f32_16x16x32_bf16 v[82:85], v[178:181], v[202:205], v[82:85]
	v_mfma_f32_16x16x32_bf16 v[70:73], v[170:173], v[210:213], v[70:73]
	v_mfma_f32_16x16x32_bf16 v[66:69], v[178:181], v[210:213], v[66:69]
	v_mfma_f32_16x16x32_bf16 v[118:121], v[174:177], v[190:193], v[118:121]
	v_mfma_f32_16x16x32_bf16 v[114:117], v[182:185], v[190:193], v[114:117]
	v_mfma_f32_16x16x32_bf16 v[102:105], v[174:177], v[198:201], v[102:105]
	v_mfma_f32_16x16x32_bf16 v[98:101], v[182:185], v[198:201], v[98:101]
	v_mfma_f32_16x16x32_bf16 v[86:89], v[174:177], v[206:209], v[86:89]
	v_mfma_f32_16x16x32_bf16 v[82:85], v[182:185], v[206:209], v[82:85]
	v_mfma_f32_16x16x32_bf16 v[70:73], v[174:177], v[214:217], v[70:73]
	v_mfma_f32_16x16x32_bf16 v[66:69], v[182:185], v[214:217], v[66:69]
	s_barrier
; #define PG8_STAGE(bufoff, gbase, voff) do { _Pragma("unroll") for (int _i = 0; _i < 2; ++_i) \
;         __builtin_amdgcn_global_load_lds((const unsigned*)((const char*)(gbase) + (voff)[_i]), (PG8_LAS unsigned*)(lds + (bufoff) + ldsw + _i * 8192), 16, 0, 0); } while (0)
; #define PG8_LDA(dst, b, h) do { _Pragma("unroll") for (int m = 0; m < 4; ++m) _Pragma("unroll") for (int k = 0; k < 2; ++k) dst[m][k] = *(const PG8_LAS bf16x8*)(lds + PG8_SA(b, h) + aoff + m * 2048 + k * 1024); } while (0)
; #define PG8_LDB(dst, b, h) do { _Pragma("unroll") for (int n = 0; n < 2; ++n) _Pragma("unroll") for (int k = 0; k < 2; ++k) dst[n][k] = *(const PG8_LAS bf16x8*)(lds + PG8_SB(b, h) + boff + n * 2048 + k * 1024); } while (0)
; #define PG8_MMA(ai, bj, At, Bt) do { __builtin_amdgcn_s_setprio(1); _Pragma("unroll") for (int m = 0; m < 4; ++m) _Pragma("unroll") for (int n = 0; n < 2; ++n) _Pragma("unroll") for (int k = 0; k < 2; ++k) \
;         acc[ai][bj][m][n] = __builtin_amdgcn_mfma_f32_16x16x32_bf16(Bt[n][k], At[m][k], acc[ai][bj][m][n], 0, 0, 0); __builtin_amdgcn_s_setprio(0); } while (0)
; #define PG8_WAIT_V(n) asm volatile("s_waitcnt vmcnt(" #n ")" ::: "memory")
; template <class Epi, class Sched, bool ALIGN_EPI = false, bool SP2 = false>
; __device__ __forceinline__ void gemm_phase(PG8_LAS unsigned char* lds, const Gemm g, const Sched& S, const Epi& E) {
;     ...
;             PG8_LDB(B0, 0, 0); PG8_LDB(B1, 0, 1); PG8_SCHED; PG8_LDA(At, 0, 0); PG8_STAGE(PG8_SA(1, 1), a1 + hstep, voffA);
;             PG8_WAIT_V(8); PG8_WAIT_L(0); PG8_BAR; PG8_MMA(0, 0, At, B0); PG8_MMA(0, 1, At, B1); PG8_BAR; PG8_SCHED;
;             PG8_LDA(At, 0, 1); PG8_STAGE(PG8_SB(0, 0), b2, voffB); PG8_STAGE(PG8_SB(0, 1), b2 + hstep, voffB); PG8_STAGE(PG8_SA(0, 0), a2, voffA);
;             PG8_WAIT_V(8); PG8_WAIT_L(0); PG8_BAR; PG8_MMA(1, 0, At, B0); PG8_MMA(1, 1, At, B1); PG8_BAR; PG8_SCHED;
;             PG8_LDB(B0, 1, 0); PG8_LDB(B1, 1, 1); PG8_SCHED; PG8_LDA(At, 1, 0); PG8_STAGE(PG8_SA(0, 1), a2 + hstep, voffA);
;             PG8_WAIT_V(8); PG8_WAIT_L(0); PG8_BAR; PG8_MMA(0, 0, At, B0); PG8_MMA(0, 1, At, B1); PG8_BAR; PG8_SCHED;
;             PG8_LDA(At, 1, 1); PG8_STAGE(PG8_SB(1, 0), b3, voffB); PG8_STAGE(PG8_SB(1, 1), b3 + hstep, voffB); PG8_STAGE(PG8_SA(1, 0), a3, voffA);
;             PG8_WAIT_V(8); PG8_WAIT_L(0); PG8_BAR; PG8_MMA(1, 0, At, B0); PG8_MMA(1, 1, At, B1); PG8_BAR; PG8_SCHED;
	s_add_i32 s40, s59, s3
	v_lshl_add_u64 v[150:151], v[150:151], 0, s[12:13]
	s_mov_b32 m0, s40
	ds_read_b128 v[186:189], v157 offset:49152
	ds_read_b128 v[190:193], v157 offset:50176
	ds_read_b128 v[194:197], v157 offset:51200
	ds_read_b128 v[198:201], v157 offset:52224
	ds_read_b128 v[202:205], v157 offset:53248
	ds_read_b128 v[206:209], v157 offset:54272
	ds_read_b128 v[210:213], v157 offset:55296
	ds_read_b128 v[214:217], v157 offset:56320
	global_load_lds_dwordx4 v[150:151], off
	s_add_i32 m0, s40, 0x2000
	s_add_u32 s38, s38, 0x80080
	v_lshl_add_u64 v[150:151], v[218:219], 0, s[12:13]
	s_addc_u32 s39, s39, 0
	s_add_i32 s40, s60, s3
	global_load_lds_dwordx4 v[150:151], off
	v_lshl_add_u64 v[150:151], s[38:39], 0, v[134:135]
	s_mov_b32 m0, s40
	s_nop 0
	global_load_lds_dwordx4 v[150:151], off
	v_lshl_add_u64 v[150:151], s[38:39], 0, v[130:131]
	s_add_i32 m0, s40, 0x2000
	s_nop 0
	global_load_lds_dwordx4 v[150:151], off
	v_lshl_add_u64 v[150:151], v[220:221], 0, s[12:13]
	s_mov_b32 m0, s48
	s_nop 0
	global_load_lds_dwordx4 v[150:151], off
	v_lshl_add_u64 v[150:151], v[222:223], 0, s[12:13]
	s_mov_b32 m0, s49
	s_nop 0
	global_load_lds_dwordx4 v[150:151], off
	s_waitcnt vmcnt(8)
	s_waitcnt lgkmcnt(0)
	s_barrier
	s_waitcnt lgkmcnt(0)
	v_mfma_f32_16x16x32_bf16 v[62:65], v[146:149], v[186:189], v[62:65]
	v_mfma_f32_16x16x32_bf16 v[58:61], v[162:165], v[186:189], v[58:61]
	v_mfma_f32_16x16x32_bf16 v[46:49], v[146:149], v[194:197], v[46:49]
	v_mfma_f32_16x16x32_bf16 v[42:45], v[162:165], v[194:197], v[42:45]
	v_mfma_f32_16x16x32_bf16 v[30:33], v[146:149], v[202:205], v[30:33]
	v_mfma_f32_16x16x32_bf16 v[26:29], v[162:165], v[202:205], v[26:29]
	v_mfma_f32_16x16x32_bf16 v[14:17], v[146:149], v[210:213], v[14:17]
	v_mfma_f32_16x16x32_bf16 v[10:13], v[162:165], v[210:213], v[10:13]
	v_mfma_f32_16x16x32_bf16 v[62:65], v[158:161], v[190:193], v[62:65]
	v_mfma_f32_16x16x32_bf16 v[58:61], v[166:169], v[190:193], v[58:61]
	v_mfma_f32_16x16x32_bf16 v[46:49], v[158:161], v[198:201], v[46:49]
	v_mfma_f32_16x16x32_bf16 v[42:45], v[166:169], v[198:201], v[42:45]
	v_mfma_f32_16x16x32_bf16 v[30:33], v[158:161], v[206:209], v[30:33]
	v_mfma_f32_16x16x32_bf16 v[26:29], v[166:169], v[206:209], v[26:29]
	v_mfma_f32_16x16x32_bf16 v[14:17], v[158:161], v[214:217], v[14:17]
	v_mfma_f32_16x16x32_bf16 v[10:13], v[166:169], v[214:217], v[10:13]
	v_mfma_f32_16x16x32_bf16 v[54:57], v[170:173], v[186:189], v[54:57]
	v_mfma_f32_16x16x32_bf16 v[50:53], v[178:181], v[186:189], v[50:53]
	v_mfma_f32_16x16x32_bf16 v[38:41], v[170:173], v[194:197], v[38:41]
	v_mfma_f32_16x16x32_bf16 v[34:37], v[178:181], v[194:197], v[34:37]
	v_mfma_f32_16x16x32_bf16 v[22:25], v[170:173], v[202:205], v[22:25]
	v_mfma_f32_16x16x32_bf16 v[18:21], v[178:181], v[202:205], v[18:21]
	v_mfma_f32_16x16x32_bf16 v[6:9], v[170:173], v[210:213], v[6:9]
	v_mfma_f32_16x16x32_bf16 v[2:5], v[178:181], v[210:213], v[2:5]
	v_mfma_f32_16x16x32_bf16 v[54:57], v[174:177], v[190:193], v[54:57]
	v_mfma_f32_16x16x32_bf16 v[50:53], v[182:185], v[190:193], v[50:53]
	v_mfma_f32_16x16x32_bf16 v[38:41], v[174:177], v[198:201], v[38:41]
	v_mfma_f32_16x16x32_bf16 v[34:37], v[182:185], v[198:201], v[34:37]
	v_mfma_f32_16x16x32_bf16 v[22:25], v[174:177], v[206:209], v[22:25]
	v_mfma_f32_16x16x32_bf16 v[18:21], v[182:185], v[206:209], v[18:21]
	v_mfma_f32_16x16x32_bf16 v[6:9], v[174:177], v[214:217], v[6:9]
	v_mfma_f32_16x16x32_bf16 v[2:5], v[182:185], v[214:217], v[2:5]
	s_barrier
	s_add_i32 s58, s58, 2
	s_add_u32 s36, s36, 0x100
	s_addc_u32 s37, s37, 0
	s_add_u32 s56, s56, 0x100
	s_addc_u32 s57, s57, 0
	s_cmp_gt_u32 s58, 29
	s_cbranch_scc0 .LBB0_1820
	s_and_b64 vcc, exec, s[14:15]
	s_cbranch_vccz .LBB0_1823
	s_barrier

; #define PG8_STAGE(bufoff, gbase, voff) do { _Pragma("unroll") for (int _i = 0; _i < 2; ++_i) \
;         __builtin_amdgcn_global_load_lds((const unsigned*)((const char*)(gbase) + (voff)[_i]), (PG8_LAS unsigned*)(lds + (bufoff) + ldsw + _i * 8192), 16, 0, 0); } while (0)
; #define PG8_LDA(dst, b, h) do { _Pragma("unroll") for (int m = 0; m < 4; ++m) _Pragma("unroll") for (int k = 0; k < 2; ++k) dst[m][k] = *(const PG8_LAS bf16x8*)(lds + PG8_SA(b, h) + aoff + m * 2048 + k * 1024); } while (0)
; #define PG8_LDB(dst, b, h) do { _Pragma("unroll") for (int n = 0; n < 2; ++n) _Pragma("unroll") for (int k = 0; k < 2; ++k) dst[n][k] = *(const PG8_LAS bf16x8*)(lds + PG8_SB(b, h) + boff + n * 2048 + k * 1024); } while (0)
; #define PG8_MMA(ai, bj, At, Bt) do { __builtin_amdgcn_s_setprio(1); _Pragma("unroll") for (int m = 0; m < 4; ++m) _Pragma("unroll") for (int n = 0; n < 2; ++n) _Pragma("unroll") for (int k = 0; k < 2; ++k) \
;         acc[ai][bj][m][n] = __builtin_amdgcn_mfma_f32_16x16x32_bf16(Bt[n][k], At[m][k], acc[ai][bj][m][n], 0, 0, 0); __builtin_amdgcn_s_setprio(0); } while (0)
; #define PG8_WAIT_V(n) asm volatile("s_waitcnt vmcnt(" #n ")" ::: "memory")
; template <class Epi, class Sched, bool ALIGN_EPI = false, bool SP2 = false>
; __device__ __forceinline__ void gemm_phase(PG8_LAS unsigned char* lds, const Gemm g, const Sched& S, const Epi& E) {
;     ...
;             PG8_LDB(B0, 0, 0); PG8_LDB(B1, 0, 1); PG8_SCHED; PG8_LDA(At, 0, 0); PG8_STAGE(PG8_SA(1, 1), a1 + hstep, voffA);
;             PG8_WAIT_V(8); PG8_WAIT_L(0); PG8_BAR; PG8_MMA(0, 0, At, B0); PG8_MMA(0, 1, At, B1); PG8_BAR; PG8_SCHED;
;             PG8_LDA(At, 0, 1); PG8_STAGE(PG8_SB(0, 0), b2, voffB); PG8_STAGE(PG8_SB(0, 1), b2 + hstep, voffB); PG8_STAGE(PG8_SA(0, 0), a2, voffA);
;             PG8_WAIT_V(8); PG8_WAIT_L(0); PG8_BAR; PG8_MMA(1, 0, At, B0); PG8_MMA(1, 1, At, B1); PG8_BAR; PG8_SCHED;
;             PG8_LDB(B0, 1, 0); PG8_LDB(B1, 1, 1); PG8_SCHED; PG8_LDA(At, 1, 0); PG8_STAGE(PG8_SA(0, 1), a2 + hstep, voffA);
;             PG8_WAIT_V(8); PG8_WAIT_L(0); PG8_BAR; PG8_MMA(0, 0, At, B0); PG8_MMA(0, 1, At, B1); PG8_BAR; PG8_SCHED;
;             PG8_LDA(At, 1, 1); PG8_STAGE(PG8_SB(1, 0), b3, voffB); PG8_STAGE(PG8_SB(1, 1), b3 + hstep, voffB); PG8_STAGE(PG8_SA(1, 0), a3, voffA);
;             PG8_WAIT_V(8); PG8_WAIT_L(0); PG8_BAR; PG8_MMA(1, 0, At, B0); PG8_MMA(1, 1, At, B1); PG8_BAR; PG8_SCHED;
.LBB0_1840:
	s_add_u32 s25, s12, s3
	s_addc_u32 s27, s13, 0
	s_add_u32 s42, s25, 0x100
	s_addc_u32 s43, s27, 0
	s_and_b64 s[40:41], s[38:39], exec
	s_cselect_b32 s43, s29, s43
	s_cselect_b32 s42, s28, s42
	s_add_u32 s3, s8, s3
	s_addc_u32 s40, s9, 0
	s_add_u32 s3, s3, 0x100
	s_addc_u32 s40, s40, 0
	s_and_b64 s[38:39], s[38:39], exec
	s_cselect_b32 s45, s31, s40
	s_cselect_b32 s44, s30, s3
	s_add_u32 s48, s25, 0x80080
	ds_read_b128 v[140:143], v137
	ds_read_b128 v[144:147], v137 offset:1024
	ds_read_b128 v[148:151], v137 offset:2048
	ds_read_b128 v[152:155], v137 offset:3072
	ds_read_b128 v[156:159], v138
	ds_read_b128 v[160:163], v138 offset:1024
	ds_read_b128 v[164:167], v138 offset:2048
	ds_read_b128 v[168:171], v138 offset:3072
	s_addc_u32 s49, s27, 0
	s_add_i32 s74, s63, s51
	s_add_i32 m0, s54, 0xc000
	s_add_i32 s77, s54, 0xe000
	s_add_i32 s71, s74, 0x2000
	s_add_u32 s46, s44, 0x80000
	s_addc_u32 s47, s45, 0
	s_add_i32 s73, s64, s51
	s_add_i32 s72, s73, 0x2000
	s_add_i32 s70, 0, 0x18000
	s_add_i32 s27, 0, 0x1c000
	s_add_u32 s40, s42, 0x80000
	s_addc_u32 s41, s43, 0
	s_add_i32 s25, s70, s51
	s_add_i32 s3, s25, 0x2000
	s_add_u32 s38, s44, 0x80080
	s_addc_u32 s39, s45, 0
	s_add_i32 s76, s27, s51
	s_add_i32 s75, s76, 0x2000
	v_lshl_add_u64 v[204:205], s[48:49], 0, v[132:133]
	ds_read_b128 v[172:175], v139
	ds_read_b128 v[176:179], v139 offset:1024
	ds_read_b128 v[180:183], v139 offset:2048
	ds_read_b128 v[184:187], v139 offset:3072
	ds_read_b128 v[188:191], v139 offset:4096
	ds_read_b128 v[192:195], v139 offset:5120
	ds_read_b128 v[196:199], v139 offset:6144
	ds_read_b128 v[200:203], v139 offset:7168
	global_load_lds_dwordx4 v[204:205], off
	v_lshl_add_u64 v[204:205], s[48:49], 0, v[130:131]
	s_mov_b32 m0, s77
	s_nop 0
	global_load_lds_dwordx4 v[204:205], off
	s_waitcnt vmcnt(8)
	s_waitcnt lgkmcnt(0)
	s_barrier
	s_waitcnt lgkmcnt(0)
	v_mfma_f32_16x16x32_bf16 v[126:129], v[140:143], v[172:175], v[126:129]
	v_mfma_f32_16x16x32_bf16 v[122:125], v[148:151], v[172:175], v[122:125]
	v_mfma_f32_16x16x32_bf16 v[118:121], v[140:143], v[180:183], v[118:121]
	v_mfma_f32_16x16x32_bf16 v[114:117], v[148:151], v[180:183], v[114:117]
	v_mfma_f32_16x16x32_bf16 v[106:109], v[140:143], v[188:191], v[106:109]
	v_mfma_f32_16x16x32_bf16 v[98:101], v[148:151], v[188:191], v[98:101]
	v_mfma_f32_16x16x32_bf16 v[90:93], v[140:143], v[196:199], v[90:93]
	v_mfma_f32_16x16x32_bf16 v[82:85], v[148:151], v[196:199], v[82:85]
	v_mfma_f32_16x16x32_bf16 v[126:129], v[144:147], v[176:179], v[126:129]
	v_mfma_f32_16x16x32_bf16 v[122:125], v[152:155], v[176:179], v[122:125]
	v_mfma_f32_16x16x32_bf16 v[118:121], v[144:147], v[184:187], v[118:121]
	v_mfma_f32_16x16x32_bf16 v[114:117], v[152:155], v[184:187], v[114:117]
	v_mfma_f32_16x16x32_bf16 v[106:109], v[144:147], v[192:195], v[106:109]
	v_mfma_f32_16x16x32_bf16 v[98:101], v[152:155], v[192:195], v[98:101]
	v_mfma_f32_16x16x32_bf16 v[90:93], v[144:147], v[200:203], v[90:93]
	v_mfma_f32_16x16x32_bf16 v[82:85], v[152:155], v[200:203], v[82:85]
	v_mfma_f32_16x16x32_bf16 v[110:113], v[156:159], v[172:175], v[110:113]
	v_mfma_f32_16x16x32_bf16 v[102:105], v[164:167], v[172:175], v[102:105]
	v_mfma_f32_16x16x32_bf16 v[94:97], v[156:159], v[180:183], v[94:97]
	v_mfma_f32_16x16x32_bf16 v[86:89], v[164:167], v[180:183], v[86:89]
	v_mfma_f32_16x16x32_bf16 v[78:81], v[156:159], v[188:191], v[78:81]
	v_mfma_f32_16x16x32_bf16 v[74:77], v[164:167], v[188:191], v[74:77]
	v_mfma_f32_16x16x32_bf16 v[70:73], v[156:159], v[196:199], v[70:73]
	v_mfma_f32_16x16x32_bf16 v[66:69], v[164:167], v[196:199], v[66:69]
	v_mfma_f32_16x16x32_bf16 v[110:113], v[160:163], v[176:179], v[110:113]
	v_mfma_f32_16x16x32_bf16 v[102:105], v[168:171], v[176:179], v[102:105]
	v_mfma_f32_16x16x32_bf16 v[94:97], v[160:163], v[184:187], v[94:97]
	v_mfma_f32_16x16x32_bf16 v[86:89], v[168:171], v[184:187], v[86:89]
	v_mfma_f32_16x16x32_bf16 v[78:81], v[160:163], v[192:195], v[78:81]
	v_mfma_f32_16x16x32_bf16 v[74:77], v[168:171], v[192:195], v[74:77]
	v_mfma_f32_16x16x32_bf16 v[70:73], v[160:163], v[200:203], v[70:73]
	v_mfma_f32_16x16x32_bf16 v[66:69], v[168:171], v[200:203], v[66:69]
	s_barrier
	s_mov_b32 m0, s74
	v_lshl_add_u64 v[204:205], s[44:45], 0, v[132:133]
	ds_read_b128 v[172:175], v139 offset:16384
	ds_read_b128 v[176:179], v139 offset:17408
	ds_read_b128 v[180:183], v139 offset:18432
	ds_read_b128 v[184:187], v139 offset:19456
	ds_read_b128 v[188:191], v139 offset:20480
	ds_read_b128 v[192:195], v139 offset:21504
	ds_read_b128 v[196:199], v139 offset:22528
	ds_read_b128 v[200:203], v139 offset:23552
	global_load_lds_dwordx4 v[204:205], off
	v_lshl_add_u64 v[206:207], s[44:45], 0, v[130:131]
	s_mov_b32 m0, s71
	v_lshl_add_u64 v[208:209], s[46:47], 0, v[132:133]
	global_load_lds_dwordx4 v[206:207], off
	s_mov_b32 m0, s73
	v_lshl_add_u64 v[210:211], s[42:43], 0, v[130:131]
	global_load_lds_dwordx4 v[208:209], off
	v_lshl_add_u64 v[208:209], s[46:47], 0, v[130:131]
	s_mov_b32 m0, s72
	s_nop 0
	global_load_lds_dwordx4 v[208:209], off
	v_lshl_add_u64 v[208:209], s[42:43], 0, v[132:133]
	s_mov_b32 m0, s54
	s_nop 0
	global_load_lds_dwordx4 v[208:209], off
	s_mov_b32 m0, s55
	s_nop 0
	global_load_lds_dwordx4 v[210:211], off
	s_waitcnt vmcnt(8)
	s_waitcnt lgkmcnt(0)
	s_barrier
; #define PG8_STAGE(bufoff, gbase, voff) do { _Pragma("unroll") for (int _i = 0; _i < 2; ++_i) \
;         __builtin_amdgcn_global_load_lds((const unsigned*)((const char*)(gbase) + (voff)[_i]), (PG8_LAS unsigned*)(lds + (bufoff) + ldsw + _i * 8192), 16, 0, 0); } while (0)
; #define PG8_LDA(dst, b, h) do { _Pragma("unroll") for (int m = 0; m < 4; ++m) _Pragma("unroll") for (int k = 0; k < 2; ++k) dst[m][k] = *(const PG8_LAS bf16x8*)(lds + PG8_SA(b, h) + aoff + m * 2048 + k * 1024); } while (0)
; #define PG8_LDB(dst, b, h) do { _Pragma("unroll") for (int n = 0; n < 2; ++n) _Pragma("unroll") for (int k = 0; k < 2; ++k) dst[n][k] = *(const PG8_LAS bf16x8*)(lds + PG8_SB(b, h) + boff + n * 2048 + k * 1024); } while (0)
; #define PG8_MMA(ai, bj, At, Bt) do { __builtin_amdgcn_s_setprio(1); _Pragma("unroll") for (int m = 0; m < 4; ++m) _Pragma("unroll") for (int n = 0; n < 2; ++n) _Pragma("unroll") for (int k = 0; k < 2; ++k) \
;         acc[ai][bj][m][n] = __builtin_amdgcn_mfma_f32_16x16x32_bf16(Bt[n][k], At[m][k], acc[ai][bj][m][n], 0, 0, 0); __builtin_amdgcn_s_setprio(0); } while (0)
; #define PG8_WAIT_V(n) asm volatile("s_waitcnt vmcnt(" #n ")" ::: "memory")
; template <class Epi, class Sched, bool ALIGN_EPI = false, bool SP2 = false>
; __device__ __forceinline__ void gemm_phase(PG8_LAS unsigned char* lds, const Gemm g, const Sched& S, const Epi& E) {
;     ...
;             PG8_LDB(B0, 0, 0); PG8_LDB(B1, 0, 1); PG8_SCHED; PG8_LDA(At, 0, 0); PG8_STAGE(PG8_SA(1, 1), a1 + hstep, voffA);
;             PG8_WAIT_V(8); PG8_WAIT_L(0); PG8_BAR; PG8_MMA(0, 0, At, B0); PG8_MMA(0, 1, At, B1); PG8_BAR; PG8_SCHED;
;             PG8_LDA(At, 0, 1); PG8_STAGE(PG8_SB(0, 0), b2, voffB); PG8_STAGE(PG8_SB(0, 1), b2 + hstep, voffB); PG8_STAGE(PG8_SA(0, 0), a2, voffA);
;             PG8_WAIT_V(8); PG8_WAIT_L(0); PG8_BAR; PG8_MMA(1, 0, At, B0); PG8_MMA(1, 1, At, B1); PG8_BAR; PG8_SCHED;
;             PG8_LDB(B0, 1, 0); PG8_LDB(B1, 1, 1); PG8_SCHED; PG8_LDA(At, 1, 0); PG8_STAGE(PG8_SA(0, 1), a2 + hstep, voffA);
;             PG8_WAIT_V(8); PG8_WAIT_L(0); PG8_BAR; PG8_MMA(0, 0, At, B0); PG8_MMA(0, 1, At, B1); PG8_BAR; PG8_SCHED;
;             PG8_LDA(At, 1, 1); PG8_STAGE(PG8_SB(1, 0), b3, voffB); PG8_STAGE(PG8_SB(1, 1), b3 + hstep, voffB); PG8_STAGE(PG8_SA(1, 0), a3, voffA);
;             PG8_WAIT_V(8); PG8_WAIT_L(0); PG8_BAR; PG8_MMA(1, 0, At, B0); PG8_MMA(1, 1, At, B1); PG8_BAR; PG8_SCHED;
	s_waitcnt lgkmcnt(0)
	v_mfma_f32_16x16x32_bf16 v[62:65], v[140:143], v[172:175], v[62:65]
	v_mfma_f32_16x16x32_bf16 v[58:61], v[148:151], v[172:175], v[58:61]
	v_mfma_f32_16x16x32_bf16 v[54:57], v[140:143], v[180:183], v[54:57]
	v_mfma_f32_16x16x32_bf16 v[50:53], v[148:151], v[180:183], v[50:53]
	v_mfma_f32_16x16x32_bf16 v[42:45], v[140:143], v[188:191], v[42:45]
	v_mfma_f32_16x16x32_bf16 v[34:37], v[148:151], v[188:191], v[34:37]
	v_mfma_f32_16x16x32_bf16 v[26:29], v[140:143], v[196:199], v[26:29]
	v_mfma_f32_16x16x32_bf16 v[18:21], v[148:151], v[196:199], v[18:21]
	v_mfma_f32_16x16x32_bf16 v[62:65], v[144:147], v[176:179], v[62:65]
	v_mfma_f32_16x16x32_bf16 v[58:61], v[152:155], v[176:179], v[58:61]
	v_mfma_f32_16x16x32_bf16 v[54:57], v[144:147], v[184:187], v[54:57]
	v_mfma_f32_16x16x32_bf16 v[50:53], v[152:155], v[184:187], v[50:53]
	v_mfma_f32_16x16x32_bf16 v[42:45], v[144:147], v[192:195], v[42:45]
	v_mfma_f32_16x16x32_bf16 v[34:37], v[152:155], v[192:195], v[34:37]
	v_mfma_f32_16x16x32_bf16 v[26:29], v[144:147], v[200:203], v[26:29]
	v_mfma_f32_16x16x32_bf16 v[18:21], v[152:155], v[200:203], v[18:21]
	v_mfma_f32_16x16x32_bf16 v[46:49], v[156:159], v[172:175], v[46:49]
	v_mfma_f32_16x16x32_bf16 v[38:41], v[164:167], v[172:175], v[38:41]
	v_mfma_f32_16x16x32_bf16 v[30:33], v[156:159], v[180:183], v[30:33]
	v_mfma_f32_16x16x32_bf16 v[22:25], v[164:167], v[180:183], v[22:25]
	v_mfma_f32_16x16x32_bf16 v[14:17], v[156:159], v[188:191], v[14:17]
	v_mfma_f32_16x16x32_bf16 v[10:13], v[164:167], v[188:191], v[10:13]
	v_mfma_f32_16x16x32_bf16 v[6:9], v[156:159], v[196:199], v[6:9]
	v_mfma_f32_16x16x32_bf16 v[2:5], v[164:167], v[196:199], v[2:5]
	v_mfma_f32_16x16x32_bf16 v[46:49], v[160:163], v[176:179], v[46:49]
	v_mfma_f32_16x16x32_bf16 v[38:41], v[168:171], v[176:179], v[38:41]
	v_mfma_f32_16x16x32_bf16 v[30:33], v[160:163], v[184:187], v[30:33]
	v_mfma_f32_16x16x32_bf16 v[22:25], v[168:171], v[184:187], v[22:25]
	v_mfma_f32_16x16x32_bf16 v[14:17], v[160:163], v[192:195], v[14:17]
	v_mfma_f32_16x16x32_bf16 v[10:13], v[168:171], v[192:195], v[10:13]
	v_mfma_f32_16x16x32_bf16 v[6:9], v[160:163], v[200:203], v[6:9]
	v_mfma_f32_16x16x32_bf16 v[2:5], v[168:171], v[200:203], v[2:5]
	s_barrier
	v_add_u32_e32 v152, s70, v134
	v_add_u32_e32 v168, s27, v134
	ds_read_b128 v[140:143], v152
	ds_read_b128 v[144:147], v152 offset:1024
	ds_read_b128 v[148:151], v152 offset:2048
	ds_read_b128 v[152:155], v152 offset:3072
	ds_read_b128 v[156:159], v168
	ds_read_b128 v[160:163], v168 offset:1024
	ds_read_b128 v[164:167], v168 offset:2048
	ds_read_b128 v[168:171], v168 offset:3072
	s_mov_b32 m0, s56
	v_lshl_add_u64 v[212:213], s[40:41], 0, v[132:133]
	ds_read_b128 v[172:175], v139 offset:32768
	ds_read_b128 v[176:179], v139 offset:33792
	ds_read_b128 v[180:183], v139 offset:34816
	ds_read_b128 v[184:187], v139 offset:35840
	ds_read_b128 v[188:191], v139 offset:36864
	ds_read_b128 v[192:195], v139 offset:37888
	ds_read_b128 v[196:199], v139 offset:38912
	ds_read_b128 v[200:203], v139 offset:39936
	global_load_lds_dwordx4 v[212:213], off
	v_lshl_add_u64 v[212:213], s[40:41], 0, v[130:131]
	s_mov_b32 m0, s57
	s_nop 0
	global_load_lds_dwordx4 v[212:213], off
	s_waitcnt vmcnt(8)
	s_waitcnt lgkmcnt(0)
	s_barrier
	s_waitcnt lgkmcnt(0)
	v_mfma_f32_16x16x32_bf16 v[126:129], v[140:143], v[172:175], v[126:129]
	v_mfma_f32_16x16x32_bf16 v[122:125], v[148:151], v[172:175], v[122:125]
	v_mfma_f32_16x16x32_bf16 v[118:121], v[140:143], v[180:183], v[118:121]
	v_mfma_f32_16x16x32_bf16 v[114:117], v[148:151], v[180:183], v[114:117]
	v_mfma_f32_16x16x32_bf16 v[106:109], v[140:143], v[188:191], v[106:109]
	v_mfma_f32_16x16x32_bf16 v[98:101], v[148:151], v[188:191], v[98:101]
	v_mfma_f32_16x16x32_bf16 v[90:93], v[140:143], v[196:199], v[90:93]
	v_mfma_f32_16x16x32_bf16 v[82:85], v[148:151], v[196:199], v[82:85]
	v_mfma_f32_16x16x32_bf16 v[126:129], v[144:147], v[176:179], v[126:129]
	v_mfma_f32_16x16x32_bf16 v[122:125], v[152:155], v[176:179], v[122:125]
	v_mfma_f32_16x16x32_bf16 v[118:121], v[144:147], v[184:187], v[118:121]
	v_mfma_f32_16x16x32_bf16 v[114:117], v[152:155], v[184:187], v[114:117]
	v_mfma_f32_16x16x32_bf16 v[106:109], v[144:147], v[192:195], v[106:109]
	v_mfma_f32_16x16x32_bf16 v[98:101], v[152:155], v[192:195], v[98:101]
	v_mfma_f32_16x16x32_bf16 v[90:93], v[144:147], v[200:203], v[90:93]
	v_mfma_f32_16x16x32_bf16 v[82:85], v[152:155], v[200:203], v[82:85]
	v_mfma_f32_16x16x32_bf16 v[110:113], v[156:159], v[172:175], v[110:113]
	v_mfma_f32_16x16x32_bf16 v[102:105], v[164:167], v[172:175], v[102:105]
	v_mfma_f32_16x16x32_bf16 v[94:97], v[156:159], v[180:183], v[94:97]
	v_mfma_f32_16x16x32_bf16 v[86:89], v[164:167], v[180:183], v[86:89]
	v_mfma_f32_16x16x32_bf16 v[78:81], v[156:159], v[188:191], v[78:81]
	v_mfma_f32_16x16x32_bf16 v[74:77], v[164:167], v[188:191], v[74:77]
	v_mfma_f32_16x16x32_bf16 v[70:73], v[156:159], v[196:199], v[70:73]
	v_mfma_f32_16x16x32_bf16 v[66:69], v[164:167], v[196:199], v[66:69]
	v_mfma_f32_16x16x32_bf16 v[110:113], v[160:163], v[176:179], v[110:113]
	v_mfma_f32_16x16x32_bf16 v[102:105], v[168:171], v[176:179], v[102:105]
	v_mfma_f32_16x16x32_bf16 v[94:97], v[160:163], v[184:187], v[94:97]
	v_mfma_f32_16x16x32_bf16 v[86:89], v[168:171], v[184:187], v[86:89]
	v_mfma_f32_16x16x32_bf16 v[78:81], v[160:163], v[192:195], v[78:81]
	v_mfma_f32_16x16x32_bf16 v[74:77], v[168:171], v[192:195], v[74:77]
	v_mfma_f32_16x16x32_bf16 v[70:73], v[160:163], v[200:203], v[70:73]
	v_mfma_f32_16x16x32_bf16 v[66:69], v[168:171], v[200:203], v[66:69]
	s_barrier
; #define PG8_STAGE(bufoff, gbase, voff) do { _Pragma("unroll") for (int _i = 0; _i < 2; ++_i) \
;         __builtin_amdgcn_global_load_lds((const unsigned*)((const char*)(gbase) + (voff)[_i]), (PG8_LAS unsigned*)(lds + (bufoff) + ldsw + _i * 8192), 16, 0, 0); } while (0)
; #define PG8_LDA(dst, b, h) do { _Pragma("unroll") for (int m = 0; m < 4; ++m) _Pragma("unroll") for (int k = 0; k < 2; ++k) dst[m][k] = *(const PG8_LAS bf16x8*)(lds + PG8_SA(b, h) + aoff + m * 2048 + k * 1024); } while (0)
; #define PG8_LDB(dst, b, h) do { _Pragma("unroll") for (int n = 0; n < 2; ++n) _Pragma("unroll") for (int k = 0; k < 2; ++k) dst[n][k] = *(const PG8_LAS bf16x8*)(lds + PG8_SB(b, h) + boff + n * 2048 + k * 1024); } while (0)
; #define PG8_MMA(ai, bj, At, Bt) do { __builtin_amdgcn_s_setprio(1); _Pragma("unroll") for (int m = 0; m < 4; ++m) _Pragma("unroll") for (int n = 0; n < 2; ++n) _Pragma("unroll") for (int k = 0; k < 2; ++k) \
;         acc[ai][bj][m][n] = __builtin_amdgcn_mfma_f32_16x16x32_bf16(Bt[n][k], At[m][k], acc[ai][bj][m][n], 0, 0, 0); __builtin_amdgcn_s_setprio(0); } while (0)
; #define PG8_WAIT_V(n) asm volatile("s_waitcnt vmcnt(" #n ")" ::: "memory")
; template <class Epi, class Sched, bool ALIGN_EPI = false, bool SP2 = false>
; __device__ __forceinline__ void gemm_phase(PG8_LAS unsigned char* lds, const Gemm g, const Sched& S, const Epi& E) {
;     ...
;             PG8_LDB(B0, 0, 0); PG8_LDB(B1, 0, 1); PG8_SCHED; PG8_LDA(At, 0, 0); PG8_STAGE(PG8_SA(1, 1), a1 + hstep, voffA);
;             PG8_WAIT_V(8); PG8_WAIT_L(0); PG8_BAR; PG8_MMA(0, 0, At, B0); PG8_MMA(0, 1, At, B1); PG8_BAR; PG8_SCHED;
;             PG8_LDA(At, 0, 1); PG8_STAGE(PG8_SB(0, 0), b2, voffB); PG8_STAGE(PG8_SB(0, 1), b2 + hstep, voffB); PG8_STAGE(PG8_SA(0, 0), a2, voffA);
;             PG8_WAIT_V(8); PG8_WAIT_L(0); PG8_BAR; PG8_MMA(1, 0, At, B0); PG8_MMA(1, 1, At, B1); PG8_BAR; PG8_SCHED;
;             PG8_LDB(B0, 1, 0); PG8_LDB(B1, 1, 1); PG8_SCHED; PG8_LDA(At, 1, 0); PG8_STAGE(PG8_SA(0, 1), a2 + hstep, voffA);
;             PG8_WAIT_V(8); PG8_WAIT_L(0); PG8_BAR; PG8_MMA(0, 0, At, B0); PG8_MMA(0, 1, At, B1); PG8_BAR; PG8_SCHED;
;             PG8_LDA(At, 1, 1); PG8_STAGE(PG8_SB(1, 0), b3, voffB); PG8_STAGE(PG8_SB(1, 1), b3 + hstep, voffB); PG8_STAGE(PG8_SA(1, 0), a3, voffA);
;             PG8_WAIT_V(8); PG8_WAIT_L(0); PG8_BAR; PG8_MMA(1, 0, At, B0); PG8_MMA(1, 1, At, B1); PG8_BAR; PG8_SCHED;
	s_mov_b32 m0, s25
	v_lshl_add_u64 v[204:205], v[204:205], 0, s[10:11]
	ds_read_b128 v[172:175], v139 offset:49152
	ds_read_b128 v[176:179], v139 offset:50176
	ds_read_b128 v[180:183], v139 offset:51200
	ds_read_b128 v[184:187], v139 offset:52224
	ds_read_b128 v[188:191], v139 offset:53248
	ds_read_b128 v[192:195], v139 offset:54272
	ds_read_b128 v[196:199], v139 offset:55296
	ds_read_b128 v[200:203], v139 offset:56320
	global_load_lds_dwordx4 v[204:205], off
	v_lshl_add_u64 v[204:205], v[206:207], 0, s[10:11]
	s_mov_b32 m0, s3
	s_nop 0
	global_load_lds_dwordx4 v[204:205], off
	v_lshl_add_u64 v[204:205], s[38:39], 0, v[132:133]
	s_mov_b32 m0, s76
	s_nop 0
	global_load_lds_dwordx4 v[204:205], off
	v_lshl_add_u64 v[204:205], s[38:39], 0, v[130:131]
	s_mov_b32 m0, s75
	s_nop 0
	global_load_lds_dwordx4 v[204:205], off
	v_lshl_add_u64 v[204:205], v[208:209], 0, s[10:11]
	s_mov_b32 m0, s60
	s_nop 0
	global_load_lds_dwordx4 v[204:205], off
	v_lshl_add_u64 v[204:205], v[210:211], 0, s[10:11]
	s_mov_b32 m0, s61
	s_nop 0
	global_load_lds_dwordx4 v[204:205], off
	s_waitcnt vmcnt(8)
	s_waitcnt lgkmcnt(0)
	s_barrier
	s_waitcnt lgkmcnt(0)
	v_mfma_f32_16x16x32_bf16 v[62:65], v[140:143], v[172:175], v[62:65]
	v_mfma_f32_16x16x32_bf16 v[58:61], v[148:151], v[172:175], v[58:61]
	v_mfma_f32_16x16x32_bf16 v[54:57], v[140:143], v[180:183], v[54:57]
	v_mfma_f32_16x16x32_bf16 v[50:53], v[148:151], v[180:183], v[50:53]
	v_mfma_f32_16x16x32_bf16 v[42:45], v[140:143], v[188:191], v[42:45]
	v_mfma_f32_16x16x32_bf16 v[34:37], v[148:151], v[188:191], v[34:37]
	v_mfma_f32_16x16x32_bf16 v[26:29], v[140:143], v[196:199], v[26:29]
	v_mfma_f32_16x16x32_bf16 v[18:21], v[148:151], v[196:199], v[18:21]
	v_mfma_f32_16x16x32_bf16 v[62:65], v[144:147], v[176:179], v[62:65]
	v_mfma_f32_16x16x32_bf16 v[58:61], v[152:155], v[176:179], v[58:61]
	v_mfma_f32_16x16x32_bf16 v[54:57], v[144:147], v[184:187], v[54:57]
	v_mfma_f32_16x16x32_bf16 v[50:53], v[152:155], v[184:187], v[50:53]
	v_mfma_f32_16x16x32_bf16 v[42:45], v[144:147], v[192:195], v[42:45]
	v_mfma_f32_16x16x32_bf16 v[34:37], v[152:155], v[192:195], v[34:37]
	v_mfma_f32_16x16x32_bf16 v[26:29], v[144:147], v[200:203], v[26:29]
	v_mfma_f32_16x16x32_bf16 v[18:21], v[152:155], v[200:203], v[18:21]
	v_mfma_f32_16x16x32_bf16 v[46:49], v[156:159], v[172:175], v[46:49]
	v_mfma_f32_16x16x32_bf16 v[38:41], v[164:167], v[172:175], v[38:41]
	v_mfma_f32_16x16x32_bf16 v[30:33], v[156:159], v[180:183], v[30:33]
	v_mfma_f32_16x16x32_bf16 v[22:25], v[164:167], v[180:183], v[22:25]
	v_mfma_f32_16x16x32_bf16 v[14:17], v[156:159], v[188:191], v[14:17]
	v_mfma_f32_16x16x32_bf16 v[10:13], v[164:167], v[188:191], v[10:13]
	v_mfma_f32_16x16x32_bf16 v[6:9], v[156:159], v[196:199], v[6:9]
	v_mfma_f32_16x16x32_bf16 v[2:5], v[164:167], v[196:199], v[2:5]
	v_mfma_f32_16x16x32_bf16 v[46:49], v[160:163], v[176:179], v[46:49]
	v_mfma_f32_16x16x32_bf16 v[38:41], v[168:171], v[176:179], v[38:41]
	v_mfma_f32_16x16x32_bf16 v[30:33], v[160:163], v[184:187], v[30:33]
	v_mfma_f32_16x16x32_bf16 v[22:25], v[168:171], v[184:187], v[22:25]
	v_mfma_f32_16x16x32_bf16 v[14:17], v[160:163], v[192:195], v[14:17]
	v_mfma_f32_16x16x32_bf16 v[10:13], v[168:171], v[192:195], v[10:13]
	v_mfma_f32_16x16x32_bf16 v[6:9], v[160:163], v[200:203], v[6:9]
	v_mfma_f32_16x16x32_bf16 v[2:5], v[168:171], v[200:203], v[2:5]
	s_barrier
	s_movk_i32 s3, 0x100
	s_andn2_b64 vcc, exec, s[36:37]
	s_mov_b64 s[38:39], -1
	s_mov_b64 s[36:37], 0
	s_cbranch_vccz .LBB0_1840
	s_and_b64 vcc, exec, s[14:15]
	s_cbranch_vccz .LBB0_1843
	s_barrier
